# LRU gate constant folding (log2e pre-scaled into bias/decay) + v_cvt_pk_bf16_f32 replaces RNE bit-trick pairs
# speedup vs baseline: 1.0776x; 1.0035x over previous
.LBB0_18:
	s_or_b64 exec, exec, s[4:5]
	s_barrier
	s_waitcnt vmcnt(0)
	ds_write_b32 v24, v0
	ds_write_b32 v24, v1 offset:1040
	ds_write_b32 v24, v2 offset:2080
	ds_write_b32 v24, v3 offset:3120
	ds_write_b32 v24, v4 offset:4160
	ds_write_b32 v24, v5 offset:5200
	ds_write_b32 v24, v6 offset:6240
	ds_write_b32 v24, v7 offset:7280
	ds_write_b32 v24, v8 offset:8320
	ds_write_b32 v24, v9 offset:9360
	ds_write_b32 v24, v10 offset:10400
	ds_write_b32 v24, v11 offset:11440
	ds_write_b32 v24, v12 offset:12480
	ds_write_b32 v24, v13 offset:13520
	ds_write_b32 v24, v14 offset:14560
	ds_write_b32 v24, v15 offset:15600
	s_waitcnt lgkmcnt(0)
	s_barrier
	ds_read2_b32 v[6:7], v23 offset1:32
	ds_read2_b32 v[8:9], v23 offset0:65 offset1:97
	ds_read2_b32 v[10:11], v23 offset0:130 offset1:162
	ds_read2_b32 v[12:13], v23 offset0:195 offset1:227
	v_add_u32_e32 v30, s14, v22
	v_and_b32_e32 v30, -2, v30
	s_ashr_i32 s3, s2, 31
	v_add_u32_e32 v0, 0x400, v23
	v_ashrrev_i32_e32 v31, 31, v30
	v_lshl_add_u64 v[4:5], s[2:3], 2, v[16:17]
	ds_read2_b32 v[14:15], v0 offset0:4 offset1:36
	ds_read2_b32 v[18:19], v0 offset0:69 offset1:101
	ds_read2_b32 v[26:27], v0 offset0:134 offset1:166
	ds_read2_b32 v[28:29], v0 offset0:199 offset1:231
	v_lshlrev_b64 v[0:1], 11, v[30:31]
	v_lshl_add_u64 v[32:33], v[4:5], 0, v[0:1]
	s_waitcnt lgkmcnt(7)
	s_nop 1
	s_waitcnt lgkmcnt(4)
	s_nop 7
	v_cvt_pk_bf16_f32 v1, v10, v12
	v_cvt_pk_bf16_f32 v0, v6, v8
	s_waitcnt lgkmcnt(3)
	s_nop 1
	s_waitcnt lgkmcnt(0)
	s_nop 7
	v_cvt_pk_bf16_f32 v3, v26, v28
	v_cvt_pk_bf16_f32 v2, v14, v18
	global_store_dwordx4 v[32:33], v[0:3], off
	s_add_i32 s13, s13, s6
	s_add_i32 s7, s7, s8
	v_add_u32_e32 v0, 32, v30
	v_ashrrev_i32_e32 v1, 31, v0
	v_lshlrev_b64 v[0:1], 11, v[0:1]
	v_lshl_add_u64 v[4:5], v[4:5], 0, v[0:1]
	s_nop 9
	v_cvt_pk_bf16_f32 v1, v11, v13
	v_cvt_pk_bf16_f32 v0, v7, v9
	s_nop 9
	v_cvt_pk_bf16_f32 v3, v27, v29
	v_cvt_pk_bf16_f32 v2, v15, v19
	s_cmpk_lt_i32 s13, 0x310
	global_store_dwordx4 v[4:5], v[0:3], off
	s_cbranch_scc0 .LBB0_51

.LBB0_53:
	s_or_b64 exec, exec, s[4:5]
	s_sub_i32 s4, 0, s3
	s_barrier
	s_waitcnt vmcnt(0)
	ds_write_b32 v26, v0
	ds_write_b32 v26, v1 offset:1040
	ds_write_b32 v26, v2 offset:2080
	ds_write_b32 v26, v3 offset:3120
	ds_write_b32 v26, v4 offset:4160
	ds_write_b32 v26, v5 offset:5200
	ds_write_b32 v26, v6 offset:6240
	ds_write_b32 v26, v7 offset:7280
	ds_write_b32 v26, v8 offset:8320
	ds_write_b32 v26, v9 offset:9360
	ds_write_b32 v26, v10 offset:10400
	ds_write_b32 v26, v11 offset:11440
	ds_write_b32 v26, v12 offset:12480
	ds_write_b32 v26, v13 offset:13520
	ds_write_b32 v26, v14 offset:14560
	ds_write_b32 v26, v15 offset:15600
	s_waitcnt lgkmcnt(0)
	s_barrier
	ds_read2_b32 v[6:7], v25 offset1:32
	ds_read2_b32 v[8:9], v25 offset0:65 offset1:97
	ds_read2_b32 v[10:11], v25 offset0:130 offset1:162
	ds_read2_b32 v[12:13], v25 offset0:195 offset1:227
	s_add_i32 s4, s4, s7
	v_add_u32_e32 v30, s4, v24
	s_ashr_i32 s3, s2, 31
	v_add_u32_e32 v0, 0x400, v25
	v_ashrrev_i32_e32 v31, 31, v30
	v_lshl_add_u64 v[4:5], s[2:3], 1, v[16:17]
	ds_read2_b32 v[14:15], v0 offset0:4 offset1:36
	ds_read2_b32 v[18:19], v0 offset0:69 offset1:101
	ds_read2_b32 v[20:21], v0 offset0:134 offset1:166
	ds_read2_b32 v[28:29], v0 offset0:199 offset1:231
	v_lshlrev_b64 v[0:1], 11, v[30:31]
	v_lshl_add_u64 v[32:33], v[4:5], 0, v[0:1]
	s_waitcnt lgkmcnt(7)
	s_nop 1
	s_waitcnt lgkmcnt(4)
	s_nop 7
	v_cvt_pk_bf16_f32 v1, v10, v12
	v_cvt_pk_bf16_f32 v0, v6, v8
	s_waitcnt lgkmcnt(3)
	s_nop 1
	s_waitcnt lgkmcnt(0)
	s_nop 7
	v_cvt_pk_bf16_f32 v3, v20, v28
	v_cvt_pk_bf16_f32 v2, v14, v18
	global_store_dwordx4 v[32:33], v[0:3], off
	s_add_i32 s12, s12, s6
	s_add_i32 s7, s7, s8
	v_add_u32_e32 v0, 32, v30
	v_ashrrev_i32_e32 v1, 31, v0
	v_lshlrev_b64 v[0:1], 11, v[0:1]
	v_lshl_add_u64 v[4:5], v[4:5], 0, v[0:1]
	s_nop 9
	v_cvt_pk_bf16_f32 v1, v11, v13
	v_cvt_pk_bf16_f32 v0, v7, v9
	s_nop 9
	v_cvt_pk_bf16_f32 v3, v21, v29
	v_cvt_pk_bf16_f32 v2, v15, v19
	s_cmpk_lt_i32 s12, 0x100
	global_store_dwordx4 v[4:5], v[0:3], off
	s_cbranch_scc0 .LBB0_86

.LBB0_123:
	s_add_i32 s45, s44, 2
	s_mul_hi_i32 s50, s45, 0x55555556
	s_lshr_b32 s51, s50, 31
	s_add_i32 s50, s50, s51
	s_mul_i32 s50, s50, 3
	s_sub_i32 s45, s45, s50
	s_mulk_i32 s45, 0x6000
	s_mul_i32 s54, s44, 0x6000
	v_readfirstlane_b32 s55, v140
	v_lshl_add_u64 v[232:233], v[132:133], 0, s[2:3]
	v_lshl_add_u64 v[234:235], v[130:131], 0, s[2:3]
	s_add_u32 s55, s55, s45
	s_waitcnt vmcnt(6) lgkmcnt(0)
	s_barrier
	s_setprio 1
	s_mov_b32 m0, s55
	v_lshl_add_u64 v[236:237], v[232:233], 0, s[20:21]
	global_load_lds_dwordx4 v[236:237], off
	s_add_u32 m0, s55, 0x1000
	v_lshl_add_u64 v[236:237], v[232:233], 0, s[22:23]
	global_load_lds_dwordx4 v[236:237], off
	s_add_u32 m0, s55, 0x2000
	v_lshl_add_u64 v[236:237], v[232:233], 0, s[24:25]
	global_load_lds_dwordx4 v[236:237], off
	s_add_u32 m0, s55, 0x3000
	v_lshl_add_u64 v[236:237], v[232:233], 0, s[26:27]
	global_load_lds_dwordx4 v[236:237], off
	s_add_u32 m0, s55, 0x4000
	v_lshl_add_u64 v[236:237], v[234:235], 0, s[28:29]
	global_load_lds_dwordx4 v[236:237], off
	s_add_u32 m0, s55, 0x5000
	v_lshl_add_u64 v[236:237], v[234:235], 0, s[30:31]
	global_load_lds_dwordx4 v[236:237], off
	v_or_b32_e32 v128, s54, v139
	v_add3_u32 v128, v128, v137, v138
	ds_read_b128 v[176:179], v128 offset:16384
	ds_read_b128 v[180:183], v128 offset:17408
	ds_read_b128 v[184:187], v128 offset:18432
	ds_read_b128 v[192:195], v128 offset:19456
	v_add_u32_e32 v128, s54, v141
	v_add3_u32 v128, v128, v137, v138
	ds_read_b128 v[144:147], v128
	ds_read_b128 v[148:151], v128 offset:1024
	ds_read_b128 v[152:155], v128 offset:2048
	ds_read_b128 v[156:159], v128 offset:3072
	ds_read_b128 v[160:163], v128 offset:4096
	ds_read_b128 v[164:167], v128 offset:5120
	ds_read_b128 v[168:171], v128 offset:6144
	ds_read_b128 v[172:175], v128 offset:7168
	s_setprio 0
	s_waitcnt lgkmcnt(7)
	v_mfma_f32_16x16x32_bf16 v[124:127], v[144:147], v[176:179], v[124:127]
	v_mfma_f32_16x16x32_bf16 v[120:123], v[144:147], v[180:183], v[120:123]
	v_mfma_f32_16x16x32_bf16 v[116:119], v[144:147], v[184:187], v[116:119]
	v_mfma_f32_16x16x32_bf16 v[112:115], v[144:147], v[192:195], v[112:115]
	s_waitcnt lgkmcnt(6)
	v_mfma_f32_16x16x32_bf16 v[108:111], v[148:151], v[176:179], v[108:111]
	v_mfma_f32_16x16x32_bf16 v[104:107], v[148:151], v[180:183], v[104:107]
	v_mfma_f32_16x16x32_bf16 v[100:103], v[148:151], v[184:187], v[100:103]
	v_mfma_f32_16x16x32_bf16 v[96:99], v[148:151], v[192:195], v[96:99]
	s_waitcnt lgkmcnt(5)
	v_mfma_f32_16x16x32_bf16 v[92:95], v[152:155], v[176:179], v[92:95]
	v_mfma_f32_16x16x32_bf16 v[88:91], v[152:155], v[180:183], v[88:91]
	v_mfma_f32_16x16x32_bf16 v[84:87], v[152:155], v[184:187], v[84:87]
	v_mfma_f32_16x16x32_bf16 v[80:83], v[152:155], v[192:195], v[80:83]
	s_waitcnt lgkmcnt(4)
	v_mfma_f32_16x16x32_bf16 v[76:79], v[156:159], v[176:179], v[76:79]
	v_mfma_f32_16x16x32_bf16 v[72:75], v[156:159], v[180:183], v[72:75]
	v_mfma_f32_16x16x32_bf16 v[68:71], v[156:159], v[184:187], v[68:71]
	v_mfma_f32_16x16x32_bf16 v[64:67], v[156:159], v[192:195], v[64:67]
	s_waitcnt lgkmcnt(3)
	v_mfma_f32_16x16x32_bf16 v[60:63], v[160:163], v[176:179], v[60:63]
	v_mfma_f32_16x16x32_bf16 v[56:59], v[160:163], v[180:183], v[56:59]
	v_mfma_f32_16x16x32_bf16 v[52:55], v[160:163], v[184:187], v[52:55]
	v_mfma_f32_16x16x32_bf16 v[48:51], v[160:163], v[192:195], v[48:51]
	s_waitcnt lgkmcnt(2)
	v_mfma_f32_16x16x32_bf16 v[44:47], v[164:167], v[176:179], v[44:47]
	v_mfma_f32_16x16x32_bf16 v[40:43], v[164:167], v[180:183], v[40:43]
	v_mfma_f32_16x16x32_bf16 v[36:39], v[164:167], v[184:187], v[36:39]
	v_mfma_f32_16x16x32_bf16 v[32:35], v[164:167], v[192:195], v[32:35]
	s_waitcnt lgkmcnt(1)
	v_mfma_f32_16x16x32_bf16 v[28:31], v[168:171], v[176:179], v[28:31]
	v_mfma_f32_16x16x32_bf16 v[24:27], v[168:171], v[180:183], v[24:27]
	v_mfma_f32_16x16x32_bf16 v[20:23], v[168:171], v[184:187], v[20:23]
	v_mfma_f32_16x16x32_bf16 v[16:19], v[168:171], v[192:195], v[16:19]
	s_waitcnt lgkmcnt(0)
	v_mfma_f32_16x16x32_bf16 v[12:15], v[172:175], v[176:179], v[12:15]
	v_mfma_f32_16x16x32_bf16 v[8:11], v[172:175], v[180:183], v[8:11]
	v_mfma_f32_16x16x32_bf16 v[4:7], v[172:175], v[184:187], v[4:7]
	v_mfma_f32_16x16x32_bf16 v[0:3], v[172:175], v[192:195], v[0:3]
	s_add_i32 s45, s44, 1
	s_cmp_lg_u32 s44, 2
	s_cselect_b32 s44, s45, 0
	s_add_u32 s2, s2, 0x80
	s_addc_u32 s3, s3, 0
	s_cmpk_lg_i32 s2, 0xf00
	s_cbranch_scc1 .LBB0_123
	s_waitcnt vmcnt(6) lgkmcnt(0)
	s_barrier
	v_add3_u32 v128, v141, v137, v138
	ds_read_b128 v[130:133], v128
	ds_read_b128 v[144:147], v128 offset:1024
	ds_read_b128 v[148:151], v128 offset:2048
	ds_read_b128 v[152:155], v128 offset:3072
	ds_read_b128 v[156:159], v128 offset:4096
	ds_read_b128 v[160:163], v128 offset:5120
	ds_read_b128 v[164:167], v128 offset:6144
	ds_read_b128 v[168:171], v128 offset:7168
	v_add3_u32 v137, v139, v137, v138
	ds_read_b128 v[138:141], v137 offset:16384
	ds_read_b128 v[172:175], v137 offset:17408
	ds_read_b128 v[176:179], v137 offset:18432
	ds_read_b128 v[180:183], v137 offset:19456
	s_setprio 1
	s_waitcnt lgkmcnt(0)
	v_mfma_f32_16x16x32_bf16 v[124:127], v[130:133], v[138:141], v[124:127]
	v_mfma_f32_16x16x32_bf16 v[120:123], v[130:133], v[172:175], v[120:123]
	v_mfma_f32_16x16x32_bf16 v[116:119], v[130:133], v[176:179], v[116:119]
	v_mfma_f32_16x16x32_bf16 v[112:115], v[130:133], v[180:183], v[112:115]
	v_mfma_f32_16x16x32_bf16 v[108:111], v[144:147], v[138:141], v[108:111]
	v_mfma_f32_16x16x32_bf16 v[104:107], v[144:147], v[172:175], v[104:107]
	v_mfma_f32_16x16x32_bf16 v[100:103], v[144:147], v[176:179], v[100:103]
	v_mfma_f32_16x16x32_bf16 v[96:99], v[144:147], v[180:183], v[96:99]
	v_mfma_f32_16x16x32_bf16 v[92:95], v[148:151], v[138:141], v[92:95]
	v_mfma_f32_16x16x32_bf16 v[88:91], v[148:151], v[172:175], v[88:91]
	v_mfma_f32_16x16x32_bf16 v[84:87], v[148:151], v[176:179], v[84:87]
	v_mfma_f32_16x16x32_bf16 v[80:83], v[148:151], v[180:183], v[80:83]
	v_mfma_f32_16x16x32_bf16 v[76:79], v[152:155], v[138:141], v[76:79]
	v_mfma_f32_16x16x32_bf16 v[72:75], v[152:155], v[172:175], v[72:75]
	v_mfma_f32_16x16x32_bf16 v[68:71], v[152:155], v[176:179], v[68:71]
	v_mfma_f32_16x16x32_bf16 v[64:67], v[152:155], v[180:183], v[64:67]
	v_mfma_f32_16x16x32_bf16 v[60:63], v[156:159], v[138:141], v[60:63]
	v_mfma_f32_16x16x32_bf16 v[56:59], v[156:159], v[172:175], v[56:59]
	v_mfma_f32_16x16x32_bf16 v[52:55], v[156:159], v[176:179], v[52:55]
	v_mfma_f32_16x16x32_bf16 v[48:51], v[156:159], v[180:183], v[48:51]
	v_mfma_f32_16x16x32_bf16 v[44:47], v[160:163], v[138:141], v[44:47]
	v_mfma_f32_16x16x32_bf16 v[40:43], v[160:163], v[172:175], v[40:43]
	v_mfma_f32_16x16x32_bf16 v[36:39], v[160:163], v[176:179], v[36:39]
	v_mfma_f32_16x16x32_bf16 v[32:35], v[160:163], v[180:183], v[32:35]
	v_mfma_f32_16x16x32_bf16 v[28:31], v[164:167], v[138:141], v[28:31]
	v_mfma_f32_16x16x32_bf16 v[24:27], v[164:167], v[172:175], v[24:27]
	v_mfma_f32_16x16x32_bf16 v[20:23], v[164:167], v[176:179], v[20:23]
	v_mfma_f32_16x16x32_bf16 v[16:19], v[164:167], v[180:183], v[16:19]
	v_mfma_f32_16x16x32_bf16 v[12:15], v[168:171], v[138:141], v[12:15]
	v_mfma_f32_16x16x32_bf16 v[8:11], v[168:171], v[172:175], v[8:11]
	v_mfma_f32_16x16x32_bf16 v[4:7], v[168:171], v[176:179], v[4:7]
	v_mfma_f32_16x16x32_bf16 v[0:3], v[168:171], v[180:183], v[0:3]
	s_setprio 0
	s_waitcnt vmcnt(0) lgkmcnt(0)
	s_barrier
	ds_read_b128 v[130:133], v128 offset:24576
	ds_read_b128 v[138:141], v128 offset:25600
	ds_read_b128 v[144:147], v128 offset:26624
	ds_read_b128 v[148:151], v128 offset:27648
	ds_read_b128 v[152:155], v128 offset:28672
	ds_read_b128 v[156:159], v128 offset:29696
	ds_read_b128 v[160:163], v128 offset:30720
	ds_read_b128 v[164:167], v128 offset:31744
	ds_read_b128 v[168:171], v137 offset:40960
	ds_read_b128 v[172:175], v137 offset:41984
	ds_read_b128 v[176:179], v137 offset:43008
	ds_read_b128 v[180:183], v137 offset:44032
	s_setprio 1
	s_waitcnt lgkmcnt(0)
	v_mfma_f32_16x16x32_bf16 v[124:127], v[130:133], v[168:171], v[124:127]
	v_mfma_f32_16x16x32_bf16 v[120:123], v[130:133], v[172:175], v[120:123]
	v_mfma_f32_16x16x32_bf16 v[116:119], v[130:133], v[176:179], v[116:119]
	v_mfma_f32_16x16x32_bf16 v[112:115], v[130:133], v[180:183], v[112:115]
	v_mfma_f32_16x16x32_bf16 v[108:111], v[138:141], v[168:171], v[108:111]
	v_mfma_f32_16x16x32_bf16 v[104:107], v[138:141], v[172:175], v[104:107]
	v_mfma_f32_16x16x32_bf16 v[100:103], v[138:141], v[176:179], v[100:103]
	v_mfma_f32_16x16x32_bf16 v[96:99], v[138:141], v[180:183], v[96:99]
	v_mfma_f32_16x16x32_bf16 v[92:95], v[144:147], v[168:171], v[92:95]
	v_mfma_f32_16x16x32_bf16 v[88:91], v[144:147], v[172:175], v[88:91]
	v_mfma_f32_16x16x32_bf16 v[84:87], v[144:147], v[176:179], v[84:87]
	v_mfma_f32_16x16x32_bf16 v[130:133], v[144:147], v[180:183], v[80:83]
	v_mfma_f32_16x16x32_bf16 v[138:141], v[148:151], v[168:171], v[76:79]
	v_mfma_f32_16x16x32_bf16 v[72:75], v[148:151], v[172:175], v[72:75]
	v_mfma_f32_16x16x32_bf16 v[68:71], v[148:151], v[176:179], v[68:71]
	v_mfma_f32_16x16x32_bf16 v[64:67], v[148:151], v[180:183], v[64:67]
	v_mfma_f32_16x16x32_bf16 v[60:63], v[152:155], v[168:171], v[60:63]
	v_mfma_f32_16x16x32_bf16 v[56:59], v[152:155], v[172:175], v[56:59]
	v_mfma_f32_16x16x32_bf16 v[52:55], v[152:155], v[176:179], v[52:55]
	v_mfma_f32_16x16x32_bf16 v[48:51], v[152:155], v[180:183], v[48:51]
	v_mfma_f32_16x16x32_bf16 v[44:47], v[156:159], v[168:171], v[44:47]
	v_mfma_f32_16x16x32_bf16 v[40:43], v[156:159], v[172:175], v[40:43]
	v_mfma_f32_16x16x32_bf16 v[36:39], v[156:159], v[176:179], v[36:39]
	v_mfma_f32_16x16x32_bf16 v[32:35], v[156:159], v[180:183], v[32:35]
	v_mfma_f32_16x16x32_bf16 v[28:31], v[160:163], v[168:171], v[28:31]
	v_mfma_f32_16x16x32_bf16 v[24:27], v[160:163], v[172:175], v[24:27]
	v_mfma_f32_16x16x32_bf16 v[20:23], v[160:163], v[176:179], v[20:23]
	v_mfma_f32_16x16x32_bf16 v[16:19], v[160:163], v[180:183], v[16:19]
	v_mfma_f32_16x16x32_bf16 v[12:15], v[164:167], v[168:171], v[12:15]
	v_mfma_f32_16x16x32_bf16 v[8:11], v[164:167], v[172:175], v[8:11]
	v_mfma_f32_16x16x32_bf16 v[4:7], v[164:167], v[176:179], v[4:7]
	v_mfma_f32_16x16x32_bf16 v[0:3], v[164:167], v[180:183], v[0:3]
	s_setprio 0
	v_and_b32_e32 v76, 0xffffff80, v134
	v_add_u32_e32 v76, s43, v76
	v_lshlrev_b32_e32 v77, 6, v136
	s_add_i32 s2, s4, 0xfffffc00
	v_ashrrev_i32_e32 v76, 6, v76
	v_or3_b32 v136, v77, s2, v135
	v_ashrrev_i32_e32 v77, 31, v76
	v_lshlrev_b64 v[78:79], 17, v[76:77]
	v_readlane_b32 s2, v254, 60
	v_lshrrev_b32_e32 v77, 1, v134
	s_nop 1
	v_readlane_b32 s3, v254, 61
	v_and_b32_e32 v128, 24, v77
	s_nop 3
	v_lshl_add_u64 v[78:79], s[2:3], 0, v[78:79]
	v_mov_b32_e32 v137, v129
	s_nop 4
	v_lshl_add_u64 v[134:135], v[78:79], 0, v[128:129]
	v_lshlrev_b64 v[78:79], 7, v[136:137]
	v_cvt_pk_bf16_f32 v81, v126, v127
	v_cvt_pk_bf16_f32 v80, v124, v125
	s_nop 2
	v_lshl_add_u64 v[144:145], v[134:135], 0, v[78:79]
	s_nop 3
	global_store_dwordx2 v[144:145], v[80:81], off
	v_or_b32_e32 v80, 16, v136
	v_mov_b32_e32 v81, v129
	s_nop 0
	v_cvt_pk_bf16_f32 v83, v122, v123
	v_and_b32_sdwa v77, v118, v142 dst_sel:DWORD dst_unused:UNUSED_PAD src0_sel:WORD_1 src1_sel:DWORD
	v_lshlrev_b64 v[80:81], 7, v[80:81]
	s_nop 0
	v_and_b32_sdwa v122, v116, v142 dst_sel:DWORD dst_unused:UNUSED_PAD src0_sel:WORD_1 src1_sel:DWORD
	v_add3_u32 v77, v118, v77, s46
	v_and_b32_sdwa v118, v119, v142 dst_sel:DWORD dst_unused:UNUSED_PAD src0_sel:WORD_1 src1_sel:DWORD
	v_lshl_add_u64 v[124:125], v[134:135], 0, v[80:81]
	v_cvt_pk_bf16_f32 v82, v120, v121
	v_add3_u32 v116, v116, v122, s46
	v_and_b32_sdwa v122, v117, v142 dst_sel:DWORD dst_unused:UNUSED_PAD src0_sel:WORD_1 src1_sel:DWORD
	v_add3_u32 v118, v119, v118, s46
	global_store_dwordx2 v[124:125], v[82:83], off
	v_or_b32_e32 v82, 32, v136
	v_mov_b32_e32 v83, v129
	v_add3_u32 v117, v117, v122, s46
	v_and_b32_e32 v118, 0xffff0000, v118
	v_lshlrev_b64 v[82:83], 7, v[82:83]
	v_and_b32_e32 v119, 0xffff0000, v117
	v_or_b32_sdwa v117, v118, v77 dst_sel:DWORD dst_unused:UNUSED_PAD src0_sel:DWORD src1_sel:WORD_1
	v_and_b32_sdwa v77, v114, v142 dst_sel:DWORD dst_unused:UNUSED_PAD src0_sel:WORD_1 src1_sel:DWORD
	v_and_b32_sdwa v122, v112, v142 dst_sel:DWORD dst_unused:UNUSED_PAD src0_sel:WORD_1 src1_sel:DWORD
	v_lshl_add_u64 v[120:121], v[134:135], 0, v[82:83]
	v_or_b32_sdwa v116, v119, v116 dst_sel:DWORD dst_unused:UNUSED_PAD src0_sel:DWORD src1_sel:WORD_1
	v_add3_u32 v112, v112, v122, s46
	v_add3_u32 v77, v114, v77, s46
	v_and_b32_sdwa v114, v115, v142 dst_sel:DWORD dst_unused:UNUSED_PAD src0_sel:WORD_1 src1_sel:DWORD
	v_and_b32_sdwa v122, v113, v142 dst_sel:DWORD dst_unused:UNUSED_PAD src0_sel:WORD_1 src1_sel:DWORD
	global_store_dwordx2 v[120:121], v[116:117], off
	v_or_b32_e32 v116, 48, v136
	v_mov_b32_e32 v117, v129
	v_add3_u32 v114, v115, v114, s46
	v_add3_u32 v113, v113, v122, s46
	v_lshlrev_b64 v[116:117], 7, v[116:117]
	v_and_b32_e32 v114, 0xffff0000, v114
	v_and_b32_e32 v115, 0xffff0000, v113
	v_lshl_add_u64 v[118:119], v[134:135], 0, v[116:117]
	v_or_b32_sdwa v113, v114, v77 dst_sel:DWORD dst_unused:UNUSED_PAD src0_sel:DWORD src1_sel:WORD_1
	v_or_b32_sdwa v112, v115, v112 dst_sel:DWORD dst_unused:UNUSED_PAD src0_sel:DWORD src1_sel:WORD_1
	global_store_dwordx2 v[118:119], v[112:113], off
	v_and_b32_sdwa v77, v110, v142 dst_sel:DWORD dst_unused:UNUSED_PAD src0_sel:WORD_1 src1_sel:DWORD
	v_and_b32_sdwa v112, v108, v142 dst_sel:DWORD dst_unused:UNUSED_PAD src0_sel:WORD_1 src1_sel:DWORD
	v_add3_u32 v108, v108, v112, s46
	v_add3_u32 v77, v110, v77, s46
	v_and_b32_sdwa v110, v111, v142 dst_sel:DWORD dst_unused:UNUSED_PAD src0_sel:WORD_1 src1_sel:DWORD
	v_and_b32_sdwa v112, v109, v142 dst_sel:DWORD dst_unused:UNUSED_PAD src0_sel:WORD_1 src1_sel:DWORD
	v_add3_u32 v110, v111, v110, s46
	v_add3_u32 v109, v109, v112, s46
	v_and_b32_e32 v110, 0xffff0000, v110
	v_and_b32_e32 v111, 0xffff0000, v109
	v_or_b32_sdwa v109, v110, v77 dst_sel:DWORD dst_unused:UNUSED_PAD src0_sel:DWORD src1_sel:WORD_1
	v_or_b32_sdwa v108, v111, v108 dst_sel:DWORD dst_unused:UNUSED_PAD src0_sel:DWORD src1_sel:WORD_1
	global_store_dwordx2 v[144:145], v[108:109], off offset:32
	v_and_b32_sdwa v77, v106, v142 dst_sel:DWORD dst_unused:UNUSED_PAD src0_sel:WORD_1 src1_sel:DWORD
	v_and_b32_sdwa v108, v104, v142 dst_sel:DWORD dst_unused:UNUSED_PAD src0_sel:WORD_1 src1_sel:DWORD
	v_add3_u32 v104, v104, v108, s46
	v_add3_u32 v77, v106, v77, s46
	v_and_b32_sdwa v106, v107, v142 dst_sel:DWORD dst_unused:UNUSED_PAD src0_sel:WORD_1 src1_sel:DWORD
	v_and_b32_sdwa v108, v105, v142 dst_sel:DWORD dst_unused:UNUSED_PAD src0_sel:WORD_1 src1_sel:DWORD
	v_add3_u32 v106, v107, v106, s46
	v_add3_u32 v105, v105, v108, s46
	v_and_b32_e32 v106, 0xffff0000, v106
	v_and_b32_e32 v107, 0xffff0000, v105
	v_or_b32_sdwa v105, v106, v77 dst_sel:DWORD dst_unused:UNUSED_PAD src0_sel:DWORD src1_sel:WORD_1
	v_or_b32_sdwa v104, v107, v104 dst_sel:DWORD dst_unused:UNUSED_PAD src0_sel:DWORD src1_sel:WORD_1
	global_store_dwordx2 v[124:125], v[104:105], off offset:32
	v_and_b32_sdwa v77, v102, v142 dst_sel:DWORD dst_unused:UNUSED_PAD src0_sel:WORD_1 src1_sel:DWORD
	v_and_b32_sdwa v104, v100, v142 dst_sel:DWORD dst_unused:UNUSED_PAD src0_sel:WORD_1 src1_sel:DWORD
	v_add3_u32 v100, v100, v104, s46
	v_add3_u32 v77, v102, v77, s46
	v_and_b32_sdwa v102, v103, v142 dst_sel:DWORD dst_unused:UNUSED_PAD src0_sel:WORD_1 src1_sel:DWORD
	v_and_b32_sdwa v104, v101, v142 dst_sel:DWORD dst_unused:UNUSED_PAD src0_sel:WORD_1 src1_sel:DWORD
	v_add3_u32 v102, v103, v102, s46
	v_add3_u32 v101, v101, v104, s46
	v_and_b32_e32 v102, 0xffff0000, v102
	v_and_b32_e32 v103, 0xffff0000, v101
	v_or_b32_sdwa v101, v102, v77 dst_sel:DWORD dst_unused:UNUSED_PAD src0_sel:DWORD src1_sel:WORD_1
	v_or_b32_sdwa v100, v103, v100 dst_sel:DWORD dst_unused:UNUSED_PAD src0_sel:DWORD src1_sel:WORD_1
	global_store_dwordx2 v[120:121], v[100:101], off offset:32
	v_and_b32_sdwa v77, v98, v142 dst_sel:DWORD dst_unused:UNUSED_PAD src0_sel:WORD_1 src1_sel:DWORD
	v_and_b32_sdwa v100, v96, v142 dst_sel:DWORD dst_unused:UNUSED_PAD src0_sel:WORD_1 src1_sel:DWORD
	v_add3_u32 v96, v96, v100, s46
	v_add3_u32 v77, v98, v77, s46
	v_and_b32_sdwa v98, v99, v142 dst_sel:DWORD dst_unused:UNUSED_PAD src0_sel:WORD_1 src1_sel:DWORD
	v_and_b32_sdwa v100, v97, v142 dst_sel:DWORD dst_unused:UNUSED_PAD src0_sel:WORD_1 src1_sel:DWORD
	v_add3_u32 v98, v99, v98, s46
	v_add3_u32 v97, v97, v100, s46
	v_and_b32_e32 v98, 0xffff0000, v98
	v_and_b32_e32 v99, 0xffff0000, v97
	v_or_b32_sdwa v97, v98, v77 dst_sel:DWORD dst_unused:UNUSED_PAD src0_sel:DWORD src1_sel:WORD_1
	v_or_b32_sdwa v96, v99, v96 dst_sel:DWORD dst_unused:UNUSED_PAD src0_sel:DWORD src1_sel:WORD_1
	global_store_dwordx2 v[118:119], v[96:97], off offset:32
	v_and_b32_sdwa v77, v94, v142 dst_sel:DWORD dst_unused:UNUSED_PAD src0_sel:WORD_1 src1_sel:DWORD
	v_and_b32_sdwa v96, v92, v142 dst_sel:DWORD dst_unused:UNUSED_PAD src0_sel:WORD_1 src1_sel:DWORD
	v_add3_u32 v92, v92, v96, s46
	v_add3_u32 v77, v94, v77, s46
	v_and_b32_sdwa v94, v95, v142 dst_sel:DWORD dst_unused:UNUSED_PAD src0_sel:WORD_1 src1_sel:DWORD
	v_and_b32_sdwa v96, v93, v142 dst_sel:DWORD dst_unused:UNUSED_PAD src0_sel:WORD_1 src1_sel:DWORD
	v_add3_u32 v94, v95, v94, s46
	v_add3_u32 v93, v93, v96, s46
	v_and_b32_e32 v94, 0xffff0000, v94
	v_and_b32_e32 v95, 0xffff0000, v93
	v_or_b32_sdwa v93, v94, v77 dst_sel:DWORD dst_unused:UNUSED_PAD src0_sel:DWORD src1_sel:WORD_1
	v_or_b32_sdwa v92, v95, v92 dst_sel:DWORD dst_unused:UNUSED_PAD src0_sel:DWORD src1_sel:WORD_1
	global_store_dwordx2 v[144:145], v[92:93], off offset:64
	v_and_b32_sdwa v77, v90, v142 dst_sel:DWORD dst_unused:UNUSED_PAD src0_sel:WORD_1 src1_sel:DWORD
	v_and_b32_sdwa v92, v88, v142 dst_sel:DWORD dst_unused:UNUSED_PAD src0_sel:WORD_1 src1_sel:DWORD
	v_add3_u32 v88, v88, v92, s46
	v_add3_u32 v77, v90, v77, s46
	v_and_b32_sdwa v90, v91, v142 dst_sel:DWORD dst_unused:UNUSED_PAD src0_sel:WORD_1 src1_sel:DWORD
	v_and_b32_sdwa v92, v89, v142 dst_sel:DWORD dst_unused:UNUSED_PAD src0_sel:WORD_1 src1_sel:DWORD
	v_add3_u32 v90, v91, v90, s46
	v_add3_u32 v89, v89, v92, s46
	v_and_b32_e32 v90, 0xffff0000, v90
	v_and_b32_e32 v91, 0xffff0000, v89
	v_or_b32_sdwa v89, v90, v77 dst_sel:DWORD dst_unused:UNUSED_PAD src0_sel:DWORD src1_sel:WORD_1
	v_or_b32_sdwa v88, v91, v88 dst_sel:DWORD dst_unused:UNUSED_PAD src0_sel:DWORD src1_sel:WORD_1
	global_store_dwordx2 v[124:125], v[88:89], off offset:64
	v_and_b32_sdwa v77, v86, v142 dst_sel:DWORD dst_unused:UNUSED_PAD src0_sel:WORD_1 src1_sel:DWORD
	v_and_b32_sdwa v88, v84, v142 dst_sel:DWORD dst_unused:UNUSED_PAD src0_sel:WORD_1 src1_sel:DWORD
	v_add3_u32 v84, v84, v88, s46
	v_add3_u32 v77, v86, v77, s46
	v_and_b32_sdwa v86, v87, v142 dst_sel:DWORD dst_unused:UNUSED_PAD src0_sel:WORD_1 src1_sel:DWORD
	v_and_b32_sdwa v88, v85, v142 dst_sel:DWORD dst_unused:UNUSED_PAD src0_sel:WORD_1 src1_sel:DWORD
	v_add3_u32 v86, v87, v86, s46
	v_add3_u32 v85, v85, v88, s46
	v_and_b32_e32 v86, 0xffff0000, v86
	v_and_b32_e32 v87, 0xffff0000, v85
	v_or_b32_sdwa v85, v86, v77 dst_sel:DWORD dst_unused:UNUSED_PAD src0_sel:DWORD src1_sel:WORD_1
	v_or_b32_sdwa v84, v87, v84 dst_sel:DWORD dst_unused:UNUSED_PAD src0_sel:DWORD src1_sel:WORD_1
	global_store_dwordx2 v[120:121], v[84:85], off offset:64
	s_nop 9
	v_cvt_pk_bf16_f32 v85, v132, v133
	v_cvt_pk_bf16_f32 v84, v130, v131
	global_store_dwordx2 v[118:119], v[84:85], off offset:64
	s_nop 9
	v_cvt_pk_bf16_f32 v85, v140, v141
	v_cvt_pk_bf16_f32 v84, v138, v139
	global_store_dwordx2 v[144:145], v[84:85], off offset:96
	s_nop 0
	v_and_b32_sdwa v84, v72, v142 dst_sel:DWORD dst_unused:UNUSED_PAD src0_sel:WORD_1 src1_sel:DWORD
	v_add3_u32 v72, v72, v84, s46
	s_nop 1
	v_and_b32_sdwa v84, v73, v142 dst_sel:DWORD dst_unused:UNUSED_PAD src0_sel:WORD_1 src1_sel:DWORD
	s_nop 0
	v_add3_u32 v73, v73, v84, s46
	s_nop 0
	v_and_b32_e32 v77, 0xffff0000, v73
	v_cvt_pk_bf16_f32 v73, v74, v75
	v_or_b32_sdwa v72, v77, v72 dst_sel:DWORD dst_unused:UNUSED_PAD src0_sel:DWORD src1_sel:WORD_1
	global_store_dwordx2 v[124:125], v[72:73], off offset:96
	s_nop 0
	v_and_b32_sdwa v73, v68, v142 dst_sel:DWORD dst_unused:UNUSED_PAD src0_sel:WORD_1 src1_sel:DWORD
	v_add3_u32 v68, v68, v73, s46
	s_nop 1
	v_and_b32_sdwa v73, v69, v142 dst_sel:DWORD dst_unused:UNUSED_PAD src0_sel:WORD_1 src1_sel:DWORD
	s_nop 0
	v_add3_u32 v69, v69, v73, s46
	s_nop 0
	v_and_b32_e32 v72, 0xffff0000, v69
	v_cvt_pk_bf16_f32 v69, v70, v71
	v_or_b32_sdwa v68, v72, v68 dst_sel:DWORD dst_unused:UNUSED_PAD src0_sel:DWORD src1_sel:WORD_1
	global_store_dwordx2 v[120:121], v[68:69], off offset:96
	s_nop 8
	v_cvt_pk_bf16_f32 v64, v64, v65
	s_nop 0
	v_and_b32_sdwa v69, v60, v142 dst_sel:DWORD dst_unused:UNUSED_PAD src0_sel:WORD_1 src1_sel:DWORD
	s_nop 1
	v_add3_u32 v60, v60, v69, s46
	v_and_b32_sdwa v69, v61, v142 dst_sel:DWORD dst_unused:UNUSED_PAD src0_sel:WORD_1 src1_sel:DWORD
	s_nop 0
	v_add3_u32 v61, v61, v69, s46
	s_nop 0
	v_and_b32_e32 v68, 0xffff0000, v61
	v_cvt_pk_bf16_f32 v61, v62, v63
	s_nop 0
	v_and_b32_sdwa v63, v56, v142 dst_sel:DWORD dst_unused:UNUSED_PAD src0_sel:WORD_1 src1_sel:DWORD
	s_nop 2
	v_add3_u32 v56, v56, v63, s46
	v_and_b32_sdwa v63, v57, v142 dst_sel:DWORD dst_unused:UNUSED_PAD src0_sel:WORD_1 src1_sel:DWORD
	s_nop 0
	v_cvt_pk_bf16_f32 v65, v66, v67
	v_add3_u32 v57, v57, v63, s46
	s_nop 0
	global_store_dwordx2 v[118:119], v[64:65], off offset:96
	v_or_b32_e32 v64, 1, v76
	v_and_b32_e32 v62, 0xffff0000, v57
	v_cvt_pk_bf16_f32 v57, v58, v59
	s_nop 0
	v_ashrrev_i32_e32 v65, 31, v64
	v_and_b32_sdwa v59, v52, v142 dst_sel:DWORD dst_unused:UNUSED_PAD src0_sel:WORD_1 src1_sel:DWORD
	s_nop 1
	v_lshlrev_b64 v[64:65], 17, v[64:65]
	v_add3_u32 v52, v52, v59, s46
	v_and_b32_sdwa v59, v53, v142 dst_sel:DWORD dst_unused:UNUSED_PAD src0_sel:WORD_1 src1_sel:DWORD
	s_nop 0
	v_lshl_add_u64 v[64:65], s[2:3], 0, v[64:65]
	v_add3_u32 v53, v53, v59, s46
	s_nop 0
	v_lshl_add_u64 v[64:65], v[64:65], 0, v[128:129]
	v_and_b32_e32 v58, 0xffff0000, v53
	v_cvt_pk_bf16_f32 v53, v54, v55
	s_nop 0
	v_and_b32_sdwa v55, v48, v142 dst_sel:DWORD dst_unused:UNUSED_PAD src0_sel:WORD_1 src1_sel:DWORD
	v_lshl_add_u64 v[66:67], v[64:65], 0, v[78:79]
	v_or_b32_sdwa v60, v68, v60 dst_sel:DWORD dst_unused:UNUSED_PAD src0_sel:DWORD src1_sel:WORD_1
	v_add3_u32 v48, v48, v55, s46
	s_nop 1
	v_and_b32_sdwa v55, v49, v142 dst_sel:DWORD dst_unused:UNUSED_PAD src0_sel:WORD_1 src1_sel:DWORD
	global_store_dwordx2 v[66:67], v[60:61], off
	v_lshl_add_u64 v[60:61], v[64:65], 0, v[80:81]
	v_or_b32_sdwa v56, v62, v56 dst_sel:DWORD dst_unused:UNUSED_PAD src0_sel:DWORD src1_sel:WORD_1
	s_nop 0
	v_add3_u32 v49, v49, v55, s46
	global_store_dwordx2 v[60:61], v[56:57], off
	v_lshl_add_u64 v[56:57], v[64:65], 0, v[82:83]
	v_or_b32_sdwa v52, v58, v52 dst_sel:DWORD dst_unused:UNUSED_PAD src0_sel:DWORD src1_sel:WORD_1
	s_nop 0
	v_and_b32_e32 v54, 0xffff0000, v49
	global_store_dwordx2 v[56:57], v[52:53], off
	v_lshl_add_u64 v[52:53], v[64:65], 0, v[116:117]
	v_cvt_pk_bf16_f32 v49, v50, v51
	v_or_b32_sdwa v48, v54, v48 dst_sel:DWORD dst_unused:UNUSED_PAD src0_sel:DWORD src1_sel:WORD_1
	global_store_dwordx2 v[52:53], v[48:49], off
	s_nop 0
	v_and_b32_sdwa v49, v44, v142 dst_sel:DWORD dst_unused:UNUSED_PAD src0_sel:WORD_1 src1_sel:DWORD
	v_add3_u32 v44, v44, v49, s46
	s_nop 1
	v_and_b32_sdwa v49, v45, v142 dst_sel:DWORD dst_unused:UNUSED_PAD src0_sel:WORD_1 src1_sel:DWORD
	s_nop 0
	v_add3_u32 v45, v45, v49, s46
	s_nop 0
	v_and_b32_e32 v48, 0xffff0000, v45
	v_cvt_pk_bf16_f32 v45, v46, v47
	v_or_b32_sdwa v44, v48, v44 dst_sel:DWORD dst_unused:UNUSED_PAD src0_sel:DWORD src1_sel:WORD_1
	global_store_dwordx2 v[66:67], v[44:45], off offset:32
	s_nop 0
	v_and_b32_sdwa v45, v40, v142 dst_sel:DWORD dst_unused:UNUSED_PAD src0_sel:WORD_1 src1_sel:DWORD
	v_add3_u32 v40, v40, v45, s46
	s_nop 1
	v_and_b32_sdwa v45, v41, v142 dst_sel:DWORD dst_unused:UNUSED_PAD src0_sel:WORD_1 src1_sel:DWORD
	s_nop 0
	v_add3_u32 v41, v41, v45, s46
	s_nop 0
	v_and_b32_e32 v44, 0xffff0000, v41
	v_cvt_pk_bf16_f32 v41, v42, v43
	v_or_b32_sdwa v40, v44, v40 dst_sel:DWORD dst_unused:UNUSED_PAD src0_sel:DWORD src1_sel:WORD_1
	global_store_dwordx2 v[60:61], v[40:41], off offset:32
	s_nop 0
	v_and_b32_sdwa v41, v36, v142 dst_sel:DWORD dst_unused:UNUSED_PAD src0_sel:WORD_1 src1_sel:DWORD
	v_add3_u32 v36, v36, v41, s46
	s_nop 1
	v_and_b32_sdwa v41, v37, v142 dst_sel:DWORD dst_unused:UNUSED_PAD src0_sel:WORD_1 src1_sel:DWORD
	s_nop 0
	v_add3_u32 v37, v37, v41, s46
	s_nop 0
	v_and_b32_e32 v40, 0xffff0000, v37
	v_cvt_pk_bf16_f32 v37, v38, v39
	v_or_b32_sdwa v36, v40, v36 dst_sel:DWORD dst_unused:UNUSED_PAD src0_sel:DWORD src1_sel:WORD_1
	global_store_dwordx2 v[56:57], v[36:37], off offset:32
	s_nop 0
	v_and_b32_sdwa v37, v32, v142 dst_sel:DWORD dst_unused:UNUSED_PAD src0_sel:WORD_1 src1_sel:DWORD
	v_add3_u32 v32, v32, v37, s46
	s_nop 1
	v_and_b32_sdwa v37, v33, v142 dst_sel:DWORD dst_unused:UNUSED_PAD src0_sel:WORD_1 src1_sel:DWORD
	s_nop 0
	v_add3_u32 v33, v33, v37, s46
	s_nop 0
	v_and_b32_e32 v36, 0xffff0000, v33
	v_cvt_pk_bf16_f32 v33, v34, v35
	v_or_b32_sdwa v32, v36, v32 dst_sel:DWORD dst_unused:UNUSED_PAD src0_sel:DWORD src1_sel:WORD_1
	global_store_dwordx2 v[52:53], v[32:33], off offset:32
	s_nop 0
	v_and_b32_sdwa v33, v28, v142 dst_sel:DWORD dst_unused:UNUSED_PAD src0_sel:WORD_1 src1_sel:DWORD
	v_add3_u32 v28, v28, v33, s46
	s_nop 1
	v_and_b32_sdwa v33, v29, v142 dst_sel:DWORD dst_unused:UNUSED_PAD src0_sel:WORD_1 src1_sel:DWORD
	s_nop 0
	v_add3_u32 v29, v29, v33, s46
	s_nop 0
	v_and_b32_e32 v32, 0xffff0000, v29
	v_cvt_pk_bf16_f32 v29, v30, v31
	v_or_b32_sdwa v28, v32, v28 dst_sel:DWORD dst_unused:UNUSED_PAD src0_sel:DWORD src1_sel:WORD_1
	global_store_dwordx2 v[66:67], v[28:29], off offset:64
	s_nop 0
	v_and_b32_sdwa v29, v24, v142 dst_sel:DWORD dst_unused:UNUSED_PAD src0_sel:WORD_1 src1_sel:DWORD
	v_add3_u32 v24, v24, v29, s46
	s_nop 1
	v_and_b32_sdwa v29, v25, v142 dst_sel:DWORD dst_unused:UNUSED_PAD src0_sel:WORD_1 src1_sel:DWORD
	s_nop 0
	v_add3_u32 v25, v25, v29, s46
	s_nop 0
	v_and_b32_e32 v28, 0xffff0000, v25
	v_cvt_pk_bf16_f32 v25, v26, v27
	v_or_b32_sdwa v24, v28, v24 dst_sel:DWORD dst_unused:UNUSED_PAD src0_sel:DWORD src1_sel:WORD_1
	global_store_dwordx2 v[60:61], v[24:25], off offset:64
	s_nop 0
	v_and_b32_sdwa v25, v20, v142 dst_sel:DWORD dst_unused:UNUSED_PAD src0_sel:WORD_1 src1_sel:DWORD
	v_add3_u32 v20, v20, v25, s46
	s_nop 1
	v_and_b32_sdwa v25, v21, v142 dst_sel:DWORD dst_unused:UNUSED_PAD src0_sel:WORD_1 src1_sel:DWORD
	s_nop 0
	v_add3_u32 v21, v21, v25, s46
	s_nop 0
	v_and_b32_e32 v24, 0xffff0000, v21
	v_cvt_pk_bf16_f32 v21, v22, v23
	v_or_b32_sdwa v20, v24, v20 dst_sel:DWORD dst_unused:UNUSED_PAD src0_sel:DWORD src1_sel:WORD_1
	global_store_dwordx2 v[56:57], v[20:21], off offset:64
	s_nop 0
	v_and_b32_sdwa v21, v16, v142 dst_sel:DWORD dst_unused:UNUSED_PAD src0_sel:WORD_1 src1_sel:DWORD
	v_add3_u32 v16, v16, v21, s46
	s_nop 1
	v_and_b32_sdwa v21, v17, v142 dst_sel:DWORD dst_unused:UNUSED_PAD src0_sel:WORD_1 src1_sel:DWORD
	s_nop 0
	v_add3_u32 v17, v17, v21, s46
	s_nop 0
	v_and_b32_e32 v20, 0xffff0000, v17
	v_cvt_pk_bf16_f32 v17, v18, v19
	v_or_b32_sdwa v16, v20, v16 dst_sel:DWORD dst_unused:UNUSED_PAD src0_sel:DWORD src1_sel:WORD_1
	global_store_dwordx2 v[52:53], v[16:17], off offset:64
	v_and_b32_sdwa v16, v14, v142 dst_sel:DWORD dst_unused:UNUSED_PAD src0_sel:WORD_1 src1_sel:DWORD
	v_and_b32_sdwa v17, v12, v142 dst_sel:DWORD dst_unused:UNUSED_PAD src0_sel:WORD_1 src1_sel:DWORD
	v_add3_u32 v12, v12, v17, s46
	v_add3_u32 v14, v14, v16, s46
	v_and_b32_sdwa v16, v15, v142 dst_sel:DWORD dst_unused:UNUSED_PAD src0_sel:WORD_1 src1_sel:DWORD
	v_and_b32_sdwa v17, v13, v142 dst_sel:DWORD dst_unused:UNUSED_PAD src0_sel:WORD_1 src1_sel:DWORD
	v_add3_u32 v15, v15, v16, s46
	v_add3_u32 v13, v13, v17, s46
	v_and_b32_e32 v15, 0xffff0000, v15
	v_and_b32_e32 v16, 0xffff0000, v13
	v_or_b32_sdwa v13, v15, v14 dst_sel:DWORD dst_unused:UNUSED_PAD src0_sel:DWORD src1_sel:WORD_1
	v_or_b32_sdwa v12, v16, v12 dst_sel:DWORD dst_unused:UNUSED_PAD src0_sel:DWORD src1_sel:WORD_1
	global_store_dwordx2 v[66:67], v[12:13], off offset:96
	v_and_b32_sdwa v12, v10, v142 dst_sel:DWORD dst_unused:UNUSED_PAD src0_sel:WORD_1 src1_sel:DWORD
	v_and_b32_sdwa v13, v8, v142 dst_sel:DWORD dst_unused:UNUSED_PAD src0_sel:WORD_1 src1_sel:DWORD
	v_add3_u32 v8, v8, v13, s46
	v_add3_u32 v10, v10, v12, s46
	v_and_b32_sdwa v12, v11, v142 dst_sel:DWORD dst_unused:UNUSED_PAD src0_sel:WORD_1 src1_sel:DWORD
	v_and_b32_sdwa v13, v9, v142 dst_sel:DWORD dst_unused:UNUSED_PAD src0_sel:WORD_1 src1_sel:DWORD
	v_add3_u32 v11, v11, v12, s46
	v_add3_u32 v9, v9, v13, s46
	v_and_b32_e32 v11, 0xffff0000, v11
	v_and_b32_e32 v12, 0xffff0000, v9
	v_or_b32_sdwa v9, v11, v10 dst_sel:DWORD dst_unused:UNUSED_PAD src0_sel:DWORD src1_sel:WORD_1
	v_or_b32_sdwa v8, v12, v8 dst_sel:DWORD dst_unused:UNUSED_PAD src0_sel:DWORD src1_sel:WORD_1
	global_store_dwordx2 v[60:61], v[8:9], off offset:96
	v_and_b32_sdwa v8, v6, v142 dst_sel:DWORD dst_unused:UNUSED_PAD src0_sel:WORD_1 src1_sel:DWORD
	v_and_b32_sdwa v9, v4, v142 dst_sel:DWORD dst_unused:UNUSED_PAD src0_sel:WORD_1 src1_sel:DWORD
	v_add3_u32 v4, v4, v9, s46
	v_add3_u32 v6, v6, v8, s46
	v_and_b32_sdwa v8, v7, v142 dst_sel:DWORD dst_unused:UNUSED_PAD src0_sel:WORD_1 src1_sel:DWORD
	v_and_b32_sdwa v9, v5, v142 dst_sel:DWORD dst_unused:UNUSED_PAD src0_sel:WORD_1 src1_sel:DWORD
	v_add3_u32 v7, v7, v8, s46
	v_add3_u32 v5, v5, v9, s46
	v_and_b32_e32 v7, 0xffff0000, v7
	v_and_b32_e32 v8, 0xffff0000, v5
	v_or_b32_sdwa v5, v7, v6 dst_sel:DWORD dst_unused:UNUSED_PAD src0_sel:DWORD src1_sel:WORD_1
	v_or_b32_sdwa v4, v8, v4 dst_sel:DWORD dst_unused:UNUSED_PAD src0_sel:DWORD src1_sel:WORD_1
	global_store_dwordx2 v[56:57], v[4:5], off offset:96
	v_and_b32_sdwa v4, v2, v142 dst_sel:DWORD dst_unused:UNUSED_PAD src0_sel:WORD_1 src1_sel:DWORD
	v_and_b32_sdwa v5, v0, v142 dst_sel:DWORD dst_unused:UNUSED_PAD src0_sel:WORD_1 src1_sel:DWORD
	v_add3_u32 v0, v0, v5, s46
	v_add3_u32 v2, v2, v4, s46
	v_and_b32_sdwa v4, v3, v142 dst_sel:DWORD dst_unused:UNUSED_PAD src0_sel:WORD_1 src1_sel:DWORD
	v_and_b32_sdwa v5, v1, v142 dst_sel:DWORD dst_unused:UNUSED_PAD src0_sel:WORD_1 src1_sel:DWORD
	v_add3_u32 v3, v3, v4, s46
	v_add3_u32 v1, v1, v5, s46
	v_and_b32_e32 v3, 0xffff0000, v3
	v_and_b32_e32 v4, 0xffff0000, v1
	v_or_b32_sdwa v1, v3, v2 dst_sel:DWORD dst_unused:UNUSED_PAD src0_sel:DWORD src1_sel:WORD_1
	v_or_b32_sdwa v0, v4, v0 dst_sel:DWORD dst_unused:UNUSED_PAD src0_sel:DWORD src1_sel:WORD_1
	global_store_dwordx2 v[52:53], v[0:1], off offset:96
	s_branch .LBB0_119

.LBB0_132:
	s_or_saveexec_b64 s[4:5], s[4:5]
	v_lshl_add_u64 v[140:141], s[94:95], 0, v[130:131]
	v_mov_b32_e32 v130, 1.0
	v_ashrrev_i32_e32 v131, 31, v128
	s_xor_b64 exec, exec, s[4:5]
	v_mov_b32_e32 v130, v128
	v_lshl_add_u64 v[138:139], v[130:131], 1, v[140:141]
	v_mov_b32_e32 v130, 0x3db504f3
	s_or_b64 exec, exec, s[4:5]
	v_mov_b32_e32 v144, v125
	v_mov_b32_e32 v145, v127
	v_mov_b32_e32 v125, v126
	v_mov_b32_e32 v126, v121
	v_mov_b32_e32 v127, v123
	v_pk_mul_f32 v[144:145], v[144:145], v[130:131] op_sel_hi:[1,0]
	v_pk_mul_f32 v[126:127], v[126:127], v[130:131] op_sel_hi:[1,0]
	v_mov_b32_e32 v121, v122
	v_pk_mul_f32 v[124:125], v[124:125], v[130:131] op_sel_hi:[1,0]
	v_pk_mul_f32 v[120:121], v[120:121], v[130:131] op_sel_hi:[1,0]
	s_nop 15
	s_nop 3
	v_cvt_pk_bf16_f32 v123, v125, v145
	v_cvt_pk_bf16_f32 v122, v124, v144
	v_cvt_pk_bf16_f32 v121, v121, v127
	v_cvt_pk_bf16_f32 v120, v120, v126
	global_store_dwordx4 v[138:139], v[120:123], off
	s_nop 1
	v_or_b32_e32 v120, 32, v128
	v_cmp_lt_i32_e64 s[4:5], s48, v120
	s_and_saveexec_b64 s[42:43], s[4:5]
	s_xor_b64 s[42:43], exec, s[42:43]
	s_cbranch_execz .LBB0_140
	s_cmpk_lt_u32 s33, 0x400
	s_mov_b64 s[44:45], -1
	s_cbranch_scc1 .LBB0_137
	v_lshl_add_u64 v[120:121], v[128:129], 1, v[136:137]
	v_lshl_add_u64 v[120:121], v[120:121], 0, s[38:39]
	s_mov_b64 s[44:45], 0

.LBB0_139:
.LBB0_140:
	s_or_saveexec_b64 s[42:43], s[42:43]
	v_mov_b32_e32 v122, 1.0
	s_xor_b64 exec, exec, s[42:43]
	v_mov_b32_e32 v130, v128
	v_lshl_add_u64 v[120:121], v[130:131], 1, v[140:141]
	v_lshl_add_u64 v[120:121], v[120:121], 0, 64
	v_mov_b32_e32 v122, 0x3db504f3
	s_or_b64 exec, exec, s[42:43]
	v_mov_b32_e32 v124, v117
	v_mov_b32_e32 v125, v119
	v_mov_b32_e32 v117, v118
	v_mov_b32_e32 v118, v113
	v_mov_b32_e32 v119, v115
	v_pk_mul_f32 v[124:125], v[124:125], v[122:123] op_sel_hi:[1,0]
	v_pk_mul_f32 v[118:119], v[118:119], v[122:123] op_sel_hi:[1,0]
	v_mov_b32_e32 v113, v114
	v_pk_mul_f32 v[116:117], v[116:117], v[122:123] op_sel_hi:[1,0]
	v_pk_mul_f32 v[112:113], v[112:113], v[122:123] op_sel_hi:[1,0]
	s_nop 15
	s_nop 3
	v_cvt_pk_bf16_f32 v115, v117, v125
	v_cvt_pk_bf16_f32 v114, v116, v124
	v_cvt_pk_bf16_f32 v113, v113, v119
	v_cvt_pk_bf16_f32 v112, v112, v118
	global_store_dwordx4 v[120:121], v[112:115], off
	v_readlane_b32 s42, v254, 62
	v_readlane_b32 s43, v254, 63
	v_or_b32_e32 v112, 16, v132
	v_ashrrev_i32_e32 v113, 31, v112
	v_lshlrev_b64 v[114:115], 11, v[112:113]
	v_lshlrev_b64 v[118:119], 10, v[112:113]
	v_lshl_add_u64 v[114:115], s[42:43], 0, v[114:115]
	v_lshl_add_u64 v[112:113], s[96:97], 0, v[118:119]
	s_and_saveexec_b64 s[42:43], s[2:3]
	s_xor_b64 s[42:43], exec, s[42:43]
	s_cbranch_execz .LBB0_147
	s_cmpk_lt_u32 s33, 0x400
	s_mov_b64 s[44:45], -1
	s_cbranch_scc1 .LBB0_145
	v_lshl_add_u64 v[116:117], v[128:129], 1, v[114:115]
	v_lshl_add_u64 v[116:117], v[116:117], 0, s[34:35]
	s_mov_b64 s[44:45], 0

.LBB0_147:
	s_or_saveexec_b64 s[42:43], s[42:43]
	v_lshl_add_u64 v[118:119], s[94:95], 0, v[118:119]
	v_mov_b32_e32 v120, 1.0
	s_xor_b64 exec, exec, s[42:43]
	v_mov_b32_e32 v130, v128
	v_lshl_add_u64 v[116:117], v[130:131], 1, v[118:119]
	v_mov_b32_e32 v120, 0x3db504f3
	s_or_b64 exec, exec, s[42:43]
	v_mov_b32_e32 v122, v109
	v_mov_b32_e32 v123, v111
	v_mov_b32_e32 v109, v110
	v_mov_b32_e32 v110, v105
	v_mov_b32_e32 v111, v107
	v_pk_mul_f32 v[122:123], v[122:123], v[120:121] op_sel_hi:[1,0]
	v_pk_mul_f32 v[110:111], v[110:111], v[120:121] op_sel_hi:[1,0]
	v_mov_b32_e32 v105, v106
	v_pk_mul_f32 v[108:109], v[108:109], v[120:121] op_sel_hi:[1,0]
	v_pk_mul_f32 v[104:105], v[104:105], v[120:121] op_sel_hi:[1,0]
	s_nop 15
	s_nop 3
	v_cvt_pk_bf16_f32 v107, v109, v123
	v_cvt_pk_bf16_f32 v106, v108, v122
	v_cvt_pk_bf16_f32 v105, v105, v111
	v_cvt_pk_bf16_f32 v104, v104, v110
	global_store_dwordx4 v[116:117], v[104:107], off
	s_and_saveexec_b64 s[42:43], s[4:5]
	s_xor_b64 s[42:43], exec, s[42:43]
	s_cbranch_execz .LBB0_155
	s_cmpk_lt_u32 s33, 0x400
	s_mov_b64 s[44:45], -1
	s_cbranch_scc1 .LBB0_152
	v_lshl_add_u64 v[104:105], v[128:129], 1, v[114:115]
	v_lshl_add_u64 v[104:105], v[104:105], 0, s[38:39]
	s_mov_b64 s[44:45], 0

.LBB0_154:
.LBB0_155:
	s_or_saveexec_b64 s[42:43], s[42:43]
	v_mov_b32_e32 v106, 1.0
	s_xor_b64 exec, exec, s[42:43]
	v_mov_b32_e32 v130, v128
	v_lshl_add_u64 v[104:105], v[130:131], 1, v[118:119]
	v_lshl_add_u64 v[104:105], v[104:105], 0, 64
	v_mov_b32_e32 v106, 0x3db504f3
	s_or_b64 exec, exec, s[42:43]
	v_mov_b32_e32 v108, v101
	v_mov_b32_e32 v109, v103
	v_mov_b32_e32 v101, v102
	v_mov_b32_e32 v102, v97
	v_mov_b32_e32 v103, v99
	v_pk_mul_f32 v[108:109], v[108:109], v[106:107] op_sel_hi:[1,0]
	v_pk_mul_f32 v[102:103], v[102:103], v[106:107] op_sel_hi:[1,0]
	v_mov_b32_e32 v97, v98
	v_pk_mul_f32 v[100:101], v[100:101], v[106:107] op_sel_hi:[1,0]
	v_pk_mul_f32 v[96:97], v[96:97], v[106:107] op_sel_hi:[1,0]
	s_nop 15
	s_nop 3
	v_cvt_pk_bf16_f32 v99, v101, v109
	v_cvt_pk_bf16_f32 v98, v100, v108
	v_cvt_pk_bf16_f32 v97, v97, v103
	v_cvt_pk_bf16_f32 v96, v96, v102
	global_store_dwordx4 v[104:105], v[96:99], off
	v_readlane_b32 s42, v254, 62
	v_readlane_b32 s43, v254, 63
	v_or_b32_e32 v96, 32, v132
	v_ashrrev_i32_e32 v97, 31, v96
	v_lshlrev_b64 v[98:99], 11, v[96:97]
	v_lshlrev_b64 v[102:103], 10, v[96:97]
	v_lshl_add_u64 v[98:99], s[42:43], 0, v[98:99]
	v_lshl_add_u64 v[96:97], s[96:97], 0, v[102:103]
	s_and_saveexec_b64 s[42:43], s[2:3]
	s_xor_b64 s[42:43], exec, s[42:43]
	s_cbranch_execz .LBB0_162
	s_cmpk_lt_u32 s33, 0x400
	s_mov_b64 s[44:45], -1
	s_cbranch_scc1 .LBB0_160
	v_lshl_add_u64 v[100:101], v[128:129], 1, v[98:99]
	v_lshl_add_u64 v[100:101], v[100:101], 0, s[34:35]
	s_mov_b64 s[44:45], 0

.LBB0_162:
	s_or_saveexec_b64 s[42:43], s[42:43]
	v_lshl_add_u64 v[102:103], s[94:95], 0, v[102:103]
	v_mov_b32_e32 v104, 1.0
	s_xor_b64 exec, exec, s[42:43]
	v_mov_b32_e32 v130, v128
	v_lshl_add_u64 v[100:101], v[130:131], 1, v[102:103]
	v_mov_b32_e32 v104, 0x3db504f3
	s_or_b64 exec, exec, s[42:43]
	v_mov_b32_e32 v106, v93
	v_mov_b32_e32 v107, v95
	v_mov_b32_e32 v93, v94
	v_mov_b32_e32 v94, v89
	v_mov_b32_e32 v95, v91
	v_pk_mul_f32 v[106:107], v[106:107], v[104:105] op_sel_hi:[1,0]
	v_pk_mul_f32 v[94:95], v[94:95], v[104:105] op_sel_hi:[1,0]
	v_mov_b32_e32 v89, v90
	v_pk_mul_f32 v[92:93], v[92:93], v[104:105] op_sel_hi:[1,0]
	v_pk_mul_f32 v[88:89], v[88:89], v[104:105] op_sel_hi:[1,0]
	s_nop 15
	s_nop 3
	v_cvt_pk_bf16_f32 v91, v93, v107
	v_cvt_pk_bf16_f32 v90, v92, v106
	v_cvt_pk_bf16_f32 v89, v89, v95
	v_cvt_pk_bf16_f32 v88, v88, v94
	global_store_dwordx4 v[100:101], v[88:91], off
	s_and_saveexec_b64 s[42:43], s[4:5]
	s_xor_b64 s[42:43], exec, s[42:43]
	s_cbranch_execz .LBB0_170
	s_cmpk_lt_u32 s33, 0x400
	s_mov_b64 s[44:45], -1
	s_cbranch_scc1 .LBB0_167
	v_lshl_add_u64 v[88:89], v[128:129], 1, v[98:99]
	v_lshl_add_u64 v[88:89], v[88:89], 0, s[38:39]
	s_mov_b64 s[44:45], 0

.LBB0_169:
.LBB0_170:
	s_or_saveexec_b64 s[42:43], s[42:43]
	v_mov_b32_e32 v90, 1.0
	s_xor_b64 exec, exec, s[42:43]
	v_mov_b32_e32 v130, v128
	v_lshl_add_u64 v[88:89], v[130:131], 1, v[102:103]
	v_lshl_add_u64 v[88:89], v[88:89], 0, 64
	v_mov_b32_e32 v90, 0x3db504f3
	s_or_b64 exec, exec, s[42:43]
	v_mov_b32_e32 v92, v85
	v_mov_b32_e32 v93, v87
	v_mov_b32_e32 v85, v86
	v_mov_b32_e32 v86, v81
	v_mov_b32_e32 v87, v83
	v_pk_mul_f32 v[92:93], v[92:93], v[90:91] op_sel_hi:[1,0]
	v_pk_mul_f32 v[86:87], v[86:87], v[90:91] op_sel_hi:[1,0]
	v_mov_b32_e32 v81, v82
	v_pk_mul_f32 v[84:85], v[84:85], v[90:91] op_sel_hi:[1,0]
	v_pk_mul_f32 v[80:81], v[80:81], v[90:91] op_sel_hi:[1,0]
	s_nop 15
	s_nop 3
	v_cvt_pk_bf16_f32 v83, v85, v93
	v_cvt_pk_bf16_f32 v82, v84, v92
	v_cvt_pk_bf16_f32 v81, v81, v87
	v_cvt_pk_bf16_f32 v80, v80, v86
	global_store_dwordx4 v[88:89], v[80:83], off
	v_readlane_b32 s42, v254, 62
	v_readlane_b32 s43, v254, 63
	v_or_b32_e32 v80, 48, v132
	v_ashrrev_i32_e32 v81, 31, v80
	v_lshlrev_b64 v[82:83], 11, v[80:81]
	v_lshlrev_b64 v[86:87], 10, v[80:81]
	v_lshl_add_u64 v[82:83], s[42:43], 0, v[82:83]
	v_lshl_add_u64 v[80:81], s[96:97], 0, v[86:87]
	s_and_saveexec_b64 s[42:43], s[2:3]
	s_xor_b64 s[42:43], exec, s[42:43]
	s_cbranch_execz .LBB0_177
	s_cmpk_lt_u32 s33, 0x400
	s_mov_b64 s[44:45], -1
	s_cbranch_scc1 .LBB0_175
	v_lshl_add_u64 v[84:85], v[128:129], 1, v[82:83]
	v_lshl_add_u64 v[84:85], v[84:85], 0, s[34:35]
	s_mov_b64 s[44:45], 0

.LBB0_177:
	s_or_saveexec_b64 s[42:43], s[42:43]
	v_lshl_add_u64 v[86:87], s[94:95], 0, v[86:87]
	v_mov_b32_e32 v88, 1.0
	s_xor_b64 exec, exec, s[42:43]
	v_mov_b32_e32 v130, v128
	v_lshl_add_u64 v[84:85], v[130:131], 1, v[86:87]
	v_mov_b32_e32 v88, 0x3db504f3
	s_or_b64 exec, exec, s[42:43]
	v_mov_b32_e32 v90, v77
	v_mov_b32_e32 v91, v79
	v_mov_b32_e32 v77, v78
	v_mov_b32_e32 v78, v73
	v_mov_b32_e32 v79, v75
	v_pk_mul_f32 v[90:91], v[90:91], v[88:89] op_sel_hi:[1,0]
	v_pk_mul_f32 v[78:79], v[78:79], v[88:89] op_sel_hi:[1,0]
	v_mov_b32_e32 v73, v74
	v_pk_mul_f32 v[76:77], v[76:77], v[88:89] op_sel_hi:[1,0]
	v_pk_mul_f32 v[72:73], v[72:73], v[88:89] op_sel_hi:[1,0]
	s_nop 15
	s_nop 3
	v_cvt_pk_bf16_f32 v75, v77, v91
	v_cvt_pk_bf16_f32 v74, v76, v90
	v_cvt_pk_bf16_f32 v73, v73, v79
	v_cvt_pk_bf16_f32 v72, v72, v78
	global_store_dwordx4 v[84:85], v[72:75], off
	s_and_saveexec_b64 s[42:43], s[4:5]
	s_xor_b64 s[42:43], exec, s[42:43]
	s_cbranch_execz .LBB0_185
	s_cmpk_lt_u32 s33, 0x400
	s_mov_b64 s[44:45], -1
	s_cbranch_scc1 .LBB0_182
	v_lshl_add_u64 v[72:73], v[128:129], 1, v[82:83]
	v_lshl_add_u64 v[72:73], v[72:73], 0, s[38:39]
	s_mov_b64 s[44:45], 0

.LBB0_184:
.LBB0_185:
	s_or_saveexec_b64 s[42:43], s[42:43]
	v_mov_b32_e32 v74, 1.0
	s_xor_b64 exec, exec, s[42:43]
	v_mov_b32_e32 v130, v128
	v_lshl_add_u64 v[72:73], v[130:131], 1, v[86:87]
	v_lshl_add_u64 v[72:73], v[72:73], 0, 64
	v_mov_b32_e32 v74, 0x3db504f3
	s_or_b64 exec, exec, s[42:43]
	v_mov_b32_e32 v76, v69
	v_mov_b32_e32 v77, v71
	v_mov_b32_e32 v69, v70
	v_mov_b32_e32 v70, v65
	v_mov_b32_e32 v71, v67
	v_pk_mul_f32 v[76:77], v[76:77], v[74:75] op_sel_hi:[1,0]
	v_pk_mul_f32 v[70:71], v[70:71], v[74:75] op_sel_hi:[1,0]
	v_mov_b32_e32 v65, v66
	v_pk_mul_f32 v[68:69], v[68:69], v[74:75] op_sel_hi:[1,0]
	v_pk_mul_f32 v[64:65], v[64:65], v[74:75] op_sel_hi:[1,0]
	s_nop 15
	s_nop 3
	v_cvt_pk_bf16_f32 v67, v69, v77
	v_cvt_pk_bf16_f32 v66, v68, v76
	v_cvt_pk_bf16_f32 v65, v65, v71
	v_cvt_pk_bf16_f32 v64, v64, v70
	global_store_dwordx4 v[72:73], v[64:67], off
	v_readlane_b32 s42, v254, 62
	v_readlane_b32 s43, v254, 63
	v_or_b32_e32 v64, 64, v132
	v_ashrrev_i32_e32 v65, 31, v64
	v_lshlrev_b64 v[66:67], 11, v[64:65]
	v_lshlrev_b64 v[70:71], 10, v[64:65]
	v_lshl_add_u64 v[66:67], s[42:43], 0, v[66:67]
	v_lshl_add_u64 v[64:65], s[96:97], 0, v[70:71]
	s_and_saveexec_b64 s[42:43], s[2:3]
	s_xor_b64 s[42:43], exec, s[42:43]
	s_cbranch_execz .LBB0_192
	s_cmpk_lt_u32 s33, 0x400
	s_mov_b64 s[44:45], -1
	s_cbranch_scc1 .LBB0_190
	v_lshl_add_u64 v[68:69], v[128:129], 1, v[66:67]
	v_lshl_add_u64 v[68:69], v[68:69], 0, s[34:35]
	s_mov_b64 s[44:45], 0

.LBB0_192:
	s_or_saveexec_b64 s[42:43], s[42:43]
	v_lshl_add_u64 v[70:71], s[94:95], 0, v[70:71]
	v_mov_b32_e32 v72, 1.0
	s_xor_b64 exec, exec, s[42:43]
	v_mov_b32_e32 v130, v128
	v_lshl_add_u64 v[68:69], v[130:131], 1, v[70:71]
	v_mov_b32_e32 v72, 0x3db504f3
	s_or_b64 exec, exec, s[42:43]
	v_mov_b32_e32 v74, v61
	v_mov_b32_e32 v75, v63
	v_mov_b32_e32 v61, v62
	v_mov_b32_e32 v62, v57
	v_mov_b32_e32 v63, v59
	v_pk_mul_f32 v[74:75], v[74:75], v[72:73] op_sel_hi:[1,0]
	v_pk_mul_f32 v[62:63], v[62:63], v[72:73] op_sel_hi:[1,0]
	v_mov_b32_e32 v57, v58
	v_pk_mul_f32 v[60:61], v[60:61], v[72:73] op_sel_hi:[1,0]
	v_pk_mul_f32 v[56:57], v[56:57], v[72:73] op_sel_hi:[1,0]
	s_nop 15
	s_nop 3
	v_cvt_pk_bf16_f32 v59, v61, v75
	v_cvt_pk_bf16_f32 v58, v60, v74
	v_cvt_pk_bf16_f32 v57, v57, v63
	v_cvt_pk_bf16_f32 v56, v56, v62
	global_store_dwordx4 v[68:69], v[56:59], off
	s_and_saveexec_b64 s[42:43], s[4:5]
	s_xor_b64 s[42:43], exec, s[42:43]
	s_cbranch_execz .LBB0_200
	s_cmpk_lt_u32 s33, 0x400
	s_mov_b64 s[44:45], -1
	s_cbranch_scc1 .LBB0_197
	v_lshl_add_u64 v[56:57], v[128:129], 1, v[66:67]
	v_lshl_add_u64 v[56:57], v[56:57], 0, s[38:39]
	s_mov_b64 s[44:45], 0

.LBB0_199:
.LBB0_200:
	s_or_saveexec_b64 s[42:43], s[42:43]
	v_mov_b32_e32 v58, 1.0
	s_xor_b64 exec, exec, s[42:43]
	v_mov_b32_e32 v130, v128
	v_lshl_add_u64 v[56:57], v[130:131], 1, v[70:71]
	v_lshl_add_u64 v[56:57], v[56:57], 0, 64
	v_mov_b32_e32 v58, 0x3db504f3
	s_or_b64 exec, exec, s[42:43]
	v_mov_b32_e32 v60, v53
	v_mov_b32_e32 v61, v55
	v_mov_b32_e32 v53, v54
	v_mov_b32_e32 v54, v49
	v_mov_b32_e32 v55, v51
	v_pk_mul_f32 v[60:61], v[60:61], v[58:59] op_sel_hi:[1,0]
	v_pk_mul_f32 v[54:55], v[54:55], v[58:59] op_sel_hi:[1,0]
	v_mov_b32_e32 v49, v50
	v_pk_mul_f32 v[52:53], v[52:53], v[58:59] op_sel_hi:[1,0]
	v_pk_mul_f32 v[48:49], v[48:49], v[58:59] op_sel_hi:[1,0]
	s_nop 15
	s_nop 3
	v_cvt_pk_bf16_f32 v51, v53, v61
	v_cvt_pk_bf16_f32 v50, v52, v60
	v_cvt_pk_bf16_f32 v49, v49, v55
	v_cvt_pk_bf16_f32 v48, v48, v54
	global_store_dwordx4 v[56:57], v[48:51], off
	v_readlane_b32 s42, v254, 62
	v_readlane_b32 s43, v254, 63
	v_or_b32_e32 v48, 0x50, v132
	v_ashrrev_i32_e32 v49, 31, v48
	v_lshlrev_b64 v[50:51], 11, v[48:49]
	v_lshlrev_b64 v[54:55], 10, v[48:49]
	v_lshl_add_u64 v[50:51], s[42:43], 0, v[50:51]
	v_lshl_add_u64 v[48:49], s[96:97], 0, v[54:55]
	s_and_saveexec_b64 s[42:43], s[2:3]
	s_xor_b64 s[42:43], exec, s[42:43]
	s_cbranch_execz .LBB0_207
	s_cmpk_lt_u32 s33, 0x400
	s_mov_b64 s[44:45], -1
	s_cbranch_scc1 .LBB0_205
	v_lshl_add_u64 v[52:53], v[128:129], 1, v[50:51]
	v_lshl_add_u64 v[52:53], v[52:53], 0, s[34:35]
	s_mov_b64 s[44:45], 0

.LBB0_207:
	s_or_saveexec_b64 s[42:43], s[42:43]
	v_lshl_add_u64 v[54:55], s[94:95], 0, v[54:55]
	v_mov_b32_e32 v56, 1.0
	s_xor_b64 exec, exec, s[42:43]
	v_mov_b32_e32 v130, v128
	v_lshl_add_u64 v[52:53], v[130:131], 1, v[54:55]
	v_mov_b32_e32 v56, 0x3db504f3
	s_or_b64 exec, exec, s[42:43]
	v_mov_b32_e32 v58, v45
	v_mov_b32_e32 v59, v47
	v_mov_b32_e32 v45, v46
	v_mov_b32_e32 v46, v41
	v_mov_b32_e32 v47, v43
	v_pk_mul_f32 v[58:59], v[58:59], v[56:57] op_sel_hi:[1,0]
	v_pk_mul_f32 v[46:47], v[46:47], v[56:57] op_sel_hi:[1,0]
	v_mov_b32_e32 v41, v42
	v_pk_mul_f32 v[44:45], v[44:45], v[56:57] op_sel_hi:[1,0]
	v_pk_mul_f32 v[40:41], v[40:41], v[56:57] op_sel_hi:[1,0]
	s_nop 15
	s_nop 3
	v_cvt_pk_bf16_f32 v43, v45, v59
	v_cvt_pk_bf16_f32 v42, v44, v58
	v_cvt_pk_bf16_f32 v41, v41, v47
	v_cvt_pk_bf16_f32 v40, v40, v46
	global_store_dwordx4 v[52:53], v[40:43], off
	s_and_saveexec_b64 s[42:43], s[4:5]
	s_xor_b64 s[42:43], exec, s[42:43]
	s_cbranch_execz .LBB0_215
	s_cmpk_lt_u32 s33, 0x400
	s_mov_b64 s[44:45], -1
	s_cbranch_scc1 .LBB0_212
	v_lshl_add_u64 v[40:41], v[128:129], 1, v[50:51]
	v_lshl_add_u64 v[40:41], v[40:41], 0, s[38:39]
	s_mov_b64 s[44:45], 0

.LBB0_214:
.LBB0_215:
	s_or_saveexec_b64 s[42:43], s[42:43]
	v_mov_b32_e32 v42, 1.0
	s_xor_b64 exec, exec, s[42:43]
	v_mov_b32_e32 v130, v128
	v_lshl_add_u64 v[40:41], v[130:131], 1, v[54:55]
	v_lshl_add_u64 v[40:41], v[40:41], 0, 64
	v_mov_b32_e32 v42, 0x3db504f3
	s_or_b64 exec, exec, s[42:43]
	v_mov_b32_e32 v44, v37
	v_mov_b32_e32 v45, v39
	v_mov_b32_e32 v37, v38
	v_mov_b32_e32 v38, v33
	v_mov_b32_e32 v39, v35
	v_pk_mul_f32 v[44:45], v[44:45], v[42:43] op_sel_hi:[1,0]
	v_pk_mul_f32 v[38:39], v[38:39], v[42:43] op_sel_hi:[1,0]
	v_mov_b32_e32 v33, v34
	v_pk_mul_f32 v[36:37], v[36:37], v[42:43] op_sel_hi:[1,0]
	v_pk_mul_f32 v[32:33], v[32:33], v[42:43] op_sel_hi:[1,0]
	s_nop 15
	s_nop 3
	v_cvt_pk_bf16_f32 v35, v37, v45
	v_cvt_pk_bf16_f32 v34, v36, v44
	v_cvt_pk_bf16_f32 v33, v33, v39
	v_cvt_pk_bf16_f32 v32, v32, v38
	global_store_dwordx4 v[40:41], v[32:35], off
	v_readlane_b32 s42, v254, 62
	v_readlane_b32 s43, v254, 63
	v_or_b32_e32 v32, 0x60, v132
	v_ashrrev_i32_e32 v33, 31, v32
	v_lshlrev_b64 v[34:35], 11, v[32:33]
	v_lshlrev_b64 v[38:39], 10, v[32:33]
	v_lshl_add_u64 v[34:35], s[42:43], 0, v[34:35]
	v_lshl_add_u64 v[32:33], s[96:97], 0, v[38:39]
	s_and_saveexec_b64 s[42:43], s[2:3]
	s_xor_b64 s[42:43], exec, s[42:43]
	s_cbranch_execz .LBB0_222
	s_cmpk_lt_u32 s33, 0x400
	s_mov_b64 s[44:45], -1
	s_cbranch_scc1 .LBB0_220
	v_lshl_add_u64 v[36:37], v[128:129], 1, v[34:35]
	v_lshl_add_u64 v[36:37], v[36:37], 0, s[34:35]
	s_mov_b64 s[44:45], 0

.LBB0_222:
	s_or_saveexec_b64 s[42:43], s[42:43]
	v_lshl_add_u64 v[38:39], s[94:95], 0, v[38:39]
	v_mov_b32_e32 v40, 1.0
	s_xor_b64 exec, exec, s[42:43]
	v_mov_b32_e32 v130, v128
	v_lshl_add_u64 v[36:37], v[130:131], 1, v[38:39]
	v_mov_b32_e32 v40, 0x3db504f3
	s_or_b64 exec, exec, s[42:43]
	v_mov_b32_e32 v42, v29
	v_mov_b32_e32 v43, v31
	v_mov_b32_e32 v29, v30
	v_mov_b32_e32 v30, v25
	v_mov_b32_e32 v31, v27
	v_pk_mul_f32 v[42:43], v[42:43], v[40:41] op_sel_hi:[1,0]
	v_pk_mul_f32 v[30:31], v[30:31], v[40:41] op_sel_hi:[1,0]
	v_mov_b32_e32 v25, v26
	v_pk_mul_f32 v[28:29], v[28:29], v[40:41] op_sel_hi:[1,0]
	v_pk_mul_f32 v[24:25], v[24:25], v[40:41] op_sel_hi:[1,0]
	s_nop 15
	s_nop 3
	v_cvt_pk_bf16_f32 v27, v29, v43
	v_cvt_pk_bf16_f32 v26, v28, v42
	v_cvt_pk_bf16_f32 v25, v25, v31
	v_cvt_pk_bf16_f32 v24, v24, v30
	global_store_dwordx4 v[36:37], v[24:27], off
	s_and_saveexec_b64 s[42:43], s[4:5]
	s_xor_b64 s[42:43], exec, s[42:43]
	s_cbranch_execz .LBB0_230
	s_cmpk_lt_u32 s33, 0x400
	s_mov_b64 s[44:45], -1
	s_cbranch_scc1 .LBB0_227
	v_lshl_add_u64 v[24:25], v[128:129], 1, v[34:35]
	v_lshl_add_u64 v[24:25], v[24:25], 0, s[38:39]
	s_mov_b64 s[44:45], 0

.LBB0_229:
.LBB0_230:
	s_or_saveexec_b64 s[42:43], s[42:43]
	v_mov_b32_e32 v26, 1.0
	s_xor_b64 exec, exec, s[42:43]
	v_mov_b32_e32 v130, v128
	v_lshl_add_u64 v[24:25], v[130:131], 1, v[38:39]
	v_lshl_add_u64 v[24:25], v[24:25], 0, 64
	v_mov_b32_e32 v26, 0x3db504f3
	s_or_b64 exec, exec, s[42:43]
	v_mov_b32_e32 v28, v21
	v_mov_b32_e32 v29, v23
	v_mov_b32_e32 v21, v22
	v_mov_b32_e32 v22, v17
	v_mov_b32_e32 v23, v19
	v_pk_mul_f32 v[28:29], v[28:29], v[26:27] op_sel_hi:[1,0]
	v_pk_mul_f32 v[22:23], v[22:23], v[26:27] op_sel_hi:[1,0]
	v_mov_b32_e32 v17, v18
	v_pk_mul_f32 v[20:21], v[20:21], v[26:27] op_sel_hi:[1,0]
	v_pk_mul_f32 v[16:17], v[16:17], v[26:27] op_sel_hi:[1,0]
	s_nop 15
	s_nop 3
	v_cvt_pk_bf16_f32 v19, v21, v29
	v_cvt_pk_bf16_f32 v18, v20, v28
	v_cvt_pk_bf16_f32 v17, v17, v23
	v_cvt_pk_bf16_f32 v16, v16, v22
	global_store_dwordx4 v[24:25], v[16:19], off
	v_readlane_b32 s42, v254, 62
	v_readlane_b32 s43, v254, 63
	v_or_b32_e32 v16, 0x70, v132
	v_ashrrev_i32_e32 v17, 31, v16
	v_lshlrev_b64 v[18:19], 11, v[16:17]
	v_lshlrev_b64 v[22:23], 10, v[16:17]
	v_lshl_add_u64 v[18:19], s[42:43], 0, v[18:19]
	v_lshl_add_u64 v[16:17], s[96:97], 0, v[22:23]
	s_and_saveexec_b64 s[42:43], s[2:3]
	s_xor_b64 s[2:3], exec, s[42:43]
	s_cbranch_execz .LBB0_237
	s_cmpk_lt_u32 s33, 0x400
	s_mov_b64 s[42:43], -1
	s_cbranch_scc1 .LBB0_235
	v_lshl_add_u64 v[20:21], v[128:129], 1, v[18:19]
	v_lshl_add_u64 v[20:21], v[20:21], 0, s[34:35]
	s_mov_b64 s[42:43], 0

.LBB0_237:
	s_or_saveexec_b64 s[2:3], s[2:3]
	v_lshl_add_u64 v[22:23], s[94:95], 0, v[22:23]
	v_mov_b32_e32 v24, 1.0
	s_xor_b64 exec, exec, s[2:3]
	v_mov_b32_e32 v130, v128
	v_lshl_add_u64 v[20:21], v[130:131], 1, v[22:23]
	v_mov_b32_e32 v24, 0x3db504f3
	s_or_b64 exec, exec, s[2:3]
	v_mov_b32_e32 v26, v13
	v_mov_b32_e32 v27, v15
	v_mov_b32_e32 v13, v14
	v_mov_b32_e32 v14, v9
	v_mov_b32_e32 v15, v11
	v_pk_mul_f32 v[26:27], v[26:27], v[24:25] op_sel_hi:[1,0]
	v_pk_mul_f32 v[14:15], v[14:15], v[24:25] op_sel_hi:[1,0]
	v_mov_b32_e32 v9, v10
	v_pk_mul_f32 v[12:13], v[12:13], v[24:25] op_sel_hi:[1,0]
	v_pk_mul_f32 v[8:9], v[8:9], v[24:25] op_sel_hi:[1,0]
	s_nop 1
	v_bfe_u32 v24, v15, 16, 1
	v_bfe_u32 v25, v14, 16, 1
	v_add3_u32 v14, v14, v25, s46
	v_add3_u32 v15, v15, v24, s46
	s_nop 1
	v_bfe_u32 v11, v8, 16, 1
	v_bfe_u32 v25, v9, 16, 1
	s_nop 3
	v_add3_u32 v9, v9, v25, s46
	v_add3_u32 v8, v8, v11, s46
	v_lshrrev_b32_e32 v8, 16, v8
	v_lshrrev_b32_e32 v9, 16, v9
	s_nop 1
	v_cvt_pk_bf16_f32 v11, v13, v27
	v_cvt_pk_bf16_f32 v10, v12, v26
	v_and_or_b32 v9, v15, s47, v9
	v_and_or_b32 v8, v14, s47, v8
	global_store_dwordx4 v[20:21], v[8:11], off
	s_and_saveexec_b64 s[2:3], s[4:5]
	s_xor_b64 s[2:3], exec, s[2:3]
	s_cbranch_execz .LBB0_245
	s_cmpk_lt_u32 s33, 0x400
	s_mov_b64 s[4:5], -1
	s_cbranch_scc1 .LBB0_242
	v_lshl_add_u64 v[8:9], v[128:129], 1, v[18:19]
	v_lshl_add_u64 v[8:9], v[8:9], 0, s[38:39]
	s_mov_b64 s[4:5], 0

.LBB0_269:
	s_andn2_b64 vcc, exec, s[10:11]
	s_cbranch_vccnz .LBB0_271
	v_add_u32_e32 v18, 0xfffffc00, v20
	v_and_b32_sdwa v23, v15, v47 dst_sel:DWORD dst_unused:UNUSED_PAD src0_sel:WORD_1 src1_sel:DWORD
	s_nop 0
	v_lshlrev_b64 v[24:25], 7, v[18:19]
	v_and_b32_sdwa v18, v14, v47 dst_sel:DWORD dst_unused:UNUSED_PAD src0_sel:WORD_1 src1_sel:DWORD
	s_nop 0
	v_add3_u32 v23, v15, v23, s16
	s_nop 1
	v_add3_u32 v18, v14, v18, s16
	v_and_b32_e32 v23, 0xffff0000, v23
	s_nop 0
	v_lshl_add_u64 v[24:25], v[28:29], 0, v[24:25]
	v_or_b32_sdwa v37, v23, v18 dst_sel:DWORD dst_unused:UNUSED_PAD src0_sel:DWORD src1_sel:WORD_1
	v_cvt_pk_bf16_f32 v36, v12, v13
	global_store_dwordx2 v[24:25], v[36:37], off

.LBB0_274:
	v_or_b32_e32 v24, v49, v42
	v_ashrrev_i32_e32 v25, 31, v24
	v_readlane_b32 s2, v254, 62
	v_lshlrev_b64 v[36:37], 11, v[24:25]
	v_or_b32_e32 v18, s18, v44
	v_readlane_b32 s3, v254, 63
	v_lshlrev_b64 v[40:41], 10, v[24:25]
	s_andn2_b64 vcc, exec, s[10:11]
	v_lshl_add_u64 v[38:39], s[2:3], 0, v[36:37]
	v_lshl_add_u64 v[36:37], s[96:97], 0, v[40:41]
	v_lshl_add_u64 v[40:41], s[94:95], 0, v[40:41]
	v_cmp_lt_i32_e64 s[2:3], s15, v18
	s_cbranch_vccnz .LBB0_283
	s_and_saveexec_b64 s[10:11], s[2:3]
	s_xor_b64 s[2:3], exec, s[10:11]
	s_cbranch_execz .LBB0_280
	s_nop 0
	v_and_b32_sdwa v23, v12, v47 dst_sel:DWORD dst_unused:UNUSED_PAD src0_sel:WORD_1 src1_sel:DWORD
	v_add3_u32 v12, v12, v23, s16
	s_nop 1
	v_and_b32_sdwa v23, v13, v47 dst_sel:DWORD dst_unused:UNUSED_PAD src0_sel:WORD_1 src1_sel:DWORD
	s_nop 0
	v_add3_u32 v13, v13, v23, s16
	s_nop 0
	v_and_b32_e32 v13, 0xffff0000, v13
	s_cmpk_gt_u32 s18, 0x3ff
	v_cvt_pk_bf16_f32 v15, v14, v15
	v_or_b32_sdwa v14, v13, v12 dst_sel:DWORD dst_unused:UNUSED_PAD src0_sel:DWORD src1_sel:WORD_1
	s_mov_b64 s[10:11], -1
	s_cbranch_scc0 .LBB0_278
	v_lshl_add_u64 v[12:13], v[18:19], 1, v[38:39]
	global_store_dwordx2 v[12:13], v[14:15], off offset:-4096
	s_mov_b64 s[10:11], 0

.LBB0_280:
	s_andn2_saveexec_b64 s[2:3], s[2:3]
	s_cbranch_execz .LBB0_282
	v_mov_b32_e32 v50, v12
	v_mov_b32_e32 v51, v14
	v_pk_mul_f32 v[50:51], v[50:51], s[8:9] op_sel_hi:[1,0]
	v_mov_b32_e32 v14, v13
	v_pk_mul_f32 v[12:13], v[14:15], s[8:9] op_sel_hi:[1,0]
	s_nop 6
	v_ashrrev_i32_e32 v15, 31, v18
	v_mov_b32_e32 v14, v18
	s_nop 2
	v_lshl_add_u64 v[14:15], v[14:15], 1, v[40:41]
	v_cvt_pk_bf16_f32 v13, v51, v13
	v_cvt_pk_bf16_f32 v12, v50, v12
	global_store_dwordx2 v[14:15], v[12:13], off

.LBB0_288:
	s_andn2_b64 vcc, exec, s[4:5]
	s_cbranch_vccnz .LBB0_290
	s_nop 1
	v_add_u32_e32 v14, 0xfffffc00, v12
	v_mov_b32_e32 v15, v19
	s_nop 3
	v_lshlrev_b64 v[14:15], 7, v[14:15]
	s_nop 3
	v_lshl_add_u64 v[14:15], v[28:29], 0, v[14:15]
	v_cvt_pk_bf16_f32 v27, v10, v11
	v_cvt_pk_bf16_f32 v26, v8, v9
	global_store_dwordx2 v[14:15], v[26:27], off

.LBB0_291:
	v_or_b32_e32 v50, 16, v18
	s_andn2_b64 vcc, exec, s[10:11]
	v_cmp_lt_i32_e64 s[4:5], s15, v50
	s_cbranch_vccnz .LBB0_300
	s_and_saveexec_b64 s[10:11], s[4:5]
	s_xor_b64 s[4:5], exec, s[10:11]
	s_cbranch_execz .LBB0_297
	s_nop 0
	v_and_b32_sdwa v14, v8, v47 dst_sel:DWORD dst_unused:UNUSED_PAD src0_sel:WORD_1 src1_sel:DWORD
	v_add3_u32 v8, v8, v14, s16
	s_nop 1
	v_and_b32_sdwa v14, v9, v47 dst_sel:DWORD dst_unused:UNUSED_PAD src0_sel:WORD_1 src1_sel:DWORD
	s_nop 0
	v_add3_u32 v9, v9, v14, s16
	s_nop 0
	v_and_b32_e32 v9, 0xffff0000, v9
	s_cmpk_lt_u32 s18, 0x400
	v_cvt_pk_bf16_f32 v11, v10, v11
	v_or_b32_sdwa v10, v9, v8 dst_sel:DWORD dst_unused:UNUSED_PAD src0_sel:DWORD src1_sel:WORD_1
	s_mov_b64 s[10:11], -1
	s_cbranch_scc1 .LBB0_295
	v_lshl_add_u64 v[8:9], v[18:19], 1, v[38:39]
	s_mov_b64 s[10:11], 0
	global_store_dwordx2 v[8:9], v[10:11], off offset:-4064

.LBB0_297:
	s_andn2_saveexec_b64 s[4:5], s[4:5]
	s_cbranch_execz .LBB0_299
	v_mov_b32_e32 v14, v8
	v_mov_b32_e32 v15, v10
	v_pk_mul_f32 v[14:15], v[14:15], s[8:9] op_sel_hi:[1,0]
	v_mov_b32_e32 v10, v9
	v_pk_mul_f32 v[8:9], v[10:11], s[8:9] op_sel_hi:[1,0]
	s_nop 7
	v_ashrrev_i32_e32 v11, 31, v18
	v_mov_b32_e32 v10, v18
	s_nop 1
	v_lshl_add_u64 v[10:11], v[10:11], 1, v[40:41]
	v_cvt_pk_bf16_f32 v9, v15, v9
	v_cvt_pk_bf16_f32 v8, v14, v8
	global_store_dwordx2 v[10:11], v[8:9], off offset:32

.LBB0_310:
	s_andn2_b64 vcc, exec, s[10:11]
	s_cbranch_vccnz .LBB0_312
	v_and_b32_sdwa v23, v7, v47 dst_sel:DWORD dst_unused:UNUSED_PAD src0_sel:WORD_1 src1_sel:DWORD
	s_nop 0
	v_add_u32_e32 v20, 0xfffffc00, v20
	v_mov_b32_e32 v21, v19
	v_and_b32_sdwa v13, v6, v47 dst_sel:DWORD dst_unused:UNUSED_PAD src0_sel:WORD_1 src1_sel:DWORD
	s_nop 0
	v_add3_u32 v23, v7, v23, s16
	s_nop 0
	v_lshlrev_b64 v[20:21], 7, v[20:21]
	s_nop 0
	v_add3_u32 v13, v6, v13, s16
	v_and_b32_e32 v23, 0xffff0000, v23
	s_nop 0
	v_lshl_add_u64 v[20:21], v[8:9], 0, v[20:21]
	v_or_b32_sdwa v23, v23, v13 dst_sel:DWORD dst_unused:UNUSED_PAD src0_sel:DWORD src1_sel:WORD_1
	v_cvt_pk_bf16_f32 v22, v4, v5
	global_store_dwordx2 v[20:21], v[22:23], off

.LBB0_323:
	s_andn2_saveexec_b64 s[4:5], s[4:5]
	s_cbranch_execz .LBB0_325
	v_mov_b32_e32 v30, v4
	v_mov_b32_e32 v31, v6
	v_pk_mul_f32 v[30:31], v[30:31], s[8:9] op_sel_hi:[1,0]
	v_mov_b32_e32 v6, v5
	v_pk_mul_f32 v[4:5], v[6:7], s[8:9] op_sel_hi:[1,0]
	v_and_b32_sdwa v13, v31, v47 dst_sel:DWORD dst_unused:UNUSED_PAD src0_sel:WORD_1 src1_sel:DWORD
	s_nop 1
	v_add3_u32 v13, v31, v13, s16
	v_and_b32_sdwa v31, v5, v47 dst_sel:DWORD dst_unused:UNUSED_PAD src0_sel:WORD_1 src1_sel:DWORD
	s_nop 0
	v_add3_u32 v5, v5, v31, s16
	s_nop 0
	v_ashrrev_i32_e32 v7, 31, v18
	v_mov_b32_e32 v6, v18
	v_and_b32_e32 v5, 0xffff0000, v5
	s_nop 0
	v_lshl_add_u64 v[6:7], v[6:7], 1, v[24:25]
	v_or_b32_sdwa v5, v5, v13 dst_sel:DWORD dst_unused:UNUSED_PAD src0_sel:DWORD src1_sel:WORD_1
	v_cvt_pk_bf16_f32 v4, v30, v4
	global_store_dwordx2 v[6:7], v[4:5], off

.LBB0_330:
	s_andn2_b64 vcc, exec, s[2:3]
	s_cbranch_vccnz .LBB0_332
	v_add_u32_e32 v4, 0xfffffc00, v12
	v_mov_b32_e32 v5, v19
	v_lshlrev_b64 v[4:5], 7, v[4:5]
	v_and_b32_sdwa v7, v0, v47 dst_sel:DWORD dst_unused:UNUSED_PAD src0_sel:WORD_1 src1_sel:DWORD
	v_lshl_add_u64 v[4:5], v[8:9], 0, v[4:5]
	v_add3_u32 v8, v0, v7, s16
	s_nop 0
	v_and_b32_sdwa v9, v1, v47 dst_sel:DWORD dst_unused:UNUSED_PAD src0_sel:WORD_1 src1_sel:DWORD
	s_nop 1
	v_add3_u32 v9, v1, v9, s16
	s_nop 1
	v_and_b32_e32 v9, 0xffff0000, v9
	v_cvt_pk_bf16_f32 v7, v2, v3
	v_or_b32_sdwa v6, v9, v8 dst_sel:DWORD dst_unused:UNUSED_PAD src0_sel:DWORD src1_sel:WORD_1
	global_store_dwordx2 v[4:5], v[6:7], off

.LBB0_521:
	s_or_b64 exec, exec, s[4:5]
	s_barrier
	s_waitcnt vmcnt(0)
	ds_write_b32 v24, v0
	ds_write_b32 v24, v1 offset:1040
	ds_write_b32 v24, v2 offset:2080
	ds_write_b32 v24, v3 offset:3120
	ds_write_b32 v24, v4 offset:4160
	ds_write_b32 v24, v5 offset:5200
	ds_write_b32 v24, v6 offset:6240
	ds_write_b32 v24, v7 offset:7280
	ds_write_b32 v24, v8 offset:8320
	ds_write_b32 v24, v9 offset:9360
	ds_write_b32 v24, v10 offset:10400
	ds_write_b32 v24, v11 offset:11440
	ds_write_b32 v24, v12 offset:12480
	ds_write_b32 v24, v13 offset:13520
	ds_write_b32 v24, v14 offset:14560
	ds_write_b32 v24, v15 offset:15600
	s_waitcnt lgkmcnt(0)
	s_barrier
	ds_read2_b32 v[6:7], v23 offset1:32
	ds_read2_b32 v[8:9], v23 offset0:65 offset1:97
	ds_read2_b32 v[10:11], v23 offset0:130 offset1:162
	ds_read2_b32 v[12:13], v23 offset0:195 offset1:227
	v_add_u32_e32 v30, s13, v22
	v_and_b32_e32 v30, -2, v30
	s_ashr_i32 s3, s2, 31
	v_add_u32_e32 v0, 0x400, v23
	v_ashrrev_i32_e32 v31, 31, v30
	v_lshl_add_u64 v[4:5], s[2:3], 2, v[16:17]
	ds_read2_b32 v[14:15], v0 offset0:4 offset1:36
	ds_read2_b32 v[18:19], v0 offset0:69 offset1:101
	ds_read2_b32 v[26:27], v0 offset0:134 offset1:166
	ds_read2_b32 v[28:29], v0 offset0:199 offset1:231
	v_lshlrev_b64 v[0:1], 11, v[30:31]
	v_lshl_add_u64 v[32:33], v[4:5], 0, v[0:1]
	s_waitcnt lgkmcnt(7)
	s_nop 1
	s_waitcnt lgkmcnt(4)
	s_nop 7
	v_cvt_pk_bf16_f32 v1, v10, v12
	v_cvt_pk_bf16_f32 v0, v6, v8
	s_waitcnt lgkmcnt(3)
	s_nop 1
	s_waitcnt lgkmcnt(0)
	s_nop 7
	v_cvt_pk_bf16_f32 v3, v26, v28
	v_cvt_pk_bf16_f32 v2, v14, v18
	global_store_dwordx4 v[32:33], v[0:3], off
	s_add_i32 s12, s12, s6
	s_add_i32 s7, s7, s8
	v_add_u32_e32 v0, 32, v30
	v_ashrrev_i32_e32 v1, 31, v0
	v_lshlrev_b64 v[0:1], 11, v[0:1]
	v_lshl_add_u64 v[4:5], v[4:5], 0, v[0:1]
	s_nop 9
	v_cvt_pk_bf16_f32 v1, v11, v13
	v_cvt_pk_bf16_f32 v0, v7, v9
	s_nop 9
	v_cvt_pk_bf16_f32 v3, v27, v29
	v_cvt_pk_bf16_f32 v2, v15, v19
	s_cmpk_lt_i32 s12, 0x2c0
	global_store_dwordx4 v[4:5], v[0:3], off
	s_cbranch_scc0 .LBB0_554

.LBB0_557:
	s_or_b64 exec, exec, s[4:5]
	s_barrier
	s_waitcnt vmcnt(0)
	ds_write_b32 v26, v0
	ds_write_b32 v26, v1 offset:1040
	ds_write_b32 v26, v2 offset:2080
	ds_write_b32 v26, v3 offset:3120
	ds_write_b32 v26, v4 offset:4160
	ds_write_b32 v26, v5 offset:5200
	ds_write_b32 v26, v6 offset:6240
	ds_write_b32 v26, v7 offset:7280
	ds_write_b32 v26, v8 offset:8320
	ds_write_b32 v26, v9 offset:9360
	ds_write_b32 v26, v10 offset:10400
	ds_write_b32 v26, v11 offset:11440
	ds_write_b32 v26, v12 offset:12480
	ds_write_b32 v26, v13 offset:13520
	ds_write_b32 v26, v14 offset:14560
	ds_write_b32 v26, v15 offset:15600
	s_waitcnt lgkmcnt(0)
	s_barrier
	ds_read2_b32 v[6:7], v25 offset1:32
	ds_read2_b32 v[8:9], v25 offset0:65 offset1:97
	ds_read2_b32 v[10:11], v25 offset0:130 offset1:162
	ds_read2_b32 v[12:13], v25 offset0:195 offset1:227
	v_add_u32_e32 v0, 0x400, v25
	ds_read2_b32 v[14:15], v0 offset0:4 offset1:36
	ds_read2_b32 v[18:19], v0 offset0:69 offset1:101
	ds_read2_b32 v[20:21], v0 offset0:134 offset1:166
	ds_read2_b32 v[28:29], v0 offset0:199 offset1:231
	s_waitcnt lgkmcnt(7)
	s_nop 1
	s_waitcnt lgkmcnt(4)
	s_nop 7
	v_cvt_pk_bf16_f32 v1, v10, v12
	v_cvt_pk_bf16_f32 v0, v6, v8
	s_waitcnt lgkmcnt(3)
	s_nop 0
	s_sub_i32 s4, 0, s3
	s_nop 0
	s_waitcnt lgkmcnt(0)
	s_nop 1
	s_ashr_i32 s3, s2, 31
	s_add_i32 s4, s4, s7
	s_nop 2
	v_lshl_add_u64 v[4:5], s[2:3], 1, v[16:17]
	v_add_u32_e32 v32, s4, v24
	s_nop 2
	v_mad_i64_i32 v[30:31], s[2:3], v32, s10, v[4:5]
	v_cvt_pk_bf16_f32 v3, v20, v28
	v_cvt_pk_bf16_f32 v2, v14, v18
	global_store_dwordx4 v[30:31], v[0:3], off
	s_add_i32 s12, s12, s6
	s_add_i32 s7, s7, s8
	s_nop 0
	v_add_u32_e32 v0, 32, v32
	s_nop 2
	v_mad_i64_i32 v[4:5], s[2:3], v0, s10, v[4:5]
	s_nop 5
	v_cvt_pk_bf16_f32 v1, v11, v13
	v_cvt_pk_bf16_f32 v0, v7, v9
	s_nop 9
	v_cvt_pk_bf16_f32 v3, v21, v29
	v_cvt_pk_bf16_f32 v2, v15, v19
	s_cmpk_lt_i32 s12, 0x160
	global_store_dwordx4 v[4:5], v[0:3], off
	s_cbranch_scc0 .LBB0_590

.LBB0_684:
	ds_read_b128 v[76:79], v135 offset:27648
	ds_read_b128 v[80:83], v137 offset:45056
	ds_read_b128 v[84:87], v135 offset:27712
	ds_read_b128 v[88:91], v137 offset:45120
	ds_read_b128 v[92:95], v137 offset:49408
	ds_read_b128 v[96:99], v137 offset:49472
	ds_read_b128 v[100:103], v137 offset:53760
	ds_read_b128 v[104:107], v137 offset:53824
	ds_read_b128 v[108:111], v137 offset:58112
	ds_read_b128 v[112:115], v137 offset:58176
	s_waitcnt lgkmcnt(8)
	v_mfma_f32_16x16x32_bf16 v[80:83], v[76:79], v[80:83], 0
	s_nop 2
	s_waitcnt lgkmcnt(5)
	v_mfma_f32_16x16x32_bf16 v[92:95], v[76:79], v[92:95], 0
	s_nop 2
	s_waitcnt lgkmcnt(3)
	v_mfma_f32_16x16x32_bf16 v[100:103], v[76:79], v[100:103], 0
	s_nop 0
	v_cvt_pk_bf16_f32 v3, v6, v7
	s_nop 0
	s_waitcnt lgkmcnt(1)
	v_mfma_f32_16x16x32_bf16 v[76:79], v[76:79], v[108:111], 0
	ds_read_b128 v[108:111], v135 offset:27776
	ds_read_b128 v[116:119], v135 offset:27840
	s_nop 0
	v_add_u32_e32 v182, s73, v173
	v_mfma_f32_16x16x32_bf16 v[80:83], v[84:87], v[88:91], v[80:83]
	ds_read_b128 v[88:91], v137 offset:45184
	ds_read_b128 v[120:123], v137 offset:45248
	ds_read_b128 v[178:181], v137 offset:49536
	ds_read_b128 v[208:211], v137 offset:49600
	v_cmp_gt_i32_e64 s[44:45], s76, v173
	v_ashrrev_i32_e32 v183, 31, v182
	v_mfma_f32_16x16x32_bf16 v[92:95], v[84:87], v[96:99], v[92:95]
	ds_read_b128 v[96:99], v137 offset:53888
	ds_read_b128 v[212:215], v137 offset:53952
	ds_read_b128 v[216:219], v137 offset:58240
	ds_read_b128 v[220:223], v137 offset:58304
	v_mfma_f32_16x16x32_bf16 v[100:103], v[84:87], v[104:107], v[100:103]
	s_waitcnt lgkmcnt(10)
	v_mfma_f32_16x16x32_bf16 v[76:79], v[84:87], v[112:115], v[76:79]
	s_nop 0
	s_waitcnt lgkmcnt(7)
	v_mfma_f32_16x16x32_bf16 v[80:83], v[108:111], v[88:91], v[80:83]
	s_nop 1
	v_cvt_pk_bf16_f32 v2, v4, v5
	s_waitcnt lgkmcnt(5)
	v_mfma_f32_16x16x32_bf16 v[84:87], v[108:111], v[178:181], v[92:95]
	s_nop 2
	s_nop 4
	s_waitcnt lgkmcnt(3)
	v_mfma_f32_16x16x32_bf16 v[88:91], v[108:111], v[96:99], v[100:103]
	s_nop 4
	v_cvt_pk_bf16_f32 v93, v10, v11
	v_cvt_pk_bf16_f32 v92, v8, v9
	s_nop 9
	v_cvt_pk_bf16_f32 v95, v14, v15
	v_cvt_pk_bf16_f32 v94, v12, v13
	s_nop 9
	v_cvt_pk_bf16_f32 v97, v18, v19
	v_cvt_pk_bf16_f32 v96, v16, v17
	s_nop 7
	v_cvt_pk_bf16_f32 v99, v22, v23
	v_cvt_pk_bf16_f32 v98, v20, v21
	ds_write2_b64 v204, v[2:3], v[98:99] offset0:128 offset1:132
	s_nop 9
	v_cvt_pk_bf16_f32 v3, v26, v27
	v_cvt_pk_bf16_f32 v2, v24, v25
	ds_write2_b64 v205, v[92:93], v[2:3] offset0:128 offset1:132
	s_nop 9
	v_mfma_f32_16x16x32_bf16 v[80:83], v[116:119], v[120:123], v[80:83]
	v_cvt_pk_bf16_f32 v3, v30, v31
	v_cvt_pk_bf16_f32 v2, v28, v29
	ds_write2_b64 v206, v[94:95], v[2:3] offset0:128 offset1:132
	s_nop 9
	v_cvt_pk_bf16_f32 v3, v34, v35
	v_cvt_pk_bf16_f32 v2, v32, v33
	v_cndmask_b32_e64 v1, v80, 0, s[6:7]
	ds_write2_b64 v207, v[96:97], v[2:3] offset0:128 offset1:132
	v_bfe_u32 v2, v1, 16, 1
	v_add3_u32 v1, v1, v2, s33
	s_waitcnt lgkmcnt(0)
	s_barrier
	ds_write_b16_d16_hi v202, v1 offset:45056
	v_cndmask_b32_e64 v1, v81, 0, s[8:9]
	v_bfe_u32 v2, v1, 16, 1
	v_add3_u32 v1, v1, v2, s33
	ds_write_b16_d16_hi v202, v1 offset:45200
	v_cndmask_b32_e64 v1, v82, 0, s[10:11]
	v_bfe_u32 v2, v1, 16, 1
	v_mfma_f32_16x16x32_bf16 v[84:87], v[116:119], v[208:211], v[84:87]
	v_add3_u32 v1, v1, v2, s33
	ds_write_b16_d16_hi v202, v1 offset:45344
	v_cndmask_b32_e64 v1, v83, 0, s[12:13]
	v_bfe_u32 v2, v1, 16, 1
	v_add3_u32 v1, v1, v2, s33
	ds_write_b16_d16_hi v202, v1 offset:45488
	s_nop 1
	v_cndmask_b32_e64 v1, v84, 0, s[14:15]
	v_bfe_u32 v2, v1, 16, 1
	v_add3_u32 v1, v1, v2, s33
	ds_write_b16_d16_hi v202, v1 offset:45088
	v_cndmask_b32_e64 v1, v85, 0, s[16:17]
	v_bfe_u32 v2, v1, 16, 1
	v_add3_u32 v1, v1, v2, s33
	ds_write_b16_d16_hi v202, v1 offset:45232
	v_cndmask_b32_e64 v1, v86, 0, s[18:19]
	v_bfe_u32 v2, v1, 16, 1
	v_mfma_f32_16x16x32_bf16 v[88:91], v[116:119], v[212:215], v[88:91]
	v_add3_u32 v1, v1, v2, s33
	ds_write_b16_d16_hi v202, v1 offset:45376
	v_cndmask_b32_e64 v1, v87, 0, s[20:21]
	v_bfe_u32 v2, v1, 16, 1
	v_add3_u32 v1, v1, v2, s33
	ds_write_b16_d16_hi v202, v1 offset:45520
	s_nop 1
	v_cndmask_b32_e64 v1, v88, 0, s[22:23]
	v_bfe_u32 v2, v1, 16, 1
	v_add3_u32 v1, v1, v2, s33
	ds_write_b16_d16_hi v202, v1 offset:45120
	v_cndmask_b32_e64 v1, v89, 0, s[24:25]
	v_mfma_f32_16x16x32_bf16 v[76:79], v[108:111], v[216:219], v[76:79]
	v_bfe_u32 v2, v1, 16, 1
	v_add3_u32 v1, v1, v2, s33
	ds_write_b16_d16_hi v202, v1 offset:45264
	v_cndmask_b32_e64 v1, v90, 0, s[26:27]
	v_bfe_u32 v2, v1, 16, 1
	v_mfma_f32_16x16x32_bf16 v[76:79], v[116:119], v[220:223], v[76:79]
	v_add3_u32 v1, v1, v2, s33
	ds_write_b16_d16_hi v202, v1 offset:45408
	v_cndmask_b32_e64 v1, v91, 0, s[28:29]
	v_bfe_u32 v2, v1, 16, 1
	v_add3_u32 v1, v1, v2, s33
	ds_write_b16_d16_hi v202, v1 offset:45552
	s_nop 1
	v_cndmask_b32_e64 v1, v76, 0, s[30:31]
	v_bfe_u32 v2, v1, 16, 1
	v_add3_u32 v1, v1, v2, s33
	ds_write_b16_d16_hi v202, v1 offset:45152
	v_cndmask_b32_e64 v1, v77, 0, s[34:35]
	v_bfe_u32 v2, v1, 16, 1
	v_add3_u32 v1, v1, v2, s33
	ds_write_b16_d16_hi v202, v1 offset:45296
	v_cndmask_b32_e64 v1, v78, 0, s[36:37]
	v_bfe_u32 v2, v1, 16, 1
	v_add3_u32 v1, v1, v2, s33
	ds_write_b16_d16_hi v202, v1 offset:45440
	v_cndmask_b32_e64 v1, v79, 0, s[38:39]
	v_bfe_u32 v2, v1, 16, 1
	v_add3_u32 v1, v1, v2, s33
	ds_write_b16_d16_hi v202, v1 offset:45584
	s_waitcnt lgkmcnt(0)
	s_barrier
	ds_read_b128 v[108:111], v184 offset:45056
	ds_read_b128 v[92:95], v134 offset:18432
	ds_read_b128 v[112:115], v184 offset:45120
	ds_read_b128 v[84:87], v134 offset:18496
	ds_read_b128 v[96:99], v134 offset:20736
	ds_read_b128 v[88:91], v134 offset:20800
	ds_read_b128 v[100:103], v134 offset:23040
	ds_read_b128 v[76:79], v134 offset:23104
	ds_read_b128 v[104:107], v134 offset:25344
	ds_read_b128 v[80:83], v134 offset:25408
	ds_read_b128 v[208:211], v135 offset:27648
	s_waitcnt lgkmcnt(9)
	v_mfma_f32_16x16x32_bf16 v[116:119], v[108:111], v[92:95], 0
	s_waitcnt lgkmcnt(6)
	v_mfma_f32_16x16x32_bf16 v[120:123], v[108:111], v[96:99], 0
	s_waitcnt lgkmcnt(4)
	v_mfma_f32_16x16x32_bf16 v[178:181], v[108:111], v[100:103], 0
	s_waitcnt lgkmcnt(2)
	v_mfma_f32_16x16x32_bf16 v[108:111], v[108:111], v[104:107], 0
	v_mfma_f32_16x16x32_bf16 v[116:119], v[112:115], v[84:87], v[116:119]
	v_mfma_f32_16x16x32_bf16 v[120:123], v[112:115], v[88:91], v[120:123]
	v_mfma_f32_16x16x32_bf16 v[178:181], v[112:115], v[76:79], v[178:181]
	s_waitcnt lgkmcnt(1)
	v_mfma_f32_16x16x32_bf16 v[108:111], v[112:115], v[80:83], v[108:111]
	ds_read_b128 v[112:115], v137 offset:62464
	ds_read_b128 v[212:215], v135 offset:27712
	ds_read_b128 v[216:219], v137 offset:62528
	s_waitcnt lgkmcnt(2)
	v_mfma_f32_16x16x32_bf16 v[112:115], v[208:211], v[112:115], v[116:119]
	s_nop 2
	ds_read_b128 v[116:119], v185 offset:4352
	ds_read_b128 v[220:223], v185 offset:8704
	s_waitcnt lgkmcnt(1)
	v_mfma_f32_16x16x32_bf16 v[116:119], v[208:211], v[116:119], v[120:123]
	s_waitcnt lgkmcnt(0)
	v_mfma_f32_16x16x32_bf16 v[120:123], v[208:211], v[220:223], v[178:181]
	s_nop 2
	ds_read_b128 v[178:181], v185 offset:13056
	ds_read_b128 v[220:223], v186 offset:4352
	s_waitcnt lgkmcnt(1)
	v_mfma_f32_16x16x32_bf16 v[108:111], v[208:211], v[178:181], v[108:111]
	ds_read_b128 v[178:181], v186 offset:8704
	ds_read_b128 v[208:211], v186 offset:13056
	s_waitcnt lgkmcnt(1)
	v_mfma_f32_16x16x32_bf16 v[120:123], v[212:215], v[178:181], v[120:123]
	ds_read_b128 v[178:181], v135 offset:27776
	v_mfma_f32_16x16x32_bf16 v[112:115], v[212:215], v[216:219], v[112:115]
	v_mfma_f32_16x16x32_bf16 v[116:119], v[212:215], v[220:223], v[116:119]
	s_waitcnt lgkmcnt(1)
	v_mfma_f32_16x16x32_bf16 v[108:111], v[212:215], v[208:211], v[108:111]
	ds_read_b128 v[208:211], v137 offset:62592
	ds_read_b128 v[212:215], v135 offset:27840
	ds_read_b128 v[216:219], v137 offset:62656
	s_waitcnt lgkmcnt(2)
	v_mfma_f32_16x16x32_bf16 v[112:115], v[178:181], v[208:211], v[112:115]
	ds_read_b128 v[208:211], v187 offset:4352
	ds_read_b128 v[220:223], v187 offset:8704
	s_waitcnt lgkmcnt(1)
	v_mfma_f32_16x16x32_bf16 v[116:119], v[178:181], v[208:211], v[116:119]
	s_waitcnt lgkmcnt(0)
	v_mfma_f32_16x16x32_bf16 v[120:123], v[178:181], v[220:223], v[120:123]
	ds_read_b128 v[208:211], v187 offset:13056
	ds_read_b128 v[220:223], v188 offset:4352
	s_waitcnt lgkmcnt(1)
	v_mfma_f32_16x16x32_bf16 v[178:181], v[178:181], v[208:211], v[108:111]
	v_mfma_f32_16x16x32_bf16 v[108:111], v[212:215], v[216:219], v[112:115]
	s_waitcnt lgkmcnt(0)
	v_mfma_f32_16x16x32_bf16 v[112:115], v[212:215], v[220:223], v[116:119]
	s_nop 2
	ds_read_b128 v[116:119], v188 offset:8704
	ds_read_b128 v[208:211], v188 offset:13056
	s_waitcnt lgkmcnt(1)
	v_mfma_f32_16x16x32_bf16 v[116:119], v[212:215], v[116:119], v[120:123]
	s_waitcnt lgkmcnt(0)
	v_mfma_f32_16x16x32_bf16 v[120:123], v[212:215], v[208:211], v[178:181]
	s_and_saveexec_b64 s[40:41], s[44:45]
	s_cbranch_execz .LBB0_686
	v_bfe_u32 v1, v108, 16, 1
	v_lshlrev_b64 v[2:3], 11, v[182:183]
	v_add3_u32 v1, v108, v1, s33
	v_lshl_add_u64 v[2:3], v[176:177], 0, v[2:3]
	global_store_short_d16_hi v[2:3], v1, off

.LBB0_789:
	s_or_b64 exec, exec, s[4:5]
	s_waitcnt vmcnt(1)
	v_add_f32_e32 v50, v50, v51
	v_add_f32_e32 v50, v50, v52
	v_add_f32_e32 v50, v50, v53
	v_fmamk_f32 v50, v50, 0x3b800000, v70
	v_cmp_gt_f32_e64 s[4:5], s12, v50
	v_mul_f32_e32 v51, 0x4b800000, v50
	v_lshlrev_b32_e32 v52, 16, v46
	v_cndmask_b32_e64 v50, v50, v51, s[4:5]
	v_rsq_f32_e32 v50, v50
	v_and_b32_e32 v46, 0xffff0000, v46
	v_lshlrev_b32_e32 v53, 16, v47
	s_waitcnt vmcnt(0)
	v_lshlrev_b32_e32 v77, 16, v43
	v_mul_f32_e32 v51, 0x45800000, v50
	v_cndmask_b32_e64 v50, v50, v51, s[4:5]
	v_mul_f32_e32 v51, 0xbfb8aa3b, v52
	v_exp_f32_e32 v51, v51
	v_lshlrev_b32_e32 v76, 16, v42
	v_and_b32_e32 v47, 0xffff0000, v47
	v_and_b32_e32 v43, 0xffff0000, v43
	v_add_f32_e32 v51, 1.0, v51
	v_rcp_f32_e32 v72, v51
	v_mul_f32_e32 v51, 0xbfb8aa3b, v46
	v_exp_f32_e32 v51, v51
	v_and_b32_e32 v42, 0xffff0000, v42
	v_add_f32_e32 v51, 1.0, v51
	v_rcp_f32_e32 v74, v51
	v_pk_mul_f32 v[76:77], v[50:51], v[76:77] op_sel_hi:[0,1]
	v_mul_f32_e32 v51, 0xbfb8aa3b, v53
	v_exp_f32_e32 v51, v51
	v_pk_mul_f32 v[76:77], v[4:5], v[76:77]
	v_add_f32_e32 v51, 1.0, v51
	v_rcp_f32_e32 v73, v51
	v_pk_mul_f32 v[42:43], v[50:51], v[42:43] op_sel_hi:[0,1]
	v_mul_f32_e32 v51, 0xbfb8aa3b, v47
	v_exp_f32_e32 v51, v51
	v_pk_mul_f32 v[42:43], v[60:61], v[42:43]
	v_pk_mul_f32 v[52:53], v[72:73], v[52:53]
	v_add_f32_e32 v51, 1.0, v51
	v_rcp_f32_e32 v75, v51
	v_pk_mul_f32 v[52:53], v[76:77], v[52:53]
	v_lshlrev_b32_e32 v77, 16, v45
	v_lshlrev_b32_e32 v76, 16, v44
	v_pk_mul_f32 v[46:47], v[74:75], v[46:47]
	v_and_b32_e32 v45, 0xffff0000, v45
	v_pk_mul_f32 v[42:43], v[42:43], v[46:47]
	v_lshlrev_b32_e32 v46, 16, v48
	v_mul_f32_e32 v51, 0xbfb8aa3b, v46
	v_exp_f32_e32 v51, v51
	v_and_b32_e32 v48, 0xffff0000, v48
	v_lshlrev_b32_e32 v47, 16, v49
	v_and_b32_e32 v49, 0xffff0000, v49
	v_add_f32_e32 v51, 1.0, v51
	v_rcp_f32_e32 v72, v51
	v_mul_f32_e32 v51, 0xbfb8aa3b, v48
	v_exp_f32_e32 v51, v51
	v_and_b32_e32 v44, 0xffff0000, v44
	v_add_f32_e32 v51, 1.0, v51
	v_rcp_f32_e32 v74, v51
	v_pk_mul_f32 v[76:77], v[50:51], v[76:77] op_sel_hi:[0,1]
	v_mul_f32_e32 v51, 0xbfb8aa3b, v47
	v_exp_f32_e32 v51, v51
	v_pk_mul_f32 v[76:77], v[0:1], v[76:77]
	v_add_f32_e32 v51, 1.0, v51
	v_pk_mul_f32 v[44:45], v[50:51], v[44:45] op_sel_hi:[0,1]
	v_mul_f32_e32 v50, 0xbfb8aa3b, v49
	v_exp_f32_e32 v50, v50
	v_rcp_f32_e32 v73, v51
	v_pk_mul_f32 v[44:45], v[62:63], v[44:45]
	s_nop 0
	v_add_f32_e32 v50, 1.0, v50
	v_rcp_f32_e32 v75, v50
	v_pk_mul_f32 v[46:47], v[72:73], v[46:47]
	s_nop 0
	v_pk_mul_f32 v[46:47], v[76:77], v[46:47]
	v_pk_mul_f32 v[48:49], v[74:75], v[48:49]
	s_nop 0
	v_pk_mul_f32 v[44:45], v[44:45], v[48:49]
	s_nop 15
	s_nop 0
	v_cvt_pk_bf16_f32 v45, v47, v45
	v_cvt_pk_bf16_f32 v44, v46, v44
	v_cvt_pk_bf16_f32 v43, v53, v43
	v_cvt_pk_bf16_f32 v42, v52, v42
	global_store_dwordx4 v[68:69], v[42:45], off
	s_and_saveexec_b64 s[4:5], s[2:3]
	s_cbranch_execnz .LBB0_792
	s_or_b64 exec, exec, s[4:5]
	s_and_saveexec_b64 s[2:3], s[0:1]
	s_cbranch_execnz .LBB0_793

.LBB0_792:
	v_add_f32_e32 v38, v39, v38
	v_add_f32_e32 v38, v40, v38
	v_add_f32_e32 v38, v41, v38
	v_fmamk_f32 v38, v38, 0x3b800000, v70
	v_cmp_gt_f32_e64 s[2:3], s12, v38
	v_mul_f32_e32 v39, 0x4b800000, v38
	v_lshlrev_b32_e32 v40, 16, v34
	v_cndmask_b32_e64 v38, v38, v39, s[2:3]
	v_rsq_f32_e32 v38, v38
	v_and_b32_e32 v34, 0xffff0000, v34
	v_lshlrev_b32_e32 v41, 16, v35
	v_lshlrev_b32_e32 v47, 16, v31
	v_mul_f32_e32 v39, 0x45800000, v38
	v_cndmask_b32_e64 v38, v38, v39, s[2:3]
	v_mul_f32_e32 v39, 0xbfb8aa3b, v40
	v_exp_f32_e32 v39, v39
	v_lshlrev_b32_e32 v46, 16, v30
	v_and_b32_e32 v35, 0xffff0000, v35
	v_and_b32_e32 v31, 0xffff0000, v31
	v_add_f32_e32 v39, 1.0, v39
	v_rcp_f32_e32 v42, v39
	v_mul_f32_e32 v39, 0xbfb8aa3b, v34
	v_exp_f32_e32 v39, v39
	v_and_b32_e32 v30, 0xffff0000, v30
	v_add_f32_e32 v39, 1.0, v39
	v_rcp_f32_e32 v44, v39
	v_pk_mul_f32 v[46:47], v[38:39], v[46:47] op_sel_hi:[0,1]
	v_mul_f32_e32 v39, 0xbfb8aa3b, v41
	v_exp_f32_e32 v39, v39
	v_pk_mul_f32 v[46:47], v[4:5], v[46:47]
	v_add_f32_e32 v39, 1.0, v39
	v_rcp_f32_e32 v43, v39
	v_pk_mul_f32 v[30:31], v[38:39], v[30:31] op_sel_hi:[0,1]
	v_mul_f32_e32 v39, 0xbfb8aa3b, v35
	v_exp_f32_e32 v39, v39
	v_pk_mul_f32 v[30:31], v[60:61], v[30:31]
	v_pk_mul_f32 v[40:41], v[42:43], v[40:41]
	v_add_f32_e32 v39, 1.0, v39
	v_rcp_f32_e32 v45, v39
	v_pk_mul_f32 v[40:41], v[46:47], v[40:41]
	v_lshlrev_b32_e32 v47, 16, v33
	v_lshlrev_b32_e32 v46, 16, v32
	v_pk_mul_f32 v[34:35], v[44:45], v[34:35]
	v_and_b32_e32 v33, 0xffff0000, v33
	v_pk_mul_f32 v[30:31], v[30:31], v[34:35]
	v_lshlrev_b32_e32 v34, 16, v36
	v_mul_f32_e32 v39, 0xbfb8aa3b, v34
	v_exp_f32_e32 v39, v39
	v_and_b32_e32 v36, 0xffff0000, v36
	v_lshlrev_b32_e32 v35, 16, v37
	v_and_b32_e32 v37, 0xffff0000, v37
	v_add_f32_e32 v39, 1.0, v39
	v_rcp_f32_e32 v42, v39
	v_mul_f32_e32 v39, 0xbfb8aa3b, v36
	v_exp_f32_e32 v39, v39
	v_and_b32_e32 v32, 0xffff0000, v32
	v_add_f32_e32 v39, 1.0, v39
	v_rcp_f32_e32 v44, v39
	v_pk_mul_f32 v[46:47], v[38:39], v[46:47] op_sel_hi:[0,1]
	v_mul_f32_e32 v39, 0xbfb8aa3b, v35
	v_exp_f32_e32 v39, v39
	v_pk_mul_f32 v[46:47], v[0:1], v[46:47]
	v_add_f32_e32 v39, 1.0, v39
	v_pk_mul_f32 v[32:33], v[38:39], v[32:33] op_sel_hi:[0,1]
	v_mul_f32_e32 v38, 0xbfb8aa3b, v37
	v_exp_f32_e32 v38, v38
	v_rcp_f32_e32 v43, v39
	v_pk_mul_f32 v[32:33], v[62:63], v[32:33]
	s_nop 0
	v_add_f32_e32 v38, 1.0, v38
	v_rcp_f32_e32 v45, v38
	v_pk_mul_f32 v[34:35], v[42:43], v[34:35]
	s_nop 0
	v_pk_mul_f32 v[34:35], v[46:47], v[34:35]
	v_pk_mul_f32 v[36:37], v[44:45], v[36:37]
	s_nop 0
	v_pk_mul_f32 v[32:33], v[32:33], v[36:37]
	s_nop 15
	s_nop 0
	v_cvt_pk_bf16_f32 v33, v35, v33
	v_cvt_pk_bf16_f32 v32, v34, v32
	v_lshlrev_b64 v[34:35], 11, v[66:67]
	v_cvt_pk_bf16_f32 v31, v41, v31
	v_cvt_pk_bf16_f32 v30, v40, v30
	v_lshl_add_u64 v[34:35], v[54:55], 0, v[34:35]
	global_store_dwordx4 v[34:35], v[30:33], off
	s_or_b64 exec, exec, s[4:5]
	s_and_saveexec_b64 s[2:3], s[0:1]
	s_cbranch_execz .LBB0_791
.LBB0_793:
	v_add_f32_e32 v26, v27, v26
	v_add_f32_e32 v26, v28, v26
	v_add_f32_e32 v26, v29, v26
	v_fmamk_f32 v26, v26, 0x3b800000, v70
	v_cmp_gt_f32_e64 s[0:1], s12, v26
	v_mul_f32_e32 v27, 0x4b800000, v26
	v_lshlrev_b32_e32 v28, 16, v22
	v_cndmask_b32_e64 v26, v26, v27, s[0:1]
	v_rsq_f32_e32 v26, v26
	v_and_b32_e32 v22, 0xffff0000, v22
	v_lshlrev_b32_e32 v29, 16, v23
	v_lshlrev_b32_e32 v35, 16, v19
	v_mul_f32_e32 v27, 0x45800000, v26
	v_cndmask_b32_e64 v26, v26, v27, s[0:1]
	v_mul_f32_e32 v27, 0xbfb8aa3b, v28
	v_exp_f32_e32 v27, v27
	v_lshlrev_b32_e32 v34, 16, v18
	v_and_b32_e32 v23, 0xffff0000, v23
	v_and_b32_e32 v19, 0xffff0000, v19
	v_add_f32_e32 v27, 1.0, v27
	v_rcp_f32_e32 v30, v27
	v_mul_f32_e32 v27, 0xbfb8aa3b, v22
	v_exp_f32_e32 v27, v27
	v_and_b32_e32 v18, 0xffff0000, v18
	v_add_f32_e32 v27, 1.0, v27
	v_rcp_f32_e32 v32, v27
	v_pk_mul_f32 v[34:35], v[26:27], v[34:35] op_sel_hi:[0,1]
	v_mul_f32_e32 v27, 0xbfb8aa3b, v29
	v_exp_f32_e32 v27, v27
	v_pk_mul_f32 v[34:35], v[4:5], v[34:35]
	v_add_f32_e32 v27, 1.0, v27
	v_rcp_f32_e32 v31, v27
	v_pk_mul_f32 v[18:19], v[26:27], v[18:19] op_sel_hi:[0,1]
	v_mul_f32_e32 v27, 0xbfb8aa3b, v23
	v_exp_f32_e32 v27, v27
	v_pk_mul_f32 v[18:19], v[60:61], v[18:19]
	v_pk_mul_f32 v[28:29], v[30:31], v[28:29]
	v_add_f32_e32 v27, 1.0, v27
	v_rcp_f32_e32 v33, v27
	v_pk_mul_f32 v[28:29], v[34:35], v[28:29]
	v_lshlrev_b32_e32 v35, 16, v21
	v_lshlrev_b32_e32 v34, 16, v20
	v_pk_mul_f32 v[22:23], v[32:33], v[22:23]
	v_and_b32_e32 v21, 0xffff0000, v21
	v_pk_mul_f32 v[18:19], v[18:19], v[22:23]
	v_lshlrev_b32_e32 v22, 16, v24
	v_mul_f32_e32 v27, 0xbfb8aa3b, v22
	v_exp_f32_e32 v27, v27
	v_and_b32_e32 v24, 0xffff0000, v24
	v_lshlrev_b32_e32 v23, 16, v25
	v_and_b32_e32 v25, 0xffff0000, v25
	v_add_f32_e32 v27, 1.0, v27
	v_rcp_f32_e32 v30, v27
	v_mul_f32_e32 v27, 0xbfb8aa3b, v24
	v_exp_f32_e32 v27, v27
	v_and_b32_e32 v20, 0xffff0000, v20
	v_add_f32_e32 v27, 1.0, v27
	v_rcp_f32_e32 v32, v27
	v_pk_mul_f32 v[34:35], v[26:27], v[34:35] op_sel_hi:[0,1]
	v_mul_f32_e32 v27, 0xbfb8aa3b, v23
	v_exp_f32_e32 v27, v27
	v_pk_mul_f32 v[34:35], v[0:1], v[34:35]
	v_add_f32_e32 v27, 1.0, v27
	v_pk_mul_f32 v[20:21], v[26:27], v[20:21] op_sel_hi:[0,1]
	v_mul_f32_e32 v26, 0xbfb8aa3b, v25
	v_exp_f32_e32 v26, v26
	v_rcp_f32_e32 v31, v27
	v_pk_mul_f32 v[20:21], v[62:63], v[20:21]
	s_nop 0
	v_add_f32_e32 v26, 1.0, v26
	v_rcp_f32_e32 v33, v26
	v_pk_mul_f32 v[22:23], v[30:31], v[22:23]
	s_nop 0
	v_pk_mul_f32 v[22:23], v[34:35], v[22:23]
	v_pk_mul_f32 v[24:25], v[32:33], v[24:25]
	s_nop 0
	v_pk_mul_f32 v[20:21], v[20:21], v[24:25]
	s_nop 15
	s_nop 0
	v_cvt_pk_bf16_f32 v21, v23, v21
	v_cvt_pk_bf16_f32 v20, v22, v20
	v_lshlrev_b64 v[22:23], 11, v[64:65]
	v_cvt_pk_bf16_f32 v19, v29, v19
	v_cvt_pk_bf16_f32 v18, v28, v18
	v_lshl_add_u64 v[22:23], v[54:55], 0, v[22:23]
	global_store_dwordx4 v[22:23], v[18:21], off
	s_or_b64 exec, exec, s[2:3]
	s_and_saveexec_b64 s[0:1], vcc
	s_cbranch_execz .LBB0_782
.LBB0_794:
	v_add_f32_e32 v14, v15, v14
	v_add_f32_e32 v14, v16, v14
	v_add_f32_e32 v14, v17, v14
	v_fmamk_f32 v14, v14, 0x3b800000, v70
	v_cmp_gt_f32_e32 vcc, s12, v14
	v_mul_f32_e32 v15, 0x4b800000, v14
	v_lshlrev_b32_e32 v16, 16, v6
	v_cndmask_b32_e32 v14, v14, v15, vcc
	v_rsq_f32_e32 v14, v14
	v_and_b32_e32 v6, 0xffff0000, v6
	v_lshlrev_b32_e32 v17, 16, v7
	v_lshlrev_b32_e32 v23, 16, v11
	v_mul_f32_e32 v15, 0x45800000, v14
	v_cndmask_b32_e32 v14, v14, v15, vcc
	v_mul_f32_e32 v15, 0xbfb8aa3b, v16
	v_exp_f32_e32 v15, v15
	v_lshlrev_b32_e32 v22, 16, v10
	v_and_b32_e32 v7, 0xffff0000, v7
	v_and_b32_e32 v11, 0xffff0000, v11
	v_add_f32_e32 v15, 1.0, v15
	v_rcp_f32_e32 v18, v15
	v_mul_f32_e32 v15, 0xbfb8aa3b, v6
	v_exp_f32_e32 v15, v15
	v_and_b32_e32 v10, 0xffff0000, v10
	v_lshlrev_b64 v[2:3], 11, v[2:3]
	v_lshl_add_u64 v[2:3], v[54:55], 0, v[2:3]
	v_add_f32_e32 v15, 1.0, v15
	v_rcp_f32_e32 v20, v15
	v_pk_mul_f32 v[22:23], v[14:15], v[22:23] op_sel_hi:[0,1]
	v_mul_f32_e32 v15, 0xbfb8aa3b, v17
	v_exp_f32_e32 v15, v15
	v_pk_mul_f32 v[22:23], v[4:5], v[22:23]
	v_add_f32_e32 v15, 1.0, v15
	v_rcp_f32_e32 v19, v15
	v_pk_mul_f32 v[10:11], v[14:15], v[10:11] op_sel_hi:[0,1]
	v_mul_f32_e32 v15, 0xbfb8aa3b, v7
	v_exp_f32_e32 v15, v15
	v_pk_mul_f32 v[10:11], v[60:61], v[10:11]
	v_pk_mul_f32 v[16:17], v[18:19], v[16:17]
	v_add_f32_e32 v15, 1.0, v15
	v_rcp_f32_e32 v21, v15
	v_pk_mul_f32 v[16:17], v[16:17], v[22:23]
	v_lshlrev_b32_e32 v23, 16, v13
	v_lshlrev_b32_e32 v22, 16, v12
	v_pk_mul_f32 v[6:7], v[20:21], v[6:7]
	v_and_b32_e32 v13, 0xffff0000, v13
	v_pk_mul_f32 v[6:7], v[6:7], v[10:11]
	v_lshlrev_b32_e32 v10, 16, v8
	v_mul_f32_e32 v15, 0xbfb8aa3b, v10
	v_exp_f32_e32 v15, v15
	v_and_b32_e32 v8, 0xffff0000, v8
	v_lshlrev_b32_e32 v11, 16, v9
	v_and_b32_e32 v9, 0xffff0000, v9
	v_add_f32_e32 v15, 1.0, v15
	v_rcp_f32_e32 v18, v15
	v_mul_f32_e32 v15, 0xbfb8aa3b, v8
	v_exp_f32_e32 v15, v15
	v_and_b32_e32 v12, 0xffff0000, v12
	v_add_f32_e32 v15, 1.0, v15
	v_rcp_f32_e32 v20, v15
	v_pk_mul_f32 v[22:23], v[14:15], v[22:23] op_sel_hi:[0,1]
	v_mul_f32_e32 v15, 0xbfb8aa3b, v11
	v_exp_f32_e32 v15, v15
	v_pk_mul_f32 v[22:23], v[0:1], v[22:23]
	v_add_f32_e32 v15, 1.0, v15
	v_pk_mul_f32 v[12:13], v[14:15], v[12:13] op_sel_hi:[0,1]
	v_mul_f32_e32 v14, 0xbfb8aa3b, v9
	v_exp_f32_e32 v14, v14
	v_rcp_f32_e32 v19, v15
	v_pk_mul_f32 v[12:13], v[62:63], v[12:13]
	s_nop 0
	v_add_f32_e32 v14, 1.0, v14
	v_rcp_f32_e32 v21, v14
	v_pk_mul_f32 v[10:11], v[18:19], v[10:11]
	s_nop 0
	v_pk_mul_f32 v[10:11], v[10:11], v[22:23]
	v_pk_mul_f32 v[8:9], v[20:21], v[8:9]
	s_nop 0
	v_pk_mul_f32 v[8:9], v[8:9], v[12:13]
	s_nop 15
	s_nop 0
	v_cvt_pk_bf16_f32 v9, v11, v9
	v_cvt_pk_bf16_f32 v8, v10, v8
	v_cvt_pk_bf16_f32 v7, v17, v7
	v_cvt_pk_bf16_f32 v6, v16, v6
	global_store_dwordx4 v[2:3], v[6:9], off
	s_branch .LBB0_782

.LBB0_887:
	s_add_i32 s20, s19, 2
	s_mul_hi_i32 s21, s20, 0x55555556
	s_lshr_b32 s22, s21, 31
	s_add_i32 s21, s21, s22
	s_mul_i32 s21, s21, 3
	s_sub_i32 s20, s20, s21
	s_mulk_i32 s20, 0x6000
	s_mul_i32 s54, s19, 0x6000
	v_readfirstlane_b32 s55, v140
	v_lshl_add_u64 v[232:233], v[132:133], 0, s[6:7]
	v_lshl_add_u64 v[234:235], v[130:131], 0, s[6:7]
	s_add_u32 s55, s55, s20
	s_waitcnt vmcnt(6) lgkmcnt(0)
	s_barrier
	s_setprio 1
	s_mov_b32 m0, s55
	s_mov_b64 s[20:21], 0x12d0100
	v_lshl_add_u64 v[236:237], v[232:233], 0, s[20:21]
	global_load_lds_dwordx4 v[236:237], off
	s_add_u32 m0, s55, 0x1000
	s_mov_b64 s[20:21], 0x12f0100
	v_lshl_add_u64 v[236:237], v[232:233], 0, s[20:21]
	global_load_lds_dwordx4 v[236:237], off
	s_add_u32 m0, s55, 0x2000
	s_mov_b64 s[20:21], 0x1310100
	v_lshl_add_u64 v[236:237], v[232:233], 0, s[20:21]
	global_load_lds_dwordx4 v[236:237], off
	s_add_u32 m0, s55, 0x3000
	s_mov_b64 s[20:21], 0x1330100
	v_lshl_add_u64 v[236:237], v[232:233], 0, s[20:21]
	global_load_lds_dwordx4 v[236:237], off
	s_add_u32 m0, s55, 0x4000
	s_mov_b64 s[20:21], 0x100
	v_lshl_add_u64 v[236:237], v[234:235], 0, s[20:21]
	global_load_lds_dwordx4 v[236:237], off
	s_add_u32 m0, s55, 0x5000
	s_mov_b64 s[20:21], 0x20100
	v_lshl_add_u64 v[236:237], v[234:235], 0, s[20:21]
	global_load_lds_dwordx4 v[236:237], off
	v_or_b32_e32 v128, s54, v138
	v_add3_u32 v128, v128, v139, v137
	ds_read_b128 v[174:177], v128 offset:16384
	ds_read_b128 v[178:181], v128 offset:16640
	ds_read_b128 v[182:185], v128 offset:18432
	ds_read_b128 v[186:189], v128 offset:18688
	v_add3_u32 v128, s54, v141, v137
	ds_read_b128 v[142:145], v128
	ds_read_b128 v[146:149], v128 offset:1024
	ds_read_b128 v[150:153], v128 offset:2048
	ds_read_b128 v[154:157], v128 offset:3072
	ds_read_b128 v[158:161], v128 offset:4096
	ds_read_b128 v[162:165], v128 offset:5120
	ds_read_b128 v[166:169], v128 offset:6144
	ds_read_b128 v[170:173], v128 offset:7168
	s_setprio 0
	s_waitcnt lgkmcnt(7)
	v_mfma_f32_16x16x32_bf16 v[124:127], v[174:177], v[142:145], v[124:127]
	v_mfma_f32_16x16x32_bf16 v[120:123], v[178:181], v[142:145], v[120:123]
	v_mfma_f32_16x16x32_bf16 v[116:119], v[182:185], v[142:145], v[116:119]
	v_mfma_f32_16x16x32_bf16 v[112:115], v[186:189], v[142:145], v[112:115]
	s_waitcnt lgkmcnt(6)
	v_mfma_f32_16x16x32_bf16 v[108:111], v[174:177], v[146:149], v[108:111]
	v_mfma_f32_16x16x32_bf16 v[104:107], v[178:181], v[146:149], v[104:107]
	v_mfma_f32_16x16x32_bf16 v[100:103], v[182:185], v[146:149], v[100:103]
	v_mfma_f32_16x16x32_bf16 v[96:99], v[186:189], v[146:149], v[96:99]
	s_waitcnt lgkmcnt(5)
	v_mfma_f32_16x16x32_bf16 v[92:95], v[174:177], v[150:153], v[92:95]
	v_mfma_f32_16x16x32_bf16 v[88:91], v[178:181], v[150:153], v[88:91]
	v_mfma_f32_16x16x32_bf16 v[84:87], v[182:185], v[150:153], v[84:87]
	v_mfma_f32_16x16x32_bf16 v[80:83], v[186:189], v[150:153], v[80:83]
	s_waitcnt lgkmcnt(4)
	v_mfma_f32_16x16x32_bf16 v[76:79], v[174:177], v[154:157], v[76:79]
	v_mfma_f32_16x16x32_bf16 v[72:75], v[178:181], v[154:157], v[72:75]
	v_mfma_f32_16x16x32_bf16 v[68:71], v[182:185], v[154:157], v[68:71]
	v_mfma_f32_16x16x32_bf16 v[64:67], v[186:189], v[154:157], v[64:67]
	s_waitcnt lgkmcnt(3)
	v_mfma_f32_16x16x32_bf16 v[60:63], v[174:177], v[158:161], v[60:63]
	v_mfma_f32_16x16x32_bf16 v[56:59], v[178:181], v[158:161], v[56:59]
	v_mfma_f32_16x16x32_bf16 v[52:55], v[182:185], v[158:161], v[52:55]
	v_mfma_f32_16x16x32_bf16 v[48:51], v[186:189], v[158:161], v[48:51]
	s_waitcnt lgkmcnt(2)
	v_mfma_f32_16x16x32_bf16 v[44:47], v[174:177], v[162:165], v[44:47]
	v_mfma_f32_16x16x32_bf16 v[40:43], v[178:181], v[162:165], v[40:43]
	v_mfma_f32_16x16x32_bf16 v[36:39], v[182:185], v[162:165], v[36:39]
	v_mfma_f32_16x16x32_bf16 v[32:35], v[186:189], v[162:165], v[32:35]
	s_waitcnt lgkmcnt(1)
	v_mfma_f32_16x16x32_bf16 v[28:31], v[174:177], v[166:169], v[28:31]
	v_mfma_f32_16x16x32_bf16 v[24:27], v[178:181], v[166:169], v[24:27]
	v_mfma_f32_16x16x32_bf16 v[20:23], v[182:185], v[166:169], v[20:23]
	v_mfma_f32_16x16x32_bf16 v[16:19], v[186:189], v[166:169], v[16:19]
	s_waitcnt lgkmcnt(0)
	v_mfma_f32_16x16x32_bf16 v[12:15], v[174:177], v[170:173], v[12:15]
	v_mfma_f32_16x16x32_bf16 v[8:11], v[178:181], v[170:173], v[8:11]
	v_mfma_f32_16x16x32_bf16 v[4:7], v[182:185], v[170:173], v[4:7]
	v_mfma_f32_16x16x32_bf16 v[0:3], v[186:189], v[170:173], v[0:3]
	s_add_i32 s20, s19, 1
	s_cmp_lg_u32 s19, 2
	s_cselect_b32 s19, s20, 0
	s_add_u32 s6, s6, 0x80
	s_addc_u32 s7, s7, 0
	s_cmpk_lg_i32 s6, 0xf00
	s_cbranch_scc1 .LBB0_887
	s_waitcnt vmcnt(6) lgkmcnt(0)
	s_barrier
	v_add_u32_e32 v128, v141, v137
	ds_read_b128 v[130:133], v128
	ds_read_b128 v[140:143], v128 offset:1024
	ds_read_b128 v[144:147], v128 offset:2048
	ds_read_b128 v[148:151], v128 offset:3072
	ds_read_b128 v[152:155], v128 offset:4096
	ds_read_b128 v[156:159], v128 offset:5120
	ds_read_b128 v[160:163], v128 offset:6144
	ds_read_b128 v[164:167], v128 offset:7168
	v_add3_u32 v137, v138, v139, v137
	ds_read_b128 v[168:171], v137 offset:16384
	ds_read_b128 v[172:175], v137 offset:16640
	ds_read_b128 v[176:179], v137 offset:18432
	ds_read_b128 v[180:183], v137 offset:18688
	s_setprio 1
	s_waitcnt lgkmcnt(0)
	v_mfma_f32_16x16x32_bf16 v[124:127], v[168:171], v[130:133], v[124:127]
	v_mfma_f32_16x16x32_bf16 v[120:123], v[172:175], v[130:133], v[120:123]
	v_mfma_f32_16x16x32_bf16 v[116:119], v[176:179], v[130:133], v[116:119]
	v_mfma_f32_16x16x32_bf16 v[112:115], v[180:183], v[130:133], v[112:115]
	v_mfma_f32_16x16x32_bf16 v[108:111], v[168:171], v[140:143], v[108:111]
	v_mfma_f32_16x16x32_bf16 v[104:107], v[172:175], v[140:143], v[104:107]
	v_mfma_f32_16x16x32_bf16 v[100:103], v[176:179], v[140:143], v[100:103]
	v_mfma_f32_16x16x32_bf16 v[96:99], v[180:183], v[140:143], v[96:99]
	v_mfma_f32_16x16x32_bf16 v[92:95], v[168:171], v[144:147], v[92:95]
	v_mfma_f32_16x16x32_bf16 v[88:91], v[172:175], v[144:147], v[88:91]
	v_mfma_f32_16x16x32_bf16 v[84:87], v[176:179], v[144:147], v[84:87]
	v_mfma_f32_16x16x32_bf16 v[80:83], v[180:183], v[144:147], v[80:83]
	v_mfma_f32_16x16x32_bf16 v[76:79], v[168:171], v[148:151], v[76:79]
	v_mfma_f32_16x16x32_bf16 v[72:75], v[172:175], v[148:151], v[72:75]
	v_mfma_f32_16x16x32_bf16 v[68:71], v[176:179], v[148:151], v[68:71]
	v_mfma_f32_16x16x32_bf16 v[64:67], v[180:183], v[148:151], v[64:67]
	v_mfma_f32_16x16x32_bf16 v[60:63], v[168:171], v[152:155], v[60:63]
	v_mfma_f32_16x16x32_bf16 v[56:59], v[172:175], v[152:155], v[56:59]
	v_mfma_f32_16x16x32_bf16 v[52:55], v[176:179], v[152:155], v[52:55]
	v_mfma_f32_16x16x32_bf16 v[48:51], v[180:183], v[152:155], v[48:51]
	v_mfma_f32_16x16x32_bf16 v[44:47], v[168:171], v[156:159], v[44:47]
	v_mfma_f32_16x16x32_bf16 v[40:43], v[172:175], v[156:159], v[40:43]
	v_mfma_f32_16x16x32_bf16 v[36:39], v[176:179], v[156:159], v[36:39]
	v_mfma_f32_16x16x32_bf16 v[32:35], v[180:183], v[156:159], v[32:35]
	v_mfma_f32_16x16x32_bf16 v[28:31], v[168:171], v[160:163], v[28:31]
	v_mfma_f32_16x16x32_bf16 v[24:27], v[172:175], v[160:163], v[24:27]
	v_mfma_f32_16x16x32_bf16 v[20:23], v[176:179], v[160:163], v[20:23]
	v_mfma_f32_16x16x32_bf16 v[16:19], v[180:183], v[160:163], v[16:19]
	v_mfma_f32_16x16x32_bf16 v[12:15], v[168:171], v[164:167], v[12:15]
	v_mfma_f32_16x16x32_bf16 v[8:11], v[172:175], v[164:167], v[8:11]
	v_mfma_f32_16x16x32_bf16 v[4:7], v[176:179], v[164:167], v[4:7]
	v_mfma_f32_16x16x32_bf16 v[0:3], v[180:183], v[164:167], v[0:3]
	s_setprio 0
	s_waitcnt vmcnt(0) lgkmcnt(0)
	s_barrier
	ds_read_b128 v[130:133], v128 offset:24576
	ds_read_b128 v[138:141], v128 offset:25600
	ds_read_b128 v[142:145], v128 offset:26624
	ds_read_b128 v[146:149], v128 offset:27648
	ds_read_b128 v[150:153], v128 offset:28672
	ds_read_b128 v[154:157], v128 offset:29696
	ds_read_b128 v[158:161], v128 offset:30720
	ds_read_b128 v[162:165], v128 offset:31744
	ds_read_b128 v[166:169], v137 offset:40960
	ds_read_b128 v[170:173], v137 offset:41216
	ds_read_b128 v[174:177], v137 offset:43008
	ds_read_b128 v[178:181], v137 offset:43264
	s_setprio 1
	s_waitcnt lgkmcnt(0)
	v_mfma_f32_16x16x32_bf16 v[124:127], v[166:169], v[130:133], v[124:127]
	v_mfma_f32_16x16x32_bf16 v[120:123], v[170:173], v[130:133], v[120:123]
	v_mfma_f32_16x16x32_bf16 v[116:119], v[174:177], v[130:133], v[116:119]
	v_mfma_f32_16x16x32_bf16 v[112:115], v[178:181], v[130:133], v[112:115]
	v_mfma_f32_16x16x32_bf16 v[108:111], v[166:169], v[138:141], v[108:111]
	v_mfma_f32_16x16x32_bf16 v[104:107], v[170:173], v[138:141], v[104:107]
	v_mfma_f32_16x16x32_bf16 v[100:103], v[174:177], v[138:141], v[100:103]
	v_mfma_f32_16x16x32_bf16 v[96:99], v[178:181], v[138:141], v[96:99]
	v_mfma_f32_16x16x32_bf16 v[92:95], v[166:169], v[142:145], v[92:95]
	v_mfma_f32_16x16x32_bf16 v[88:91], v[170:173], v[142:145], v[88:91]
	v_mfma_f32_16x16x32_bf16 v[84:87], v[174:177], v[142:145], v[84:87]
	v_mfma_f32_16x16x32_bf16 v[80:83], v[178:181], v[142:145], v[80:83]
	v_mfma_f32_16x16x32_bf16 v[130:133], v[166:169], v[146:149], v[76:79]
	v_mfma_f32_16x16x32_bf16 v[72:75], v[170:173], v[146:149], v[72:75]
	v_mfma_f32_16x16x32_bf16 v[68:71], v[174:177], v[146:149], v[68:71]
	v_mfma_f32_16x16x32_bf16 v[64:67], v[178:181], v[146:149], v[64:67]
	v_mfma_f32_16x16x32_bf16 v[60:63], v[166:169], v[150:153], v[60:63]
	v_mfma_f32_16x16x32_bf16 v[56:59], v[170:173], v[150:153], v[56:59]
	v_mfma_f32_16x16x32_bf16 v[52:55], v[174:177], v[150:153], v[52:55]
	v_mfma_f32_16x16x32_bf16 v[48:51], v[178:181], v[150:153], v[48:51]
	v_mfma_f32_16x16x32_bf16 v[44:47], v[166:169], v[154:157], v[44:47]
	v_mfma_f32_16x16x32_bf16 v[40:43], v[170:173], v[154:157], v[40:43]
	v_mfma_f32_16x16x32_bf16 v[36:39], v[174:177], v[154:157], v[36:39]
	v_mfma_f32_16x16x32_bf16 v[32:35], v[178:181], v[154:157], v[32:35]
	v_mfma_f32_16x16x32_bf16 v[28:31], v[166:169], v[158:161], v[28:31]
	v_mfma_f32_16x16x32_bf16 v[24:27], v[170:173], v[158:161], v[24:27]
	v_mfma_f32_16x16x32_bf16 v[20:23], v[174:177], v[158:161], v[20:23]
	v_mfma_f32_16x16x32_bf16 v[16:19], v[178:181], v[158:161], v[16:19]
	v_mfma_f32_16x16x32_bf16 v[12:15], v[166:169], v[162:165], v[12:15]
	v_mfma_f32_16x16x32_bf16 v[8:11], v[170:173], v[162:165], v[8:11]
	v_mfma_f32_16x16x32_bf16 v[4:7], v[174:177], v[162:165], v[4:7]
	v_mfma_f32_16x16x32_bf16 v[0:3], v[178:181], v[162:165], v[0:3]
	s_setprio 0
	v_and_b32_e32 v76, 0xffffff80, v134
	v_add_u32_e32 v76, s17, v76
	v_lshrrev_b32_e32 v77, 1, v134
	v_or_b32_e32 v128, v76, v135
	v_lshlrev_b32_e32 v76, 6, v136
	v_and_b32_e32 v77, 24, v77
	v_or3_b32 v78, v76, v77, s18
	v_ashrrev_i32_e32 v79, 31, v78
	v_lshl_add_u64 v[76:77], v[78:79], 1, s[94:95]
	v_mov_b32_e32 v79, v129
	v_lshl_add_u64 v[134:135], v[78:79], 1, s[40:41]
	s_nop 4
	v_cvt_pk_bf16_f32 v124, v124, v125
	s_nop 4
	v_cvt_pk_bf16_f32 v125, v126, v127
	s_nop 4
	v_cvt_pk_bf16_f32 v126, v120, v121
	s_nop 0
	v_lshl_add_u64 v[134:135], v[134:135], 0, s[4:5]
	v_cmp_gt_i32_e32 vcc, s12, v78
	s_nop 1
	v_cndmask_b32_e32 v77, v135, v77, vcc
	v_cndmask_b32_e32 v76, v134, v76, vcc
	s_nop 1
	v_or_b32_e32 v78, 32, v78
	v_cvt_pk_bf16_f32 v127, v122, v123
	v_mad_i64_i32 v[120:121], s[6:7], v128, s15, v[76:77]
	v_ashrrev_i32_e32 v79, 31, v78
	global_store_dwordx4 v[120:121], v[124:127], off
	v_lshl_add_u64 v[120:121], v[78:79], 1, s[94:95]
	v_mov_b32_e32 v79, v129
	v_lshl_add_u64 v[122:123], v[78:79], 1, s[40:41]
	v_lshl_add_u64 v[122:123], v[122:123], 0, s[4:5]
	v_cmp_gt_i32_e32 vcc, s12, v78
	s_add_i32 s16, s16, s86
	s_add_i32 s8, s8, s9
	v_cndmask_b32_e32 v78, v122, v120, vcc
	s_nop 4
	v_cvt_pk_bf16_f32 v116, v116, v117
	s_nop 4
	v_cvt_pk_bf16_f32 v117, v118, v119
	s_nop 4
	v_cvt_pk_bf16_f32 v118, v112, v113
	s_nop 2
	v_cndmask_b32_e32 v79, v123, v121, vcc
	s_nop 1
	v_cvt_pk_bf16_f32 v119, v114, v115
	v_mad_i64_i32 v[112:113], s[6:7], v128, s15, v[78:79]
	global_store_dwordx4 v[112:113], v[116:119], off
	s_nop 4
	v_cvt_pk_bf16_f32 v108, v108, v109
	s_nop 4
	v_cvt_pk_bf16_f32 v109, v110, v111
	s_nop 4
	v_cvt_pk_bf16_f32 v110, v104, v105
	s_nop 2
	v_or_b32_e32 v112, 16, v128
	s_nop 1
	v_cvt_pk_bf16_f32 v111, v106, v107
	v_mad_i64_i32 v[104:105], s[6:7], v112, s15, v[76:77]
	global_store_dwordx4 v[104:105], v[108:111], off
	s_nop 4
	v_cvt_pk_bf16_f32 v100, v100, v101
	s_nop 4
	v_cvt_pk_bf16_f32 v101, v102, v103
	s_nop 4
	v_cvt_pk_bf16_f32 v102, v96, v97
	s_nop 4
	v_cvt_pk_bf16_f32 v103, v98, v99
	v_mad_i64_i32 v[96:97], s[6:7], v112, s15, v[78:79]
	global_store_dwordx4 v[96:97], v[100:103], off
	s_nop 4
	v_cvt_pk_bf16_f32 v92, v92, v93
	s_nop 4
	v_cvt_pk_bf16_f32 v93, v94, v95
	s_nop 4
	v_cvt_pk_bf16_f32 v94, v88, v89
	s_nop 2
	v_or_b32_e32 v96, 32, v128
	s_nop 1
	v_cvt_pk_bf16_f32 v95, v90, v91
	v_mad_i64_i32 v[88:89], s[6:7], v96, s15, v[76:77]
	global_store_dwordx4 v[88:89], v[92:95], off
	s_nop 4
	v_cvt_pk_bf16_f32 v84, v84, v85
	s_nop 4
	v_cvt_pk_bf16_f32 v85, v86, v87
	s_nop 4
	v_cvt_pk_bf16_f32 v86, v80, v81
	s_nop 4
	v_cvt_pk_bf16_f32 v87, v82, v83
	v_mad_i64_i32 v[80:81], s[6:7], v96, s15, v[78:79]
	global_store_dwordx4 v[80:81], v[84:87], off
	s_nop 4
	v_cvt_pk_bf16_f32 v80, v130, v131
	s_nop 4
	v_cvt_pk_bf16_f32 v81, v132, v133
	s_nop 4
	v_cvt_pk_bf16_f32 v82, v72, v73
	s_nop 2
	v_or_b32_e32 v84, 48, v128
	s_nop 1
	v_cvt_pk_bf16_f32 v83, v74, v75
	v_mad_i64_i32 v[72:73], s[6:7], v84, s15, v[76:77]
	global_store_dwordx4 v[72:73], v[80:83], off
	s_nop 4
	v_cvt_pk_bf16_f32 v68, v68, v69
	s_nop 4
	v_cvt_pk_bf16_f32 v69, v70, v71
	s_nop 4
	v_cvt_pk_bf16_f32 v70, v64, v65
	s_nop 4
	v_cvt_pk_bf16_f32 v71, v66, v67
	v_mad_i64_i32 v[64:65], s[6:7], v84, s15, v[78:79]
	global_store_dwordx4 v[64:65], v[68:71], off
	s_nop 4
	v_cvt_pk_bf16_f32 v60, v60, v61
	s_nop 4
	v_cvt_pk_bf16_f32 v61, v62, v63
	s_nop 4
	v_cvt_pk_bf16_f32 v62, v56, v57
	s_nop 2
	v_or_b32_e32 v64, 64, v128
	s_nop 1
	v_cvt_pk_bf16_f32 v63, v58, v59
	v_mad_i64_i32 v[56:57], s[6:7], v64, s15, v[76:77]
	global_store_dwordx4 v[56:57], v[60:63], off
	s_nop 4
	v_cvt_pk_bf16_f32 v52, v52, v53
	s_nop 4
	v_cvt_pk_bf16_f32 v53, v54, v55
	s_nop 4
	v_cvt_pk_bf16_f32 v54, v48, v49
	s_nop 4
	v_cvt_pk_bf16_f32 v55, v50, v51
	v_mad_i64_i32 v[48:49], s[6:7], v64, s15, v[78:79]
	global_store_dwordx4 v[48:49], v[52:55], off
	s_nop 4
	v_cvt_pk_bf16_f32 v44, v44, v45
	s_nop 4
	v_cvt_pk_bf16_f32 v45, v46, v47
	s_nop 4
	v_cvt_pk_bf16_f32 v46, v40, v41
	s_nop 2
	v_or_b32_e32 v48, 0x50, v128
	s_nop 1
	v_cvt_pk_bf16_f32 v47, v42, v43
	v_mad_i64_i32 v[40:41], s[6:7], v48, s15, v[76:77]
	global_store_dwordx4 v[40:41], v[44:47], off
	s_nop 4
	v_cvt_pk_bf16_f32 v36, v36, v37
	s_nop 4
	v_cvt_pk_bf16_f32 v37, v38, v39
	s_nop 4
	v_cvt_pk_bf16_f32 v38, v32, v33
	s_nop 4
	v_cvt_pk_bf16_f32 v39, v34, v35
	v_mad_i64_i32 v[32:33], s[6:7], v48, s15, v[78:79]
	global_store_dwordx4 v[32:33], v[36:39], off
	s_nop 4
	v_cvt_pk_bf16_f32 v28, v28, v29
	s_nop 4
	v_cvt_pk_bf16_f32 v29, v30, v31
	s_nop 4
	v_cvt_pk_bf16_f32 v30, v24, v25
	s_nop 2
	v_or_b32_e32 v32, 0x60, v128
	s_nop 1
	v_cvt_pk_bf16_f32 v31, v26, v27
	v_mad_i64_i32 v[24:25], s[6:7], v32, s15, v[76:77]
	global_store_dwordx4 v[24:25], v[28:31], off
	s_nop 4
	v_cvt_pk_bf16_f32 v20, v20, v21
	s_nop 4
	v_cvt_pk_bf16_f32 v21, v22, v23
	s_nop 4
	v_cvt_pk_bf16_f32 v22, v16, v17
	s_nop 4
	v_cvt_pk_bf16_f32 v23, v18, v19
	v_mad_i64_i32 v[16:17], s[6:7], v32, s15, v[78:79]
	global_store_dwordx4 v[16:17], v[20:23], off
	s_nop 4
	v_cvt_pk_bf16_f32 v12, v12, v13
	s_nop 4
	v_cvt_pk_bf16_f32 v13, v14, v15
	s_nop 4
	v_cvt_pk_bf16_f32 v14, v8, v9
	s_nop 2
	v_or_b32_e32 v16, 0x70, v128
	s_nop 1
	v_cvt_pk_bf16_f32 v15, v10, v11
	v_mad_i64_i32 v[8:9], s[6:7], v16, s15, v[76:77]
	global_store_dwordx4 v[8:9], v[12:15], off
	s_nop 4
	v_cvt_pk_bf16_f32 v4, v4, v5
	s_nop 4
	v_cvt_pk_bf16_f32 v5, v6, v7
	s_nop 4
	v_cvt_pk_bf16_f32 v6, v0, v1
	s_nop 4
	s_add_i32 s10, s10, s11
	v_cvt_pk_bf16_f32 v7, v2, v3
	v_mad_i64_i32 v[0:1], s[6:7], v16, s15, v[78:79]
	s_cmpk_lt_i32 s16, 0x580
	global_store_dwordx4 v[0:1], v[4:7], off
	s_cbranch_scc1 .LBB0_886
	v_readlane_b32 s16, v254, 56

.LBB0_893:
	v_lshl_add_u64 v[36:37], v[28:29], 0, v[20:21]
	s_mov_b32 s9, 0x12d0000
	v_add_co_u32_e32 v48, vcc, s9, v36
	s_mov_b32 s9, 0x12d8000
	s_nop 0
	v_addc_co_u32_e32 v49, vcc, 0, v37, vcc
	v_add_co_u32_e32 v50, vcc, s9, v36
	v_lshl_add_u64 v[52:53], v[26:27], 0, v[20:21]
	s_nop 0
	v_addc_co_u32_e32 v51, vcc, 0, v37, vcc
	s_mov_b32 s9, 0x8000
	v_add_co_u32_e32 v54, vcc, s9, v52
	global_load_dwordx4 v[40:43], v[52:53], off
	s_nop 0
	v_addc_co_u32_e32 v55, vcc, 0, v53, vcc
	global_load_dwordx4 v[44:47], v[54:55], off
	global_load_dwordx4 v[32:35], v[48:49], off
	global_load_dwordx4 v[36:39], v[50:51], off
	s_addk_i32 s8, 0x80
	v_lshl_add_u64 v[26:27], v[26:27], 0, s[0:1]
	v_lshl_add_u64 v[28:29], v[28:29], 0, s[0:1]
	s_cmpk_gt_u32 s8, 0x3df
	s_waitcnt vmcnt(0)
	v_mfma_f32_16x16x32_bf16 v[12:15], v[40:43], v[32:35], v[12:15]
	v_mfma_f32_16x16x32_bf16 v[8:11], v[44:47], v[32:35], v[8:11]
	v_mfma_f32_16x16x32_bf16 v[4:7], v[40:43], v[36:39], v[4:7]
	v_mfma_f32_16x16x32_bf16 v[0:3], v[44:47], v[36:39], v[0:3]
	global_load_dwordx4 v[32:35], v[48:49], off offset:128
	global_load_dwordx4 v[36:39], v[50:51], off offset:128
	global_load_dwordx4 v[40:43], v[52:53], off offset:128
	global_load_dwordx4 v[44:47], v[54:55], off offset:128
	s_waitcnt vmcnt(1)
	v_mfma_f32_16x16x32_bf16 v[12:15], v[40:43], v[32:35], v[12:15]
	s_waitcnt vmcnt(0)
	v_mfma_f32_16x16x32_bf16 v[8:11], v[44:47], v[32:35], v[8:11]
	v_mfma_f32_16x16x32_bf16 v[4:7], v[40:43], v[36:39], v[4:7]
	v_mfma_f32_16x16x32_bf16 v[0:3], v[44:47], v[36:39], v[0:3]
	global_load_dwordx4 v[32:35], v[48:49], off offset:256
	global_load_dwordx4 v[36:39], v[50:51], off offset:256
	global_load_dwordx4 v[40:43], v[52:53], off offset:256
	global_load_dwordx4 v[44:47], v[54:55], off offset:256
	s_waitcnt vmcnt(1)
	v_mfma_f32_16x16x32_bf16 v[12:15], v[40:43], v[32:35], v[12:15]
	s_waitcnt vmcnt(0)
	v_mfma_f32_16x16x32_bf16 v[8:11], v[44:47], v[32:35], v[8:11]
	v_mfma_f32_16x16x32_bf16 v[4:7], v[40:43], v[36:39], v[4:7]
	v_mfma_f32_16x16x32_bf16 v[0:3], v[44:47], v[36:39], v[0:3]
	global_load_dwordx4 v[32:35], v[48:49], off offset:384
	global_load_dwordx4 v[36:39], v[50:51], off offset:384
	global_load_dwordx4 v[40:43], v[52:53], off offset:384
	global_load_dwordx4 v[44:47], v[54:55], off offset:384
	s_waitcnt vmcnt(1)
	v_mfma_f32_16x16x32_bf16 v[12:15], v[40:43], v[32:35], v[12:15]
	s_waitcnt vmcnt(0)
	v_mfma_f32_16x16x32_bf16 v[8:11], v[44:47], v[32:35], v[8:11]
	v_mfma_f32_16x16x32_bf16 v[4:7], v[40:43], v[36:39], v[4:7]
	v_mfma_f32_16x16x32_bf16 v[0:3], v[44:47], v[36:39], v[0:3]
	s_cbranch_scc0 .LBB0_893
	v_lshl_or_b32 v26, s7, 5, v30
	v_ashrrev_i32_e32 v27, 31, v26
	v_lshl_add_u64 v[28:29], v[26:27], 1, s[94:95]
	v_mov_b32_e32 v27, v21
	v_lshl_add_u64 v[32:33], v[26:27], 1, s[40:41]
	s_nop 0
	v_and_b32_sdwa v27, v12, v31 dst_sel:DWORD dst_unused:UNUSED_PAD src0_sel:WORD_1 src1_sel:DWORD
	v_add3_u32 v12, v12, v27, s6
	s_nop 1
	v_and_b32_sdwa v27, v13, v31 dst_sel:DWORD dst_unused:UNUSED_PAD src0_sel:WORD_1 src1_sel:DWORD
	v_lshl_add_u64 v[32:33], v[32:33], 0, s[2:3]
	v_cmp_gt_i32_e32 vcc, s5, v26
	s_nop 0
	v_add3_u32 v13, v13, v27, s6
	v_cndmask_b32_e32 v29, v33, v29, vcc
	v_cndmask_b32_e32 v28, v32, v28, vcc
	s_nop 0
	v_and_b32_e32 v23, 0xffff0000, v13
	v_lshl_add_u64 v[32:33], v[28:29], 0, v[16:17]
	v_cvt_pk_bf16_f32 v13, v14, v15
	v_or_b32_sdwa v12, v23, v12 dst_sel:DWORD dst_unused:UNUSED_PAD src0_sel:DWORD src1_sel:WORD_1
	global_store_dwordx2 v[32:33], v[12:13], off
	v_or_b32_e32 v12, 16, v26
	v_ashrrev_i32_e32 v13, 31, v12
	v_lshl_add_u64 v[14:15], v[12:13], 1, s[94:95]
	v_mov_b32_e32 v13, v21
	v_lshl_add_u64 v[26:27], v[12:13], 1, s[40:41]
	v_lshl_add_u64 v[26:27], v[26:27], 0, s[2:3]
	v_cmp_gt_i32_e32 vcc, s5, v12
	s_nop 1
	v_cndmask_b32_e32 v12, v26, v14, vcc
	v_and_b32_sdwa v26, v8, v31 dst_sel:DWORD dst_unused:UNUSED_PAD src0_sel:WORD_1 src1_sel:DWORD
	s_nop 0
	v_add3_u32 v8, v8, v26, s6
	v_and_b32_sdwa v26, v9, v31 dst_sel:DWORD dst_unused:UNUSED_PAD src0_sel:WORD_1 src1_sel:DWORD
	s_nop 0
	v_add3_u32 v9, v9, v26, s6
	s_nop 0
	v_and_b32_e32 v23, 0xffff0000, v9
	v_cvt_pk_bf16_f32 v9, v10, v11
	s_nop 0
	v_and_b32_sdwa v11, v4, v31 dst_sel:DWORD dst_unused:UNUSED_PAD src0_sel:WORD_1 src1_sel:DWORD
	s_nop 1
	v_add3_u32 v4, v4, v11, s6
	v_and_b32_sdwa v11, v5, v31 dst_sel:DWORD dst_unused:UNUSED_PAD src0_sel:WORD_1 src1_sel:DWORD
	s_nop 0
	v_add3_u32 v5, v5, v11, s6
	s_nop 0
	v_and_b32_e32 v10, 0xffff0000, v5
	v_cvt_pk_bf16_f32 v5, v6, v7
	s_nop 0
	v_and_b32_sdwa v7, v0, v31 dst_sel:DWORD dst_unused:UNUSED_PAD src0_sel:WORD_1 src1_sel:DWORD
	v_cndmask_b32_e32 v13, v27, v15, vcc
	v_add3_u32 v0, v0, v7, s6
	s_nop 1
	v_and_b32_sdwa v7, v1, v31 dst_sel:DWORD dst_unused:UNUSED_PAD src0_sel:WORD_1 src1_sel:DWORD
	v_lshl_add_u64 v[14:15], v[12:13], 0, v[16:17]
	v_or_b32_sdwa v8, v23, v8 dst_sel:DWORD dst_unused:UNUSED_PAD src0_sel:DWORD src1_sel:WORD_1
	s_nop 0
	v_add3_u32 v1, v1, v7, s6
	global_store_dwordx2 v[14:15], v[8:9], off
	v_lshl_add_u64 v[8:9], v[28:29], 0, v[18:19]
	v_or_b32_sdwa v4, v10, v4 dst_sel:DWORD dst_unused:UNUSED_PAD src0_sel:DWORD src1_sel:WORD_1
	s_nop 0
	v_and_b32_e32 v6, 0xffff0000, v1
	s_add_i32 s7, s7, s86
	global_store_dwordx2 v[8:9], v[4:5], off
	v_lshl_add_u64 v[4:5], v[12:13], 0, v[18:19]
	v_cvt_pk_bf16_f32 v1, v2, v3
	v_or_b32_sdwa v0, v6, v0 dst_sel:DWORD dst_unused:UNUSED_PAD src0_sel:DWORD src1_sel:WORD_1
	s_cmpk_gt_i32 s7, 0x57
	v_add_u32_e32 v22, s4, v22
	global_store_dwordx2 v[4:5], v[0:1], off
	s_cbranch_scc0 .LBB0_892

.LBB0_920:
	s_or_b64 exec, exec, s[42:43]
	s_mov_b32 s64, 0xbfb8aa3b
	s_abs_i32 s8, s86
	v_cvt_f32_u32_e32 v1, s8
	s_add_i32 s0, s86, 0x107f
	s_ashr_i32 s9, s0, 31
	s_abs_i32 s10, s0
	v_rcp_iflag_f32_e32 v1, v1
	s_sub_i32 s0, 0, s8
	v_mov_b32_e32 v0, v190
	s_waitcnt lgkmcnt(0)
	v_mul_f32_e32 v1, 0x4f7ffffe, v1
	v_cvt_u32_f32_e32 v1, v1
	s_barrier
	v_readfirstlane_b32 s1, v1
	s_mul_i32 s0, s0, s1
	s_mul_hi_u32 s0, s1, s0
	s_add_i32 s1, s1, s0
	s_movk_i32 s0, 0x200
	s_ashr_i32 s11, s86, 31
	s_mul_hi_u32 s12, s10, s1
	v_cmp_gt_i32_e32 vcc, s0, v0
	s_and_saveexec_b64 s[0:1], vcc
	s_cbranch_execz .LBB0_933
	v_max_i32_e32 v1, 0x100, v0
	v_sub_u32_e32 v1, v1, v0
	v_add_u32_e32 v2, 0xff, v1
	s_movk_i32 s2, 0x2ff
	v_and_b32_e32 v8, 7, v0
	v_cmp_lt_u32_e32 vcc, s2, v2
	s_mov_b64 s[4:5], -1
	v_mov_b32_e32 v1, v0
	s_and_saveexec_b64 s[2:3], vcc
	s_cbranch_execz .LBB0_930
	v_lshrrev_b32_e32 v9, 8, v2
	v_add_u32_e32 v4, -3, v9
	v_add_u32_e32 v3, 0x300, v0
	v_add_u32_e32 v2, 0x200, v0
	v_lshrrev_b32_e32 v5, 2, v4
	v_add_u32_e32 v1, 0x100, v0
	v_add_u32_e32 v10, 1, v5
	v_cmp_lt_u32_e32 vcc, 11, v4
	v_mov_b64_e32 v[6:7], v[2:3]
	v_mov_b64_e32 v[4:5], v[0:1]
	s_and_saveexec_b64 s[4:5], vcc
	s_cbranch_execz .LBB0_926
	v_mov_b64_e32 v[6:7], v[2:3]
	v_and_b32_e32 v11, 0x7ffffffc, v10
	v_lshlrev_b32_e32 v12, 1, v8
	s_mov_b64 s[6:7], 0
	s_movk_i32 s13, 0xd0
	v_mov_b32_e32 v13, 0
	v_mov_b64_e32 v[4:5], v[0:1]

.LBB0_936:
	s_mul_hi_i32 s20, s45, 0x3e0f83e1
	s_lshr_b32 s21, s20, 31
	s_ashr_i32 s51, s20, 6
	s_add_i32 s51, s51, s21
	s_mul_i32 s49, s51, 0xfffffef8
	s_add_i32 s49, s49, s45
	s_lshl_b32 s20, s49, 4
	s_addk_i32 s20, 0x3000
	s_lshl_b32 s21, s49, 6
	s_cmpk_lt_i32 s49, 0x100
	s_cselect_b32 s52, s21, s20
	s_cselect_b32 s50, 64, 16
	s_add_i32 s21, s49, 0xffffff00
	s_add_i32 s20, s49, -1
	s_cmpk_lt_u32 s20, 0xff
	s_cselect_b64 s[30:31], -1, 0
	s_or_b32 s53, s50, 3
	v_readlane_b32 s4, v254, 2
	s_mul_i32 s20, s51, 0x58
	s_cmpk_gt_i32 s49, 0xff
	v_readlane_b32 s5, v254, 3
	v_readlane_b32 s6, v254, 4
	v_readlane_b32 s7, v254, 5
	v_readlane_b32 s8, v254, 6
	v_readlane_b32 s9, v254, 7
	v_readlane_b32 s10, v254, 8
	v_readlane_b32 s11, v254, 9
	v_readlane_b32 s12, v254, 10
	v_readlane_b32 s13, v254, 11
	v_readlane_b32 s14, v254, 12
	v_readlane_b32 s15, v254, 13
	s_cselect_b64 s[28:29], -1, 0
	s_mul_hi_u32 s25, s21, 3
	s_mul_i32 s24, s21, 3
	s_ashr_i32 s21, s20, 31
	v_readlane_b32 s16, v254, 14
	v_readlane_b32 s17, v254, 15
	v_readlane_b32 s18, v254, 16
	v_readlane_b32 s19, v254, 17
	s_mov_b64 s[4:5], s[8:9]
	s_lshl_b64 s[22:23], s[20:21], 2
	s_mov_b64 s[6:7], s[10:11]
	s_add_u32 s26, s6, s22
	s_addc_u32 s27, s7, s23
	s_add_i32 s52, s52, -3
	s_lshl_b64 s[22:23], s[20:21], 1
	s_add_u32 s22, s94, s22
	s_addc_u32 s23, s95, s23
	v_cmp_gt_i32_e32 vcc, s53, v138
	v_mov_b32_e32 v126, 0
	v_mov_b32_e32 v127, 0
	v_mov_b32_e32 v128, 0
	v_mov_b32_e32 v129, 0
	s_mov_b64 s[8:9], s[12:13]
	s_mov_b64 s[10:11], s[14:15]
	s_mov_b64 s[12:13], s[16:17]
	s_mov_b64 s[14:15], s[18:19]
	s_and_saveexec_b64 s[34:35], vcc
	s_cbranch_execz .LBB0_943
	s_nor_b64 s[36:37], s[74:75], s[30:31]
	s_and_saveexec_b64 s[46:47], s[36:37]
	s_xor_b64 s[46:47], exec, s[46:47]
	s_cbranch_execz .LBB0_940
	v_mov_b32_e32 v129, 0
	s_andn2_b64 vcc, exec, s[28:29]
	v_mov_b32_e32 v128, 0
	v_mov_b32_e32 v127, 0
	v_mov_b32_e32 v126, 0
	s_cbranch_vccnz .LBB0_940
	v_lshl_add_u64 v[126:127], s[24:25], 0, v[138:139]
	v_mov_b64_e32 v[128:129], s[26:27]
	v_mad_u64_u32 v[128:129], s[36:37], v126, s33, v[128:129]
	v_mad_i32_i24 v129, v127, s33, v129
	v_lshl_add_u64 v[126:127], v[146:147], 2, v[128:129]
	global_load_dwordx4 v[128:131], v[126:127], off offset:16
	global_load_dwordx4 v[132:135], v[126:127], off
	s_waitcnt vmcnt(0)
	s_nop 9
	v_cvt_pk_bf16_f32 v127, v134, v135
	v_cvt_pk_bf16_f32 v126, v132, v133
	s_nop 0
	v_and_b32_sdwa v133, v128, v198 dst_sel:DWORD dst_unused:UNUSED_PAD src0_sel:WORD_1 src1_sel:DWORD
	v_add3_u32 v128, v128, v133, s38
	s_nop 1
	v_and_b32_sdwa v133, v129, v198 dst_sel:DWORD dst_unused:UNUSED_PAD src0_sel:WORD_1 src1_sel:DWORD
	s_nop 0
	v_add3_u32 v129, v129, v133, s38
	s_nop 0
	v_and_b32_e32 v132, 0xffff0000, v129
	v_cvt_pk_bf16_f32 v129, v130, v131
	v_or_b32_sdwa v128, v132, v128 dst_sel:DWORD dst_unused:UNUSED_PAD src0_sel:DWORD src1_sel:WORD_1

.LBB0_943:
	s_or_b64 exec, exec, s[34:35]
	v_cmp_gt_i32_e32 vcc, s53, v148
	v_mov_b32_e32 v130, 0
	v_mov_b32_e32 v134, 0
	v_mov_b32_e32 v135, 0
	v_mov_b32_e32 v136, 0
	v_mov_b32_e32 v137, 0
	s_and_saveexec_b64 s[34:35], vcc
	s_cbranch_execz .LBB0_950
	s_nor_b64 s[36:37], s[76:77], s[30:31]
	s_and_saveexec_b64 s[46:47], s[36:37]
	s_xor_b64 s[46:47], exec, s[46:47]
	s_cbranch_execz .LBB0_947
	v_mov_b32_e32 v137, 0
	s_andn2_b64 vcc, exec, s[28:29]
	v_mov_b32_e32 v136, 0
	v_mov_b32_e32 v135, 0
	v_mov_b32_e32 v134, 0
	s_cbranch_vccnz .LBB0_947
	v_lshl_add_u64 v[132:133], s[24:25], 0, v[148:149]
	v_mov_b64_e32 v[134:135], s[26:27]
	v_mad_u64_u32 v[134:135], s[36:37], v132, s33, v[134:135]
	v_mad_i32_i24 v135, v133, s33, v135
	v_lshl_add_u64 v[132:133], v[150:151], 2, v[134:135]
	global_load_dwordx4 v[160:163], v[132:133], off offset:16
	s_nop 0
	global_load_dwordx4 v[132:135], v[132:133], off
	s_waitcnt vmcnt(0)
	s_nop 9
	v_cvt_pk_bf16_f32 v135, v134, v135
	v_cvt_pk_bf16_f32 v134, v132, v133
	s_nop 9
	v_cvt_pk_bf16_f32 v137, v162, v163
	v_cvt_pk_bf16_f32 v136, v160, v161

.LBB0_950:
	s_or_b64 exec, exec, s[34:35]
	v_cmp_gt_i32_e32 vcc, s53, v152
	v_mov_b32_e32 v131, 0
	v_mov_b32_e32 v132, 0
	v_mov_b32_e32 v133, 0
	s_and_saveexec_b64 s[34:35], vcc
	s_cbranch_execz .LBB0_957
	s_nor_b64 s[30:31], s[80:81], s[30:31]
	s_and_saveexec_b64 s[36:37], s[30:31]
	s_xor_b64 s[30:31], exec, s[36:37]
	s_cbranch_execz .LBB0_954
	v_mov_b32_e32 v133, 0
	s_andn2_b64 vcc, exec, s[28:29]
	v_mov_b32_e32 v132, 0
	v_mov_b32_e32 v131, 0
	v_mov_b32_e32 v130, 0
	s_cbranch_vccnz .LBB0_954
	v_lshl_add_u64 v[130:131], s[24:25], 0, v[152:153]
	v_mov_b64_e32 v[132:133], s[26:27]
	v_mad_u64_u32 v[132:133], s[24:25], v130, s33, v[132:133]
	v_mad_i32_i24 v133, v131, s33, v133
	v_lshl_add_u64 v[130:131], v[154:155], 2, v[132:133]
	global_load_dwordx4 v[160:163], v[130:131], off offset:16
	s_nop 0
	global_load_dwordx4 v[130:133], v[130:131], off
	s_waitcnt vmcnt(0)
	s_nop 0
	v_and_b32_sdwa v164, v130, v198 dst_sel:DWORD dst_unused:UNUSED_PAD src0_sel:WORD_1 src1_sel:DWORD
	s_nop 1
	v_add3_u32 v130, v130, v164, s38
	v_and_b32_sdwa v164, v131, v198 dst_sel:DWORD dst_unused:UNUSED_PAD src0_sel:WORD_1 src1_sel:DWORD
	s_nop 0
	v_add3_u32 v131, v131, v164, s38
	s_nop 0
	v_and_b32_e32 v159, 0xffff0000, v131
	v_cvt_pk_bf16_f32 v131, v132, v133
	s_nop 0
	v_or_b32_sdwa v130, v159, v130 dst_sel:DWORD dst_unused:UNUSED_PAD src0_sel:DWORD src1_sel:WORD_1
	s_nop 8
	v_cvt_pk_bf16_f32 v133, v162, v163
	v_cvt_pk_bf16_f32 v132, v160, v161

.LBB0_962:
	s_or_b64 exec, exec, s[22:23]
	s_and_b64 vcc, exec, s[20:21]
	s_waitcnt lgkmcnt(0)
	s_barrier
	s_cbranch_vccz .LBB0_969
	v_add_u32_e32 v2, 0x12ea0, v177
	v_add_u32_e32 v10, 0x13020, v177
	v_add_u32_e32 v18, 0x131a0, v177
	v_add_u32_e32 v22, 0x13320, v177
	v_add_u32_e32 v30, 0x134a0, v177
	v_add_u32_e32 v50, 0x12a20, v144
	ds_read_b128 v[14:17], v2
	ds_read_b128 v[2:5], v2 offset:16
	ds_read_b128 v[6:9], v10
	ds_read_b128 v[10:13], v10 offset:16
	ds_read_b128 v[26:29], v18
	ds_read_b128 v[18:21], v18 offset:16
	ds_read_b128 v[34:37], v22
	ds_read_b128 v[22:25], v22 offset:16
	ds_read_b128 v[38:41], v30
	ds_read_b128 v[30:33], v30 offset:16
	ds_read_b128 v[42:45], v50
	ds_read_b128 v[46:49], v50 offset:384
	ds_read_b128 v[50:53], v50 offset:768
	s_waitcnt lgkmcnt(0)
	v_mul_f32_e32 v42, 0x3fb8aa3b, v42
	v_mul_f32_e32 v43, 0x3fb8aa3b, v43
	v_mul_f32_e32 v44, 0x3fb8aa3b, v44
	v_mul_f32_e32 v45, 0x3fb8aa3b, v45
	v_mul_f32_e32 v46, 0xbfb8aa3b, v46
	v_mul_f32_e32 v47, 0xbfb8aa3b, v47
	v_mul_f32_e32 v48, 0xbfb8aa3b, v48
	v_mul_f32_e32 v49, 0xbfb8aa3b, v49
	v_mul_f32_e32 v50, 0xbfb8aa3b, v50
	v_mul_f32_e32 v51, 0xbfb8aa3b, v51
	v_mul_f32_e32 v52, 0xbfb8aa3b, v52
	v_mul_f32_e32 v53, 0xbfb8aa3b, v53
	s_waitcnt vmcnt(0) lgkmcnt(6)
	v_mov_b32_e32 v136, v34
	v_mov_b32_e32 v137, v36
	s_waitcnt lgkmcnt(4)
	v_mov_b32_e32 v132, v38
	v_mov_b32_e32 v133, v40
	v_mov_b32_e32 v164, v26
	v_mov_b32_e32 v165, v28
	v_mov_b32_e32 v174, v6
	v_mov_b32_e32 v175, v8
	v_mov_b32_e32 v168, v14
	v_mov_b32_e32 v169, v16
	v_mov_b32_e32 v134, v39
	v_mov_b32_e32 v135, v41
	v_mov_b32_e32 v162, v35
	v_mov_b32_e32 v163, v37
	v_mov_b32_e32 v166, v27
	v_mov_b32_e32 v167, v29
	v_mov_b32_e32 v170, v7
	v_mov_b32_e32 v171, v9
	v_mov_b32_e32 v172, v15
	v_mov_b32_e32 v173, v17
	s_mov_b32 s48, s51
	s_and_saveexec_b64 s[20:21], s[2:3]
	s_cbranch_execnz .LBB0_970
	s_branch .LBB0_978

.LBB0_970:
	v_cmp_gt_i32_e32 vcc, s50, v138
	v_mov_b32_e32 v126, 0
	v_mov_b32_e32 v128, 0
	v_mov_b32_e32 v129, 0
	v_mov_b32_e32 v130, 0
	v_mov_b32_e32 v131, 0
	s_and_saveexec_b64 s[22:23], vcc
	s_cbranch_execz .LBB0_972
	v_add_u32_e32 v127, v178, v179
	ds_read_b128 v[128:131], v127
	ds_read_b128 v[206:209], v127 offset:176
	ds_read_b128 v[210:213], v127 offset:352
	ds_read_b128 v[214:217], v127 offset:528
	s_waitcnt lgkmcnt(3)
	v_lshlrev_b32_e32 v218, 16, v128
	v_and_b32_e32 v128, 0xffff0000, v128
	v_lshlrev_b32_e32 v219, 16, v129
	v_and_b32_e32 v129, 0xffff0000, v129
	s_waitcnt lgkmcnt(2)
	v_lshlrev_b32_e32 v221, 16, v207
	v_lshlrev_b32_e32 v220, 16, v206
	v_pk_fma_f32 v[128:129], v[170:171], v[128:129], v[172:173]
	v_and_b32_e32 v207, 0xffff0000, v207
	v_and_b32_e32 v206, 0xffff0000, v206
	v_pk_fma_f32 v[128:129], v[166:167], v[206:207], v[128:129]
	s_waitcnt lgkmcnt(1)
	v_and_b32_e32 v207, 0xffff0000, v211
	v_and_b32_e32 v206, 0xffff0000, v210
	v_pk_fma_f32 v[218:219], v[174:175], v[218:219], v[168:169]
	v_pk_fma_f32 v[128:129], v[162:163], v[206:207], v[128:129]
	s_waitcnt lgkmcnt(0)
	v_and_b32_e32 v207, 0xffff0000, v215
	v_and_b32_e32 v206, 0xffff0000, v214
	v_pk_fma_f32 v[218:219], v[164:165], v[220:221], v[218:219]
	v_lshlrev_b32_e32 v221, 16, v211
	v_lshlrev_b32_e32 v220, 16, v210
	v_pk_fma_f32 v[128:129], v[134:135], v[206:207], v[128:129]
	v_and_b32_e32 v207, 0xffff0000, v130
	v_lshlrev_b32_e32 v206, 16, v130
	v_pk_fma_f32 v[218:219], v[136:137], v[220:221], v[218:219]
	v_lshlrev_b32_e32 v221, 16, v215
	v_lshlrev_b32_e32 v220, 16, v214
	v_pk_fma_f32 v[206:207], v[10:11], v[206:207], v[2:3]
	v_and_b32_e32 v211, 0xffff0000, v208
	v_lshlrev_b32_e32 v210, 16, v208
	v_pk_fma_f32 v[218:219], v[132:133], v[220:221], v[218:219]
	s_nop 0
	v_pk_fma_f32 v[206:207], v[18:19], v[210:211], v[206:207]
	v_and_b32_e32 v211, 0xffff0000, v212
	v_lshlrev_b32_e32 v210, 16, v212
	s_nop 1
	v_pk_fma_f32 v[206:207], v[22:23], v[210:211], v[206:207]
	v_and_b32_e32 v211, 0xffff0000, v216
	v_lshlrev_b32_e32 v210, 16, v216
	s_nop 1
	v_pk_fma_f32 v[206:207], v[30:31], v[210:211], v[206:207]
	v_cvt_pk_bf16_f32 v129, v219, v129
	v_and_b32_sdwa v127, v207, v198 dst_sel:DWORD dst_unused:UNUSED_PAD src0_sel:WORD_1 src1_sel:DWORD
	v_and_b32_sdwa v130, v206, v198 dst_sel:DWORD dst_unused:UNUSED_PAD src0_sel:WORD_1 src1_sel:DWORD
	v_add3_u32 v127, v207, v127, s38
	v_add3_u32 v130, v206, v130, s38
	v_and_b32_e32 v207, 0xffff0000, v131
	v_lshlrev_b32_e32 v206, 16, v131
	v_pk_fma_f32 v[206:207], v[12:13], v[206:207], v[4:5]
	v_and_b32_e32 v211, 0xffff0000, v209
	v_lshlrev_b32_e32 v210, 16, v209
	v_pk_fma_f32 v[206:207], v[20:21], v[210:211], v[206:207]
	v_and_b32_e32 v209, 0xffff0000, v213
	v_lshlrev_b32_e32 v208, 16, v213
	v_pk_fma_f32 v[206:207], v[24:25], v[208:209], v[206:207]
	v_and_b32_e32 v209, 0xffff0000, v217
	v_lshlrev_b32_e32 v208, 16, v217
	v_pk_fma_f32 v[206:207], v[32:33], v[208:209], v[206:207]
	s_nop 0
	v_lshrrev_b32_e32 v130, 16, v130
	s_nop 2
	v_and_or_b32 v130, v127, s39, v130
	s_nop 5
	v_cvt_pk_bf16_f32 v128, v218, v128
	v_cvt_pk_bf16_f32 v131, v206, v207
.LBB0_972:
	s_or_b64 exec, exec, s[22:23]
	ds_write_b128 v202, v[128:131] offset:11808
	v_cmp_gt_i32_e32 vcc, s50, v180
	v_mov_b32_e32 v127, 0
	v_mov_b32_e32 v128, 0
	v_mov_b32_e32 v129, 0
	s_and_saveexec_b64 s[22:23], vcc
	s_cbranch_execz .LBB0_974
	v_add_u32_e32 v126, v178, v181
	ds_read_b128 v[126:129], v126
	v_add_u32_e32 v130, v178, v179
	ds_read_b128 v[206:209], v130 offset:4224
	ds_read_b128 v[210:213], v130 offset:4400
	ds_read_b128 v[214:217], v130 offset:4576
	s_waitcnt lgkmcnt(2)
	v_lshlrev_b32_e32 v219, 16, v207
	v_lshlrev_b32_e32 v130, 16, v126
	v_lshlrev_b32_e32 v131, 16, v127
	v_and_b32_e32 v126, 0xffff0000, v126
	v_and_b32_e32 v127, 0xffff0000, v127
	v_pk_fma_f32 v[130:131], v[174:175], v[130:131], v[168:169]
	v_lshlrev_b32_e32 v218, 16, v206
	v_pk_fma_f32 v[130:131], v[164:165], v[218:219], v[130:131]
	s_waitcnt lgkmcnt(1)
	v_lshlrev_b32_e32 v219, 16, v211
	v_lshlrev_b32_e32 v218, 16, v210
	v_pk_fma_f32 v[126:127], v[170:171], v[126:127], v[172:173]
	v_and_b32_e32 v207, 0xffff0000, v207
	v_and_b32_e32 v206, 0xffff0000, v206
	v_pk_fma_f32 v[130:131], v[136:137], v[218:219], v[130:131]
	s_waitcnt lgkmcnt(0)
	v_lshlrev_b32_e32 v219, 16, v215
	v_lshlrev_b32_e32 v218, 16, v214
	v_pk_fma_f32 v[126:127], v[166:167], v[206:207], v[126:127]
	v_and_b32_e32 v207, 0xffff0000, v211
	v_and_b32_e32 v206, 0xffff0000, v210
	v_pk_fma_f32 v[130:131], v[132:133], v[218:219], v[130:131]
	v_pk_fma_f32 v[126:127], v[162:163], v[206:207], v[126:127]
	v_and_b32_e32 v207, 0xffff0000, v215
	v_and_b32_e32 v206, 0xffff0000, v214
	v_pk_fma_f32 v[126:127], v[134:135], v[206:207], v[126:127]
	s_nop 9
	v_cvt_pk_bf16_f32 v127, v131, v127
	v_cvt_pk_bf16_f32 v126, v130, v126
	v_and_b32_e32 v131, 0xffff0000, v128
	v_lshlrev_b32_e32 v130, 16, v128
	v_pk_fma_f32 v[130:131], v[10:11], v[130:131], v[2:3]
	v_and_b32_e32 v207, 0xffff0000, v208
	v_lshlrev_b32_e32 v206, 16, v208
	v_pk_fma_f32 v[130:131], v[18:19], v[206:207], v[130:131]
	v_and_b32_e32 v207, 0xffff0000, v212
	v_lshlrev_b32_e32 v206, 16, v212
	v_pk_fma_f32 v[130:131], v[22:23], v[206:207], v[130:131]
	v_and_b32_e32 v207, 0xffff0000, v216
	v_lshlrev_b32_e32 v206, 16, v216
	v_pk_fma_f32 v[130:131], v[30:31], v[206:207], v[130:131]
	v_and_b32_e32 v207, 0xffff0000, v209
	s_nop 4
	v_cvt_pk_bf16_f32 v128, v130, v131
	v_and_b32_e32 v131, 0xffff0000, v129
	v_lshlrev_b32_e32 v130, 16, v129
	v_pk_fma_f32 v[130:131], v[12:13], v[130:131], v[4:5]
	v_lshlrev_b32_e32 v206, 16, v209
	v_pk_fma_f32 v[130:131], v[20:21], v[206:207], v[130:131]
	v_and_b32_e32 v207, 0xffff0000, v213
	v_lshlrev_b32_e32 v206, 16, v213
	v_pk_fma_f32 v[130:131], v[24:25], v[206:207], v[130:131]
	v_and_b32_e32 v207, 0xffff0000, v217
	v_lshlrev_b32_e32 v206, 16, v217
	v_pk_fma_f32 v[130:131], v[32:33], v[206:207], v[130:131]
	s_nop 0
	s_nop 4
	v_cvt_pk_bf16_f32 v129, v130, v131
.LBB0_974:
	s_or_b64 exec, exec, s[22:23]
	ds_write_b128 v202, v[126:129] offset:16592
	s_and_b64 exec, exec, s[92:93]
	s_cbranch_execz .LBB0_978
	v_cmp_gt_i32_e32 vcc, s50, v182
	v_mov_b32_e32 v126, 0
	v_mov_b32_e32 v127, 0
	v_mov_b32_e32 v128, 0
	v_mov_b32_e32 v129, 0
	s_and_saveexec_b64 s[22:23], vcc
	s_cbranch_execz .LBB0_977
	v_add_u32_e32 v126, v178, v181
	ds_read_b128 v[126:129], v126 offset:4048
	v_add_u32_e32 v130, v178, v179
	ds_read_b128 v[206:209], v130 offset:8272
	ds_read_b128 v[210:213], v130 offset:8448
	ds_read_b128 v[214:217], v130 offset:8624
	s_waitcnt lgkmcnt(3)
	v_lshlrev_b32_e32 v130, 16, v126
	v_lshlrev_b32_e32 v131, 16, v127
	v_pk_fma_f32 v[130:131], v[174:175], v[130:131], v[168:169]
	s_waitcnt lgkmcnt(2)
	v_lshlrev_b32_e32 v169, 16, v207
	v_lshlrev_b32_e32 v168, 16, v206
	v_pk_fma_f32 v[130:131], v[164:165], v[168:169], v[130:131]
	s_waitcnt lgkmcnt(1)
	v_lshlrev_b32_e32 v165, 16, v211
	v_lshlrev_b32_e32 v164, 16, v210
	v_and_b32_e32 v126, 0xffff0000, v126
	v_and_b32_e32 v127, 0xffff0000, v127
	v_pk_fma_f32 v[130:131], v[136:137], v[164:165], v[130:131]
	s_waitcnt lgkmcnt(0)
	v_lshlrev_b32_e32 v137, 16, v215
	v_lshlrev_b32_e32 v136, 16, v214
	v_pk_fma_f32 v[130:131], v[132:133], v[136:137], v[130:131]
	v_pk_fma_f32 v[126:127], v[170:171], v[126:127], v[172:173]
	v_and_b32_e32 v133, 0xffff0000, v207
	v_and_b32_e32 v132, 0xffff0000, v206
	v_pk_fma_f32 v[126:127], v[166:167], v[132:133], v[126:127]
	v_and_b32_e32 v133, 0xffff0000, v211
	v_and_b32_e32 v132, 0xffff0000, v210
	v_pk_fma_f32 v[126:127], v[162:163], v[132:133], v[126:127]
	v_and_b32_e32 v133, 0xffff0000, v215
	v_and_b32_e32 v132, 0xffff0000, v214
	v_pk_fma_f32 v[126:127], v[134:135], v[132:133], v[126:127]
	s_nop 9
	v_cvt_pk_bf16_f32 v127, v131, v127
	v_cvt_pk_bf16_f32 v126, v130, v126
	v_and_b32_e32 v131, 0xffff0000, v128
	v_lshlrev_b32_e32 v130, 16, v128
	v_pk_fma_f32 v[130:131], v[10:11], v[130:131], v[2:3]
	v_and_b32_e32 v133, 0xffff0000, v208
	v_lshlrev_b32_e32 v132, 16, v208
	v_pk_fma_f32 v[130:131], v[18:19], v[132:133], v[130:131]
	v_and_b32_e32 v133, 0xffff0000, v212
	v_lshlrev_b32_e32 v132, 16, v212
	v_pk_fma_f32 v[130:131], v[22:23], v[132:133], v[130:131]
	v_and_b32_e32 v133, 0xffff0000, v216
	v_lshlrev_b32_e32 v132, 16, v216
	v_pk_fma_f32 v[130:131], v[30:31], v[132:133], v[130:131]
	v_and_b32_e32 v133, 0xffff0000, v209
	s_nop 4
	v_cvt_pk_bf16_f32 v128, v130, v131
	v_and_b32_e32 v131, 0xffff0000, v129
	v_lshlrev_b32_e32 v130, 16, v129
	v_pk_fma_f32 v[130:131], v[12:13], v[130:131], v[4:5]
	v_lshlrev_b32_e32 v132, 16, v209
	v_pk_fma_f32 v[130:131], v[20:21], v[132:133], v[130:131]
	v_and_b32_e32 v133, 0xffff0000, v213
	v_lshlrev_b32_e32 v132, 16, v213
	v_pk_fma_f32 v[130:131], v[24:25], v[132:133], v[130:131]
	v_and_b32_e32 v133, 0xffff0000, v217
	v_lshlrev_b32_e32 v132, 16, v217
	v_pk_fma_f32 v[130:131], v[32:33], v[132:133], v[130:131]
	s_nop 0
	s_nop 4
	v_cvt_pk_bf16_f32 v129, v130, v131

.LBB0_985:
	ds_read_b64 v[134:135], v203 offset:23248
	ds_read_b128 v[126:129], v185 offset:38320
	ds_read_b128 v[130:133], v185 offset:63920
	s_waitcnt lgkmcnt(2)
	v_lshlrev_b32_e32 v136, 16, v134
	s_waitcnt lgkmcnt(1)
	v_fma_f32 v126, v126, s64, v46
	v_exp_f32_e32 v126, v126
	v_fma_f32 v127, v127, s64, v47
	v_exp_f32_e32 v127, v127
	v_fma_f32 v128, v128, s64, v48
	v_add_f32_e32 v126, 1.0, v126
	v_exp_f32_e32 v128, v128
	v_fma_f32 v129, v129, s64, v49
	v_rcp_f32_e32 v126, v126
	v_add_f32_e32 v127, 1.0, v127
	v_exp_f32_e32 v129, v129
	v_rcp_f32_e32 v127, v127
	v_add_f32_e32 v128, 1.0, v128
	v_mul_f32_e32 v126, v42, v126
	v_rcp_f32_e32 v128, v128
	v_add_f32_e32 v129, 1.0, v129
	v_exp_f32_e32 v126, v126
	v_mul_f32_e32 v127, v43, v127
	v_rcp_f32_e32 v129, v129
	v_exp_f32_e32 v127, v127
	v_mul_f32_e32 v128, v44, v128
	v_and_b32_e32 v137, 0xffff0000, v134
	v_fma_f32 v134, -v126, v126, 1.0
	v_exp_f32_e32 v128, v128
	v_mul_f32_e32 v129, v45, v129
	s_waitcnt lgkmcnt(0)
	v_fma_f32 v130, v130, s64, v50
	v_max_f32_e32 v134, 0, v134
	v_fma_f32 v131, v131, s64, v51
	v_fma_f32 v132, v132, s64, v52
	v_fma_f32 v133, v133, s64, v53
	v_sqrt_f32_e32 v162, v134
	v_fma_f32 v134, -v127, v127, 1.0
	v_exp_f32_e32 v129, v129
	v_exp_f32_e32 v130, v130
	v_exp_f32_e32 v131, v131
	v_exp_f32_e32 v132, v132
	v_max_f32_e32 v134, 0, v134
	v_exp_f32_e32 v133, v133
	v_sqrt_f32_e32 v163, v134
	v_fma_f32 v134, -v128, v128, 1.0
	v_max_f32_e32 v134, 0, v134
	v_sqrt_f32_e32 v164, v134
	v_fma_f32 v134, -v129, v129, 1.0
	v_add_f32_e32 v130, 1.0, v130
	v_add_f32_e32 v131, 1.0, v131
	v_add_f32_e32 v132, 1.0, v132
	v_add_f32_e32 v133, 1.0, v133
	v_max_f32_e32 v134, 0, v134
	v_rcp_f32_e32 v130, v130
	v_rcp_f32_e32 v131, v131
	v_rcp_f32_e32 v132, v132
	v_rcp_f32_e32 v133, v133
	v_sqrt_f32_e32 v165, v134
	v_lshlrev_b32_e32 v134, 16, v135
	v_and_b32_e32 v135, 0xffff0000, v135
	v_pk_mul_f32 v[130:131], v[130:131], v[162:163]
	v_pk_mul_f32 v[132:133], v[132:133], v[164:165]
	v_pk_mul_f32 v[130:131], v[130:131], v[136:137]
	v_pk_mul_f32 v[132:133], v[132:133], v[134:135]
	ds_write_b128 v185, v[126:129] offset:38320
	ds_write_b128 v185, v[130:133] offset:63920

.LBB0_990:
	ds_read_b64 v[134:135], v203 offset:11808
	ds_read_b128 v[126:129], v156 offset:25120
	ds_read_b128 v[130:133], v156 offset:50720
	s_waitcnt lgkmcnt(2)
	v_lshlrev_b32_e32 v136, 16, v134
	s_waitcnt lgkmcnt(1)
	v_fma_f32 v126, v126, s64, v46
	v_exp_f32_e32 v126, v126
	v_fma_f32 v127, v127, s64, v47
	v_exp_f32_e32 v127, v127
	v_fma_f32 v128, v128, s64, v48
	v_add_f32_e32 v126, 1.0, v126
	v_exp_f32_e32 v128, v128
	v_fma_f32 v129, v129, s64, v49
	v_rcp_f32_e32 v126, v126
	v_add_f32_e32 v127, 1.0, v127
	v_exp_f32_e32 v129, v129
	v_rcp_f32_e32 v127, v127
	v_add_f32_e32 v128, 1.0, v128
	v_mul_f32_e32 v126, v42, v126
	v_rcp_f32_e32 v128, v128
	v_add_f32_e32 v129, 1.0, v129
	v_exp_f32_e32 v126, v126
	v_mul_f32_e32 v127, v43, v127
	v_rcp_f32_e32 v129, v129
	v_exp_f32_e32 v127, v127
	v_mul_f32_e32 v128, v44, v128
	v_and_b32_e32 v137, 0xffff0000, v134
	v_fma_f32 v134, -v126, v126, 1.0
	v_exp_f32_e32 v128, v128
	v_mul_f32_e32 v129, v45, v129
	s_waitcnt lgkmcnt(0)
	v_fma_f32 v130, v130, s64, v50
	v_max_f32_e32 v134, 0, v134
	v_fma_f32 v131, v131, s64, v51
	v_fma_f32 v132, v132, s64, v52
	v_fma_f32 v133, v133, s64, v53
	v_sqrt_f32_e32 v162, v134
	v_fma_f32 v134, -v127, v127, 1.0
	v_exp_f32_e32 v129, v129
	v_exp_f32_e32 v130, v130
	v_exp_f32_e32 v131, v131
	v_exp_f32_e32 v132, v132
	v_max_f32_e32 v134, 0, v134
	v_exp_f32_e32 v133, v133
	v_sqrt_f32_e32 v163, v134
	v_fma_f32 v134, -v128, v128, 1.0
	v_max_f32_e32 v134, 0, v134
	v_sqrt_f32_e32 v164, v134
	v_fma_f32 v134, -v129, v129, 1.0
	v_add_f32_e32 v130, 1.0, v130
	v_add_f32_e32 v131, 1.0, v131
	v_add_f32_e32 v132, 1.0, v132
	v_add_f32_e32 v133, 1.0, v133
	v_max_f32_e32 v134, 0, v134
	v_rcp_f32_e32 v130, v130
	v_rcp_f32_e32 v131, v131
	v_rcp_f32_e32 v132, v132
	v_rcp_f32_e32 v133, v133
	v_sqrt_f32_e32 v165, v134
	v_lshlrev_b32_e32 v134, 16, v135
	v_and_b32_e32 v135, 0xffff0000, v135
	v_pk_mul_f32 v[130:131], v[130:131], v[162:163]
	v_pk_mul_f32 v[132:133], v[132:133], v[164:165]
	v_pk_mul_f32 v[130:131], v[130:131], v[136:137]
	v_pk_mul_f32 v[132:133], v[132:133], v[134:135]
	ds_write_b128 v156, v[126:129] offset:25120
	ds_write_b128 v156, v[130:133] offset:50720
	s_or_b64 exec, exec, s[22:23]
	v_cmp_gt_i32_e32 vcc, s50, v157
	s_and_saveexec_b64 s[22:23], vcc
	s_cbranch_execz .LBB0_981
.LBB0_991:
	ds_read_b64 v[134:135], v203 offset:14096
	ds_read_b128 v[126:129], v183 offset:25120
	ds_read_b128 v[130:133], v183 offset:50720
	s_waitcnt lgkmcnt(2)
	v_lshlrev_b32_e32 v136, 16, v134
	s_waitcnt lgkmcnt(1)
	v_fma_f32 v126, v126, s64, v46
	v_exp_f32_e32 v126, v126
	v_fma_f32 v127, v127, s64, v47
	v_exp_f32_e32 v127, v127
	v_fma_f32 v128, v128, s64, v48
	v_add_f32_e32 v126, 1.0, v126
	v_exp_f32_e32 v128, v128
	v_fma_f32 v129, v129, s64, v49
	v_rcp_f32_e32 v126, v126
	v_add_f32_e32 v127, 1.0, v127
	v_exp_f32_e32 v129, v129
	v_rcp_f32_e32 v127, v127
	v_add_f32_e32 v128, 1.0, v128
	v_mul_f32_e32 v126, v42, v126
	v_rcp_f32_e32 v128, v128
	v_add_f32_e32 v129, 1.0, v129
	v_exp_f32_e32 v126, v126
	v_mul_f32_e32 v127, v43, v127
	v_rcp_f32_e32 v129, v129
	v_exp_f32_e32 v127, v127
	v_mul_f32_e32 v128, v44, v128
	v_and_b32_e32 v137, 0xffff0000, v134
	v_fma_f32 v134, -v126, v126, 1.0
	v_exp_f32_e32 v128, v128
	v_mul_f32_e32 v129, v45, v129
	s_waitcnt lgkmcnt(0)
	v_fma_f32 v130, v130, s64, v50
	v_max_f32_e32 v134, 0, v134
	v_fma_f32 v131, v131, s64, v51
	v_fma_f32 v132, v132, s64, v52
	v_fma_f32 v133, v133, s64, v53
	v_sqrt_f32_e32 v162, v134
	v_fma_f32 v134, -v127, v127, 1.0
	v_exp_f32_e32 v129, v129
	v_exp_f32_e32 v130, v130
	v_exp_f32_e32 v131, v131
	v_exp_f32_e32 v132, v132
	v_max_f32_e32 v134, 0, v134
	v_exp_f32_e32 v133, v133
	v_sqrt_f32_e32 v163, v134
	v_fma_f32 v134, -v128, v128, 1.0
	v_max_f32_e32 v134, 0, v134
	v_sqrt_f32_e32 v164, v134
	v_fma_f32 v134, -v129, v129, 1.0
	v_add_f32_e32 v130, 1.0, v130
	v_add_f32_e32 v131, 1.0, v131
	v_add_f32_e32 v132, 1.0, v132
	v_add_f32_e32 v133, 1.0, v133
	v_max_f32_e32 v134, 0, v134
	v_rcp_f32_e32 v130, v130
	v_rcp_f32_e32 v131, v131
	v_rcp_f32_e32 v132, v132
	v_rcp_f32_e32 v133, v133
	v_sqrt_f32_e32 v165, v134
	v_lshlrev_b32_e32 v134, 16, v135
	v_and_b32_e32 v135, 0xffff0000, v135
	v_pk_mul_f32 v[130:131], v[130:131], v[162:163]
	v_pk_mul_f32 v[132:133], v[132:133], v[164:165]
	v_pk_mul_f32 v[130:131], v[130:131], v[136:137]
	v_pk_mul_f32 v[132:133], v[132:133], v[134:135]
	ds_write_b128 v183, v[126:129] offset:25120
	ds_write_b128 v183, v[130:133] offset:50720
	s_or_b64 exec, exec, s[22:23]
	v_cmp_gt_i32_e32 vcc, s50, v184
	s_and_saveexec_b64 s[22:23], vcc
	s_cbranch_execz .LBB0_982
.LBB0_992:
	ds_read_b64 v[134:135], v203 offset:16384
	ds_read_b128 v[126:129], v185 offset:25120
	ds_read_b128 v[130:133], v185 offset:50720
	s_waitcnt lgkmcnt(2)
	v_lshlrev_b32_e32 v136, 16, v134
	s_waitcnt lgkmcnt(1)
	v_fma_f32 v126, v126, s64, v46
	v_exp_f32_e32 v126, v126
	v_fma_f32 v127, v127, s64, v47
	v_exp_f32_e32 v127, v127
	v_fma_f32 v128, v128, s64, v48
	v_add_f32_e32 v126, 1.0, v126
	v_exp_f32_e32 v128, v128
	v_fma_f32 v129, v129, s64, v49
	v_rcp_f32_e32 v126, v126
	v_add_f32_e32 v127, 1.0, v127
	v_exp_f32_e32 v129, v129
	v_rcp_f32_e32 v127, v127
	v_add_f32_e32 v128, 1.0, v128
	v_mul_f32_e32 v126, v42, v126
	v_rcp_f32_e32 v128, v128
	v_add_f32_e32 v129, 1.0, v129
	v_exp_f32_e32 v126, v126
	v_mul_f32_e32 v127, v43, v127
	v_rcp_f32_e32 v129, v129
	v_exp_f32_e32 v127, v127
	v_mul_f32_e32 v128, v44, v128
	v_and_b32_e32 v137, 0xffff0000, v134
	v_fma_f32 v134, -v126, v126, 1.0
	v_exp_f32_e32 v128, v128
	v_mul_f32_e32 v129, v45, v129
	s_waitcnt lgkmcnt(0)
	v_fma_f32 v130, v130, s64, v50
	v_max_f32_e32 v134, 0, v134
	v_fma_f32 v131, v131, s64, v51
	v_fma_f32 v132, v132, s64, v52
	v_fma_f32 v133, v133, s64, v53
	v_sqrt_f32_e32 v162, v134
	v_fma_f32 v134, -v127, v127, 1.0
	v_exp_f32_e32 v129, v129
	v_exp_f32_e32 v130, v130
	v_exp_f32_e32 v131, v131
	v_exp_f32_e32 v132, v132
	v_max_f32_e32 v134, 0, v134
	v_exp_f32_e32 v133, v133
	v_sqrt_f32_e32 v163, v134
	v_fma_f32 v134, -v128, v128, 1.0
	v_max_f32_e32 v134, 0, v134
	v_sqrt_f32_e32 v164, v134
	v_fma_f32 v134, -v129, v129, 1.0
	v_add_f32_e32 v130, 1.0, v130
	v_add_f32_e32 v131, 1.0, v131
	v_add_f32_e32 v132, 1.0, v132
	v_add_f32_e32 v133, 1.0, v133
	v_max_f32_e32 v134, 0, v134
	v_rcp_f32_e32 v130, v130
	v_rcp_f32_e32 v131, v131
	v_rcp_f32_e32 v132, v132
	v_rcp_f32_e32 v133, v133
	v_sqrt_f32_e32 v165, v134
	v_lshlrev_b32_e32 v134, 16, v135
	v_and_b32_e32 v135, 0xffff0000, v135
	v_pk_mul_f32 v[130:131], v[130:131], v[162:163]
	v_pk_mul_f32 v[132:133], v[132:133], v[164:165]
	v_pk_mul_f32 v[130:131], v[130:131], v[136:137]
	v_pk_mul_f32 v[132:133], v[132:133], v[134:135]
	ds_write_b128 v185, v[126:129] offset:25120
	ds_write_b128 v185, v[130:133] offset:50720
	s_or_b64 exec, exec, s[22:23]
	v_cmp_gt_i32_e32 vcc, s50, v186
	s_and_saveexec_b64 s[22:23], vcc
	s_cbranch_execz .LBB0_983
.LBB0_993:
	ds_read_b64 v[134:135], v203 offset:18672
	ds_read_b128 v[126:129], v185 offset:29520
	ds_read_b128 v[130:133], v185 offset:55120
	s_waitcnt lgkmcnt(2)
	v_lshlrev_b32_e32 v136, 16, v134
	s_waitcnt lgkmcnt(1)
	v_fma_f32 v126, v126, s64, v46
	v_exp_f32_e32 v126, v126
	v_fma_f32 v127, v127, s64, v47
	v_exp_f32_e32 v127, v127
	v_fma_f32 v128, v128, s64, v48
	v_add_f32_e32 v126, 1.0, v126
	v_exp_f32_e32 v128, v128
	v_fma_f32 v129, v129, s64, v49
	v_rcp_f32_e32 v126, v126
	v_add_f32_e32 v127, 1.0, v127
	v_exp_f32_e32 v129, v129
	v_rcp_f32_e32 v127, v127
	v_add_f32_e32 v128, 1.0, v128
	v_mul_f32_e32 v126, v42, v126
	v_rcp_f32_e32 v128, v128
	v_add_f32_e32 v129, 1.0, v129
	v_exp_f32_e32 v126, v126
	v_mul_f32_e32 v127, v43, v127
	v_rcp_f32_e32 v129, v129
	v_exp_f32_e32 v127, v127
	v_mul_f32_e32 v128, v44, v128
	v_and_b32_e32 v137, 0xffff0000, v134
	v_fma_f32 v134, -v126, v126, 1.0
	v_exp_f32_e32 v128, v128
	v_mul_f32_e32 v129, v45, v129
	s_waitcnt lgkmcnt(0)
	v_fma_f32 v130, v130, s64, v50
	v_max_f32_e32 v134, 0, v134
	v_fma_f32 v131, v131, s64, v51
	v_fma_f32 v132, v132, s64, v52
	v_fma_f32 v133, v133, s64, v53
	v_sqrt_f32_e32 v162, v134
	v_fma_f32 v134, -v127, v127, 1.0
	v_exp_f32_e32 v129, v129
	v_exp_f32_e32 v130, v130
	v_exp_f32_e32 v131, v131
	v_exp_f32_e32 v132, v132
	v_max_f32_e32 v134, 0, v134
	v_exp_f32_e32 v133, v133
	v_sqrt_f32_e32 v163, v134
	v_fma_f32 v134, -v128, v128, 1.0
	v_max_f32_e32 v134, 0, v134
	v_sqrt_f32_e32 v164, v134
	v_fma_f32 v134, -v129, v129, 1.0
	v_add_f32_e32 v130, 1.0, v130
	v_add_f32_e32 v131, 1.0, v131
	v_add_f32_e32 v132, 1.0, v132
	v_add_f32_e32 v133, 1.0, v133
	v_max_f32_e32 v134, 0, v134
	v_rcp_f32_e32 v130, v130
	v_rcp_f32_e32 v131, v131
	v_rcp_f32_e32 v132, v132
	v_rcp_f32_e32 v133, v133
	v_sqrt_f32_e32 v165, v134
	v_lshlrev_b32_e32 v134, 16, v135
	v_and_b32_e32 v135, 0xffff0000, v135
	v_pk_mul_f32 v[130:131], v[130:131], v[162:163]
	v_pk_mul_f32 v[132:133], v[132:133], v[164:165]
	v_pk_mul_f32 v[130:131], v[130:131], v[136:137]
	v_pk_mul_f32 v[132:133], v[132:133], v[134:135]
	ds_write_b128 v185, v[126:129] offset:29520
	ds_write_b128 v185, v[130:133] offset:55120
	s_or_b64 exec, exec, s[22:23]
	v_cmp_gt_i32_e32 vcc, s50, v187
	s_and_saveexec_b64 s[22:23], vcc
	s_cbranch_execz .LBB0_984
.LBB0_994:
	ds_read_b64 v[134:135], v203 offset:20960
	ds_read_b128 v[126:129], v185 offset:33920
	ds_read_b128 v[130:133], v185 offset:59520
	s_waitcnt lgkmcnt(2)
	v_lshlrev_b32_e32 v136, 16, v134
	s_waitcnt lgkmcnt(1)
	v_fma_f32 v126, v126, s64, v46
	v_exp_f32_e32 v126, v126
	v_fma_f32 v127, v127, s64, v47
	v_exp_f32_e32 v127, v127
	v_fma_f32 v128, v128, s64, v48
	v_add_f32_e32 v126, 1.0, v126
	v_exp_f32_e32 v128, v128
	v_fma_f32 v129, v129, s64, v49
	v_rcp_f32_e32 v126, v126
	v_add_f32_e32 v127, 1.0, v127
	v_exp_f32_e32 v129, v129
	v_rcp_f32_e32 v127, v127
	v_add_f32_e32 v128, 1.0, v128
	v_mul_f32_e32 v126, v42, v126
	v_rcp_f32_e32 v128, v128
	v_add_f32_e32 v129, 1.0, v129
	v_exp_f32_e32 v126, v126
	v_mul_f32_e32 v127, v43, v127
	v_rcp_f32_e32 v129, v129
	v_exp_f32_e32 v127, v127
	v_mul_f32_e32 v128, v44, v128
	v_and_b32_e32 v137, 0xffff0000, v134
	v_fma_f32 v134, -v126, v126, 1.0
	v_exp_f32_e32 v128, v128
	v_mul_f32_e32 v129, v45, v129
	s_waitcnt lgkmcnt(0)
	v_fma_f32 v130, v130, s64, v50
	v_max_f32_e32 v134, 0, v134
	v_fma_f32 v131, v131, s64, v51
	v_fma_f32 v132, v132, s64, v52
	v_fma_f32 v133, v133, s64, v53
	v_sqrt_f32_e32 v162, v134
	v_fma_f32 v134, -v127, v127, 1.0
	v_exp_f32_e32 v129, v129
	v_exp_f32_e32 v130, v130
	v_exp_f32_e32 v131, v131
	v_exp_f32_e32 v132, v132
	v_max_f32_e32 v134, 0, v134
	v_exp_f32_e32 v133, v133
	v_sqrt_f32_e32 v163, v134
	v_fma_f32 v134, -v128, v128, 1.0
	v_max_f32_e32 v134, 0, v134
	v_sqrt_f32_e32 v164, v134
	v_fma_f32 v134, -v129, v129, 1.0
	v_add_f32_e32 v130, 1.0, v130
	v_add_f32_e32 v131, 1.0, v131
	v_add_f32_e32 v132, 1.0, v132
	v_add_f32_e32 v133, 1.0, v133
	v_max_f32_e32 v134, 0, v134
	v_rcp_f32_e32 v130, v130
	v_rcp_f32_e32 v131, v131
	v_rcp_f32_e32 v132, v132
	v_rcp_f32_e32 v133, v133
	v_sqrt_f32_e32 v165, v134
	v_lshlrev_b32_e32 v134, 16, v135
	v_and_b32_e32 v135, 0xffff0000, v135
	v_pk_mul_f32 v[130:131], v[130:131], v[162:163]
	v_pk_mul_f32 v[132:133], v[132:133], v[164:165]
	v_pk_mul_f32 v[130:131], v[130:131], v[136:137]
	v_pk_mul_f32 v[132:133], v[132:133], v[134:135]
	ds_write_b128 v185, v[126:129] offset:33920
	ds_write_b128 v185, v[130:133] offset:59520
	s_or_b64 exec, exec, s[22:23]
	v_cmp_gt_i32_e32 vcc, s50, v188
	s_and_b64 exec, exec, vcc
	s_cbranch_execnz .LBB0_985
	s_branch .LBB0_986

.LBB0_1036:
	s_or_b64 exec, exec, s[2:3]
	s_barrier
	s_waitcnt vmcnt(0)
	ds_write_b32 v24, v0
	ds_write_b32 v24, v1 offset:1040
	ds_write_b32 v24, v2 offset:2080
	ds_write_b32 v24, v3 offset:3120
	ds_write_b32 v24, v4 offset:4160
	ds_write_b32 v24, v5 offset:5200
	ds_write_b32 v24, v6 offset:6240
	ds_write_b32 v24, v7 offset:7280
	ds_write_b32 v24, v8 offset:8320
	ds_write_b32 v24, v9 offset:9360
	ds_write_b32 v24, v10 offset:10400
	ds_write_b32 v24, v11 offset:11440
	ds_write_b32 v24, v12 offset:12480
	ds_write_b32 v24, v13 offset:13520
	ds_write_b32 v24, v14 offset:14560
	ds_write_b32 v24, v15 offset:15600
	s_waitcnt lgkmcnt(0)
	s_barrier
	ds_read2_b32 v[6:7], v23 offset1:32
	ds_read2_b32 v[8:9], v23 offset0:65 offset1:97
	ds_read2_b32 v[10:11], v23 offset0:130 offset1:162
	ds_read2_b32 v[12:13], v23 offset0:195 offset1:227
	v_add_u32_e32 v30, s10, v22
	v_and_b32_e32 v30, -2, v30
	s_ashr_i32 s1, s0, 31
	v_add_u32_e32 v0, 0x400, v23
	v_ashrrev_i32_e32 v31, 31, v30
	v_lshl_add_u64 v[4:5], s[0:1], 2, v[16:17]
	ds_read2_b32 v[14:15], v0 offset0:4 offset1:36
	ds_read2_b32 v[18:19], v0 offset0:69 offset1:101
	ds_read2_b32 v[26:27], v0 offset0:134 offset1:166
	ds_read2_b32 v[28:29], v0 offset0:199 offset1:231
	v_lshlrev_b64 v[0:1], 11, v[30:31]
	v_lshl_add_u64 v[32:33], v[4:5], 0, v[0:1]
	s_waitcnt lgkmcnt(7)
	s_nop 1
	s_waitcnt lgkmcnt(4)
	s_nop 7
	v_cvt_pk_bf16_f32 v1, v10, v12
	v_cvt_pk_bf16_f32 v0, v6, v8
	s_waitcnt lgkmcnt(3)
	s_nop 1
	s_waitcnt lgkmcnt(0)
	s_nop 7
	v_cvt_pk_bf16_f32 v3, v26, v28
	v_cvt_pk_bf16_f32 v2, v14, v18
	global_store_dwordx4 v[32:33], v[0:3], off
	s_add_i32 s9, s9, s86
	s_add_i32 s4, s4, s5
	v_add_u32_e32 v0, 32, v30
	v_ashrrev_i32_e32 v1, 31, v0
	v_lshlrev_b64 v[0:1], 11, v[0:1]
	v_lshl_add_u64 v[4:5], v[4:5], 0, v[0:1]
	s_nop 9
	v_cvt_pk_bf16_f32 v1, v11, v13
	v_cvt_pk_bf16_f32 v0, v7, v9
	s_nop 9
	v_cvt_pk_bf16_f32 v3, v27, v29
	v_cvt_pk_bf16_f32 v2, v15, v19
	s_cmpk_lt_i32 s9, 0x510
	global_store_dwordx4 v[4:5], v[0:3], off
	s_cbranch_scc0 .LBB0_1069

.LBB0_1071:
	s_sub_i32 s4, 0, s3
	s_barrier
	s_waitcnt vmcnt(0)
	ds_write_b32 v26, v2
	ds_write_b32 v26, v3 offset:1040
	ds_write_b32 v26, v4 offset:2080
	ds_write_b32 v26, v5 offset:3120
	ds_write_b32 v26, v8 offset:4160
	ds_write_b32 v26, v9 offset:5200
	ds_write_b32 v26, v12 offset:6240
	ds_write_b32 v26, v13 offset:7280
	ds_write_b32 v26, v14 offset:8320
	ds_write_b32 v26, v15 offset:9360
	ds_write_b32 v26, v16 offset:10400
	ds_write_b32 v26, v17 offset:11440
	ds_write_b32 v26, v18 offset:12480
	ds_write_b32 v26, v19 offset:13520
	ds_write_b32 v26, v20 offset:14560
	ds_write_b32 v26, v21 offset:15600
	s_waitcnt lgkmcnt(0)
	s_barrier
	ds_read2_b32 v[8:9], v25 offset1:32
	ds_read2_b32 v[10:11], v25 offset0:65 offset1:97
	ds_read2_b32 v[12:13], v25 offset0:130 offset1:162
	ds_read2_b32 v[14:15], v25 offset0:195 offset1:227
	s_add_i32 s4, s4, s6
	v_add_u32_e32 v30, s4, v24
	s_ashr_i32 s3, s2, 31
	v_add_u32_e32 v2, 0x400, v25
	v_ashrrev_i32_e32 v31, 31, v30
	v_lshl_add_u64 v[6:7], s[2:3], 1, v[0:1]
	ds_read2_b32 v[16:17], v2 offset0:4 offset1:36
	ds_read2_b32 v[18:19], v2 offset0:69 offset1:101
	ds_read2_b32 v[20:21], v2 offset0:134 offset1:166
	ds_read2_b32 v[28:29], v2 offset0:199 offset1:231
	v_lshlrev_b64 v[2:3], 12, v[30:31]
	v_lshl_add_u64 v[32:33], v[6:7], 0, v[2:3]
	s_waitcnt lgkmcnt(7)
	s_nop 1
	s_waitcnt lgkmcnt(4)
	s_nop 7
	v_cvt_pk_bf16_f32 v3, v12, v14
	v_cvt_pk_bf16_f32 v2, v8, v10
	s_waitcnt lgkmcnt(3)
	s_nop 1
	s_waitcnt lgkmcnt(0)
	s_nop 7
	v_cvt_pk_bf16_f32 v5, v20, v28
	v_cvt_pk_bf16_f32 v4, v16, v18
	global_store_dwordx4 v[32:33], v[2:5], off
	s_add_i32 s10, s10, s86
	s_add_i32 s6, s6, s7
	v_add_u32_e32 v2, 32, v30
	v_ashrrev_i32_e32 v3, 31, v2
	v_lshlrev_b64 v[2:3], 12, v[2:3]
	v_lshl_add_u64 v[6:7], v[6:7], 0, v[2:3]
	s_nop 9
	v_cvt_pk_bf16_f32 v3, v13, v15
	v_cvt_pk_bf16_f32 v2, v9, v11
	s_nop 9
	v_cvt_pk_bf16_f32 v5, v21, v29
	v_cvt_pk_bf16_f32 v4, v17, v19
	s_cmpk_lt_i32 s10, 0x200
	global_store_dwordx4 v[6:7], v[2:5], off
	s_cbranch_scc0 .LBB0_1106

.LBB0_1132:
	s_or_b64 exec, exec, s[0:1]
	s_mov_b32 s64, 0xbfb8aa3b
	v_mov_b32_e32 v0, v190
	s_movk_i32 s0, 0x200
	s_waitcnt lgkmcnt(0)
	s_barrier
	s_nop 0
	v_cmp_gt_i32_e32 vcc, s0, v0
	s_and_saveexec_b64 s[0:1], vcc
	s_cbranch_execz .LBB0_1145
	v_max_i32_e32 v1, 0x100, v0
	v_sub_u32_e32 v1, v1, v0
	v_add_u32_e32 v2, 0xff, v1
	s_movk_i32 s2, 0x2ff
	v_and_b32_e32 v8, 7, v0
	v_cmp_lt_u32_e32 vcc, s2, v2
	s_mov_b64 s[4:5], -1
	v_mov_b32_e32 v1, v0
	s_and_saveexec_b64 s[2:3], vcc
	s_cbranch_execz .LBB0_1142
	v_lshrrev_b32_e32 v9, 8, v2
	v_add_u32_e32 v4, -3, v9
	v_add_u32_e32 v3, 0x300, v0
	v_add_u32_e32 v2, 0x200, v0
	v_lshrrev_b32_e32 v5, 2, v4
	v_add_u32_e32 v1, 0x100, v0
	v_add_u32_e32 v10, 1, v5
	v_cmp_lt_u32_e32 vcc, 11, v4
	v_mov_b64_e32 v[6:7], v[2:3]
	v_mov_b64_e32 v[4:5], v[0:1]
	s_and_saveexec_b64 s[4:5], vcc
	s_cbranch_execz .LBB0_1138
	v_mov_b64_e32 v[6:7], v[2:3]
	v_and_b32_e32 v11, 0x7ffffffc, v10
	v_lshlrev_b32_e32 v12, 1, v8
	s_mov_b64 s[6:7], 0
	s_movk_i32 s8, 0xd0
	v_mov_b32_e32 v13, 0
	v_mov_b64_e32 v[4:5], v[0:1]

.LBB0_1148:
	s_mul_hi_i32 s0, s78, 0x3e0f83e1
	s_lshr_b32 s1, s0, 31
	s_ashr_i32 s73, s0, 6
	s_add_i32 s73, s73, s1
	s_mul_i32 s28, s73, 0xfffffef8
	s_add_i32 s28, s28, s78
	s_lshl_b32 s0, s28, 4
	s_add_i32 s22, s0, 0x3000
	s_lshl_b32 s23, s28, 6
	s_cmpk_gt_i32 s28, 0xff
	s_cselect_b64 s[0:1], -1, 0
	s_cmpk_lt_i32 s28, 0x100
	s_cselect_b32 s81, s23, s22
	s_cselect_b32 s72, 64, 16
	s_add_i32 s33, s28, 0xffffff00
	s_add_i32 s22, s28, -1
	v_readlane_b32 s4, v254, 2
	s_cmpk_lt_u32 s22, 0xff
	s_mul_i32 s46, s73, 0x58
	v_readlane_b32 s5, v254, 3
	v_readlane_b32 s6, v254, 4
	v_readlane_b32 s7, v254, 5
	v_readlane_b32 s8, v254, 6
	v_readlane_b32 s9, v254, 7
	v_readlane_b32 s10, v254, 8
	v_readlane_b32 s11, v254, 9
	v_readlane_b32 s12, v254, 10
	v_readlane_b32 s13, v254, 11
	v_readlane_b32 s14, v254, 12
	v_readlane_b32 s15, v254, 13
	s_cselect_b64 s[66:67], -1, 0
	s_ashr_i32 s47, s46, 31
	v_readlane_b32 s16, v254, 14
	v_readlane_b32 s17, v254, 15
	v_readlane_b32 s18, v254, 16
	v_readlane_b32 s19, v254, 17
	s_mov_b64 s[4:5], s[8:9]
	s_or_b32 s83, s72, 3
	s_lshl_b64 s[22:23], s[46:47], 2
	s_mov_b64 s[6:7], s[10:11]
	s_add_u32 s54, s6, s22
	s_addc_u32 s55, s7, s23
	s_add_i32 s82, s81, -3
	s_lshl_b64 s[44:45], s[46:47], 1
	s_add_u32 s22, s94, s44
	s_mul_hi_u32 s51, s33, 3
	s_mul_i32 s50, s33, 3
	s_addc_u32 s23, s95, s45
	v_cmp_gt_i32_e32 vcc, s83, v150
	v_mov_b32_e32 v138, 0
	v_mov_b32_e32 v139, 0
	v_mov_b32_e32 v140, 0
	v_mov_b32_e32 v141, 0
	s_mov_b64 s[8:9], s[12:13]
	s_mov_b64 s[10:11], s[14:15]
	s_mov_b64 s[12:13], s[16:17]
	s_mov_b64 s[14:15], s[18:19]
	s_and_saveexec_b64 s[24:25], vcc
	s_cbranch_execz .LBB0_1155
	s_nor_b64 s[26:27], s[92:93], s[66:67]
	s_and_saveexec_b64 s[38:39], s[26:27]
	s_xor_b64 s[26:27], exec, s[38:39]
	s_cbranch_execz .LBB0_1152
	v_mov_b32_e32 v141, 0
	s_andn2_b64 vcc, exec, s[0:1]
	v_mov_b32_e32 v140, 0
	v_mov_b32_e32 v139, 0
	v_mov_b32_e32 v138, 0
	s_cbranch_vccnz .LBB0_1152
	v_lshl_add_u64 v[54:55], s[50:51], 0, v[150:151]
	v_mov_b64_e32 v[56:57], s[54:55]
	v_mad_u64_u32 v[56:57], s[38:39], v54, s48, v[56:57]
	v_mad_i32_i24 v57, v55, s48, v57
	v_lshl_add_u64 v[62:63], v[158:159], 2, v[56:57]
	global_load_dwordx4 v[54:57], v[62:63], off offset:16
	s_nop 0
	global_load_dwordx4 v[62:65], v[62:63], off
	s_waitcnt vmcnt(0)
	s_nop 5
	v_cvt_pk_bf16_f32 v138, v62, v63
	s_nop 13
	v_cvt_pk_bf16_f32 v139, v64, v65
	v_cvt_pk_bf16_f32 v141, v56, v57
	v_cvt_pk_bf16_f32 v140, v54, v55

.LBB0_1157:
	s_or_b64 exec, exec, s[24:25]
	v_cmp_gt_i32_e32 vcc, s83, v160
	v_mov_b32_e32 v143, 0
	v_mov_b32_e32 v144, 0
	v_mov_b32_e32 v145, 0
	s_and_saveexec_b64 s[24:25], vcc
	s_cbranch_execz .LBB0_1164
	s_nor_b64 s[38:39], s[30:31], s[66:67]
	s_and_saveexec_b64 s[74:75], s[38:39]
	s_xor_b64 s[74:75], exec, s[74:75]
	s_cbranch_execz .LBB0_1161
	v_mov_b32_e32 v145, 0
	s_andn2_b64 vcc, exec, s[0:1]
	v_mov_b32_e32 v144, 0
	v_mov_b32_e32 v143, 0
	v_mov_b32_e32 v142, 0
	s_cbranch_vccnz .LBB0_1161
	v_lshl_add_u64 v[54:55], s[50:51], 0, v[160:161]
	v_mov_b64_e32 v[56:57], s[54:55]
	v_mad_u64_u32 v[56:57], s[38:39], v54, s48, v[56:57]
	v_mad_i32_i24 v57, v55, s48, v57
	v_lshl_add_u64 v[62:63], v[162:163], 2, v[56:57]
	global_load_dwordx4 v[54:57], v[62:63], off offset:16
	s_nop 0
	global_load_dwordx4 v[62:65], v[62:63], off
	s_waitcnt vmcnt(0)
	s_nop 8
	v_cvt_pk_bf16_f32 v142, v62, v63
	s_nop 10
	v_cvt_pk_bf16_f32 v143, v64, v65
	v_cvt_pk_bf16_f32 v145, v56, v57
	v_cvt_pk_bf16_f32 v144, v54, v55

.LBB0_1166:
	s_or_b64 exec, exec, s[38:39]
	v_cmp_gt_i32_e32 vcc, s83, v164
	v_mov_b32_e32 v147, 0
	v_mov_b32_e32 v148, 0
	v_mov_b32_e32 v149, 0
	s_and_saveexec_b64 s[74:75], vcc
	s_cbranch_execz .LBB0_1173
	s_nor_b64 s[38:39], s[34:35], s[66:67]
	s_and_saveexec_b64 s[66:67], s[38:39]
	s_xor_b64 s[66:67], exec, s[66:67]
	s_cbranch_execz .LBB0_1170
	v_mov_b32_e32 v149, 0
	s_andn2_b64 vcc, exec, s[0:1]
	v_mov_b32_e32 v148, 0
	v_mov_b32_e32 v147, 0
	v_mov_b32_e32 v146, 0
	s_cbranch_vccnz .LBB0_1170
	v_lshl_add_u64 v[54:55], s[50:51], 0, v[164:165]
	v_mov_b64_e32 v[56:57], s[54:55]
	v_mad_u64_u32 v[56:57], s[38:39], v54, s48, v[56:57]
	v_mad_i32_i24 v57, v55, s48, v57
	v_lshl_add_u64 v[146:147], v[166:167], 2, v[56:57]
	global_load_dwordx4 v[54:57], v[146:147], off offset:16
	s_nop 0
	global_load_dwordx4 v[146:149], v[146:147], off
	s_waitcnt vmcnt(0)
	s_nop 0
	v_and_b32_sdwa v172, v146, v217 dst_sel:DWORD dst_unused:UNUSED_PAD src0_sel:WORD_1 src1_sel:DWORD
	s_nop 1
	v_add3_u32 v146, v146, v172, s49
	v_and_b32_sdwa v172, v147, v217 dst_sel:DWORD dst_unused:UNUSED_PAD src0_sel:WORD_1 src1_sel:DWORD
	s_nop 0
	v_add3_u32 v147, v147, v172, s49
	s_nop 0
	v_and_b32_e32 v171, 0xffff0000, v147
	v_cvt_pk_bf16_f32 v147, v148, v149
	s_nop 9
	v_or_b32_sdwa v146, v171, v146 dst_sel:DWORD dst_unused:UNUSED_PAD src0_sel:DWORD src1_sel:WORD_1
	v_cvt_pk_bf16_f32 v149, v56, v57
	v_cvt_pk_bf16_f32 v148, v54, v55

.LBB0_1186:
	s_or_b64 exec, exec, s[38:39]
	s_and_b64 vcc, exec, s[46:47]
	s_waitcnt lgkmcnt(0)
	s_barrier
	s_cbranch_vccz .LBB0_1193
	v_add_u32_e32 v2, 0x12ea0, v194
	v_add_u32_e32 v10, 0x13020, v194
	v_add_u32_e32 v18, 0x131a0, v194
	v_add_u32_e32 v22, 0x13320, v194
	v_add_u32_e32 v30, 0x134a0, v194
	v_add_u32_e32 v50, 0x12a20, v156
	ds_read_b128 v[14:17], v2
	ds_read_b128 v[2:5], v2 offset:16
	ds_read_b128 v[6:9], v10
	ds_read_b128 v[10:13], v10 offset:16
	ds_read_b128 v[26:29], v18
	ds_read_b128 v[18:21], v18 offset:16
	ds_read_b128 v[34:37], v22
	ds_read_b128 v[22:25], v22 offset:16
	ds_read_b128 v[38:41], v30
	ds_read_b128 v[30:33], v30 offset:16
	ds_read_b128 v[42:45], v50
	ds_read_b128 v[46:49], v50 offset:384
	ds_read_b128 v[50:53], v50 offset:768
	s_waitcnt lgkmcnt(0)
	v_mul_f32_e32 v42, 0x3fb8aa3b, v42
	v_mul_f32_e32 v43, 0x3fb8aa3b, v43
	v_mul_f32_e32 v44, 0x3fb8aa3b, v44
	v_mul_f32_e32 v45, 0x3fb8aa3b, v45
	v_mul_f32_e32 v46, 0xbfb8aa3b, v46
	v_mul_f32_e32 v47, 0xbfb8aa3b, v47
	v_mul_f32_e32 v48, 0xbfb8aa3b, v48
	v_mul_f32_e32 v49, 0xbfb8aa3b, v49
	v_mul_f32_e32 v50, 0xbfb8aa3b, v50
	v_mul_f32_e32 v51, 0xbfb8aa3b, v51
	v_mul_f32_e32 v52, 0xbfb8aa3b, v52
	v_mul_f32_e32 v53, 0xbfb8aa3b, v53
	s_waitcnt vmcnt(0) lgkmcnt(6)
	v_mov_b32_e32 v148, v34
	v_mov_b32_e32 v149, v36
	s_waitcnt lgkmcnt(4)
	v_mov_b32_e32 v144, v38
	v_mov_b32_e32 v145, v40
	v_mov_b32_e32 v178, v26
	v_mov_b32_e32 v179, v28
	v_mov_b32_e32 v188, v6
	v_mov_b32_e32 v189, v8
	v_mov_b32_e32 v182, v14
	v_mov_b32_e32 v183, v16
	v_mov_b32_e32 v146, v39
	v_mov_b32_e32 v147, v41
	v_mov_b32_e32 v176, v35
	v_mov_b32_e32 v177, v37
	v_mov_b32_e32 v180, v27
	v_mov_b32_e32 v181, v29
	v_mov_b32_e32 v184, v7
	v_mov_b32_e32 v185, v9
	v_mov_b32_e32 v186, v15
	v_mov_b32_e32 v187, v17
	s_mov_b32 s80, s73
	s_and_saveexec_b64 s[46:47], s[84:85]
	s_cbranch_execnz .LBB0_1194
	s_branch .LBB0_1202

.LBB0_1194:
	v_mov_b32_e32 v138, 0
	v_mov_b32_e32 v140, 0
	v_mov_b32_e32 v141, 0
	v_mov_b32_e32 v142, 0
	v_mov_b32_e32 v143, 0
	s_and_saveexec_b64 s[50:51], s[26:27]
	s_cbranch_execz .LBB0_1196
	v_add_u32_e32 v139, v195, v197
	ds_read_b128 v[140:143], v139
	ds_read_b128 v[226:229], v139 offset:176
	ds_read_b128 v[230:233], v139 offset:352
	ds_read_b128 v[234:237], v139 offset:528
	s_waitcnt lgkmcnt(3)
	v_lshlrev_b32_e32 v238, 16, v140
	v_and_b32_e32 v140, 0xffff0000, v140
	v_lshlrev_b32_e32 v239, 16, v141
	v_and_b32_e32 v141, 0xffff0000, v141
	s_waitcnt lgkmcnt(2)
	v_lshlrev_b32_e32 v241, 16, v227
	v_lshlrev_b32_e32 v240, 16, v226
	v_pk_fma_f32 v[140:141], v[184:185], v[140:141], v[186:187]
	v_and_b32_e32 v227, 0xffff0000, v227
	v_and_b32_e32 v226, 0xffff0000, v226
	v_pk_fma_f32 v[140:141], v[180:181], v[226:227], v[140:141]
	s_waitcnt lgkmcnt(1)
	v_and_b32_e32 v227, 0xffff0000, v231
	v_and_b32_e32 v226, 0xffff0000, v230
	v_pk_fma_f32 v[238:239], v[188:189], v[238:239], v[182:183]
	v_pk_fma_f32 v[140:141], v[176:177], v[226:227], v[140:141]
	s_waitcnt lgkmcnt(0)
	v_and_b32_e32 v227, 0xffff0000, v235
	v_and_b32_e32 v226, 0xffff0000, v234
	v_pk_fma_f32 v[238:239], v[178:179], v[240:241], v[238:239]
	v_lshlrev_b32_e32 v241, 16, v231
	v_lshlrev_b32_e32 v240, 16, v230
	v_pk_fma_f32 v[140:141], v[146:147], v[226:227], v[140:141]
	v_and_b32_e32 v227, 0xffff0000, v142
	v_lshlrev_b32_e32 v226, 16, v142
	v_pk_fma_f32 v[238:239], v[148:149], v[240:241], v[238:239]
	v_lshlrev_b32_e32 v241, 16, v235
	v_lshlrev_b32_e32 v240, 16, v234
	v_pk_fma_f32 v[226:227], v[10:11], v[226:227], v[2:3]
	v_and_b32_e32 v231, 0xffff0000, v228
	v_lshlrev_b32_e32 v230, 16, v228
	v_pk_fma_f32 v[238:239], v[144:145], v[240:241], v[238:239]
	s_nop 0
	v_pk_fma_f32 v[226:227], v[18:19], v[230:231], v[226:227]
	v_and_b32_e32 v231, 0xffff0000, v232
	v_lshlrev_b32_e32 v230, 16, v232
	s_nop 1
	v_pk_fma_f32 v[226:227], v[22:23], v[230:231], v[226:227]
	v_and_b32_e32 v231, 0xffff0000, v236
	v_lshlrev_b32_e32 v230, 16, v236
	s_nop 1
	v_pk_fma_f32 v[226:227], v[30:31], v[230:231], v[226:227]
	v_cvt_pk_bf16_f32 v141, v239, v141
	v_and_b32_sdwa v139, v227, v217 dst_sel:DWORD dst_unused:UNUSED_PAD src0_sel:WORD_1 src1_sel:DWORD
	v_and_b32_sdwa v142, v226, v217 dst_sel:DWORD dst_unused:UNUSED_PAD src0_sel:WORD_1 src1_sel:DWORD
	v_add3_u32 v139, v227, v139, s49
	v_add3_u32 v142, v226, v142, s49
	v_and_b32_e32 v227, 0xffff0000, v143
	v_lshlrev_b32_e32 v226, 16, v143
	v_pk_fma_f32 v[226:227], v[12:13], v[226:227], v[4:5]
	v_and_b32_e32 v231, 0xffff0000, v229
	v_lshlrev_b32_e32 v230, 16, v229
	v_pk_fma_f32 v[226:227], v[20:21], v[230:231], v[226:227]
	v_and_b32_e32 v229, 0xffff0000, v233
	v_lshlrev_b32_e32 v228, 16, v233
	v_pk_fma_f32 v[226:227], v[24:25], v[228:229], v[226:227]
	v_and_b32_e32 v229, 0xffff0000, v237
	v_lshlrev_b32_e32 v228, 16, v237
	v_pk_fma_f32 v[226:227], v[32:33], v[228:229], v[226:227]
	v_and_b32_sdwa v174, v140, v217 dst_sel:DWORD dst_unused:UNUSED_PAD src0_sel:WORD_1 src1_sel:DWORD
	v_lshrrev_b32_e32 v142, 16, v142
	s_nop 0
	v_and_b32_sdwa v171, v238, v217 dst_sel:DWORD dst_unused:UNUSED_PAD src0_sel:WORD_1 src1_sel:DWORD
	v_add3_u32 v140, v140, v174, s49
	v_and_or_b32 v142, v139, s76, v142
	s_nop 1
	v_add3_u32 v171, v238, v171, s49
	v_and_b32_e32 v140, 0xffff0000, v140
	s_nop 1
	v_or_b32_sdwa v140, v140, v171 dst_sel:DWORD dst_unused:UNUSED_PAD src0_sel:DWORD src1_sel:WORD_1
	v_cvt_pk_bf16_f32 v143, v226, v227
.LBB0_1196:
	s_or_b64 exec, exec, s[50:51]
	ds_write_b128 v221, v[140:143] offset:11808
	v_cmp_gt_i32_e32 vcc, s72, v198
	v_mov_b32_e32 v139, 0
	v_mov_b32_e32 v140, 0
	v_mov_b32_e32 v141, 0
	s_and_saveexec_b64 s[50:51], vcc
	s_cbranch_execz .LBB0_1198
	v_add_u32_e32 v138, v195, v199
	ds_read_b128 v[138:141], v138
	v_add_u32_e32 v142, v195, v197
	ds_read_b128 v[226:229], v142 offset:4224
	ds_read_b128 v[230:233], v142 offset:4400
	ds_read_b128 v[234:237], v142 offset:4576
	s_waitcnt lgkmcnt(2)
	v_lshlrev_b32_e32 v239, 16, v227
	v_lshlrev_b32_e32 v142, 16, v138
	v_lshlrev_b32_e32 v143, 16, v139
	v_and_b32_e32 v138, 0xffff0000, v138
	v_and_b32_e32 v139, 0xffff0000, v139
	v_pk_fma_f32 v[142:143], v[188:189], v[142:143], v[182:183]
	v_lshlrev_b32_e32 v238, 16, v226
	v_pk_fma_f32 v[142:143], v[178:179], v[238:239], v[142:143]
	s_waitcnt lgkmcnt(1)
	v_lshlrev_b32_e32 v239, 16, v231
	v_lshlrev_b32_e32 v238, 16, v230
	v_pk_fma_f32 v[138:139], v[184:185], v[138:139], v[186:187]
	v_and_b32_e32 v227, 0xffff0000, v227
	v_and_b32_e32 v226, 0xffff0000, v226
	v_pk_fma_f32 v[142:143], v[148:149], v[238:239], v[142:143]
	s_waitcnt lgkmcnt(0)
	v_lshlrev_b32_e32 v239, 16, v235
	v_lshlrev_b32_e32 v238, 16, v234
	v_pk_fma_f32 v[138:139], v[180:181], v[226:227], v[138:139]
	v_and_b32_e32 v227, 0xffff0000, v231
	v_and_b32_e32 v226, 0xffff0000, v230
	v_pk_fma_f32 v[142:143], v[144:145], v[238:239], v[142:143]
	v_pk_fma_f32 v[138:139], v[176:177], v[226:227], v[138:139]
	v_and_b32_e32 v227, 0xffff0000, v235
	v_and_b32_e32 v226, 0xffff0000, v234
	v_pk_fma_f32 v[138:139], v[146:147], v[226:227], v[138:139]
	s_nop 9
	v_cvt_pk_bf16_f32 v139, v143, v139
	v_cvt_pk_bf16_f32 v138, v142, v138
	v_and_b32_e32 v143, 0xffff0000, v140
	v_lshlrev_b32_e32 v142, 16, v140
	v_pk_fma_f32 v[142:143], v[10:11], v[142:143], v[2:3]
	v_and_b32_e32 v227, 0xffff0000, v228
	v_lshlrev_b32_e32 v226, 16, v228
	v_pk_fma_f32 v[142:143], v[18:19], v[226:227], v[142:143]
	v_and_b32_e32 v227, 0xffff0000, v232
	v_lshlrev_b32_e32 v226, 16, v232
	v_pk_fma_f32 v[142:143], v[22:23], v[226:227], v[142:143]
	v_and_b32_e32 v227, 0xffff0000, v236
	v_lshlrev_b32_e32 v226, 16, v236
	v_pk_fma_f32 v[142:143], v[30:31], v[226:227], v[142:143]
	v_and_b32_e32 v227, 0xffff0000, v229
	s_nop 4
	v_cvt_pk_bf16_f32 v140, v142, v143
	v_and_b32_e32 v143, 0xffff0000, v141
	v_lshlrev_b32_e32 v142, 16, v141
	v_pk_fma_f32 v[142:143], v[12:13], v[142:143], v[4:5]
	v_lshlrev_b32_e32 v226, 16, v229
	v_pk_fma_f32 v[142:143], v[20:21], v[226:227], v[142:143]
	v_and_b32_e32 v227, 0xffff0000, v233
	v_lshlrev_b32_e32 v226, 16, v233
	v_pk_fma_f32 v[142:143], v[24:25], v[226:227], v[142:143]
	v_and_b32_e32 v227, 0xffff0000, v237
	v_lshlrev_b32_e32 v226, 16, v237
	v_pk_fma_f32 v[142:143], v[32:33], v[226:227], v[142:143]
	s_nop 0
	s_nop 4
	v_cvt_pk_bf16_f32 v141, v142, v143
.LBB0_1198:
	s_or_b64 exec, exec, s[50:51]
	ds_write_b128 v221, v[138:141] offset:16592
	s_and_b64 exec, exec, s[60:61]
	s_cbranch_execz .LBB0_1202
	v_cmp_gt_i32_e32 vcc, s72, v200
	v_mov_b32_e32 v138, 0
	v_mov_b32_e32 v139, 0
	v_mov_b32_e32 v140, 0
	v_mov_b32_e32 v141, 0
	s_and_saveexec_b64 s[50:51], vcc
	s_cbranch_execz .LBB0_1201
	v_add_u32_e32 v138, v195, v199
	ds_read_b128 v[138:141], v138 offset:4048
	v_add_u32_e32 v142, v195, v197
	ds_read_b128 v[226:229], v142 offset:8272
	ds_read_b128 v[230:233], v142 offset:8448
	ds_read_b128 v[234:237], v142 offset:8624
	s_waitcnt lgkmcnt(3)
	v_lshlrev_b32_e32 v142, 16, v138
	v_lshlrev_b32_e32 v143, 16, v139
	v_pk_fma_f32 v[142:143], v[188:189], v[142:143], v[182:183]
	s_waitcnt lgkmcnt(2)
	v_lshlrev_b32_e32 v183, 16, v227
	v_lshlrev_b32_e32 v182, 16, v226
	v_pk_fma_f32 v[142:143], v[178:179], v[182:183], v[142:143]
	s_waitcnt lgkmcnt(1)
	v_lshlrev_b32_e32 v179, 16, v231
	v_lshlrev_b32_e32 v178, 16, v230
	v_and_b32_e32 v138, 0xffff0000, v138
	v_and_b32_e32 v139, 0xffff0000, v139
	v_pk_fma_f32 v[142:143], v[148:149], v[178:179], v[142:143]
	s_waitcnt lgkmcnt(0)
	v_lshlrev_b32_e32 v149, 16, v235
	v_lshlrev_b32_e32 v148, 16, v234
	v_pk_fma_f32 v[142:143], v[144:145], v[148:149], v[142:143]
	v_pk_fma_f32 v[138:139], v[184:185], v[138:139], v[186:187]
	v_and_b32_e32 v145, 0xffff0000, v227
	v_and_b32_e32 v144, 0xffff0000, v226
	v_pk_fma_f32 v[138:139], v[180:181], v[144:145], v[138:139]
	v_and_b32_e32 v145, 0xffff0000, v231
	v_and_b32_e32 v144, 0xffff0000, v230
	v_pk_fma_f32 v[138:139], v[176:177], v[144:145], v[138:139]
	v_and_b32_e32 v145, 0xffff0000, v235
	v_and_b32_e32 v144, 0xffff0000, v234
	v_pk_fma_f32 v[138:139], v[146:147], v[144:145], v[138:139]
	s_nop 9
	v_cvt_pk_bf16_f32 v139, v143, v139
	v_cvt_pk_bf16_f32 v138, v142, v138
	v_and_b32_e32 v143, 0xffff0000, v140
	v_lshlrev_b32_e32 v142, 16, v140
	v_pk_fma_f32 v[142:143], v[10:11], v[142:143], v[2:3]
	v_and_b32_e32 v145, 0xffff0000, v228
	v_lshlrev_b32_e32 v144, 16, v228
	v_pk_fma_f32 v[142:143], v[18:19], v[144:145], v[142:143]
	v_and_b32_e32 v145, 0xffff0000, v232
	v_lshlrev_b32_e32 v144, 16, v232
	v_pk_fma_f32 v[142:143], v[22:23], v[144:145], v[142:143]
	v_and_b32_e32 v145, 0xffff0000, v236
	v_lshlrev_b32_e32 v144, 16, v236
	v_pk_fma_f32 v[142:143], v[30:31], v[144:145], v[142:143]
	v_and_b32_e32 v145, 0xffff0000, v229
	s_nop 4
	v_cvt_pk_bf16_f32 v140, v142, v143
	v_and_b32_e32 v143, 0xffff0000, v141
	v_lshlrev_b32_e32 v142, 16, v141
	v_pk_fma_f32 v[142:143], v[12:13], v[142:143], v[4:5]
	v_lshlrev_b32_e32 v144, 16, v229
	v_pk_fma_f32 v[142:143], v[20:21], v[144:145], v[142:143]
	v_and_b32_e32 v145, 0xffff0000, v233
	v_lshlrev_b32_e32 v144, 16, v233
	v_pk_fma_f32 v[142:143], v[24:25], v[144:145], v[142:143]
	v_and_b32_e32 v145, 0xffff0000, v237
	v_lshlrev_b32_e32 v144, 16, v237
	v_pk_fma_f32 v[142:143], v[32:33], v[144:145], v[142:143]
	s_nop 0
	s_nop 4
	v_cvt_pk_bf16_f32 v141, v142, v143

.LBB0_1209:
	ds_read_b64 v[146:147], v222 offset:23248
	ds_read_b128 v[138:141], v203 offset:38320
	ds_read_b128 v[142:145], v203 offset:63920
	s_waitcnt lgkmcnt(2)
	v_lshlrev_b32_e32 v148, 16, v146
	s_waitcnt lgkmcnt(1)
	v_fma_f32 v138, v138, s64, v46
	v_exp_f32_e32 v138, v138
	v_fma_f32 v139, v139, s64, v47
	v_exp_f32_e32 v139, v139
	v_fma_f32 v140, v140, s64, v48
	v_add_f32_e32 v138, 1.0, v138
	v_exp_f32_e32 v140, v140
	v_fma_f32 v141, v141, s64, v49
	v_rcp_f32_e32 v138, v138
	v_add_f32_e32 v139, 1.0, v139
	v_exp_f32_e32 v141, v141
	v_rcp_f32_e32 v139, v139
	v_add_f32_e32 v140, 1.0, v140
	v_mul_f32_e32 v138, v42, v138
	v_rcp_f32_e32 v140, v140
	v_add_f32_e32 v141, 1.0, v141
	v_exp_f32_e32 v138, v138
	v_mul_f32_e32 v139, v43, v139
	v_rcp_f32_e32 v141, v141
	v_exp_f32_e32 v139, v139
	v_mul_f32_e32 v140, v44, v140
	v_and_b32_e32 v149, 0xffff0000, v146
	v_fma_f32 v146, -v138, v138, 1.0
	v_exp_f32_e32 v140, v140
	v_mul_f32_e32 v141, v45, v141
	s_waitcnt lgkmcnt(0)
	v_fma_f32 v142, v142, s64, v50
	v_max_f32_e32 v146, 0, v146
	v_fma_f32 v143, v143, s64, v51
	v_fma_f32 v144, v144, s64, v52
	v_fma_f32 v145, v145, s64, v53
	v_sqrt_f32_e32 v176, v146
	v_fma_f32 v146, -v139, v139, 1.0
	v_exp_f32_e32 v141, v141
	v_exp_f32_e32 v142, v142
	v_exp_f32_e32 v143, v143
	v_exp_f32_e32 v144, v144
	v_max_f32_e32 v146, 0, v146
	v_exp_f32_e32 v145, v145
	v_sqrt_f32_e32 v177, v146
	v_fma_f32 v146, -v140, v140, 1.0
	v_max_f32_e32 v146, 0, v146
	v_sqrt_f32_e32 v178, v146
	v_fma_f32 v146, -v141, v141, 1.0
	v_add_f32_e32 v142, 1.0, v142
	v_add_f32_e32 v143, 1.0, v143
	v_add_f32_e32 v144, 1.0, v144
	v_add_f32_e32 v145, 1.0, v145
	v_max_f32_e32 v146, 0, v146
	v_rcp_f32_e32 v142, v142
	v_rcp_f32_e32 v143, v143
	v_rcp_f32_e32 v144, v144
	v_rcp_f32_e32 v145, v145
	v_sqrt_f32_e32 v179, v146
	v_lshlrev_b32_e32 v146, 16, v147
	v_and_b32_e32 v147, 0xffff0000, v147
	v_pk_mul_f32 v[142:143], v[142:143], v[176:177]
	v_pk_mul_f32 v[144:145], v[144:145], v[178:179]
	v_pk_mul_f32 v[142:143], v[142:143], v[148:149]
	v_pk_mul_f32 v[144:145], v[144:145], v[146:147]
	ds_write_b128 v203, v[138:141] offset:38320
	ds_write_b128 v203, v[142:145] offset:63920

.LBB0_1222:
	v_lshlrev_b32_e32 v138, 16, v134
	v_and_b32_e32 v134, 0xffff0000, v134
	v_mul_f32_e32 v141, 0xbfb8aa3b, v134
	v_exp_f32_e32 v141, v141
	v_lshlrev_b32_e32 v139, 16, v135
	v_mul_f32_e32 v140, 0xbfb8aa3b, v138
	v_exp_f32_e32 v140, v140
	v_add_f32_e32 v141, 1.0, v141
	v_rcp_f32_e32 v146, v141
	v_mul_f32_e32 v141, 0xbfb8aa3b, v139
	v_exp_f32_e32 v141, v141
	v_add_f32_e32 v140, 1.0, v140
	v_rcp_f32_e32 v140, v140
	v_and_b32_e32 v135, 0xffff0000, v135
	v_add_f32_e32 v141, 1.0, v141
	v_rcp_f32_e32 v141, v141
	s_nop 0
	v_pk_mul_f32 v[148:149], v[140:141], v[138:139]
	ds_read_b128 v[138:141], v207 offset:50720
	ds_read_b128 v[142:145], v207 offset:50736
	s_waitcnt lgkmcnt(1)
	v_mov_b32_e32 v172, v138
	v_mul_f32_e32 v138, 0xbfb8aa3b, v135
	v_exp_f32_e32 v138, v138
	v_mov_b32_e32 v173, v140
	v_mov_b32_e32 v140, v139
	v_lshlrev_b32_e32 v139, 16, v137
	v_add_f32_e32 v138, 1.0, v138
	v_rcp_f32_e32 v147, v138
	v_lshlrev_b32_e32 v138, 16, v136
	v_and_b32_e32 v136, 0xffff0000, v136
	v_and_b32_e32 v137, 0xffff0000, v137
	v_pk_mul_f32 v[134:135], v[146:147], v[134:135]
	v_pk_mul_f32 v[148:149], v[148:149], v[172:173]
	v_pk_mul_f32 v[134:135], v[134:135], v[140:141]
	v_mul_f32_e32 v141, 0xbfb8aa3b, v136
	v_exp_f32_e32 v141, v141
	v_mul_f32_e32 v140, 0xbfb8aa3b, v138
	v_exp_f32_e32 v140, v140
	v_add_f32_e32 v141, 1.0, v141
	v_rcp_f32_e32 v146, v141
	v_mul_f32_e32 v141, 0xbfb8aa3b, v139
	v_exp_f32_e32 v141, v141
	v_add_f32_e32 v140, 1.0, v140
	v_rcp_f32_e32 v140, v140
	v_add_f32_e32 v141, 1.0, v141
	v_rcp_f32_e32 v141, v141
	s_nop 0
	v_pk_mul_f32 v[138:139], v[140:141], v[138:139]
	s_waitcnt lgkmcnt(0)
	v_mov_b32_e32 v140, v142
	v_mov_b32_e32 v141, v144
	v_pk_mul_f32 v[138:139], v[138:139], v[140:141]
	v_mul_f32_e32 v140, 0xbfb8aa3b, v137
	v_exp_f32_e32 v140, v140
	v_mov_b32_e32 v144, v143
	s_nop 1
	v_add_f32_e32 v140, 1.0, v140
	v_rcp_f32_e32 v147, v140
	s_nop 2
	v_pk_mul_f32 v[136:137], v[146:147], v[136:137]
	s_nop 0
	v_pk_mul_f32 v[136:137], v[136:137], v[144:145]
	s_nop 11
	v_cvt_pk_bf16_f32 v137, v139, v137
	v_cvt_pk_bf16_f32 v136, v138, v136
	v_mov_b64_e32 v[138:139], s[0:1]
	s_nop 1
	v_mad_i64_i32 v[138:139], s[26:27], v225, s77, v[138:139]
	v_cvt_pk_bf16_f32 v135, v149, v135
	v_cvt_pk_bf16_f32 v134, v148, v134
	v_lshl_add_u64 v[138:139], v[158:159], 1, v[138:139]
	global_store_dwordx4 v[138:139], v[134:137], off
	s_or_b64 exec, exec, s[44:45]
	s_and_saveexec_b64 s[26:27], s[24:25]
	s_cbranch_execz .LBB0_1221
.LBB0_1223:
	v_lshlrev_b32_e32 v134, 16, v62
	v_and_b32_e32 v62, 0xffff0000, v62
	v_mul_f32_e32 v137, 0xbfb8aa3b, v62
	v_exp_f32_e32 v137, v137
	v_lshlrev_b32_e32 v135, 16, v63
	v_mul_f32_e32 v136, 0xbfb8aa3b, v134
	v_exp_f32_e32 v136, v136
	v_add_f32_e32 v137, 1.0, v137
	v_rcp_f32_e32 v142, v137
	v_mul_f32_e32 v137, 0xbfb8aa3b, v135
	v_exp_f32_e32 v137, v137
	v_add_f32_e32 v136, 1.0, v136
	v_rcp_f32_e32 v136, v136
	v_and_b32_e32 v63, 0xffff0000, v63
	v_add_f32_e32 v137, 1.0, v137
	v_rcp_f32_e32 v137, v137
	s_nop 0
	v_pk_mul_f32 v[144:145], v[136:137], v[134:135]
	ds_read_b128 v[134:137], v208 offset:50720
	ds_read_b128 v[138:141], v208 offset:50736
	s_waitcnt lgkmcnt(1)
	v_mov_b32_e32 v146, v134
	v_mul_f32_e32 v134, 0xbfb8aa3b, v63
	v_exp_f32_e32 v134, v134
	v_mov_b32_e32 v147, v136
	v_mov_b32_e32 v136, v135
	v_lshlrev_b32_e32 v135, 16, v65
	v_add_f32_e32 v134, 1.0, v134
	v_rcp_f32_e32 v143, v134
	v_lshlrev_b32_e32 v134, 16, v64
	v_and_b32_e32 v64, 0xffff0000, v64
	v_and_b32_e32 v65, 0xffff0000, v65
	v_pk_mul_f32 v[62:63], v[142:143], v[62:63]
	v_pk_mul_f32 v[144:145], v[144:145], v[146:147]
	v_pk_mul_f32 v[62:63], v[62:63], v[136:137]
	v_mul_f32_e32 v137, 0xbfb8aa3b, v64
	v_exp_f32_e32 v137, v137
	v_mul_f32_e32 v136, 0xbfb8aa3b, v134
	v_exp_f32_e32 v136, v136
	v_add_f32_e32 v137, 1.0, v137
	v_rcp_f32_e32 v142, v137
	v_mul_f32_e32 v137, 0xbfb8aa3b, v135
	v_exp_f32_e32 v137, v137
	v_add_f32_e32 v136, 1.0, v136
	v_rcp_f32_e32 v136, v136
	v_add_f32_e32 v137, 1.0, v137
	v_rcp_f32_e32 v137, v137
	s_nop 0
	v_pk_mul_f32 v[134:135], v[136:137], v[134:135]
	s_waitcnt lgkmcnt(0)
	v_mov_b32_e32 v136, v138
	v_mov_b32_e32 v137, v140
	v_pk_mul_f32 v[134:135], v[134:135], v[136:137]
	v_mul_f32_e32 v136, 0xbfb8aa3b, v65
	v_exp_f32_e32 v136, v136
	v_mov_b32_e32 v140, v139
	s_nop 1
	v_add_f32_e32 v136, 1.0, v136
	v_rcp_f32_e32 v143, v136
	s_nop 2
	v_pk_mul_f32 v[64:65], v[142:143], v[64:65]
	s_nop 0
	v_pk_mul_f32 v[64:65], v[64:65], v[140:141]
	s_nop 11
	v_cvt_pk_bf16_f32 v65, v135, v65
	v_cvt_pk_bf16_f32 v64, v134, v64
	v_mov_b64_e32 v[134:135], s[0:1]
	s_nop 1
	v_mad_i64_i32 v[134:135], s[24:25], v224, s77, v[134:135]
	v_cvt_pk_bf16_f32 v63, v145, v63
	v_cvt_pk_bf16_f32 v62, v144, v62
	v_lshl_add_u64 v[134:135], v[162:163], 1, v[134:135]
	global_store_dwordx4 v[134:135], v[62:65], off
	s_or_b64 exec, exec, s[26:27]
	s_and_saveexec_b64 s[24:25], s[22:23]
	s_cbranch_execz .LBB0_1147
.LBB0_1224:
	v_lshlrev_b32_e32 v62, 16, v54
	v_and_b32_e32 v54, 0xffff0000, v54
	v_mul_f32_e32 v65, 0xbfb8aa3b, v54
	v_exp_f32_e32 v65, v65
	v_lshlrev_b32_e32 v63, 16, v55
	v_mul_f32_e32 v64, 0xbfb8aa3b, v62
	v_exp_f32_e32 v64, v64
	v_add_f32_e32 v65, 1.0, v65
	v_rcp_f32_e32 v138, v65
	v_mul_f32_e32 v65, 0xbfb8aa3b, v63
	v_exp_f32_e32 v65, v65
	v_add_f32_e32 v64, 1.0, v64
	v_rcp_f32_e32 v64, v64
	v_and_b32_e32 v55, 0xffff0000, v55
	v_add_f32_e32 v65, 1.0, v65
	v_rcp_f32_e32 v65, v65
	s_nop 0
	v_pk_mul_f32 v[140:141], v[64:65], v[62:63]
	ds_read_b128 v[62:65], v209 offset:50720
	ds_read_b128 v[134:137], v209 offset:50736
	s_waitcnt lgkmcnt(1)
	v_mov_b32_e32 v142, v62
	v_mul_f32_e32 v62, 0xbfb8aa3b, v55
	v_exp_f32_e32 v62, v62
	v_mov_b32_e32 v143, v64
	v_mov_b32_e32 v64, v63
	v_lshlrev_b32_e32 v63, 16, v57
	v_add_f32_e32 v62, 1.0, v62
	v_rcp_f32_e32 v139, v62
	v_lshlrev_b32_e32 v62, 16, v56
	v_and_b32_e32 v56, 0xffff0000, v56
	v_and_b32_e32 v57, 0xffff0000, v57
	v_pk_mul_f32 v[54:55], v[138:139], v[54:55]
	v_pk_mul_f32 v[140:141], v[140:141], v[142:143]
	v_pk_mul_f32 v[54:55], v[54:55], v[64:65]
	v_mul_f32_e32 v65, 0xbfb8aa3b, v56
	v_exp_f32_e32 v65, v65
	v_mul_f32_e32 v64, 0xbfb8aa3b, v62
	v_exp_f32_e32 v64, v64
	v_add_f32_e32 v65, 1.0, v65
	v_rcp_f32_e32 v138, v65
	v_mul_f32_e32 v65, 0xbfb8aa3b, v63
	v_exp_f32_e32 v65, v65
	v_add_f32_e32 v64, 1.0, v64
	v_rcp_f32_e32 v64, v64
	v_add_f32_e32 v65, 1.0, v65
	v_rcp_f32_e32 v65, v65
	s_nop 0
	v_pk_mul_f32 v[62:63], v[64:65], v[62:63]
	s_waitcnt lgkmcnt(0)
	v_mov_b32_e32 v64, v134
	v_mov_b32_e32 v65, v136
	v_pk_mul_f32 v[62:63], v[62:63], v[64:65]
	v_mul_f32_e32 v64, 0xbfb8aa3b, v57
	v_exp_f32_e32 v64, v64
	v_mov_b32_e32 v136, v135
	s_nop 1
	v_add_f32_e32 v64, 1.0, v64
	v_rcp_f32_e32 v139, v64
	s_nop 2
	v_pk_mul_f32 v[56:57], v[138:139], v[56:57]
	s_nop 0
	v_pk_mul_f32 v[56:57], v[56:57], v[136:137]
	s_nop 11
	v_cvt_pk_bf16_f32 v57, v63, v57
	v_cvt_pk_bf16_f32 v56, v62, v56
	v_mov_b64_e32 v[62:63], s[0:1]
	s_nop 1
	v_mad_i64_i32 v[62:63], s[0:1], v223, s77, v[62:63]
	v_cvt_pk_bf16_f32 v55, v141, v55
	v_cvt_pk_bf16_f32 v54, v140, v54
	v_lshl_add_u64 v[62:63], v[166:167], 1, v[62:63]
	global_store_dwordx4 v[62:63], v[54:57], off
	s_branch .LBB0_1147
.LBB0_1225:
	ds_read_b64 v[146:147], v222 offset:11808
	ds_read_b128 v[138:141], v168 offset:25120
	ds_read_b128 v[142:145], v168 offset:50720
	s_waitcnt lgkmcnt(2)
	v_lshlrev_b32_e32 v148, 16, v146
	s_waitcnt lgkmcnt(1)
	v_fma_f32 v138, v138, s64, v46
	v_exp_f32_e32 v138, v138
	v_fma_f32 v139, v139, s64, v47
	v_exp_f32_e32 v139, v139
	v_fma_f32 v140, v140, s64, v48
	v_add_f32_e32 v138, 1.0, v138
	v_exp_f32_e32 v140, v140
	v_fma_f32 v141, v141, s64, v49
	v_rcp_f32_e32 v138, v138
	v_add_f32_e32 v139, 1.0, v139
	v_exp_f32_e32 v141, v141
	v_rcp_f32_e32 v139, v139
	v_add_f32_e32 v140, 1.0, v140
	v_mul_f32_e32 v138, v42, v138
	v_rcp_f32_e32 v140, v140
	v_add_f32_e32 v141, 1.0, v141
	v_exp_f32_e32 v138, v138
	v_mul_f32_e32 v139, v43, v139
	v_rcp_f32_e32 v141, v141
	v_exp_f32_e32 v139, v139
	v_mul_f32_e32 v140, v44, v140
	v_and_b32_e32 v149, 0xffff0000, v146
	v_fma_f32 v146, -v138, v138, 1.0
	v_exp_f32_e32 v140, v140
	v_mul_f32_e32 v141, v45, v141
	s_waitcnt lgkmcnt(0)
	v_fma_f32 v142, v142, s64, v50
	v_max_f32_e32 v146, 0, v146
	v_fma_f32 v143, v143, s64, v51
	v_fma_f32 v144, v144, s64, v52
	v_fma_f32 v145, v145, s64, v53
	v_sqrt_f32_e32 v176, v146
	v_fma_f32 v146, -v139, v139, 1.0
	v_exp_f32_e32 v141, v141
	v_exp_f32_e32 v142, v142
	v_exp_f32_e32 v143, v143
	v_exp_f32_e32 v144, v144
	v_max_f32_e32 v146, 0, v146
	v_exp_f32_e32 v145, v145
	v_sqrt_f32_e32 v177, v146
	v_fma_f32 v146, -v140, v140, 1.0
	v_max_f32_e32 v146, 0, v146
	v_sqrt_f32_e32 v178, v146
	v_fma_f32 v146, -v141, v141, 1.0
	v_add_f32_e32 v142, 1.0, v142
	v_add_f32_e32 v143, 1.0, v143
	v_add_f32_e32 v144, 1.0, v144
	v_add_f32_e32 v145, 1.0, v145
	v_max_f32_e32 v146, 0, v146
	v_rcp_f32_e32 v142, v142
	v_rcp_f32_e32 v143, v143
	v_rcp_f32_e32 v144, v144
	v_rcp_f32_e32 v145, v145
	v_sqrt_f32_e32 v179, v146
	v_lshlrev_b32_e32 v146, 16, v147
	v_and_b32_e32 v147, 0xffff0000, v147
	v_pk_mul_f32 v[142:143], v[142:143], v[176:177]
	v_pk_mul_f32 v[144:145], v[144:145], v[178:179]
	v_pk_mul_f32 v[142:143], v[142:143], v[148:149]
	v_pk_mul_f32 v[144:145], v[144:145], v[146:147]
	ds_write_b128 v168, v[138:141] offset:25120
	ds_write_b128 v168, v[142:145] offset:50720
	s_or_b64 exec, exec, s[50:51]
	v_cmp_gt_i32_e32 vcc, s72, v169
	s_and_saveexec_b64 s[50:51], vcc
	s_cbranch_execz .LBB0_1205
.LBB0_1226:
	ds_read_b64 v[146:147], v222 offset:14096
	ds_read_b128 v[138:141], v201 offset:25120
	ds_read_b128 v[142:145], v201 offset:50720
	s_waitcnt lgkmcnt(2)
	v_lshlrev_b32_e32 v148, 16, v146
	s_waitcnt lgkmcnt(1)
	v_fma_f32 v138, v138, s64, v46
	v_exp_f32_e32 v138, v138
	v_fma_f32 v139, v139, s64, v47
	v_exp_f32_e32 v139, v139
	v_fma_f32 v140, v140, s64, v48
	v_add_f32_e32 v138, 1.0, v138
	v_exp_f32_e32 v140, v140
	v_fma_f32 v141, v141, s64, v49
	v_rcp_f32_e32 v138, v138
	v_add_f32_e32 v139, 1.0, v139
	v_exp_f32_e32 v141, v141
	v_rcp_f32_e32 v139, v139
	v_add_f32_e32 v140, 1.0, v140
	v_mul_f32_e32 v138, v42, v138
	v_rcp_f32_e32 v140, v140
	v_add_f32_e32 v141, 1.0, v141
	v_exp_f32_e32 v138, v138
	v_mul_f32_e32 v139, v43, v139
	v_rcp_f32_e32 v141, v141
	v_exp_f32_e32 v139, v139
	v_mul_f32_e32 v140, v44, v140
	v_and_b32_e32 v149, 0xffff0000, v146
	v_fma_f32 v146, -v138, v138, 1.0
	v_exp_f32_e32 v140, v140
	v_mul_f32_e32 v141, v45, v141
	s_waitcnt lgkmcnt(0)
	v_fma_f32 v142, v142, s64, v50
	v_max_f32_e32 v146, 0, v146
	v_fma_f32 v143, v143, s64, v51
	v_fma_f32 v144, v144, s64, v52
	v_fma_f32 v145, v145, s64, v53
	v_sqrt_f32_e32 v176, v146
	v_fma_f32 v146, -v139, v139, 1.0
	v_exp_f32_e32 v141, v141
	v_exp_f32_e32 v142, v142
	v_exp_f32_e32 v143, v143
	v_exp_f32_e32 v144, v144
	v_max_f32_e32 v146, 0, v146
	v_exp_f32_e32 v145, v145
	v_sqrt_f32_e32 v177, v146
	v_fma_f32 v146, -v140, v140, 1.0
	v_max_f32_e32 v146, 0, v146
	v_sqrt_f32_e32 v178, v146
	v_fma_f32 v146, -v141, v141, 1.0
	v_add_f32_e32 v142, 1.0, v142
	v_add_f32_e32 v143, 1.0, v143
	v_add_f32_e32 v144, 1.0, v144
	v_add_f32_e32 v145, 1.0, v145
	v_max_f32_e32 v146, 0, v146
	v_rcp_f32_e32 v142, v142
	v_rcp_f32_e32 v143, v143
	v_rcp_f32_e32 v144, v144
	v_rcp_f32_e32 v145, v145
	v_sqrt_f32_e32 v179, v146
	v_lshlrev_b32_e32 v146, 16, v147
	v_and_b32_e32 v147, 0xffff0000, v147
	v_pk_mul_f32 v[142:143], v[142:143], v[176:177]
	v_pk_mul_f32 v[144:145], v[144:145], v[178:179]
	v_pk_mul_f32 v[142:143], v[142:143], v[148:149]
	v_pk_mul_f32 v[144:145], v[144:145], v[146:147]
	ds_write_b128 v201, v[138:141] offset:25120
	ds_write_b128 v201, v[142:145] offset:50720
	s_or_b64 exec, exec, s[50:51]
	v_cmp_gt_i32_e32 vcc, s72, v202
	s_and_saveexec_b64 s[50:51], vcc
	s_cbranch_execz .LBB0_1206
.LBB0_1227:
	ds_read_b64 v[146:147], v222 offset:16384
	ds_read_b128 v[138:141], v203 offset:25120
	ds_read_b128 v[142:145], v203 offset:50720
	s_waitcnt lgkmcnt(2)
	v_lshlrev_b32_e32 v148, 16, v146
	s_waitcnt lgkmcnt(1)
	v_fma_f32 v138, v138, s64, v46
	v_exp_f32_e32 v138, v138
	v_fma_f32 v139, v139, s64, v47
	v_exp_f32_e32 v139, v139
	v_fma_f32 v140, v140, s64, v48
	v_add_f32_e32 v138, 1.0, v138
	v_exp_f32_e32 v140, v140
	v_fma_f32 v141, v141, s64, v49
	v_rcp_f32_e32 v138, v138
	v_add_f32_e32 v139, 1.0, v139
	v_exp_f32_e32 v141, v141
	v_rcp_f32_e32 v139, v139
	v_add_f32_e32 v140, 1.0, v140
	v_mul_f32_e32 v138, v42, v138
	v_rcp_f32_e32 v140, v140
	v_add_f32_e32 v141, 1.0, v141
	v_exp_f32_e32 v138, v138
	v_mul_f32_e32 v139, v43, v139
	v_rcp_f32_e32 v141, v141
	v_exp_f32_e32 v139, v139
	v_mul_f32_e32 v140, v44, v140
	v_and_b32_e32 v149, 0xffff0000, v146
	v_fma_f32 v146, -v138, v138, 1.0
	v_exp_f32_e32 v140, v140
	v_mul_f32_e32 v141, v45, v141
	s_waitcnt lgkmcnt(0)
	v_fma_f32 v142, v142, s64, v50
	v_max_f32_e32 v146, 0, v146
	v_fma_f32 v143, v143, s64, v51
	v_fma_f32 v144, v144, s64, v52
	v_fma_f32 v145, v145, s64, v53
	v_sqrt_f32_e32 v176, v146
	v_fma_f32 v146, -v139, v139, 1.0
	v_exp_f32_e32 v141, v141
	v_exp_f32_e32 v142, v142
	v_exp_f32_e32 v143, v143
	v_exp_f32_e32 v144, v144
	v_max_f32_e32 v146, 0, v146
	v_exp_f32_e32 v145, v145
	v_sqrt_f32_e32 v177, v146
	v_fma_f32 v146, -v140, v140, 1.0
	v_max_f32_e32 v146, 0, v146
	v_sqrt_f32_e32 v178, v146
	v_fma_f32 v146, -v141, v141, 1.0
	v_add_f32_e32 v142, 1.0, v142
	v_add_f32_e32 v143, 1.0, v143
	v_add_f32_e32 v144, 1.0, v144
	v_add_f32_e32 v145, 1.0, v145
	v_max_f32_e32 v146, 0, v146
	v_rcp_f32_e32 v142, v142
	v_rcp_f32_e32 v143, v143
	v_rcp_f32_e32 v144, v144
	v_rcp_f32_e32 v145, v145
	v_sqrt_f32_e32 v179, v146
	v_lshlrev_b32_e32 v146, 16, v147
	v_and_b32_e32 v147, 0xffff0000, v147
	v_pk_mul_f32 v[142:143], v[142:143], v[176:177]
	v_pk_mul_f32 v[144:145], v[144:145], v[178:179]
	v_pk_mul_f32 v[142:143], v[142:143], v[148:149]
	v_pk_mul_f32 v[144:145], v[144:145], v[146:147]
	ds_write_b128 v203, v[138:141] offset:25120
	ds_write_b128 v203, v[142:145] offset:50720
	s_or_b64 exec, exec, s[50:51]
	v_cmp_gt_i32_e32 vcc, s72, v204
	s_and_saveexec_b64 s[50:51], vcc
	s_cbranch_execz .LBB0_1207
.LBB0_1228:
	ds_read_b64 v[146:147], v222 offset:18672
	ds_read_b128 v[138:141], v203 offset:29520
	ds_read_b128 v[142:145], v203 offset:55120
	s_waitcnt lgkmcnt(2)
	v_lshlrev_b32_e32 v148, 16, v146
	s_waitcnt lgkmcnt(1)
	v_fma_f32 v138, v138, s64, v46
	v_exp_f32_e32 v138, v138
	v_fma_f32 v139, v139, s64, v47
	v_exp_f32_e32 v139, v139
	v_fma_f32 v140, v140, s64, v48
	v_add_f32_e32 v138, 1.0, v138
	v_exp_f32_e32 v140, v140
	v_fma_f32 v141, v141, s64, v49
	v_rcp_f32_e32 v138, v138
	v_add_f32_e32 v139, 1.0, v139
	v_exp_f32_e32 v141, v141
	v_rcp_f32_e32 v139, v139
	v_add_f32_e32 v140, 1.0, v140
	v_mul_f32_e32 v138, v42, v138
	v_rcp_f32_e32 v140, v140
	v_add_f32_e32 v141, 1.0, v141
	v_exp_f32_e32 v138, v138
	v_mul_f32_e32 v139, v43, v139
	v_rcp_f32_e32 v141, v141
	v_exp_f32_e32 v139, v139
	v_mul_f32_e32 v140, v44, v140
	v_and_b32_e32 v149, 0xffff0000, v146
	v_fma_f32 v146, -v138, v138, 1.0
	v_exp_f32_e32 v140, v140
	v_mul_f32_e32 v141, v45, v141
	s_waitcnt lgkmcnt(0)
	v_fma_f32 v142, v142, s64, v50
	v_max_f32_e32 v146, 0, v146
	v_fma_f32 v143, v143, s64, v51
	v_fma_f32 v144, v144, s64, v52
	v_fma_f32 v145, v145, s64, v53
	v_sqrt_f32_e32 v176, v146
	v_fma_f32 v146, -v139, v139, 1.0
	v_exp_f32_e32 v141, v141
	v_exp_f32_e32 v142, v142
	v_exp_f32_e32 v143, v143
	v_exp_f32_e32 v144, v144
	v_max_f32_e32 v146, 0, v146
	v_exp_f32_e32 v145, v145
	v_sqrt_f32_e32 v177, v146
	v_fma_f32 v146, -v140, v140, 1.0
	v_max_f32_e32 v146, 0, v146
	v_sqrt_f32_e32 v178, v146
	v_fma_f32 v146, -v141, v141, 1.0
	v_add_f32_e32 v142, 1.0, v142
	v_add_f32_e32 v143, 1.0, v143
	v_add_f32_e32 v144, 1.0, v144
	v_add_f32_e32 v145, 1.0, v145
	v_max_f32_e32 v146, 0, v146
	v_rcp_f32_e32 v142, v142
	v_rcp_f32_e32 v143, v143
	v_rcp_f32_e32 v144, v144
	v_rcp_f32_e32 v145, v145
	v_sqrt_f32_e32 v179, v146
	v_lshlrev_b32_e32 v146, 16, v147
	v_and_b32_e32 v147, 0xffff0000, v147
	v_pk_mul_f32 v[142:143], v[142:143], v[176:177]
	v_pk_mul_f32 v[144:145], v[144:145], v[178:179]
	v_pk_mul_f32 v[142:143], v[142:143], v[148:149]
	v_pk_mul_f32 v[144:145], v[144:145], v[146:147]
	ds_write_b128 v203, v[138:141] offset:29520
	ds_write_b128 v203, v[142:145] offset:55120
	s_or_b64 exec, exec, s[50:51]
	v_cmp_gt_i32_e32 vcc, s72, v205
	s_and_saveexec_b64 s[50:51], vcc
	s_cbranch_execz .LBB0_1208
.LBB0_1229:
	ds_read_b64 v[146:147], v222 offset:20960
	ds_read_b128 v[138:141], v203 offset:33920
	ds_read_b128 v[142:145], v203 offset:59520
	s_waitcnt lgkmcnt(2)
	v_lshlrev_b32_e32 v148, 16, v146
	s_waitcnt lgkmcnt(1)
	v_fma_f32 v138, v138, s64, v46
	v_exp_f32_e32 v138, v138
	v_fma_f32 v139, v139, s64, v47
	v_exp_f32_e32 v139, v139
	v_fma_f32 v140, v140, s64, v48
	v_add_f32_e32 v138, 1.0, v138
	v_exp_f32_e32 v140, v140
	v_fma_f32 v141, v141, s64, v49
	v_rcp_f32_e32 v138, v138
	v_add_f32_e32 v139, 1.0, v139
	v_exp_f32_e32 v141, v141
	v_rcp_f32_e32 v139, v139
	v_add_f32_e32 v140, 1.0, v140
	v_mul_f32_e32 v138, v42, v138
	v_rcp_f32_e32 v140, v140
	v_add_f32_e32 v141, 1.0, v141
	v_exp_f32_e32 v138, v138
	v_mul_f32_e32 v139, v43, v139
	v_rcp_f32_e32 v141, v141
	v_exp_f32_e32 v139, v139
	v_mul_f32_e32 v140, v44, v140
	v_and_b32_e32 v149, 0xffff0000, v146
	v_fma_f32 v146, -v138, v138, 1.0
	v_exp_f32_e32 v140, v140
	v_mul_f32_e32 v141, v45, v141
	s_waitcnt lgkmcnt(0)
	v_fma_f32 v142, v142, s64, v50
	v_max_f32_e32 v146, 0, v146
	v_fma_f32 v143, v143, s64, v51
	v_fma_f32 v144, v144, s64, v52
	v_fma_f32 v145, v145, s64, v53
	v_sqrt_f32_e32 v176, v146
	v_fma_f32 v146, -v139, v139, 1.0
	v_exp_f32_e32 v141, v141
	v_exp_f32_e32 v142, v142
	v_exp_f32_e32 v143, v143
	v_exp_f32_e32 v144, v144
	v_max_f32_e32 v146, 0, v146
	v_exp_f32_e32 v145, v145
	v_sqrt_f32_e32 v177, v146
	v_fma_f32 v146, -v140, v140, 1.0
	v_max_f32_e32 v146, 0, v146
	v_sqrt_f32_e32 v178, v146
	v_fma_f32 v146, -v141, v141, 1.0
	v_add_f32_e32 v142, 1.0, v142
	v_add_f32_e32 v143, 1.0, v143
	v_add_f32_e32 v144, 1.0, v144
	v_add_f32_e32 v145, 1.0, v145
	v_max_f32_e32 v146, 0, v146
	v_rcp_f32_e32 v142, v142
	v_rcp_f32_e32 v143, v143
	v_rcp_f32_e32 v144, v144
	v_rcp_f32_e32 v145, v145
	v_sqrt_f32_e32 v179, v146
	v_lshlrev_b32_e32 v146, 16, v147
	v_and_b32_e32 v147, 0xffff0000, v147
	v_pk_mul_f32 v[142:143], v[142:143], v[176:177]
	v_pk_mul_f32 v[144:145], v[144:145], v[178:179]
	v_pk_mul_f32 v[142:143], v[142:143], v[148:149]
	v_pk_mul_f32 v[144:145], v[144:145], v[146:147]
	ds_write_b128 v203, v[138:141] offset:33920
	ds_write_b128 v203, v[142:145] offset:59520
	s_or_b64 exec, exec, s[50:51]
	v_cmp_gt_i32_e32 vcc, s72, v206
	s_and_b64 exec, exec, vcc
	s_cbranch_execnz .LBB0_1209
	s_branch .LBB0_1210

.LBB0_1322:
	s_add_i32 s46, s45, 2
	s_mul_hi_i32 s47, s46, 0x55555556
	s_lshr_b32 s48, s47, 31
	s_add_i32 s47, s47, s48
	s_mul_i32 s47, s47, 3
	s_sub_i32 s46, s46, s47
	s_mulk_i32 s46, 0x6000
	s_mul_i32 s54, s45, 0x6000
	v_readfirstlane_b32 s55, v141
	v_lshl_add_u64 v[232:233], v[132:133], 0, s[24:25]
	v_lshl_add_u64 v[234:235], v[130:131], 0, s[24:25]
	s_add_u32 s55, s55, s46
	s_waitcnt vmcnt(6) lgkmcnt(0)
	s_barrier
	s_setprio 1
	s_mov_b32 m0, s55
	v_lshl_add_u64 v[236:237], v[232:233], 0, s[12:13]
	global_load_lds_dwordx4 v[236:237], off
	s_add_u32 m0, s55, 0x1000
	v_lshl_add_u64 v[236:237], v[232:233], 0, s[14:15]
	global_load_lds_dwordx4 v[236:237], off
	s_add_u32 m0, s55, 0x2000
	v_lshl_add_u64 v[236:237], v[232:233], 0, s[16:17]
	global_load_lds_dwordx4 v[236:237], off
	s_add_u32 m0, s55, 0x3000
	v_lshl_add_u64 v[236:237], v[232:233], 0, s[18:19]
	global_load_lds_dwordx4 v[236:237], off
	s_add_u32 m0, s55, 0x4000
	v_lshl_add_u64 v[236:237], v[234:235], 0, s[20:21]
	global_load_lds_dwordx4 v[236:237], off
	s_add_u32 m0, s55, 0x5000
	v_lshl_add_u64 v[236:237], v[234:235], 0, s[22:23]
	global_load_lds_dwordx4 v[236:237], off
	v_or_b32_e32 v128, s54, v140
	v_add3_u32 v128, v128, v138, v139
	ds_read_b128 v[176:179], v128 offset:16384
	ds_read_b128 v[180:183], v128 offset:17408
	ds_read_b128 v[184:187], v128 offset:18432
	ds_read_b128 v[192:195], v128 offset:19456
	v_add_u32_e32 v128, s54, v142
	v_add3_u32 v128, v128, v138, v139
	ds_read_b128 v[144:147], v128
	ds_read_b128 v[148:151], v128 offset:1024
	ds_read_b128 v[152:155], v128 offset:2048
	ds_read_b128 v[156:159], v128 offset:3072
	ds_read_b128 v[160:163], v128 offset:4096
	ds_read_b128 v[164:167], v128 offset:5120
	ds_read_b128 v[168:171], v128 offset:6144
	ds_read_b128 v[172:175], v128 offset:7168
	s_setprio 0
	s_waitcnt lgkmcnt(7)
	v_mfma_f32_16x16x32_bf16 v[124:127], v[144:147], v[176:179], v[124:127]
	v_mfma_f32_16x16x32_bf16 v[120:123], v[144:147], v[180:183], v[120:123]
	v_mfma_f32_16x16x32_bf16 v[116:119], v[144:147], v[184:187], v[116:119]
	v_mfma_f32_16x16x32_bf16 v[112:115], v[144:147], v[192:195], v[112:115]
	s_waitcnt lgkmcnt(6)
	v_mfma_f32_16x16x32_bf16 v[108:111], v[148:151], v[176:179], v[108:111]
	v_mfma_f32_16x16x32_bf16 v[104:107], v[148:151], v[180:183], v[104:107]
	v_mfma_f32_16x16x32_bf16 v[100:103], v[148:151], v[184:187], v[100:103]
	v_mfma_f32_16x16x32_bf16 v[96:99], v[148:151], v[192:195], v[96:99]
	s_waitcnt lgkmcnt(5)
	v_mfma_f32_16x16x32_bf16 v[92:95], v[152:155], v[176:179], v[92:95]
	v_mfma_f32_16x16x32_bf16 v[88:91], v[152:155], v[180:183], v[88:91]
	v_mfma_f32_16x16x32_bf16 v[84:87], v[152:155], v[184:187], v[84:87]
	v_mfma_f32_16x16x32_bf16 v[80:83], v[152:155], v[192:195], v[80:83]
	s_waitcnt lgkmcnt(4)
	v_mfma_f32_16x16x32_bf16 v[76:79], v[156:159], v[176:179], v[76:79]
	v_mfma_f32_16x16x32_bf16 v[72:75], v[156:159], v[180:183], v[72:75]
	v_mfma_f32_16x16x32_bf16 v[68:71], v[156:159], v[184:187], v[68:71]
	v_mfma_f32_16x16x32_bf16 v[64:67], v[156:159], v[192:195], v[64:67]
	s_waitcnt lgkmcnt(3)
	v_mfma_f32_16x16x32_bf16 v[60:63], v[160:163], v[176:179], v[60:63]
	v_mfma_f32_16x16x32_bf16 v[56:59], v[160:163], v[180:183], v[56:59]
	v_mfma_f32_16x16x32_bf16 v[52:55], v[160:163], v[184:187], v[52:55]
	v_mfma_f32_16x16x32_bf16 v[48:51], v[160:163], v[192:195], v[48:51]
	s_waitcnt lgkmcnt(2)
	v_mfma_f32_16x16x32_bf16 v[44:47], v[164:167], v[176:179], v[44:47]
	v_mfma_f32_16x16x32_bf16 v[40:43], v[164:167], v[180:183], v[40:43]
	v_mfma_f32_16x16x32_bf16 v[36:39], v[164:167], v[184:187], v[36:39]
	v_mfma_f32_16x16x32_bf16 v[32:35], v[164:167], v[192:195], v[32:35]
	s_waitcnt lgkmcnt(1)
	v_mfma_f32_16x16x32_bf16 v[28:31], v[168:171], v[176:179], v[28:31]
	v_mfma_f32_16x16x32_bf16 v[24:27], v[168:171], v[180:183], v[24:27]
	v_mfma_f32_16x16x32_bf16 v[20:23], v[168:171], v[184:187], v[20:23]
	v_mfma_f32_16x16x32_bf16 v[16:19], v[168:171], v[192:195], v[16:19]
	s_waitcnt lgkmcnt(0)
	v_mfma_f32_16x16x32_bf16 v[12:15], v[172:175], v[176:179], v[12:15]
	v_mfma_f32_16x16x32_bf16 v[8:11], v[172:175], v[180:183], v[8:11]
	v_mfma_f32_16x16x32_bf16 v[4:7], v[172:175], v[184:187], v[4:7]
	v_mfma_f32_16x16x32_bf16 v[0:3], v[172:175], v[192:195], v[0:3]
	s_add_i32 s46, s45, 1
	s_cmp_lg_u32 s45, 2
	s_cselect_b32 s45, s46, 0
	s_add_u32 s24, s24, 0x80
	s_addc_u32 s25, s25, 0
	s_cmpk_eq_i32 s24, 0xf00
	s_cbranch_scc0 .LBB0_1322
	s_waitcnt vmcnt(6) lgkmcnt(0)
	s_barrier
	v_add3_u32 v128, v142, v138, v139
	ds_read_b128 v[130:133], v128
	ds_read_b128 v[142:145], v128 offset:1024
	ds_read_b128 v[146:149], v128 offset:2048
	ds_read_b128 v[150:153], v128 offset:3072
	ds_read_b128 v[154:157], v128 offset:4096
	ds_read_b128 v[158:161], v128 offset:5120
	ds_read_b128 v[162:165], v128 offset:6144
	ds_read_b128 v[166:169], v128 offset:7168
	v_add3_u32 v182, v140, v138, v139
	ds_read_b128 v[138:141], v182 offset:16384
	ds_read_b128 v[170:173], v182 offset:17408
	ds_read_b128 v[174:177], v182 offset:18432
	ds_read_b128 v[178:181], v182 offset:19456
	s_setprio 1
	s_waitcnt lgkmcnt(0)
	v_mfma_f32_16x16x32_bf16 v[100:103], v[142:145], v[174:177], v[100:103]
	v_mfma_f32_16x16x32_bf16 v[96:99], v[142:145], v[178:181], v[96:99]
	v_mfma_f32_16x16x32_bf16 v[92:95], v[146:149], v[138:141], v[92:95]
	v_mfma_f32_16x16x32_bf16 v[88:91], v[146:149], v[170:173], v[88:91]
	v_mfma_f32_16x16x32_bf16 v[84:87], v[146:149], v[174:177], v[84:87]
	v_mfma_f32_16x16x32_bf16 v[80:83], v[146:149], v[178:181], v[80:83]
	v_mfma_f32_16x16x32_bf16 v[76:79], v[150:153], v[138:141], v[76:79]
	v_mfma_f32_16x16x32_bf16 v[72:75], v[150:153], v[170:173], v[72:75]
	v_mfma_f32_16x16x32_bf16 v[68:71], v[150:153], v[174:177], v[68:71]
	v_mfma_f32_16x16x32_bf16 v[64:67], v[150:153], v[178:181], v[64:67]
	v_mfma_f32_16x16x32_bf16 v[60:63], v[154:157], v[138:141], v[60:63]
	v_mfma_f32_16x16x32_bf16 v[56:59], v[154:157], v[170:173], v[56:59]
	v_mfma_f32_16x16x32_bf16 v[52:55], v[154:157], v[174:177], v[52:55]
	v_mfma_f32_16x16x32_bf16 v[48:51], v[154:157], v[178:181], v[48:51]
	v_mfma_f32_16x16x32_bf16 v[44:47], v[158:161], v[138:141], v[44:47]
	v_mfma_f32_16x16x32_bf16 v[40:43], v[158:161], v[170:173], v[40:43]
	v_mfma_f32_16x16x32_bf16 v[36:39], v[158:161], v[174:177], v[36:39]
	v_mfma_f32_16x16x32_bf16 v[32:35], v[158:161], v[178:181], v[32:35]
	v_mfma_f32_16x16x32_bf16 v[28:31], v[162:165], v[138:141], v[28:31]
	v_mfma_f32_16x16x32_bf16 v[24:27], v[162:165], v[170:173], v[24:27]
	v_mfma_f32_16x16x32_bf16 v[20:23], v[162:165], v[174:177], v[20:23]
	v_mfma_f32_16x16x32_bf16 v[16:19], v[162:165], v[178:181], v[16:19]
	v_mfma_f32_16x16x32_bf16 v[12:15], v[166:169], v[138:141], v[12:15]
	v_mfma_f32_16x16x32_bf16 v[8:11], v[166:169], v[170:173], v[8:11]
	v_mfma_f32_16x16x32_bf16 v[4:7], v[166:169], v[174:177], v[4:7]
	v_mfma_f32_16x16x32_bf16 v[0:3], v[166:169], v[178:181], v[0:3]
	v_mfma_f32_16x16x32_bf16 v[124:127], v[130:133], v[138:141], v[124:127]
	v_mfma_f32_16x16x32_bf16 v[120:123], v[130:133], v[170:173], v[120:123]
	v_mfma_f32_16x16x32_bf16 v[116:119], v[130:133], v[174:177], v[116:119]
	v_mfma_f32_16x16x32_bf16 v[112:115], v[130:133], v[178:181], v[112:115]
	v_mfma_f32_16x16x32_bf16 v[108:111], v[142:145], v[138:141], v[108:111]
	v_mfma_f32_16x16x32_bf16 v[104:107], v[142:145], v[170:173], v[104:107]
	s_setprio 0
	s_waitcnt vmcnt(0) lgkmcnt(0)
	s_barrier
	ds_read_b128 v[130:133], v128 offset:24576
	ds_read_b128 v[138:141], v128 offset:25600
	ds_read_b128 v[142:145], v128 offset:26624
	ds_read_b128 v[146:149], v128 offset:27648
	ds_read_b128 v[150:153], v128 offset:28672
	ds_read_b128 v[154:157], v128 offset:29696
	ds_read_b128 v[158:161], v128 offset:30720
	ds_read_b128 v[162:165], v128 offset:31744
	ds_read_b128 v[166:169], v182 offset:40960
	ds_read_b128 v[170:173], v182 offset:41984
	ds_read_b128 v[174:177], v182 offset:43008
	ds_read_b128 v[178:181], v182 offset:44032
	s_setprio 1
	s_waitcnt lgkmcnt(0)
	v_mfma_f32_16x16x32_bf16 v[72:75], v[146:149], v[170:173], v[72:75]
	v_mfma_f32_16x16x32_bf16 v[68:71], v[146:149], v[174:177], v[68:71]
	v_mfma_f32_16x16x32_bf16 v[64:67], v[146:149], v[178:181], v[64:67]
	v_mfma_f32_16x16x32_bf16 v[60:63], v[150:153], v[166:169], v[60:63]
	v_mfma_f32_16x16x32_bf16 v[56:59], v[150:153], v[170:173], v[56:59]
	v_mfma_f32_16x16x32_bf16 v[52:55], v[150:153], v[174:177], v[52:55]
	v_mfma_f32_16x16x32_bf16 v[48:51], v[150:153], v[178:181], v[48:51]
	v_mfma_f32_16x16x32_bf16 v[44:47], v[154:157], v[166:169], v[44:47]
	v_mfma_f32_16x16x32_bf16 v[40:43], v[154:157], v[170:173], v[40:43]
	v_mfma_f32_16x16x32_bf16 v[36:39], v[154:157], v[174:177], v[36:39]
	v_mfma_f32_16x16x32_bf16 v[32:35], v[154:157], v[178:181], v[32:35]
	v_mfma_f32_16x16x32_bf16 v[28:31], v[158:161], v[166:169], v[28:31]
	v_mfma_f32_16x16x32_bf16 v[24:27], v[158:161], v[170:173], v[24:27]
	v_mfma_f32_16x16x32_bf16 v[20:23], v[158:161], v[174:177], v[20:23]
	v_mfma_f32_16x16x32_bf16 v[16:19], v[158:161], v[178:181], v[16:19]
	v_mfma_f32_16x16x32_bf16 v[12:15], v[162:165], v[166:169], v[12:15]
	v_mfma_f32_16x16x32_bf16 v[8:11], v[162:165], v[170:173], v[8:11]
	v_mfma_f32_16x16x32_bf16 v[4:7], v[162:165], v[174:177], v[4:7]
	v_mfma_f32_16x16x32_bf16 v[0:3], v[162:165], v[178:181], v[0:3]
	v_mfma_f32_16x16x32_bf16 v[124:127], v[130:133], v[166:169], v[124:127]
	v_mfma_f32_16x16x32_bf16 v[120:123], v[130:133], v[170:173], v[120:123]
	v_mfma_f32_16x16x32_bf16 v[116:119], v[130:133], v[174:177], v[116:119]
	v_mfma_f32_16x16x32_bf16 v[112:115], v[130:133], v[178:181], v[112:115]
	v_mfma_f32_16x16x32_bf16 v[108:111], v[138:141], v[166:169], v[108:111]
	v_mfma_f32_16x16x32_bf16 v[104:107], v[138:141], v[170:173], v[104:107]
	v_mfma_f32_16x16x32_bf16 v[130:133], v[138:141], v[174:177], v[100:103]
	v_mfma_f32_16x16x32_bf16 v[138:141], v[138:141], v[178:181], v[96:99]
	v_mfma_f32_16x16x32_bf16 v[182:185], v[142:145], v[166:169], v[92:95]
	v_mfma_f32_16x16x32_bf16 v[186:189], v[142:145], v[170:173], v[88:91]
	v_mfma_f32_16x16x32_bf16 v[192:195], v[142:145], v[174:177], v[84:87]
	v_mfma_f32_16x16x32_bf16 v[142:145], v[142:145], v[178:181], v[80:83]
	v_mfma_f32_16x16x32_bf16 v[196:199], v[146:149], v[166:169], v[76:79]
	s_setprio 0
	s_nop 1
	v_lshrrev_b32_e32 v77, 2, v136
	v_and_b32_e32 v76, 0xffffff80, v136
	v_and_b32_e32 v101, 12, v77
	v_lshlrev_b32_e32 v77, 6, v137
	s_add_i32 s24, s35, 0xfffff800
	v_add_u32_e32 v76, s44, v76
	v_or3_b32 v84, v77, s24, v135
	v_lshlrev_b32_e32 v128, 1, v101
	v_ashrrev_i32_e32 v100, 6, v76
	v_lshl_add_u64 v[76:77], s[40:41], 0, v[128:129]
	v_mov_b32_e32 v128, v84
	v_mad_i64_i32 v[92:93], s[24:25], v100, s30, v[128:129]
	v_lshlrev_b64 v[78:79], 7, v[92:93]
	v_lshl_add_u64 v[102:103], v[76:77], 0, v[78:79]
	s_nop 9
	v_cvt_pk_bf16_f32 v79, v126, v127
	v_cvt_pk_bf16_f32 v78, v124, v125
	global_store_dwordx2 v[102:103], v[78:79], off
	v_or_b32_e32 v78, 16, v84
	v_mov_b32_e32 v79, v129
	v_mad_i64_i32 v[88:89], s[24:25], v100, s30, v[78:79]
	v_lshlrev_b64 v[80:81], 7, v[88:89]
	v_lshl_add_u64 v[96:97], v[76:77], 0, v[80:81]
	s_nop 9
	v_cvt_pk_bf16_f32 v81, v122, v123
	v_cvt_pk_bf16_f32 v80, v120, v121
	global_store_dwordx2 v[96:97], v[80:81], off
	v_or_b32_e32 v80, 32, v84
	v_mov_b32_e32 v81, v129
	v_mad_i64_i32 v[86:87], s[24:25], v100, s30, v[80:81]
	v_lshlrev_b64 v[82:83], 7, v[86:87]
	v_lshl_add_u64 v[94:95], v[76:77], 0, v[82:83]
	s_nop 9
	v_cvt_pk_bf16_f32 v83, v118, v119
	v_cvt_pk_bf16_f32 v82, v116, v117
	s_nop 1
	global_store_dwordx2 v[94:95], v[82:83], off
	v_or_b32_e32 v82, 48, v84
	v_mov_b32_e32 v83, v129
	s_nop 3
	v_mad_i64_i32 v[84:85], s[24:25], v100, s30, v[82:83]
	s_nop 1
	v_lshlrev_b64 v[90:91], 7, v[84:85]
	s_nop 1
	v_lshl_add_u64 v[90:91], v[76:77], 0, v[90:91]
	v_cvt_pk_bf16_f32 v99, v114, v115
	v_cvt_pk_bf16_f32 v98, v112, v113
	global_store_dwordx2 v[90:91], v[98:99], off
	s_nop 9
	v_cvt_pk_bf16_f32 v99, v110, v111
	v_cvt_pk_bf16_f32 v98, v108, v109
	global_store_dwordx2 v[102:103], v[98:99], off offset:32
	s_nop 9
	v_cvt_pk_bf16_f32 v99, v106, v107
	v_cvt_pk_bf16_f32 v98, v104, v105
	global_store_dwordx2 v[96:97], v[98:99], off offset:32
	s_nop 9
	v_cvt_pk_bf16_f32 v99, v132, v133
	v_cvt_pk_bf16_f32 v98, v130, v131
	global_store_dwordx2 v[94:95], v[98:99], off offset:32
	s_nop 9
	v_cvt_pk_bf16_f32 v99, v140, v141
	v_cvt_pk_bf16_f32 v98, v138, v139
	global_store_dwordx2 v[90:91], v[98:99], off offset:32
	s_nop 9
	v_cvt_pk_bf16_f32 v99, v184, v185
	v_cvt_pk_bf16_f32 v98, v182, v183
	global_store_dwordx2 v[102:103], v[98:99], off offset:64
	s_nop 9
	v_cvt_pk_bf16_f32 v99, v188, v189
	v_cvt_pk_bf16_f32 v98, v186, v187
	global_store_dwordx2 v[96:97], v[98:99], off offset:64
	s_nop 9
	v_cvt_pk_bf16_f32 v99, v194, v195
	v_cvt_pk_bf16_f32 v98, v192, v193
	global_store_dwordx2 v[94:95], v[98:99], off offset:64
	s_nop 9
	v_cvt_pk_bf16_f32 v99, v144, v145
	v_cvt_pk_bf16_f32 v98, v142, v143
	global_store_dwordx2 v[90:91], v[98:99], off offset:64
	s_nop 0
	v_cmp_eq_u32_e32 vcc, 12, v101
	s_nop 8
	v_cvt_pk_bf16_f32 v99, v198, v199
	v_cvt_pk_bf16_f32 v98, v196, v197
	global_store_dwordx2 v[102:103], v[98:99], off offset:96
	s_and_saveexec_b64 s[24:25], vcc
	s_cbranch_execz .LBB0_1325
	v_lshl_add_u64 v[92:93], v[92:93], 3, s[42:43]
	global_store_dwordx2 v[92:93], v[98:99], off
.LBB0_1325:
	s_or_b64 exec, exec, s[24:25]
	s_nop 0
	v_and_b32_sdwa v93, v72, v134 dst_sel:DWORD dst_unused:UNUSED_PAD src0_sel:WORD_1 src1_sel:DWORD
	v_add3_u32 v72, v72, v93, s31
	s_nop 1
	v_and_b32_sdwa v93, v73, v134 dst_sel:DWORD dst_unused:UNUSED_PAD src0_sel:WORD_1 src1_sel:DWORD
	s_nop 0
	v_add3_u32 v73, v73, v93, s31
	s_nop 0
	v_and_b32_e32 v92, 0xffff0000, v73
	v_cvt_pk_bf16_f32 v73, v74, v75
	v_or_b32_sdwa v72, v92, v72 dst_sel:DWORD dst_unused:UNUSED_PAD src0_sel:DWORD src1_sel:WORD_1
	global_store_dwordx2 v[96:97], v[72:73], off offset:96
	s_and_saveexec_b64 s[24:25], vcc
	s_cbranch_execz .LBB0_1327
	v_lshl_add_u64 v[74:75], v[88:89], 3, s[42:43]
	global_store_dwordx2 v[74:75], v[72:73], off
.LBB0_1327:
	s_or_b64 exec, exec, s[24:25]
	s_nop 0
	v_and_b32_sdwa v73, v68, v134 dst_sel:DWORD dst_unused:UNUSED_PAD src0_sel:WORD_1 src1_sel:DWORD
	v_add3_u32 v68, v68, v73, s31
	s_nop 1
	v_and_b32_sdwa v73, v69, v134 dst_sel:DWORD dst_unused:UNUSED_PAD src0_sel:WORD_1 src1_sel:DWORD
	s_nop 0
	v_add3_u32 v69, v69, v73, s31
	s_nop 0
	v_and_b32_e32 v72, 0xffff0000, v69
	v_cvt_pk_bf16_f32 v69, v70, v71
	v_or_b32_sdwa v68, v72, v68 dst_sel:DWORD dst_unused:UNUSED_PAD src0_sel:DWORD src1_sel:WORD_1
	global_store_dwordx2 v[94:95], v[68:69], off offset:96
	s_and_saveexec_b64 s[24:25], vcc
	s_cbranch_execz .LBB0_1329
	v_lshl_add_u64 v[70:71], v[86:87], 3, s[42:43]
	global_store_dwordx2 v[70:71], v[68:69], off
.LBB0_1329:
	s_or_b64 exec, exec, s[24:25]
	s_nop 0
	v_and_b32_sdwa v69, v64, v134 dst_sel:DWORD dst_unused:UNUSED_PAD src0_sel:WORD_1 src1_sel:DWORD
	v_add3_u32 v64, v64, v69, s31
	s_nop 1
	v_and_b32_sdwa v69, v65, v134 dst_sel:DWORD dst_unused:UNUSED_PAD src0_sel:WORD_1 src1_sel:DWORD
	s_nop 0
	v_add3_u32 v65, v65, v69, s31
	s_nop 0
	v_and_b32_e32 v68, 0xffff0000, v65
	v_cvt_pk_bf16_f32 v65, v66, v67
	v_or_b32_sdwa v64, v68, v64 dst_sel:DWORD dst_unused:UNUSED_PAD src0_sel:DWORD src1_sel:WORD_1
	global_store_dwordx2 v[90:91], v[64:65], off offset:96
	s_and_saveexec_b64 s[24:25], vcc
	s_cbranch_execz .LBB0_1331
	v_lshl_add_u64 v[66:67], v[84:85], 3, s[42:43]
	global_store_dwordx2 v[66:67], v[64:65], off
.LBB0_1331:
	s_or_b64 exec, exec, s[24:25]
	s_nop 3
	v_or_b32_e32 v68, 1, v100
	s_nop 2
	v_mad_i64_i32 v[64:65], s[24:25], v68, s30, v[128:129]
	s_nop 2
	v_lshlrev_b64 v[66:67], 7, v[64:65]
	s_nop 0
	v_cvt_pk_bf16_f32 v60, v60, v61
	s_nop 2
	v_lshl_add_u64 v[66:67], v[76:77], 0, v[66:67]
	v_cvt_pk_bf16_f32 v61, v62, v63
	s_nop 2
	global_store_dwordx2 v[66:67], v[60:61], off
	v_mad_i64_i32 v[60:61], s[24:25], v68, s30, v[78:79]
	s_nop 1
	v_lshlrev_b64 v[62:63], 7, v[60:61]
	s_nop 0
	v_cvt_pk_bf16_f32 v56, v56, v57
	s_nop 0
	v_and_b32_sdwa v70, v52, v134 dst_sel:DWORD dst_unused:UNUSED_PAD src0_sel:WORD_1 src1_sel:DWORD
	v_lshl_add_u64 v[62:63], v[76:77], 0, v[62:63]
	v_cvt_pk_bf16_f32 v57, v58, v59
	v_add3_u32 v52, v52, v70, s31
	s_nop 1
	v_and_b32_sdwa v70, v53, v134 dst_sel:DWORD dst_unused:UNUSED_PAD src0_sel:WORD_1 src1_sel:DWORD
	global_store_dwordx2 v[62:63], v[56:57], off
	v_mad_i64_i32 v[56:57], s[24:25], v68, s30, v[80:81]
	s_nop 0
	v_add3_u32 v53, v53, v70, s31
	v_lshlrev_b64 v[58:59], 7, v[56:57]
	s_nop 0
	v_and_b32_e32 v69, 0xffff0000, v53
	v_lshl_add_u64 v[58:59], v[76:77], 0, v[58:59]
	v_cvt_pk_bf16_f32 v53, v54, v55
	v_or_b32_sdwa v52, v69, v52 dst_sel:DWORD dst_unused:UNUSED_PAD src0_sel:DWORD src1_sel:WORD_1
	global_store_dwordx2 v[58:59], v[52:53], off
	v_mad_i64_i32 v[52:53], s[24:25], v68, s30, v[82:83]
	s_nop 0
	v_and_b32_sdwa v69, v48, v134 dst_sel:DWORD dst_unused:UNUSED_PAD src0_sel:WORD_1 src1_sel:DWORD
	v_add3_u32 v48, v48, v69, s31
	s_nop 1
	v_and_b32_sdwa v69, v49, v134 dst_sel:DWORD dst_unused:UNUSED_PAD src0_sel:WORD_1 src1_sel:DWORD
	s_nop 0
	v_add3_u32 v49, v49, v69, s31
	v_lshlrev_b64 v[54:55], 7, v[52:53]
	s_nop 0
	v_and_b32_e32 v68, 0xffff0000, v49
	v_lshl_add_u64 v[54:55], v[76:77], 0, v[54:55]
	v_cvt_pk_bf16_f32 v49, v50, v51
	v_or_b32_sdwa v48, v68, v48 dst_sel:DWORD dst_unused:UNUSED_PAD src0_sel:DWORD src1_sel:WORD_1
	global_store_dwordx2 v[54:55], v[48:49], off
	s_nop 0
	v_and_b32_sdwa v49, v44, v134 dst_sel:DWORD dst_unused:UNUSED_PAD src0_sel:WORD_1 src1_sel:DWORD
	v_add3_u32 v44, v44, v49, s31
	s_nop 1
	v_and_b32_sdwa v49, v45, v134 dst_sel:DWORD dst_unused:UNUSED_PAD src0_sel:WORD_1 src1_sel:DWORD
	s_nop 0
	v_add3_u32 v45, v45, v49, s31
	s_nop 0
	v_and_b32_e32 v48, 0xffff0000, v45
	v_cvt_pk_bf16_f32 v45, v46, v47
	v_or_b32_sdwa v44, v48, v44 dst_sel:DWORD dst_unused:UNUSED_PAD src0_sel:DWORD src1_sel:WORD_1
	global_store_dwordx2 v[66:67], v[44:45], off offset:32
	s_nop 0
	v_and_b32_sdwa v45, v40, v134 dst_sel:DWORD dst_unused:UNUSED_PAD src0_sel:WORD_1 src1_sel:DWORD
	v_add3_u32 v40, v40, v45, s31
	s_nop 1
	v_and_b32_sdwa v45, v41, v134 dst_sel:DWORD dst_unused:UNUSED_PAD src0_sel:WORD_1 src1_sel:DWORD
	s_nop 0
	v_add3_u32 v41, v41, v45, s31
	s_nop 0
	v_and_b32_e32 v44, 0xffff0000, v41
	v_cvt_pk_bf16_f32 v41, v42, v43
	v_or_b32_sdwa v40, v44, v40 dst_sel:DWORD dst_unused:UNUSED_PAD src0_sel:DWORD src1_sel:WORD_1
	global_store_dwordx2 v[62:63], v[40:41], off offset:32
	s_nop 0
	v_and_b32_sdwa v41, v36, v134 dst_sel:DWORD dst_unused:UNUSED_PAD src0_sel:WORD_1 src1_sel:DWORD
	v_add3_u32 v36, v36, v41, s31
	s_nop 1
	v_and_b32_sdwa v41, v37, v134 dst_sel:DWORD dst_unused:UNUSED_PAD src0_sel:WORD_1 src1_sel:DWORD
	s_nop 0
	v_add3_u32 v37, v37, v41, s31
	s_nop 0
	v_and_b32_e32 v40, 0xffff0000, v37
	v_cvt_pk_bf16_f32 v37, v38, v39
	v_or_b32_sdwa v36, v40, v36 dst_sel:DWORD dst_unused:UNUSED_PAD src0_sel:DWORD src1_sel:WORD_1
	global_store_dwordx2 v[58:59], v[36:37], off offset:32
	s_nop 0
	v_and_b32_sdwa v37, v32, v134 dst_sel:DWORD dst_unused:UNUSED_PAD src0_sel:WORD_1 src1_sel:DWORD
	v_add3_u32 v32, v32, v37, s31
	s_nop 1
	v_and_b32_sdwa v37, v33, v134 dst_sel:DWORD dst_unused:UNUSED_PAD src0_sel:WORD_1 src1_sel:DWORD
	s_nop 0
	v_add3_u32 v33, v33, v37, s31
	s_nop 0
	v_and_b32_e32 v36, 0xffff0000, v33
	v_cvt_pk_bf16_f32 v33, v34, v35
	v_or_b32_sdwa v32, v36, v32 dst_sel:DWORD dst_unused:UNUSED_PAD src0_sel:DWORD src1_sel:WORD_1
	global_store_dwordx2 v[54:55], v[32:33], off offset:32
	s_nop 0
	v_and_b32_sdwa v33, v28, v134 dst_sel:DWORD dst_unused:UNUSED_PAD src0_sel:WORD_1 src1_sel:DWORD
	v_add3_u32 v28, v28, v33, s31
	s_nop 1
	v_and_b32_sdwa v33, v29, v134 dst_sel:DWORD dst_unused:UNUSED_PAD src0_sel:WORD_1 src1_sel:DWORD
	s_nop 0
	v_add3_u32 v29, v29, v33, s31
	s_nop 0
	v_and_b32_e32 v32, 0xffff0000, v29
	v_cvt_pk_bf16_f32 v29, v30, v31
	v_or_b32_sdwa v28, v32, v28 dst_sel:DWORD dst_unused:UNUSED_PAD src0_sel:DWORD src1_sel:WORD_1
	global_store_dwordx2 v[66:67], v[28:29], off offset:64
	s_nop 0
	v_and_b32_sdwa v29, v24, v134 dst_sel:DWORD dst_unused:UNUSED_PAD src0_sel:WORD_1 src1_sel:DWORD
	v_add3_u32 v24, v24, v29, s31
	s_nop 1
	v_and_b32_sdwa v29, v25, v134 dst_sel:DWORD dst_unused:UNUSED_PAD src0_sel:WORD_1 src1_sel:DWORD
	s_nop 0
	v_add3_u32 v25, v25, v29, s31
	s_nop 0
	v_and_b32_e32 v28, 0xffff0000, v25
	v_cvt_pk_bf16_f32 v25, v26, v27
	v_or_b32_sdwa v24, v28, v24 dst_sel:DWORD dst_unused:UNUSED_PAD src0_sel:DWORD src1_sel:WORD_1
	global_store_dwordx2 v[62:63], v[24:25], off offset:64
	s_nop 0
	v_and_b32_sdwa v25, v20, v134 dst_sel:DWORD dst_unused:UNUSED_PAD src0_sel:WORD_1 src1_sel:DWORD
	v_add3_u32 v20, v20, v25, s31
	s_nop 1
	v_and_b32_sdwa v25, v21, v134 dst_sel:DWORD dst_unused:UNUSED_PAD src0_sel:WORD_1 src1_sel:DWORD
	s_nop 0
	v_add3_u32 v21, v21, v25, s31
	s_nop 0
	v_and_b32_e32 v24, 0xffff0000, v21
	v_cvt_pk_bf16_f32 v21, v22, v23
	v_or_b32_sdwa v20, v24, v20 dst_sel:DWORD dst_unused:UNUSED_PAD src0_sel:DWORD src1_sel:WORD_1
	global_store_dwordx2 v[58:59], v[20:21], off offset:64
	s_nop 0
	v_and_b32_sdwa v21, v16, v134 dst_sel:DWORD dst_unused:UNUSED_PAD src0_sel:WORD_1 src1_sel:DWORD
	v_add3_u32 v16, v16, v21, s31
	s_nop 1
	v_and_b32_sdwa v21, v17, v134 dst_sel:DWORD dst_unused:UNUSED_PAD src0_sel:WORD_1 src1_sel:DWORD
	s_nop 0
	v_add3_u32 v17, v17, v21, s31
	s_nop 0
	v_and_b32_e32 v20, 0xffff0000, v17
	v_cvt_pk_bf16_f32 v17, v18, v19
	v_or_b32_sdwa v16, v20, v16 dst_sel:DWORD dst_unused:UNUSED_PAD src0_sel:DWORD src1_sel:WORD_1
	global_store_dwordx2 v[54:55], v[16:17], off offset:64
	v_and_b32_sdwa v16, v14, v134 dst_sel:DWORD dst_unused:UNUSED_PAD src0_sel:WORD_1 src1_sel:DWORD
	v_and_b32_sdwa v17, v12, v134 dst_sel:DWORD dst_unused:UNUSED_PAD src0_sel:WORD_1 src1_sel:DWORD
	v_add3_u32 v12, v12, v17, s31
	v_add3_u32 v14, v14, v16, s31
	v_and_b32_sdwa v16, v15, v134 dst_sel:DWORD dst_unused:UNUSED_PAD src0_sel:WORD_1 src1_sel:DWORD
	v_and_b32_sdwa v17, v13, v134 dst_sel:DWORD dst_unused:UNUSED_PAD src0_sel:WORD_1 src1_sel:DWORD
	v_add3_u32 v15, v15, v16, s31
	v_add3_u32 v13, v13, v17, s31
	v_and_b32_e32 v15, 0xffff0000, v15
	v_and_b32_e32 v16, 0xffff0000, v13
	v_or_b32_sdwa v13, v15, v14 dst_sel:DWORD dst_unused:UNUSED_PAD src0_sel:DWORD src1_sel:WORD_1
	v_or_b32_sdwa v12, v16, v12 dst_sel:DWORD dst_unused:UNUSED_PAD src0_sel:DWORD src1_sel:WORD_1
	global_store_dwordx2 v[66:67], v[12:13], off offset:96
	s_and_saveexec_b64 s[24:25], vcc
	s_cbranch_execz .LBB0_1333
	v_lshl_add_u64 v[14:15], v[64:65], 3, s[42:43]
	global_store_dwordx2 v[14:15], v[12:13], off

.LBB0_1342:
	s_add_i32 s37, s36, 2
	s_mul_hi_i32 s38, s37, 0x55555556
	s_lshr_b32 s44, s38, 31
	s_add_i32 s38, s38, s44
	s_mul_i32 s38, s38, 3
	s_sub_i32 s37, s37, s38
	s_mulk_i32 s37, 0x6000
	s_mul_i32 s54, s36, 0x6000
	v_readfirstlane_b32 s55, v141
	v_lshl_add_u64 v[232:233], v[132:133], 0, s[24:25]
	v_lshl_add_u64 v[234:235], v[130:131], 0, s[24:25]
	s_add_u32 s55, s55, s37
	s_waitcnt vmcnt(6) lgkmcnt(0)
	s_barrier
	s_setprio 1
	s_mov_b32 m0, s55
	v_lshl_add_u64 v[236:237], v[232:233], 0, s[12:13]
	global_load_lds_dwordx4 v[236:237], off
	s_add_u32 m0, s55, 0x1000
	v_lshl_add_u64 v[236:237], v[232:233], 0, s[14:15]
	global_load_lds_dwordx4 v[236:237], off
	s_add_u32 m0, s55, 0x2000
	v_lshl_add_u64 v[236:237], v[232:233], 0, s[16:17]
	global_load_lds_dwordx4 v[236:237], off
	s_add_u32 m0, s55, 0x3000
	v_lshl_add_u64 v[236:237], v[232:233], 0, s[18:19]
	global_load_lds_dwordx4 v[236:237], off
	s_add_u32 m0, s55, 0x4000
	v_lshl_add_u64 v[236:237], v[234:235], 0, s[20:21]
	global_load_lds_dwordx4 v[236:237], off
	s_add_u32 m0, s55, 0x5000
	v_lshl_add_u64 v[236:237], v[234:235], 0, s[22:23]
	global_load_lds_dwordx4 v[236:237], off
	v_or_b32_e32 v128, s54, v139
	v_add3_u32 v128, v128, v140, v138
	ds_read_b128 v[176:179], v128 offset:16384
	ds_read_b128 v[180:183], v128 offset:16640
	ds_read_b128 v[184:187], v128 offset:18432
	ds_read_b128 v[192:195], v128 offset:18688
	v_add3_u32 v128, s54, v142, v138
	ds_read_b128 v[144:147], v128
	ds_read_b128 v[148:151], v128 offset:1024
	ds_read_b128 v[152:155], v128 offset:2048
	ds_read_b128 v[156:159], v128 offset:3072
	ds_read_b128 v[160:163], v128 offset:4096
	ds_read_b128 v[164:167], v128 offset:5120
	ds_read_b128 v[168:171], v128 offset:6144
	ds_read_b128 v[172:175], v128 offset:7168
	s_setprio 0
	s_waitcnt lgkmcnt(7)
	v_mfma_f32_16x16x32_bf16 v[124:127], v[176:179], v[144:147], v[124:127]
	v_mfma_f32_16x16x32_bf16 v[120:123], v[180:183], v[144:147], v[120:123]
	v_mfma_f32_16x16x32_bf16 v[116:119], v[184:187], v[144:147], v[116:119]
	v_mfma_f32_16x16x32_bf16 v[112:115], v[192:195], v[144:147], v[112:115]
	s_waitcnt lgkmcnt(6)
	v_mfma_f32_16x16x32_bf16 v[108:111], v[176:179], v[148:151], v[108:111]
	v_mfma_f32_16x16x32_bf16 v[104:107], v[180:183], v[148:151], v[104:107]
	v_mfma_f32_16x16x32_bf16 v[100:103], v[184:187], v[148:151], v[100:103]
	v_mfma_f32_16x16x32_bf16 v[96:99], v[192:195], v[148:151], v[96:99]
	s_waitcnt lgkmcnt(5)
	v_mfma_f32_16x16x32_bf16 v[92:95], v[176:179], v[152:155], v[92:95]
	v_mfma_f32_16x16x32_bf16 v[88:91], v[180:183], v[152:155], v[88:91]
	v_mfma_f32_16x16x32_bf16 v[84:87], v[184:187], v[152:155], v[84:87]
	v_mfma_f32_16x16x32_bf16 v[80:83], v[192:195], v[152:155], v[80:83]
	s_waitcnt lgkmcnt(4)
	v_mfma_f32_16x16x32_bf16 v[76:79], v[176:179], v[156:159], v[76:79]
	v_mfma_f32_16x16x32_bf16 v[72:75], v[180:183], v[156:159], v[72:75]
	v_mfma_f32_16x16x32_bf16 v[68:71], v[184:187], v[156:159], v[68:71]
	v_mfma_f32_16x16x32_bf16 v[64:67], v[192:195], v[156:159], v[64:67]
	s_waitcnt lgkmcnt(3)
	v_mfma_f32_16x16x32_bf16 v[60:63], v[176:179], v[160:163], v[60:63]
	v_mfma_f32_16x16x32_bf16 v[56:59], v[180:183], v[160:163], v[56:59]
	v_mfma_f32_16x16x32_bf16 v[52:55], v[184:187], v[160:163], v[52:55]
	v_mfma_f32_16x16x32_bf16 v[48:51], v[192:195], v[160:163], v[48:51]
	s_waitcnt lgkmcnt(2)
	v_mfma_f32_16x16x32_bf16 v[44:47], v[176:179], v[164:167], v[44:47]
	v_mfma_f32_16x16x32_bf16 v[40:43], v[180:183], v[164:167], v[40:43]
	v_mfma_f32_16x16x32_bf16 v[36:39], v[184:187], v[164:167], v[36:39]
	v_mfma_f32_16x16x32_bf16 v[32:35], v[192:195], v[164:167], v[32:35]
	s_waitcnt lgkmcnt(1)
	v_mfma_f32_16x16x32_bf16 v[28:31], v[176:179], v[168:171], v[28:31]
	v_mfma_f32_16x16x32_bf16 v[24:27], v[180:183], v[168:171], v[24:27]
	v_mfma_f32_16x16x32_bf16 v[20:23], v[184:187], v[168:171], v[20:23]
	v_mfma_f32_16x16x32_bf16 v[16:19], v[192:195], v[168:171], v[16:19]
	s_waitcnt lgkmcnt(0)
	v_mfma_f32_16x16x32_bf16 v[12:15], v[176:179], v[172:175], v[12:15]
	v_mfma_f32_16x16x32_bf16 v[8:11], v[180:183], v[172:175], v[8:11]
	v_mfma_f32_16x16x32_bf16 v[4:7], v[184:187], v[172:175], v[4:7]
	v_mfma_f32_16x16x32_bf16 v[0:3], v[192:195], v[172:175], v[0:3]
	s_add_i32 s37, s36, 1
	s_cmp_lg_u32 s36, 2
	s_cselect_b32 s36, s37, 0
	s_add_u32 s24, s24, 0x80
	s_addc_u32 s25, s25, 0
	s_cmpk_lg_i32 s24, 0xf00
	s_cbranch_scc1 .LBB0_1342
	s_waitcnt vmcnt(6) lgkmcnt(0)
	s_barrier
	v_add_u32_e32 v128, v142, v138
	ds_read_b128 v[130:133], v128
	ds_read_b128 v[142:145], v128 offset:1024
	ds_read_b128 v[146:149], v128 offset:2048
	ds_read_b128 v[150:153], v128 offset:3072
	ds_read_b128 v[154:157], v128 offset:4096
	ds_read_b128 v[158:161], v128 offset:5120
	ds_read_b128 v[162:165], v128 offset:6144
	ds_read_b128 v[166:169], v128 offset:7168
	v_add3_u32 v182, v139, v140, v138
	ds_read_b128 v[138:141], v182 offset:16384
	ds_read_b128 v[170:173], v182 offset:16640
	ds_read_b128 v[174:177], v182 offset:18432
	ds_read_b128 v[178:181], v182 offset:18688
	s_setprio 1
	s_waitcnt lgkmcnt(0)
	v_mfma_f32_16x16x32_bf16 v[124:127], v[138:141], v[130:133], v[124:127]
	v_mfma_f32_16x16x32_bf16 v[120:123], v[170:173], v[130:133], v[120:123]
	v_mfma_f32_16x16x32_bf16 v[116:119], v[174:177], v[130:133], v[116:119]
	v_mfma_f32_16x16x32_bf16 v[112:115], v[178:181], v[130:133], v[112:115]
	v_mfma_f32_16x16x32_bf16 v[108:111], v[138:141], v[142:145], v[108:111]
	v_mfma_f32_16x16x32_bf16 v[104:107], v[170:173], v[142:145], v[104:107]
	v_mfma_f32_16x16x32_bf16 v[100:103], v[174:177], v[142:145], v[100:103]
	v_mfma_f32_16x16x32_bf16 v[96:99], v[178:181], v[142:145], v[96:99]
	v_mfma_f32_16x16x32_bf16 v[92:95], v[138:141], v[146:149], v[92:95]
	v_mfma_f32_16x16x32_bf16 v[88:91], v[170:173], v[146:149], v[88:91]
	v_mfma_f32_16x16x32_bf16 v[84:87], v[174:177], v[146:149], v[84:87]
	v_mfma_f32_16x16x32_bf16 v[80:83], v[178:181], v[146:149], v[80:83]
	v_mfma_f32_16x16x32_bf16 v[76:79], v[138:141], v[150:153], v[76:79]
	v_mfma_f32_16x16x32_bf16 v[72:75], v[170:173], v[150:153], v[72:75]
	v_mfma_f32_16x16x32_bf16 v[68:71], v[174:177], v[150:153], v[68:71]
	v_mfma_f32_16x16x32_bf16 v[64:67], v[178:181], v[150:153], v[64:67]
	v_mfma_f32_16x16x32_bf16 v[60:63], v[138:141], v[154:157], v[60:63]
	v_mfma_f32_16x16x32_bf16 v[56:59], v[170:173], v[154:157], v[56:59]
	v_mfma_f32_16x16x32_bf16 v[52:55], v[174:177], v[154:157], v[52:55]
	v_mfma_f32_16x16x32_bf16 v[48:51], v[178:181], v[154:157], v[48:51]
	v_mfma_f32_16x16x32_bf16 v[44:47], v[138:141], v[158:161], v[44:47]
	v_mfma_f32_16x16x32_bf16 v[40:43], v[170:173], v[158:161], v[40:43]
	v_mfma_f32_16x16x32_bf16 v[36:39], v[174:177], v[158:161], v[36:39]
	v_mfma_f32_16x16x32_bf16 v[32:35], v[178:181], v[158:161], v[32:35]
	v_mfma_f32_16x16x32_bf16 v[28:31], v[138:141], v[162:165], v[28:31]
	v_mfma_f32_16x16x32_bf16 v[24:27], v[170:173], v[162:165], v[24:27]
	v_mfma_f32_16x16x32_bf16 v[20:23], v[174:177], v[162:165], v[20:23]
	v_mfma_f32_16x16x32_bf16 v[16:19], v[178:181], v[162:165], v[16:19]
	v_mfma_f32_16x16x32_bf16 v[12:15], v[138:141], v[166:169], v[12:15]
	v_mfma_f32_16x16x32_bf16 v[8:11], v[170:173], v[166:169], v[8:11]
	v_mfma_f32_16x16x32_bf16 v[4:7], v[174:177], v[166:169], v[4:7]
	v_mfma_f32_16x16x32_bf16 v[0:3], v[178:181], v[166:169], v[0:3]
	s_setprio 0
	s_waitcnt vmcnt(0) lgkmcnt(0)
	s_barrier
	ds_read_b128 v[130:133], v128 offset:24576
	ds_read_b128 v[138:141], v128 offset:25600
	ds_read_b128 v[142:145], v128 offset:26624
	ds_read_b128 v[146:149], v128 offset:27648
	ds_read_b128 v[150:153], v128 offset:28672
	ds_read_b128 v[154:157], v128 offset:29696
	ds_read_b128 v[158:161], v128 offset:30720
	ds_read_b128 v[162:165], v128 offset:31744
	ds_read_b128 v[166:169], v182 offset:40960
	ds_read_b128 v[170:173], v182 offset:41216
	ds_read_b128 v[174:177], v182 offset:43008
	ds_read_b128 v[178:181], v182 offset:43264
	s_setprio 1
	s_waitcnt lgkmcnt(0)
	v_mfma_f32_16x16x32_bf16 v[124:127], v[166:169], v[130:133], v[124:127]
	v_mfma_f32_16x16x32_bf16 v[120:123], v[170:173], v[130:133], v[120:123]
	v_mfma_f32_16x16x32_bf16 v[116:119], v[174:177], v[130:133], v[116:119]
	v_mfma_f32_16x16x32_bf16 v[112:115], v[178:181], v[130:133], v[112:115]
	v_mfma_f32_16x16x32_bf16 v[108:111], v[166:169], v[138:141], v[108:111]
	v_mfma_f32_16x16x32_bf16 v[104:107], v[170:173], v[138:141], v[104:107]
	v_mfma_f32_16x16x32_bf16 v[100:103], v[174:177], v[138:141], v[100:103]
	v_mfma_f32_16x16x32_bf16 v[96:99], v[178:181], v[138:141], v[96:99]
	v_mfma_f32_16x16x32_bf16 v[92:95], v[166:169], v[142:145], v[92:95]
	v_mfma_f32_16x16x32_bf16 v[88:91], v[170:173], v[142:145], v[88:91]
	v_mfma_f32_16x16x32_bf16 v[84:87], v[174:177], v[142:145], v[84:87]
	v_mfma_f32_16x16x32_bf16 v[80:83], v[178:181], v[142:145], v[80:83]
	v_mfma_f32_16x16x32_bf16 v[130:133], v[166:169], v[146:149], v[76:79]
	v_mfma_f32_16x16x32_bf16 v[72:75], v[170:173], v[146:149], v[72:75]
	v_mfma_f32_16x16x32_bf16 v[68:71], v[174:177], v[146:149], v[68:71]
	v_mfma_f32_16x16x32_bf16 v[64:67], v[178:181], v[146:149], v[64:67]
	v_mfma_f32_16x16x32_bf16 v[60:63], v[166:169], v[150:153], v[60:63]
	v_mfma_f32_16x16x32_bf16 v[56:59], v[170:173], v[150:153], v[56:59]
	v_mfma_f32_16x16x32_bf16 v[52:55], v[174:177], v[150:153], v[52:55]
	v_mfma_f32_16x16x32_bf16 v[48:51], v[178:181], v[150:153], v[48:51]
	v_mfma_f32_16x16x32_bf16 v[44:47], v[166:169], v[154:157], v[44:47]
	v_mfma_f32_16x16x32_bf16 v[40:43], v[170:173], v[154:157], v[40:43]
	v_mfma_f32_16x16x32_bf16 v[36:39], v[174:177], v[154:157], v[36:39]
	v_mfma_f32_16x16x32_bf16 v[32:35], v[178:181], v[154:157], v[32:35]
	v_mfma_f32_16x16x32_bf16 v[28:31], v[166:169], v[158:161], v[28:31]
	v_mfma_f32_16x16x32_bf16 v[24:27], v[170:173], v[158:161], v[24:27]
	v_mfma_f32_16x16x32_bf16 v[20:23], v[174:177], v[158:161], v[20:23]
	v_mfma_f32_16x16x32_bf16 v[16:19], v[178:181], v[158:161], v[16:19]
	v_mfma_f32_16x16x32_bf16 v[12:15], v[166:169], v[162:165], v[12:15]
	v_mfma_f32_16x16x32_bf16 v[8:11], v[170:173], v[162:165], v[8:11]
	v_mfma_f32_16x16x32_bf16 v[4:7], v[174:177], v[162:165], v[4:7]
	v_mfma_f32_16x16x32_bf16 v[0:3], v[178:181], v[162:165], v[0:3]
	s_setprio 0
	v_and_b32_e32 v76, 0xffffff80, v135
	v_add_u32_e32 v76, s39, v76
	v_lshrrev_b32_e32 v78, 1, v135
	v_or_b32_e32 v76, v76, v136
	v_lshlrev_b32_e32 v77, 6, v137
	v_and_b32_e32 v78, 24, v78
	v_or3_b32 v78, v77, v78, s35
	v_ashrrev_i32_e32 v77, 31, v76
	v_lshlrev_b64 v[136:137], 12, v[76:77]
	s_nop 4
	v_cvt_pk_bf16_f32 v124, v124, v125
	s_nop 4
	v_cvt_pk_bf16_f32 v125, v126, v127
	s_nop 4
	v_cvt_pk_bf16_f32 v126, v120, v121
	s_nop 4
	v_cvt_pk_bf16_f32 v127, v122, v123
	s_nop 4
	v_cvt_pk_bf16_f32 v116, v116, v117
	s_nop 4
	v_cvt_pk_bf16_f32 v117, v118, v119
	s_nop 4
	v_cvt_pk_bf16_f32 v118, v112, v113
	s_nop 4
	v_cvt_pk_bf16_f32 v119, v114, v115
	s_nop 4
	v_cvt_pk_bf16_f32 v108, v108, v109
	s_nop 4
	v_cvt_pk_bf16_f32 v109, v110, v111
	s_nop 4
	v_cvt_pk_bf16_f32 v110, v104, v105
	s_nop 4
	v_cvt_pk_bf16_f32 v111, v106, v107
	s_nop 4
	v_cvt_pk_bf16_f32 v100, v100, v101
	s_nop 4
	v_cvt_pk_bf16_f32 v101, v102, v103
	s_nop 4
	v_cvt_pk_bf16_f32 v102, v96, v97
	s_nop 4
	v_cvt_pk_bf16_f32 v103, v98, v99
	s_nop 4
	v_cvt_pk_bf16_f32 v92, v92, v93
	s_nop 4
	v_cvt_pk_bf16_f32 v93, v94, v95
	s_nop 4
	v_cvt_pk_bf16_f32 v94, v88, v89
	s_nop 4
	v_cvt_pk_bf16_f32 v95, v90, v91
	s_nop 4
	v_cvt_pk_bf16_f32 v84, v84, v85
	s_nop 4
	v_cvt_pk_bf16_f32 v85, v86, v87
	s_nop 4
	v_cvt_pk_bf16_f32 v86, v80, v81
	s_nop 0
	v_or_b32_e32 v96, 32, v76
	s_nop 1
	v_ashrrev_i32_e32 v97, 31, v96
	s_nop 1
	v_ashrrev_i32_e32 v79, 31, v78
	v_lshlrev_b64 v[96:97], 12, v[96:97]
	v_cvt_pk_bf16_f32 v87, v82, v83
	v_or_b32_e32 v80, 48, v76
	v_lshlrev_b64 v[78:79], 1, v[78:79]
	v_lshl_add_u64 v[96:97], s[94:95], 0, v[96:97]
	v_ashrrev_i32_e32 v81, 31, v80
	v_lshl_add_u64 v[88:89], v[96:97], 0, v[78:79]
	v_lshlrev_b64 v[80:81], 12, v[80:81]
	s_nop 0
	global_store_dwordx4 v[88:89], v[84:87], off offset:64
	s_nop 1
	v_lshl_add_u64 v[84:85], s[94:95], 0, v[80:81]
	s_nop 1
	v_cvt_pk_bf16_f32 v80, v130, v131
	s_nop 4
	v_cvt_pk_bf16_f32 v81, v132, v133
	s_nop 4
	v_cvt_pk_bf16_f32 v82, v72, v73
	s_nop 6
	v_cvt_pk_bf16_f32 v68, v68, v69
	s_nop 4
	v_cvt_pk_bf16_f32 v69, v70, v71
	s_nop 4
	v_cvt_pk_bf16_f32 v70, v64, v65
	s_nop 6
	v_cvt_pk_bf16_f32 v60, v60, v61
	s_nop 4
	v_cvt_pk_bf16_f32 v61, v62, v63
	s_nop 4
	v_cvt_pk_bf16_f32 v62, v56, v57
	s_nop 6
	v_cvt_pk_bf16_f32 v52, v52, v53
	s_nop 4
	v_cvt_pk_bf16_f32 v53, v54, v55
	s_nop 4
	v_cvt_pk_bf16_f32 v54, v48, v49
	s_nop 6
	v_cvt_pk_bf16_f32 v44, v44, v45
	s_nop 4
	v_cvt_pk_bf16_f32 v45, v46, v47
	s_nop 4
	v_cvt_pk_bf16_f32 v46, v40, v41
	s_nop 6
	v_cvt_pk_bf16_f32 v36, v36, v37
	s_nop 4
	v_cvt_pk_bf16_f32 v37, v38, v39
	s_nop 4
	v_cvt_pk_bf16_f32 v38, v32, v33
	s_nop 6
	v_cvt_pk_bf16_f32 v28, v28, v29
	s_nop 4
	v_cvt_pk_bf16_f32 v29, v30, v31
	s_nop 4
	v_cvt_pk_bf16_f32 v30, v24, v25
	s_nop 6
	v_cvt_pk_bf16_f32 v20, v20, v21
	s_nop 4
	v_cvt_pk_bf16_f32 v21, v22, v23
	s_nop 4
	v_cvt_pk_bf16_f32 v22, v16, v17
	s_nop 6
	v_cvt_pk_bf16_f32 v12, v12, v13
	s_nop 4
	v_cvt_pk_bf16_f32 v13, v14, v15
	s_nop 4
	v_cvt_pk_bf16_f32 v14, v8, v9
	v_bfe_u32 v8, v10, 16, 1
	v_add3_u32 v8, v10, v8, s31
	v_bfe_u32 v10, v4, 16, 1
	v_add3_u32 v4, v4, v10, s31
	v_bfe_u32 v10, v5, 16, 1
	v_lshrrev_b32_e32 v4, 16, v4
	v_add3_u32 v5, v5, v10, s31
	v_and_or_b32 v4, v5, s33, v4
	s_nop 8
	v_cvt_pk_bf16_f32 v5, v6, v7
	s_nop 10
	v_or_b32_e32 v112, 16, v76
	v_cvt_pk_bf16_f32 v71, v66, v67
	v_or_b32_e32 v64, 64, v76
	v_cvt_pk_bf16_f32 v55, v50, v51
	v_or_b32_e32 v48, 0x50, v76
	v_cvt_pk_bf16_f32 v39, v34, v35
	v_or_b32_e32 v32, 0x60, v76
	v_cvt_pk_bf16_f32 v23, v18, v19
	v_or_b32_e32 v16, 0x70, v76
	s_nop 1
	v_ashrrev_i32_e32 v113, 31, v112
	v_ashrrev_i32_e32 v65, 31, v64
	v_ashrrev_i32_e32 v49, 31, v48
	v_ashrrev_i32_e32 v33, 31, v32
	v_ashrrev_i32_e32 v17, 31, v16
	v_cvt_pk_bf16_f32 v6, v0, v1
	s_nop 0
	v_lshlrev_b64 v[112:113], 12, v[112:113]
	s_nop 0
	v_lshlrev_b64 v[64:65], 12, v[64:65]
	s_nop 0
	v_lshlrev_b64 v[48:49], 12, v[48:49]
	s_nop 0
	v_lshlrev_b64 v[32:33], 12, v[32:33]
	s_nop 0
	v_lshlrev_b64 v[16:17], 12, v[16:17]
	v_bfe_u32 v9, v11, 16, 1
	s_nop 1
	v_lshl_add_u64 v[136:137], s[94:95], 0, v[136:137]
	v_lshl_add_u64 v[112:113], s[94:95], 0, v[112:113]
	s_nop 1
	v_lshl_add_u64 v[64:65], s[94:95], 0, v[64:65]
	s_nop 1
	v_lshl_add_u64 v[48:49], s[94:95], 0, v[48:49]
	s_nop 1
	v_lshl_add_u64 v[32:33], s[94:95], 0, v[32:33]
	s_nop 1
	v_lshl_add_u64 v[16:17], s[94:95], 0, v[16:17]
	v_lshrrev_b32_e32 v8, 16, v8
	v_add3_u32 v9, v11, v9, s31
	s_nop 1
	v_lshl_add_u64 v[120:121], v[136:137], 0, v[78:79]
	v_lshl_add_u64 v[104:105], v[112:113], 0, v[78:79]
	v_cvt_pk_bf16_f32 v83, v74, v75
	v_lshl_add_u64 v[72:73], v[84:85], 0, v[78:79]
	v_cvt_pk_bf16_f32 v63, v58, v59
	v_lshl_add_u64 v[56:57], v[64:65], 0, v[78:79]
	v_cvt_pk_bf16_f32 v47, v42, v43
	v_lshl_add_u64 v[40:41], v[48:49], 0, v[78:79]
	v_cvt_pk_bf16_f32 v31, v26, v27
	v_lshl_add_u64 v[24:25], v[32:33], 0, v[78:79]
	v_and_or_b32 v15, v9, s33, v8
	v_lshl_add_u64 v[8:9], v[16:17], 0, v[78:79]
	v_cvt_pk_bf16_f32 v7, v2, v3
	global_store_dwordx4 v[120:121], v[124:127], off
	global_store_dwordx4 v[120:121], v[116:119], off offset:64
	global_store_dwordx4 v[104:105], v[108:111], off
	global_store_dwordx4 v[104:105], v[100:103], off offset:64
	global_store_dwordx4 v[88:89], v[92:95], off
	global_store_dwordx4 v[72:73], v[80:83], off
	global_store_dwordx4 v[72:73], v[68:71], off offset:64
	global_store_dwordx4 v[56:57], v[60:63], off
	global_store_dwordx4 v[56:57], v[52:55], off offset:64
	global_store_dwordx4 v[40:41], v[44:47], off
	global_store_dwordx4 v[40:41], v[36:39], off offset:64
	global_store_dwordx4 v[24:25], v[28:31], off
	global_store_dwordx4 v[24:25], v[20:23], off offset:64
	global_store_dwordx4 v[8:9], v[12:15], off
	global_store_dwordx4 v[8:9], v[4:7], off offset:64
	s_branch .LBB0_1319

.LBB0_1361:
	s_andn2_b64 vcc, exec, s[8:9]
	s_cbranch_vccnz .LBB0_1365
	v_add_u32_e32 v18, 0xfffff800, v20
	s_nop 0
	v_and_b32_sdwa v25, v13, v46 dst_sel:DWORD dst_unused:UNUSED_PAD src0_sel:WORD_1 src1_sel:DWORD
	s_nop 0
	v_and_b32_sdwa v22, v12, v46 dst_sel:DWORD dst_unused:UNUSED_PAD src0_sel:WORD_1 src1_sel:DWORD
	s_nop 0
	v_add3_u32 v25, v13, v25, s16
	v_lshl_add_u64 v[26:27], v[28:29], 0, v[18:19]
	v_add3_u32 v22, v12, v22, s16
	s_nop 1
	v_and_b32_e32 v25, 0xffff0000, v25
	v_lshlrev_b64 v[40:41], 7, v[26:27]
	v_cvt_pk_bf16_f32 v23, v14, v15
	v_or_b32_sdwa v22, v25, v22 dst_sel:DWORD dst_unused:UNUSED_PAD src0_sel:DWORD src1_sel:WORD_1
	v_lshl_add_u64 v[40:41], v[30:31], 0, v[40:41]
	global_store_dwordx2 v[40:41], v[22:23], off
	s_and_saveexec_b64 s[8:9], s[6:7]
	s_cbranch_execz .LBB0_1364
	v_lshl_add_u64 v[26:27], v[26:27], 3, s[42:43]
	global_store_dwordx2 v[26:27], v[22:23], off

.LBB0_1368:
	v_or_b32_e32 v26, v48, v42
	v_ashrrev_i32_e32 v27, 31, v26
	v_or_b32_e32 v22, s18, v44
	v_lshlrev_b64 v[40:41], 12, v[26:27]
	v_lshl_add_u64 v[40:41], s[94:95], 0, v[40:41]
	s_andn2_b64 vcc, exec, s[8:9]
	v_ashrrev_i32_e32 v23, 31, v22
	s_cbranch_vccnz .LBB0_1370
	s_nop 0
	v_and_b32_sdwa v21, v12, v46 dst_sel:DWORD dst_unused:UNUSED_PAD src0_sel:WORD_1 src1_sel:DWORD
	v_add3_u32 v12, v12, v21, s16
	s_nop 1
	v_and_b32_sdwa v21, v13, v46 dst_sel:DWORD dst_unused:UNUSED_PAD src0_sel:WORD_1 src1_sel:DWORD
	s_nop 0
	v_add3_u32 v13, v13, v21, s16
	s_nop 0
	v_and_b32_e32 v18, 0xffff0000, v13
	v_lshl_add_u64 v[50:51], v[22:23], 1, v[40:41]
	v_cvt_pk_bf16_f32 v13, v14, v15
	v_or_b32_sdwa v12, v18, v12 dst_sel:DWORD dst_unused:UNUSED_PAD src0_sel:DWORD src1_sel:WORD_1
	global_store_dwordx2 v[50:51], v[12:13], off

.LBB0_1375:
	s_andn2_b64 vcc, exec, s[2:3]
	s_cbranch_vccnz .LBB0_1379
	s_nop 6
	v_add_u32_e32 v18, 0xfffff810, v20
	s_nop 2
	v_cvt_pk_bf16_f32 v13, v10, v11
	v_cvt_pk_bf16_f32 v12, v8, v9
	v_lshl_add_u64 v[14:15], v[28:29], 0, v[18:19]
	v_lshlrev_b64 v[28:29], 7, v[14:15]
	v_lshl_add_u64 v[28:29], v[30:31], 0, v[28:29]
	global_store_dwordx2 v[28:29], v[12:13], off
	s_and_saveexec_b64 s[2:3], s[6:7]
	s_cbranch_execz .LBB0_1378
	v_lshl_add_u64 v[14:15], v[14:15], 3, s[42:43]
	global_store_dwordx2 v[14:15], v[12:13], off

.LBB0_1380:
	s_andn2_b64 vcc, exec, s[2:3]
	s_cbranch_vccnz .LBB0_1382
	s_nop 0
	v_and_b32_sdwa v15, v8, v46 dst_sel:DWORD dst_unused:UNUSED_PAD src0_sel:WORD_1 src1_sel:DWORD
	v_add3_u32 v8, v8, v15, s16
	s_nop 1
	v_and_b32_sdwa v15, v9, v46 dst_sel:DWORD dst_unused:UNUSED_PAD src0_sel:WORD_1 src1_sel:DWORD
	s_nop 0
	v_add3_u32 v9, v9, v15, s16
	s_nop 0
	v_and_b32_e32 v14, 0xffff0000, v9
	v_lshl_add_u64 v[12:13], v[22:23], 1, v[40:41]
	v_cvt_pk_bf16_f32 v9, v10, v11
	v_or_b32_sdwa v8, v14, v8 dst_sel:DWORD dst_unused:UNUSED_PAD src0_sel:DWORD src1_sel:WORD_1
	global_store_dwordx2 v[12:13], v[8:9], off offset:32

.LBB0_1388:
	s_andn2_b64 vcc, exec, s[8:9]
	s_cbranch_vccnz .LBB0_1392
	v_add_u32_e32 v18, 0xfffff800, v20
	s_nop 5
	v_lshl_add_u64 v[32:33], v[8:9], 0, v[18:19]
	s_nop 3
	v_lshlrev_b64 v[34:35], 7, v[32:33]
	v_cvt_pk_bf16_f32 v25, v6, v7
	v_cvt_pk_bf16_f32 v24, v4, v5
	v_lshl_add_u64 v[34:35], v[10:11], 0, v[34:35]
	global_store_dwordx2 v[34:35], v[24:25], off
	s_and_saveexec_b64 s[8:9], s[6:7]
	s_cbranch_execz .LBB0_1391
	v_lshl_add_u64 v[32:33], v[32:33], 3, s[42:43]
	global_store_dwordx2 v[32:33], v[24:25], off

.LBB0_1403:
	s_andn2_b64 vcc, exec, s[2:3]
	s_cbranch_vccnz .LBB0_1407
	s_nop 6
	v_add_u32_e32 v18, 0xfffff810, v20
	s_nop 2
	v_cvt_pk_bf16_f32 v5, v2, v3
	v_cvt_pk_bf16_f32 v4, v0, v1
	v_lshl_add_u64 v[6:7], v[8:9], 0, v[18:19]
	v_lshlrev_b64 v[8:9], 7, v[6:7]
	v_lshl_add_u64 v[8:9], v[10:11], 0, v[8:9]
	global_store_dwordx2 v[8:9], v[4:5], off
	s_and_saveexec_b64 s[2:3], s[6:7]
	s_cbranch_execz .LBB0_1406
	v_lshl_add_u64 v[6:7], v[6:7], 3, s[42:43]
	global_store_dwordx2 v[6:7], v[4:5], off

.LBB0_1514:
	s_or_b64 exec, exec, s[22:23]
	ds_read_b32 v97, v118
	ds_read_b128 v[132:135], v113
	ds_read_b128 v[136:139], v115
	s_add_u32 s30, s30, 0x60000
	s_addc_u32 s31, s31, 0
	s_add_i32 s2, s2, 16
	s_waitcnt lgkmcnt(1)
	v_sub_f32_e32 v2, v97, v132
	s_waitcnt lgkmcnt(0)
	v_sub_f32_e32 v132, v97, v136
	v_mul_f32_e32 v132, 0x3fb8aa3b, v132
	v_exp_f32_e32 v140, v132
	v_sub_f32_e32 v132, v97, v137
	v_mul_f32_e32 v132, 0x3fb8aa3b, v132
	v_sub_f32_e32 v3, v97, v133
	v_exp_f32_e32 v142, v132
	v_sub_f32_e32 v132, v97, v138
	v_mul_f32_e32 v3, 0x3fb8aa3b, v3
	v_mul_f32_e32 v132, 0x3fb8aa3b, v132
	v_sub_f32_e32 v136, v97, v139
	v_exp_f32_e32 v110, v3
	v_sub_f32_e32 v3, v97, v134
	v_sub_f32_e32 v111, v97, v135
	v_exp_f32_e32 v141, v132
	ds_read_b128 v[132:135], v114
	v_mul_f32_e32 v136, 0x3fb8aa3b, v136
	v_mul_f32_e32 v2, 0x3fb8aa3b, v2
	v_mul_f32_e32 v3, 0x3fb8aa3b, v3
	v_exp_f32_e32 v143, v136
	ds_read_b128 v[136:139], v123 offset:35840
	v_exp_f32_e32 v2, v2
	v_exp_f32_e32 v3, v3
	v_mul_f32_e32 v111, 0x3fb8aa3b, v111
	v_exp_f32_e32 v111, v111
	s_waitcnt lgkmcnt(1)
	v_mov_b32_e32 v144, v132
	v_mov_b32_e32 v145, v134
	v_pk_mul_f32 v[2:3], v[144:145], v[2:3]
	v_mov_b32_e32 v134, v133
	s_waitcnt lgkmcnt(0)
	v_lshlrev_b32_e32 v133, 16, v137
	v_lshlrev_b32_e32 v132, 16, v136
	v_pk_mul_f32 v[110:111], v[134:135], v[110:111]
	v_pk_mul_f32 v[2:3], v[2:3], v[132:133]
	v_and_b32_e32 v133, 0xffff0000, v137
	v_and_b32_e32 v132, 0xffff0000, v136
	v_pk_mul_f32 v[110:111], v[110:111], v[132:133]
	s_nop 7
	ds_read_b128 v[132:135], v116
	s_nop 1
	v_cvt_pk_bf16_f32 v137, v3, v111
	v_cvt_pk_bf16_f32 v136, v2, v110
	s_waitcnt lgkmcnt(0)
	v_mov_b32_e32 v2, v132
	v_mov_b32_e32 v3, v134
	v_pk_mul_f32 v[2:3], v[2:3], v[140:141]
	v_mov_b32_e32 v134, v133
	v_lshlrev_b32_e32 v133, 16, v139
	v_lshlrev_b32_e32 v132, 16, v138
	v_pk_mul_f32 v[110:111], v[134:135], v[142:143]
	v_pk_mul_f32 v[2:3], v[2:3], v[132:133]
	v_and_b32_e32 v133, 0xffff0000, v139
	v_and_b32_e32 v132, 0xffff0000, v138
	v_pk_mul_f32 v[110:111], v[110:111], v[132:133]
	s_nop 9
	v_cvt_pk_bf16_f32 v139, v3, v111
	v_cvt_pk_bf16_f32 v138, v2, v110
	ds_write_b128 v123, v[136:139] offset:62464
	ds_read_b128 v[132:135], v113
	ds_read_b128 v[136:139], v115
	s_add_i32 s27, s27, 1
	v_add_f32_e32 v128, v128, v97
	s_cmp_eq_u32 s30, 0x5a0000
	s_waitcnt lgkmcnt(1)
	v_sub_f32_e32 v2, v97, v132
	v_mul_f32_e32 v2, 0x3fb8aa3b, v2
	v_exp_f32_e32 v140, v2
	v_sub_f32_e32 v2, v97, v133
	v_mul_f32_e32 v2, 0x3fb8aa3b, v2
	v_exp_f32_e32 v142, v2
	v_sub_f32_e32 v2, v97, v134
	v_mul_f32_e32 v2, 0x3fb8aa3b, v2
	v_exp_f32_e32 v141, v2
	v_sub_f32_e32 v2, v97, v135
	v_mul_f32_e32 v2, 0x3fb8aa3b, v2
	v_exp_f32_e32 v143, v2
	s_waitcnt lgkmcnt(0)
	v_sub_f32_e32 v2, v97, v136
	v_sub_f32_e32 v3, v97, v138
	v_mul_f32_e32 v2, 0x3fb8aa3b, v2
	v_mul_f32_e32 v3, 0x3fb8aa3b, v3
	ds_read_b128 v[132:135], v114
	v_exp_f32_e32 v110, v2
	v_sub_f32_e32 v2, v97, v137
	v_exp_f32_e32 v111, v3
	v_sub_f32_e32 v3, v97, v139
	ds_read_b128 v[136:139], v124 offset:35840
	s_waitcnt lgkmcnt(1)
	v_mov_b32_e32 v144, v132
	v_mov_b32_e32 v145, v134
	v_mov_b32_e32 v134, v133
	v_pk_mul_f32 v[140:141], v[144:145], v[140:141]
	v_pk_mul_f32 v[132:133], v[134:135], v[142:143]
	s_waitcnt lgkmcnt(0)
	v_lshlrev_b32_e32 v135, 16, v137
	v_lshlrev_b32_e32 v134, 16, v136
	v_pk_mul_f32 v[134:135], v[140:141], v[134:135]
	v_and_b32_e32 v137, 0xffff0000, v137
	v_and_b32_e32 v136, 0xffff0000, v136
	v_pk_mul_f32 v[132:133], v[132:133], v[136:137]
	v_and_b32_sdwa v136, v135, v127 dst_sel:DWORD dst_unused:UNUSED_PAD src0_sel:WORD_1 src1_sel:DWORD
	v_and_b32_sdwa v137, v134, v127 dst_sel:DWORD dst_unused:UNUSED_PAD src0_sel:WORD_1 src1_sel:DWORD
	v_add3_u32 v140, v134, v137, s42
	v_add3_u32 v136, v135, v136, s42
	v_and_b32_sdwa v134, v133, v127 dst_sel:DWORD dst_unused:UNUSED_PAD src0_sel:WORD_1 src1_sel:DWORD
	v_and_b32_sdwa v135, v132, v127 dst_sel:DWORD dst_unused:UNUSED_PAD src0_sel:WORD_1 src1_sel:DWORD
	v_add3_u32 v137, v133, v134, s42
	v_add3_u32 v141, v132, v135, s42
	ds_read_b128 v[132:135], v116
	v_mul_f32_e32 v2, 0x3fb8aa3b, v2
	v_mul_f32_e32 v3, 0x3fb8aa3b, v3
	v_exp_f32_e32 v2, v2
	v_exp_f32_e32 v3, v3
	v_and_b32_e32 v137, 0xffff0000, v137
	v_and_b32_e32 v141, 0xffff0000, v141
	v_or_b32_sdwa v137, v137, v136 dst_sel:DWORD dst_unused:UNUSED_PAD src0_sel:DWORD src1_sel:WORD_1
	v_or_b32_sdwa v136, v141, v140 dst_sel:DWORD dst_unused:UNUSED_PAD src0_sel:DWORD src1_sel:WORD_1
	s_waitcnt lgkmcnt(0)
	v_mov_b32_e32 v140, v132
	v_mov_b32_e32 v141, v134
	v_pk_mul_f32 v[110:111], v[140:141], v[110:111]
	v_mov_b32_e32 v134, v133
	v_lshlrev_b32_e32 v133, 16, v139
	v_lshlrev_b32_e32 v132, 16, v138
	v_pk_mul_f32 v[2:3], v[134:135], v[2:3]
	v_pk_mul_f32 v[110:111], v[110:111], v[132:133]
	v_and_b32_e32 v133, 0xffff0000, v139
	v_and_b32_e32 v132, 0xffff0000, v138
	v_pk_mul_f32 v[2:3], v[2:3], v[132:133]
	v_and_b32_sdwa v132, v111, v127 dst_sel:DWORD dst_unused:UNUSED_PAD src0_sel:WORD_1 src1_sel:DWORD
	s_nop 1
	v_add3_u32 v111, v111, v132, s42
	v_and_b32_sdwa v132, v3, v127 dst_sel:DWORD dst_unused:UNUSED_PAD src0_sel:WORD_1 src1_sel:DWORD
	s_nop 0
	v_add3_u32 v3, v3, v132, s42
	s_nop 0
	v_and_b32_e32 v3, 0xffff0000, v3
	s_nop 0
	v_or_b32_sdwa v139, v3, v111 dst_sel:DWORD dst_unused:UNUSED_PAD src0_sel:DWORD src1_sel:WORD_1
	v_cvt_pk_bf16_f32 v138, v110, v2
	ds_write_b128 v124, v[136:139] offset:62464
	s_waitcnt lgkmcnt(0)
	s_barrier
	ds_read_b128 v[132:135], v66 offset:17408
	ds_read_b128 v[144:147], v67 offset:4608
	v_mul_f32_e32 v2, 0x3fb8aa3b, v97
	v_exp_f32_e32 v2, v2
	ds_read_b128 v[136:139], v64 offset:62464
	ds_read_b128 v[140:143], v64 offset:64768
	ds_read_b128 v[148:151], v67 offset:6912
	v_pk_mul_f32 v[34:35], v[34:35], v[2:3] op_sel_hi:[1,0]
	v_pk_mul_f32 v[32:33], v[32:33], v[2:3] op_sel_hi:[1,0]
	v_pk_mul_f32 v[30:31], v[30:31], v[2:3] op_sel_hi:[1,0]
	v_pk_mul_f32 v[28:29], v[28:29], v[2:3] op_sel_hi:[1,0]
	v_pk_mul_f32 v[22:23], v[22:23], v[2:3] op_sel_hi:[1,0]
	v_pk_mul_f32 v[20:21], v[20:21], v[2:3] op_sel_hi:[1,0]
	v_pk_mul_f32 v[10:11], v[10:11], v[2:3] op_sel_hi:[1,0]
	v_pk_mul_f32 v[8:9], v[8:9], v[2:3] op_sel_hi:[1,0]
	s_waitcnt lgkmcnt(2)
	v_mfma_f32_16x16x32_bf16 v[32:35], v[132:135], v[136:139], v[32:35]
	v_mul_f32_e64 v26, v26, v2
	v_mul_f32_e64 v27, v27, v2
	v_pk_mul_f32 v[24:25], v[24:25], v[2:3] op_sel_hi:[1,0]
	v_pk_mul_f32 v[18:19], v[18:19], v[2:3] op_sel_hi:[1,0]
	s_waitcnt lgkmcnt(1)
	v_mfma_f32_16x16x32_bf16 v[28:31], v[132:135], v[140:143], v[28:31]
	v_mul_f32_e64 v16, v16, v2
	v_mul_f32_e64 v17, v17, v2
	v_pk_mul_f32 v[14:15], v[14:15], v[2:3] op_sel_hi:[1,0]
	v_pk_mul_f32 v[12:13], v[12:13], v[2:3] op_sel_hi:[1,0]
	v_mfma_f32_16x16x32_bf16 v[20:23], v[132:135], v[144:147], v[20:23]
	v_mul_f32_e64 v6, v6, v2
	v_mul_f32_e64 v7, v7, v2
	v_pk_mul_f32 v[4:5], v[4:5], v[2:3] op_sel_hi:[1,0]
	v_add_u32_e32 v131, 64, v131
	s_waitcnt lgkmcnt(0)
	v_mfma_f32_16x16x32_bf16 v[8:11], v[132:135], v[148:151], v[8:11]
	ds_read_b128 v[132:135], v66 offset:19712
	s_waitcnt lgkmcnt(0)
	v_mfma_f32_16x16x32_bf16 v[24:27], v[132:135], v[136:139], v[24:27]
	ds_read_b128 v[136:139], v66 offset:17472
	v_mfma_f32_16x16x32_bf16 v[16:19], v[132:135], v[140:143], v[16:19]
	ds_read_b128 v[140:143], v64 offset:64832
	v_mfma_f32_16x16x32_bf16 v[12:15], v[132:135], v[144:147], v[12:15]
	ds_read_b128 v[144:147], v73 offset:4608
	v_mfma_f32_16x16x32_bf16 v[2:5], v[132:135], v[148:151], v[4:7]
	ds_read_b128 v[132:135], v64 offset:62528
	ds_read_b128 v[148:151], v73 offset:6912
	s_waitcnt lgkmcnt(1)
	v_mfma_f32_16x16x32_bf16 v[32:35], v[136:139], v[132:135], v[32:35]
	v_mfma_f32_16x16x32_bf16 v[28:31], v[136:139], v[140:143], v[28:31]
	v_mfma_f32_16x16x32_bf16 v[20:23], v[136:139], v[144:147], v[20:23]
	s_waitcnt lgkmcnt(0)
	v_mfma_f32_16x16x32_bf16 v[8:11], v[136:139], v[148:151], v[8:11]
	ds_read_b128 v[136:139], v66 offset:19776
	s_waitcnt lgkmcnt(0)
	v_mfma_f32_16x16x32_bf16 v[24:27], v[136:139], v[132:135], v[24:27]
	v_mfma_f32_16x16x32_bf16 v[16:19], v[136:139], v[140:143], v[16:19]
	v_mfma_f32_16x16x32_bf16 v[12:15], v[136:139], v[144:147], v[12:15]
	v_mfma_f32_16x16x32_bf16 v[4:7], v[136:139], v[148:151], v[2:5]
	s_cbranch_scc1 .LBB0_1533

.LBB0_1535:
	s_or_b64 exec, exec, s[22:23]
	s_waitcnt vmcnt(0)
	ds_write_b128 v123, v[40:43] offset:17408
	ds_write_b128 v124, v[36:39] offset:17408
	ds_write_b128 v125, v[44:47] offset:17408
	ds_write_b128 v126, v[48:51] offset:17408
	ds_write_b128 v123, v[52:55] offset:35840
	ds_write_b128 v124, v[56:59] offset:35840
	s_waitcnt lgkmcnt(0)
	s_barrier
	ds_read_b32 v1, v118
	ds_read_b128 v[36:39], v113
	ds_read_b128 v[40:43], v115
	s_ashr_i32 s27, s26, 31
	s_lshl_b64 s[20:21], s[26:27], 11
	s_or_b32 s2, s20, s25
	s_waitcnt lgkmcnt(1)
	v_sub_f32_e32 v2, v1, v36
	v_sub_f32_e32 v36, v1, v39
	v_mul_f32_e32 v36, 0x3fb8aa3b, v36
	v_exp_f32_e32 v45, v36
	s_waitcnt lgkmcnt(0)
	v_sub_f32_e32 v36, v1, v40
	v_mul_f32_e32 v36, 0x3fb8aa3b, v36
	v_exp_f32_e32 v46, v36
	v_sub_f32_e32 v36, v1, v41
	v_mul_f32_e32 v36, 0x3fb8aa3b, v36
	v_sub_f32_e32 v3, v1, v37
	v_exp_f32_e32 v48, v36
	v_sub_f32_e32 v36, v1, v42
	v_mul_f32_e32 v3, 0x3fb8aa3b, v3
	v_mul_f32_e32 v36, 0x3fb8aa3b, v36
	v_sub_f32_e32 v40, v1, v43
	v_exp_f32_e32 v44, v3
	v_sub_f32_e32 v3, v1, v38
	v_exp_f32_e32 v47, v36
	ds_read_b128 v[36:39], v114
	v_mul_f32_e32 v40, 0x3fb8aa3b, v40
	v_mul_f32_e32 v2, 0x3fb8aa3b, v2
	v_mul_f32_e32 v3, 0x3fb8aa3b, v3
	v_exp_f32_e32 v49, v40
	ds_read_b128 v[40:43], v123 offset:35840
	v_exp_f32_e32 v2, v2
	v_exp_f32_e32 v3, v3
	s_waitcnt lgkmcnt(1)
	v_mov_b32_e32 v50, v36
	v_mov_b32_e32 v51, v38
	v_mov_b32_e32 v38, v37
	v_pk_mul_f32 v[2:3], v[50:51], v[2:3]
	v_pk_mul_f32 v[36:37], v[38:39], v[44:45]
	s_waitcnt lgkmcnt(0)
	v_lshlrev_b32_e32 v39, 16, v41
	v_lshlrev_b32_e32 v38, 16, v40
	v_pk_mul_f32 v[2:3], v[2:3], v[38:39]
	v_and_b32_e32 v39, 0xffff0000, v41
	v_and_b32_e32 v38, 0xffff0000, v40
	v_pk_mul_f32 v[36:37], v[36:37], v[38:39]
	v_and_b32_sdwa v38, v3, v127 dst_sel:DWORD dst_unused:UNUSED_PAD src0_sel:WORD_1 src1_sel:DWORD
	v_and_b32_sdwa v39, v2, v127 dst_sel:DWORD dst_unused:UNUSED_PAD src0_sel:WORD_1 src1_sel:DWORD
	v_add3_u32 v2, v2, v39, s42
	v_add3_u32 v3, v3, v38, s42
	v_and_b32_sdwa v38, v37, v127 dst_sel:DWORD dst_unused:UNUSED_PAD src0_sel:WORD_1 src1_sel:DWORD
	v_and_b32_sdwa v39, v36, v127 dst_sel:DWORD dst_unused:UNUSED_PAD src0_sel:WORD_1 src1_sel:DWORD
	v_add3_u32 v40, v37, v38, s42
	v_add3_u32 v41, v36, v39, s42
	ds_read_b128 v[36:39], v116
	v_and_b32_e32 v40, 0xffff0000, v40
	v_and_b32_e32 v44, 0xffff0000, v41
	v_or_b32_sdwa v41, v40, v3 dst_sel:DWORD dst_unused:UNUSED_PAD src0_sel:DWORD src1_sel:WORD_1
	v_or_b32_sdwa v40, v44, v2 dst_sel:DWORD dst_unused:UNUSED_PAD src0_sel:DWORD src1_sel:WORD_1
	s_waitcnt lgkmcnt(0)
	v_mov_b32_e32 v2, v36
	v_mov_b32_e32 v3, v38
	v_mov_b32_e32 v38, v37
	v_pk_mul_f32 v[2:3], v[2:3], v[46:47]
	v_pk_mul_f32 v[36:37], v[38:39], v[48:49]
	v_lshlrev_b32_e32 v39, 16, v43
	v_lshlrev_b32_e32 v38, 16, v42
	v_pk_mul_f32 v[2:3], v[2:3], v[38:39]
	v_and_b32_e32 v39, 0xffff0000, v43
	v_and_b32_e32 v38, 0xffff0000, v42
	v_pk_mul_f32 v[36:37], v[36:37], v[38:39]
	s_nop 9
	v_cvt_pk_bf16_f32 v43, v3, v37
	v_cvt_pk_bf16_f32 v42, v2, v36
	ds_write_b128 v123, v[40:43] offset:62464
	ds_read_b128 v[36:39], v113
	ds_read_b128 v[40:43], v115
	s_waitcnt lgkmcnt(1)
	v_sub_f32_e32 v2, v1, v36
	v_mul_f32_e32 v2, 0x3fb8aa3b, v2
	v_exp_f32_e32 v46, v2
	v_sub_f32_e32 v2, v1, v37
	v_mul_f32_e32 v2, 0x3fb8aa3b, v2
	v_exp_f32_e32 v48, v2
	v_sub_f32_e32 v2, v1, v38
	v_mul_f32_e32 v2, 0x3fb8aa3b, v2
	v_exp_f32_e32 v47, v2
	v_sub_f32_e32 v2, v1, v39
	v_mul_f32_e32 v2, 0x3fb8aa3b, v2
	v_exp_f32_e32 v49, v2
	s_waitcnt lgkmcnt(0)
	v_sub_f32_e32 v2, v1, v40
	v_mul_f32_e32 v2, 0x3fb8aa3b, v2
	v_sub_f32_e32 v3, v1, v42
	v_exp_f32_e32 v36, v2
	v_sub_f32_e32 v2, v1, v41
	v_mul_f32_e32 v3, 0x3fb8aa3b, v3
	ds_read_b128 v[38:41], v114
	v_exp_f32_e32 v37, v3
	v_sub_f32_e32 v3, v1, v43
	ds_read_b128 v[42:45], v124 offset:35840
	v_mul_f32_e32 v2, 0x3fb8aa3b, v2
	s_waitcnt lgkmcnt(1)
	v_mov_b32_e32 v50, v38
	v_mov_b32_e32 v51, v40
	v_mov_b32_e32 v40, v39
	v_pk_mul_f32 v[46:47], v[50:51], v[46:47]
	v_pk_mul_f32 v[38:39], v[40:41], v[48:49]
	s_waitcnt lgkmcnt(0)
	v_lshlrev_b32_e32 v41, 16, v43
	v_lshlrev_b32_e32 v40, 16, v42
	v_pk_mul_f32 v[40:41], v[46:47], v[40:41]
	v_and_b32_e32 v43, 0xffff0000, v43
	v_and_b32_e32 v42, 0xffff0000, v42
	v_pk_mul_f32 v[38:39], v[38:39], v[42:43]
	v_and_b32_sdwa v42, v41, v127 dst_sel:DWORD dst_unused:UNUSED_PAD src0_sel:WORD_1 src1_sel:DWORD
	v_and_b32_sdwa v43, v40, v127 dst_sel:DWORD dst_unused:UNUSED_PAD src0_sel:WORD_1 src1_sel:DWORD
	v_add3_u32 v46, v40, v43, s42
	v_add3_u32 v42, v41, v42, s42
	v_and_b32_sdwa v40, v39, v127 dst_sel:DWORD dst_unused:UNUSED_PAD src0_sel:WORD_1 src1_sel:DWORD
	v_and_b32_sdwa v41, v38, v127 dst_sel:DWORD dst_unused:UNUSED_PAD src0_sel:WORD_1 src1_sel:DWORD
	v_add3_u32 v43, v39, v40, s42
	v_add3_u32 v47, v38, v41, s42
	ds_read_b128 v[38:41], v116
	v_mul_f32_e32 v3, 0x3fb8aa3b, v3
	v_exp_f32_e32 v2, v2
	v_exp_f32_e32 v3, v3
	v_and_b32_e32 v43, 0xffff0000, v43
	v_and_b32_e32 v47, 0xffff0000, v47
	v_or_b32_sdwa v43, v43, v42 dst_sel:DWORD dst_unused:UNUSED_PAD src0_sel:DWORD src1_sel:WORD_1
	v_or_b32_sdwa v42, v47, v46 dst_sel:DWORD dst_unused:UNUSED_PAD src0_sel:DWORD src1_sel:WORD_1
	s_waitcnt lgkmcnt(0)
	v_mov_b32_e32 v46, v38
	v_mov_b32_e32 v47, v40
	v_pk_mul_f32 v[36:37], v[46:47], v[36:37]
	v_mov_b32_e32 v40, v39
	v_lshlrev_b32_e32 v39, 16, v45
	v_lshlrev_b32_e32 v38, 16, v44
	v_pk_mul_f32 v[2:3], v[40:41], v[2:3]
	v_pk_mul_f32 v[36:37], v[36:37], v[38:39]
	v_and_b32_e32 v39, 0xffff0000, v45
	v_and_b32_e32 v38, 0xffff0000, v44
	v_pk_mul_f32 v[2:3], v[2:3], v[38:39]
	v_and_b32_sdwa v38, v37, v127 dst_sel:DWORD dst_unused:UNUSED_PAD src0_sel:WORD_1 src1_sel:DWORD
	s_nop 1
	v_add3_u32 v37, v37, v38, s42
	v_and_b32_sdwa v38, v3, v127 dst_sel:DWORD dst_unused:UNUSED_PAD src0_sel:WORD_1 src1_sel:DWORD
	s_nop 0
	v_add3_u32 v3, v3, v38, s42
	s_nop 0
	v_and_b32_e32 v3, 0xffff0000, v3
	s_nop 0
	v_or_b32_sdwa v45, v3, v37 dst_sel:DWORD dst_unused:UNUSED_PAD src0_sel:DWORD src1_sel:WORD_1
	v_cvt_pk_bf16_f32 v44, v36, v2
	ds_write_b128 v124, v[42:45] offset:62464
	s_waitcnt lgkmcnt(0)
	s_barrier
	ds_read_b128 v[36:39], v66 offset:17408
	ds_read_b128 v[48:51], v67 offset:4608
	v_mul_f32_e32 v2, 0x3fb8aa3b, v1
	v_exp_f32_e32 v2, v2
	ds_read_b128 v[40:43], v64 offset:62464
	ds_read_b128 v[44:47], v64 offset:64768
	ds_read_b128 v[52:55], v67 offset:6912
	v_pk_mul_f32 v[34:35], v[34:35], v[2:3] op_sel_hi:[1,0]
	v_pk_mul_f32 v[32:33], v[32:33], v[2:3] op_sel_hi:[1,0]
	v_pk_mul_f32 v[30:31], v[30:31], v[2:3] op_sel_hi:[1,0]
	v_pk_mul_f32 v[28:29], v[28:29], v[2:3] op_sel_hi:[1,0]
	v_pk_mul_f32 v[22:23], v[22:23], v[2:3] op_sel_hi:[1,0]
	v_pk_mul_f32 v[20:21], v[20:21], v[2:3] op_sel_hi:[1,0]
	v_pk_mul_f32 v[10:11], v[10:11], v[2:3] op_sel_hi:[1,0]
	v_pk_mul_f32 v[8:9], v[8:9], v[2:3] op_sel_hi:[1,0]
	s_waitcnt lgkmcnt(2)
	v_mfma_f32_16x16x32_bf16 v[32:35], v[36:39], v[40:43], v[32:35]
	v_mul_f32_e64 v26, v26, v2
	v_mul_f32_e64 v27, v27, v2
	v_pk_mul_f32 v[24:25], v[24:25], v[2:3] op_sel_hi:[1,0]
	v_pk_mul_f32 v[18:19], v[18:19], v[2:3] op_sel_hi:[1,0]
	s_waitcnt lgkmcnt(1)
	v_mfma_f32_16x16x32_bf16 v[28:31], v[36:39], v[44:47], v[28:31]
	v_mul_f32_e64 v16, v16, v2
	v_mul_f32_e64 v17, v17, v2
	v_pk_mul_f32 v[14:15], v[14:15], v[2:3] op_sel_hi:[1,0]
	v_pk_mul_f32 v[12:13], v[12:13], v[2:3] op_sel_hi:[1,0]
	v_mfma_f32_16x16x32_bf16 v[20:23], v[36:39], v[48:51], v[20:23]
	v_mul_f32_e64 v6, v6, v2
	v_mul_f32_e64 v7, v7, v2
	v_pk_mul_f32 v[4:5], v[4:5], v[2:3] op_sel_hi:[1,0]
	s_waitcnt lgkmcnt(0)
	v_mfma_f32_16x16x32_bf16 v[8:11], v[36:39], v[52:55], v[8:11]
	ds_read_b128 v[36:39], v66 offset:19712
	s_waitcnt lgkmcnt(0)
	v_mfma_f32_16x16x32_bf16 v[24:27], v[36:39], v[40:43], v[24:27]
	ds_read_b128 v[40:43], v66 offset:17472
	v_mfma_f32_16x16x32_bf16 v[16:19], v[36:39], v[44:47], v[16:19]
	ds_read_b128 v[44:47], v64 offset:64832
	v_mfma_f32_16x16x32_bf16 v[12:15], v[36:39], v[48:51], v[12:15]
	ds_read_b128 v[48:51], v73 offset:4608
	v_mfma_f32_16x16x32_bf16 v[2:5], v[36:39], v[52:55], v[4:7]
	ds_read_b128 v[36:39], v64 offset:62528
	ds_read_b128 v[52:55], v73 offset:6912
	s_waitcnt lgkmcnt(1)
	v_mfma_f32_16x16x32_bf16 v[32:35], v[40:43], v[36:39], v[32:35]
	v_mfma_f32_16x16x32_bf16 v[28:31], v[40:43], v[44:47], v[28:31]
	v_mfma_f32_16x16x32_bf16 v[20:23], v[40:43], v[48:51], v[20:23]
	s_waitcnt lgkmcnt(0)
	v_mfma_f32_16x16x32_bf16 v[6:9], v[40:43], v[52:55], v[8:11]
	ds_read_b128 v[40:43], v66 offset:19776
	s_waitcnt lgkmcnt(0)
	v_mfma_f32_16x16x32_bf16 v[10:13], v[40:43], v[48:51], v[12:15]
	s_nop 2
	v_mov_b32_e32 v15, s21
	v_or_b32_e32 v14, s2, v60
	v_lshlrev_b64 v[14:15], 9, v[14:15]
	v_lshl_add_u64 v[14:15], v[68:69], 0, v[14:15]
	global_store_dwordx4 v[14:15], v[32:35], off
	v_mfma_f32_16x16x32_bf16 v[24:27], v[40:43], v[36:39], v[24:27]
	s_nop 0
	v_mov_b32_e32 v33, s21
	v_or_b32_e32 v32, s2, v70
	v_lshlrev_b64 v[32:33], 9, v[32:33]
	v_lshl_add_u64 v[32:33], v[68:69], 0, v[32:33]
	global_store_dwordx4 v[32:33], v[28:31], off
	v_mfma_f32_16x16x32_bf16 v[16:19], v[40:43], v[44:47], v[16:19]
	s_nop 0
	v_mov_b32_e32 v29, s21
	v_or_b32_e32 v28, s2, v72
	v_lshlrev_b64 v[28:29], 9, v[28:29]
	v_lshl_add_u64 v[28:29], v[68:69], 0, v[28:29]
	global_store_dwordx4 v[28:29], v[20:23], off
	v_mfma_f32_16x16x32_bf16 v[2:5], v[40:43], v[52:55], v[2:5]
	s_nop 0
	v_mov_b32_e32 v21, s21
	v_or_b32_e32 v20, s2, v74
	v_lshlrev_b64 v[20:21], 9, v[20:21]
	v_lshl_add_u64 v[20:21], v[68:69], 0, v[20:21]
	global_store_dwordx4 v[20:21], v[6:9], off
	global_store_dwordx4 v[14:15], v[24:27], off offset:64
	global_store_dwordx4 v[32:33], v[16:19], off offset:64
	global_store_dwordx4 v[28:29], v[10:13], off offset:64
	global_store_dwordx4 v[20:21], v[2:5], off offset:64
	s_and_saveexec_b64 s[20:21], s[6:7]
	s_cbranch_execz .LBB0_1508
	v_add_f32_e32 v1, v128, v1
	v_mul_f32_e32 v1, 0x3fb8aa3b, v1
	s_ashr_i32 s25, s24, 31
	v_exp_f32_e32 v1, v1
	s_lshl_b64 s[22:23], s[24:25], 2
	s_add_u32 s22, s0, s22
	s_addc_u32 s23, s1, s23
	global_store_dword v0, v1, s[22:23]
	s_branch .LBB0_1508

.LBB0_1568:
	s_or_b64 exec, exec, s[4:5]
	s_waitcnt vmcnt(63) expcnt(7) lgkmcnt(15)
	s_barrier
	s_waitcnt vmcnt(0)
	ds_write_b32 v24, v0
	ds_write_b32 v24, v1 offset:1040
	ds_write_b32 v24, v2 offset:2080
	ds_write_b32 v24, v3 offset:3120
	ds_write_b32 v24, v4 offset:4160
	ds_write_b32 v24, v5 offset:5200
	ds_write_b32 v24, v6 offset:6240
	ds_write_b32 v24, v7 offset:7280
	ds_write_b32 v24, v8 offset:8320
	ds_write_b32 v24, v9 offset:9360
	ds_write_b32 v24, v10 offset:10400
	ds_write_b32 v24, v11 offset:11440
	ds_write_b32 v24, v12 offset:12480
	ds_write_b32 v24, v13 offset:13520
	ds_write_b32 v24, v14 offset:14560
	ds_write_b32 v24, v15 offset:15600
	s_waitcnt lgkmcnt(0)
	s_barrier
	ds_read2_b32 v[6:7], v23 offset1:32
	ds_read2_b32 v[8:9], v23 offset0:65 offset1:97
	ds_read2_b32 v[10:11], v23 offset0:130 offset1:162
	ds_read2_b32 v[12:13], v23 offset0:195 offset1:227
	v_add_u32_e32 v30, s13, v22
	v_and_b32_e32 v30, -2, v30
	s_ashr_i32 s3, s2, 31
	v_add_u32_e32 v0, 0x400, v23
	v_ashrrev_i32_e32 v31, 31, v30
	v_lshl_add_u64 v[4:5], s[2:3], 2, v[16:17]
	ds_read2_b32 v[14:15], v0 offset0:4 offset1:36
	ds_read2_b32 v[18:19], v0 offset0:69 offset1:101
	ds_read2_b32 v[26:27], v0 offset0:134 offset1:166
	ds_read2_b32 v[28:29], v0 offset0:199 offset1:231
	v_lshlrev_b64 v[0:1], 11, v[30:31]
	v_lshl_add_u64 v[32:33], v[4:5], 0, v[0:1]
	s_waitcnt lgkmcnt(7)
	s_nop 1
	s_waitcnt lgkmcnt(4)
	s_nop 7
	v_cvt_pk_bf16_f32 v1, v10, v12
	v_cvt_pk_bf16_f32 v0, v6, v8
	s_waitcnt lgkmcnt(3)
	s_nop 1
	s_waitcnt lgkmcnt(0)
	s_nop 7
	v_cvt_pk_bf16_f32 v3, v26, v28
	v_cvt_pk_bf16_f32 v2, v14, v18
	global_store_dwordx4 v[32:33], v[0:3], off
	s_add_i32 s12, s12, s86
	s_add_i32 s6, s6, s7
	v_add_u32_e32 v0, 32, v30
	v_ashrrev_i32_e32 v1, 31, v0
	v_lshlrev_b64 v[0:1], 11, v[0:1]
	v_lshl_add_u64 v[4:5], v[4:5], 0, v[0:1]
	s_nop 9
	v_cvt_pk_bf16_f32 v1, v11, v13
	v_cvt_pk_bf16_f32 v0, v7, v9
	s_nop 9
	v_cvt_pk_bf16_f32 v3, v27, v29
	v_cvt_pk_bf16_f32 v2, v15, v19
	s_cmpk_lt_i32 s12, 0x310
	global_store_dwordx4 v[4:5], v[0:3], off
	s_cbranch_scc0 .LBB0_1601

.LBB0_1603:
	s_or_b64 exec, exec, s[4:5]
	s_sub_i32 s4, 0, s3
	s_waitcnt vmcnt(63) expcnt(7) lgkmcnt(15)
	s_barrier
	s_waitcnt vmcnt(0)
	ds_write_b32 v26, v0
	ds_write_b32 v26, v1 offset:1040
	ds_write_b32 v26, v2 offset:2080
	ds_write_b32 v26, v3 offset:3120
	ds_write_b32 v26, v4 offset:4160
	ds_write_b32 v26, v5 offset:5200
	ds_write_b32 v26, v6 offset:6240
	ds_write_b32 v26, v7 offset:7280
	ds_write_b32 v26, v8 offset:8320
	ds_write_b32 v26, v9 offset:9360
	ds_write_b32 v26, v10 offset:10400
	ds_write_b32 v26, v11 offset:11440
	ds_write_b32 v26, v12 offset:12480
	ds_write_b32 v26, v13 offset:13520
	ds_write_b32 v26, v14 offset:14560
	ds_write_b32 v26, v15 offset:15600
	s_waitcnt lgkmcnt(0)
	s_barrier
	ds_read2_b32 v[6:7], v25 offset1:32
	ds_read2_b32 v[8:9], v25 offset0:65 offset1:97
	ds_read2_b32 v[10:11], v25 offset0:130 offset1:162
	ds_read2_b32 v[12:13], v25 offset0:195 offset1:227
	s_add_i32 s4, s4, s6
	v_add_u32_e32 v30, s4, v24
	s_ashr_i32 s3, s2, 31
	v_add_u32_e32 v0, 0x400, v25
	v_ashrrev_i32_e32 v31, 31, v30
	v_lshl_add_u64 v[4:5], s[2:3], 1, v[16:17]
	ds_read2_b32 v[14:15], v0 offset0:4 offset1:36
	ds_read2_b32 v[18:19], v0 offset0:69 offset1:101
	ds_read2_b32 v[20:21], v0 offset0:134 offset1:166
	ds_read2_b32 v[28:29], v0 offset0:199 offset1:231
	v_lshlrev_b64 v[0:1], 11, v[30:31]
	v_lshl_add_u64 v[32:33], v[4:5], 0, v[0:1]
	s_waitcnt lgkmcnt(7)
	s_nop 1
	s_waitcnt lgkmcnt(4)
	s_nop 7
	v_cvt_pk_bf16_f32 v1, v10, v12
	v_cvt_pk_bf16_f32 v0, v6, v8
	s_waitcnt lgkmcnt(3)
	s_nop 1
	s_waitcnt lgkmcnt(0)
	s_nop 7
	v_cvt_pk_bf16_f32 v3, v20, v28
	v_cvt_pk_bf16_f32 v2, v14, v18
	global_store_dwordx4 v[32:33], v[0:3], off
	s_add_i32 s11, s11, s86
	s_add_i32 s6, s6, s7
	v_add_u32_e32 v0, 32, v30
	v_ashrrev_i32_e32 v1, 31, v0
	v_lshlrev_b64 v[0:1], 11, v[0:1]
	v_lshl_add_u64 v[4:5], v[4:5], 0, v[0:1]
	s_nop 9
	v_cvt_pk_bf16_f32 v1, v11, v13
	v_cvt_pk_bf16_f32 v0, v7, v9
	s_nop 9
	v_cvt_pk_bf16_f32 v3, v21, v29
	v_cvt_pk_bf16_f32 v2, v15, v19
	s_cmpk_lt_i32 s11, 0x100
	global_store_dwordx4 v[4:5], v[0:3], off
	s_cbranch_scc0 .LBB0_1636

.LBB0_1708:
	ds_read_b32 v139, v215
	ds_read_b128 v[60:63], v157
	ds_read_b128 v[64:67], v159
	ds_read_b128 v[68:71], v159 offset:4352
	ds_read_b128 v[72:75], v159 offset:8704
	ds_read_b128 v[76:79], v159 offset:13056
	s_nop 0
	s_waitcnt lgkmcnt(3)
	v_mfma_f32_16x16x32_bf16 v[64:67], v[60:63], v[64:67], 0
	s_nop 1
	s_waitcnt lgkmcnt(2)
	v_mfma_f32_16x16x32_bf16 v[68:71], v[60:63], v[68:71], 0
	s_waitcnt lgkmcnt(1)
	v_mfma_f32_16x16x32_bf16 v[72:75], v[60:63], v[72:75], 0
	s_waitcnt lgkmcnt(0)
	v_mfma_f32_16x16x32_bf16 v[60:63], v[60:63], v[76:79], 0
	ds_read_b128 v[76:79], v157 offset:64
	ds_read_b128 v[80:83], v160
	ds_read_b128 v[84:87], v160 offset:4352
	ds_read_b128 v[88:91], v160 offset:8704
	ds_read_b128 v[92:95], v160 offset:13056
	s_waitcnt lgkmcnt(3)
	v_mfma_f32_16x16x32_bf16 v[64:67], v[76:79], v[80:83], v[64:67]
	s_waitcnt lgkmcnt(2)
	v_mfma_f32_16x16x32_bf16 v[68:71], v[76:79], v[84:87], v[68:71]
	s_waitcnt lgkmcnt(1)
	v_mfma_f32_16x16x32_bf16 v[72:75], v[76:79], v[88:91], v[72:75]
	s_waitcnt lgkmcnt(0)
	v_mfma_f32_16x16x32_bf16 v[60:63], v[76:79], v[92:95], v[60:63]
	ds_read_b128 v[76:79], v157 offset:128
	ds_read_b128 v[80:83], v161
	ds_read_b128 v[84:87], v161 offset:4352
	ds_read_b128 v[88:91], v161 offset:8704
	ds_read_b128 v[92:95], v161 offset:13056
	s_waitcnt lgkmcnt(3)
	v_mfma_f32_16x16x32_bf16 v[64:67], v[76:79], v[80:83], v[64:67]
	s_waitcnt lgkmcnt(2)
	v_mfma_f32_16x16x32_bf16 v[68:71], v[76:79], v[84:87], v[68:71]
	s_waitcnt lgkmcnt(1)
	v_mfma_f32_16x16x32_bf16 v[80:83], v[76:79], v[88:91], v[72:75]
	s_waitcnt lgkmcnt(0)
	v_mfma_f32_16x16x32_bf16 v[60:63], v[76:79], v[92:95], v[60:63]
	ds_read_b128 v[76:79], v157 offset:192
	ds_read_b128 v[72:75], v162
	ds_read_b128 v[84:87], v162 offset:4352
	ds_read_b128 v[88:91], v162 offset:8704
	ds_read_b128 v[92:95], v162 offset:13056
	s_waitcnt lgkmcnt(3)
	v_mfma_f32_16x16x32_bf16 v[72:75], v[76:79], v[72:75], v[64:67]
	s_waitcnt lgkmcnt(2)
	v_mfma_f32_16x16x32_bf16 v[68:71], v[76:79], v[84:87], v[68:71]
	s_nop 2
	s_waitcnt lgkmcnt(1)
	v_mfma_f32_16x16x32_bf16 v[64:67], v[76:79], v[88:91], v[80:83]
	s_waitcnt lgkmcnt(0)
	v_mfma_f32_16x16x32_bf16 v[60:63], v[76:79], v[92:95], v[60:63]
	s_nop 6
	v_cvt_pk_bf16_f32 v3, v34, v35
	v_cvt_pk_bf16_f32 v2, v32, v33
	s_nop 9
	v_cvt_pk_bf16_f32 v77, v30, v31
	v_cvt_pk_bf16_f32 v76, v28, v29
	s_nop 9
	v_cvt_pk_bf16_f32 v79, v26, v27
	v_cvt_pk_bf16_f32 v78, v24, v25
	s_nop 9
	v_cvt_pk_bf16_f32 v81, v22, v23
	v_cvt_pk_bf16_f32 v80, v20, v21
	s_nop 6
	v_cvt_pk_bf16_f32 v83, v18, v19
	v_cvt_pk_bf16_f32 v82, v16, v17
	v_add_u32_e32 v84, 0xb000, v216
	ds_write2_b64 v84, v[2:3], v[82:83] offset1:4
	s_nop 9
	v_cvt_pk_bf16_f32 v3, v14, v15
	v_cvt_pk_bf16_f32 v2, v12, v13
	v_add_u32_e32 v82, 0xc000, v216
	ds_write2_b64 v82, v[76:77], v[2:3] offset0:32 offset1:36
	s_nop 9
	v_cvt_pk_bf16_f32 v3, v10, v11
	v_cvt_pk_bf16_f32 v2, v8, v9
	v_add_u32_e32 v76, 0xd000, v216
	ds_write2_b64 v76, v[78:79], v[2:3] offset0:64 offset1:68
	s_nop 9
	v_cvt_pk_bf16_f32 v3, v6, v7
	v_cvt_pk_bf16_f32 v2, v4, v5
	v_add_u32_e32 v76, 0xe000, v216
	ds_write2_b64 v76, v[80:81], v[2:3] offset0:96 offset1:100
	v_mov_b32_e32 v2, 0
	v_mov_b32_e32 v3, 0
	s_waitcnt lgkmcnt(0)
	s_barrier
	s_and_saveexec_b64 s[54:55], s[20:21]
	s_cbranch_execz .LBB0_1710
	ds_read_b32 v3, v168
	ds_read_b32 v76, v166
	s_waitcnt lgkmcnt(0)
	v_sub_f32_e32 v3, v3, v76
	v_mul_f32_e32 v3, 0x3fb8aa3b, v3
	v_exp_f32_e32 v3, v3
	s_nop 0
	v_mul_f32_e32 v3, v72, v3
	ds_read_b32 v72, v167
	s_waitcnt lgkmcnt(0)
	v_mul_f32_e32 v3, v72, v3

.LBB0_1740:
	s_or_b64 exec, exec, s[54:55]
	ds_read_b128 v[60:63], v196
	ds_read_b128 v[64:67], v199
	v_bfe_u32 v3, v2, 16, 1
	v_add3_u32 v2, v2, v3, s85
	ds_write_b16_d16_hi v195, v2
	s_waitcnt lgkmcnt(2)
	v_sub_f32_e32 v2, v139, v60
	v_sub_f32_e32 v60, v139, v63
	v_mul_f32_e32 v60, 0x3fb8aa3b, v60
	v_exp_f32_e32 v69, v60
	s_waitcnt lgkmcnt(1)
	v_sub_f32_e32 v60, v139, v64
	v_mul_f32_e32 v60, 0x3fb8aa3b, v60
	v_exp_f32_e32 v70, v60
	v_sub_f32_e32 v60, v139, v65
	v_mul_f32_e32 v60, 0x3fb8aa3b, v60
	v_sub_f32_e32 v3, v139, v61
	v_exp_f32_e32 v72, v60
	v_sub_f32_e32 v60, v139, v66
	v_mul_f32_e32 v3, 0x3fb8aa3b, v3
	v_mul_f32_e32 v60, 0x3fb8aa3b, v60
	v_sub_f32_e32 v64, v139, v67
	v_exp_f32_e32 v68, v3
	v_sub_f32_e32 v3, v139, v62
	v_exp_f32_e32 v71, v60
	ds_read_b128 v[60:63], v198
	v_mul_f32_e32 v64, 0x3fb8aa3b, v64
	v_mul_f32_e32 v2, 0x3fb8aa3b, v2
	v_mul_f32_e32 v3, 0x3fb8aa3b, v3
	v_exp_f32_e32 v73, v64
	ds_read_b128 v[64:67], v197 offset:35840
	v_exp_f32_e32 v2, v2
	v_exp_f32_e32 v3, v3
	s_waitcnt lgkmcnt(1)
	v_mov_b32_e32 v74, v60
	v_mov_b32_e32 v75, v62
	v_mov_b32_e32 v62, v61
	v_pk_mul_f32 v[2:3], v[74:75], v[2:3]
	v_pk_mul_f32 v[60:61], v[62:63], v[68:69]
	s_waitcnt lgkmcnt(0)
	v_lshlrev_b32_e32 v63, 16, v65
	v_lshlrev_b32_e32 v62, 16, v64
	v_pk_mul_f32 v[2:3], v[2:3], v[62:63]
	v_and_b32_e32 v63, 0xffff0000, v65
	v_and_b32_e32 v62, 0xffff0000, v64
	v_pk_mul_f32 v[60:61], v[60:61], v[62:63]
	v_and_b32_sdwa v62, v3, v224 dst_sel:DWORD dst_unused:UNUSED_PAD src0_sel:WORD_1 src1_sel:DWORD
	v_and_b32_sdwa v63, v2, v224 dst_sel:DWORD dst_unused:UNUSED_PAD src0_sel:WORD_1 src1_sel:DWORD
	v_add3_u32 v2, v2, v63, s85
	v_add3_u32 v3, v3, v62, s85
	v_and_b32_sdwa v62, v61, v224 dst_sel:DWORD dst_unused:UNUSED_PAD src0_sel:WORD_1 src1_sel:DWORD
	v_and_b32_sdwa v63, v60, v224 dst_sel:DWORD dst_unused:UNUSED_PAD src0_sel:WORD_1 src1_sel:DWORD
	v_add3_u32 v64, v61, v62, s85
	v_add3_u32 v65, v60, v63, s85
	ds_read_b128 v[60:63], v200
	v_and_b32_e32 v64, 0xffff0000, v64
	v_and_b32_e32 v68, 0xffff0000, v65
	v_or_b32_sdwa v65, v64, v3 dst_sel:DWORD dst_unused:UNUSED_PAD src0_sel:DWORD src1_sel:WORD_1
	v_or_b32_sdwa v64, v68, v2 dst_sel:DWORD dst_unused:UNUSED_PAD src0_sel:DWORD src1_sel:WORD_1
	s_waitcnt lgkmcnt(0)
	v_mov_b32_e32 v2, v60
	v_mov_b32_e32 v3, v62
	v_mov_b32_e32 v62, v61
	v_pk_mul_f32 v[2:3], v[2:3], v[70:71]
	v_pk_mul_f32 v[60:61], v[62:63], v[72:73]
	v_lshlrev_b32_e32 v63, 16, v67
	v_lshlrev_b32_e32 v62, 16, v66
	v_pk_mul_f32 v[2:3], v[2:3], v[62:63]
	v_and_b32_e32 v63, 0xffff0000, v67
	v_and_b32_e32 v62, 0xffff0000, v66
	v_pk_mul_f32 v[60:61], v[60:61], v[62:63]
	s_nop 9
	v_cvt_pk_bf16_f32 v67, v3, v61
	v_cvt_pk_bf16_f32 v66, v2, v60
	ds_write_b128 v197, v[64:67] offset:62464
	ds_read_b128 v[60:63], v196
	ds_read_b128 v[64:67], v199
	v_cmp_gt_i32_e32 vcc, s76, v163
	s_waitcnt lgkmcnt(1)
	v_sub_f32_e32 v2, v139, v60
	v_mul_f32_e32 v2, 0x3fb8aa3b, v2
	v_exp_f32_e32 v68, v2
	v_sub_f32_e32 v2, v139, v61
	v_mul_f32_e32 v2, 0x3fb8aa3b, v2
	v_exp_f32_e32 v70, v2
	v_sub_f32_e32 v2, v139, v62
	v_mul_f32_e32 v2, 0x3fb8aa3b, v2
	v_exp_f32_e32 v69, v2
	v_sub_f32_e32 v2, v139, v63
	v_mul_f32_e32 v2, 0x3fb8aa3b, v2
	v_exp_f32_e32 v71, v2
	s_waitcnt lgkmcnt(0)
	v_sub_f32_e32 v2, v139, v64
	v_sub_f32_e32 v3, v139, v66
	v_mul_f32_e32 v2, 0x3fb8aa3b, v2
	v_mul_f32_e32 v3, 0x3fb8aa3b, v3
	ds_read_b128 v[60:63], v198
	v_exp_f32_e32 v72, v2
	v_sub_f32_e32 v2, v139, v65
	v_exp_f32_e32 v73, v3
	v_sub_f32_e32 v3, v139, v67
	ds_read_b128 v[64:67], v201 offset:35840
	s_waitcnt lgkmcnt(1)
	v_mov_b32_e32 v74, v60
	v_mov_b32_e32 v75, v62
	v_mov_b32_e32 v62, v61
	v_pk_mul_f32 v[68:69], v[74:75], v[68:69]
	v_pk_mul_f32 v[60:61], v[62:63], v[70:71]
	s_waitcnt lgkmcnt(0)
	v_lshlrev_b32_e32 v63, 16, v65
	v_lshlrev_b32_e32 v62, 16, v64
	v_pk_mul_f32 v[62:63], v[68:69], v[62:63]
	v_and_b32_e32 v65, 0xffff0000, v65
	v_and_b32_e32 v64, 0xffff0000, v64
	v_pk_mul_f32 v[60:61], v[60:61], v[64:65]
	v_and_b32_sdwa v64, v63, v224 dst_sel:DWORD dst_unused:UNUSED_PAD src0_sel:WORD_1 src1_sel:DWORD
	v_and_b32_sdwa v65, v62, v224 dst_sel:DWORD dst_unused:UNUSED_PAD src0_sel:WORD_1 src1_sel:DWORD
	v_add3_u32 v68, v62, v65, s85
	v_add3_u32 v64, v63, v64, s85
	v_and_b32_sdwa v62, v61, v224 dst_sel:DWORD dst_unused:UNUSED_PAD src0_sel:WORD_1 src1_sel:DWORD
	v_and_b32_sdwa v63, v60, v224 dst_sel:DWORD dst_unused:UNUSED_PAD src0_sel:WORD_1 src1_sel:DWORD
	v_add3_u32 v65, v61, v62, s85
	v_add3_u32 v69, v60, v63, s85
	ds_read_b128 v[60:63], v200
	v_mul_f32_e32 v2, 0x3fb8aa3b, v2
	v_mul_f32_e32 v3, 0x3fb8aa3b, v3
	v_exp_f32_e32 v2, v2
	v_exp_f32_e32 v3, v3
	v_and_b32_e32 v65, 0xffff0000, v65
	v_and_b32_e32 v69, 0xffff0000, v69
	v_or_b32_sdwa v65, v65, v64 dst_sel:DWORD dst_unused:UNUSED_PAD src0_sel:DWORD src1_sel:WORD_1
	v_or_b32_sdwa v64, v69, v68 dst_sel:DWORD dst_unused:UNUSED_PAD src0_sel:DWORD src1_sel:WORD_1
	s_waitcnt lgkmcnt(0)
	v_mov_b32_e32 v68, v60
	v_mov_b32_e32 v69, v62
	v_pk_mul_f32 v[68:69], v[68:69], v[72:73]
	v_mov_b32_e32 v62, v61
	v_lshlrev_b32_e32 v61, 16, v67
	v_lshlrev_b32_e32 v60, 16, v66
	v_pk_mul_f32 v[2:3], v[62:63], v[2:3]
	v_pk_mul_f32 v[60:61], v[68:69], v[60:61]
	v_and_b32_e32 v63, 0xffff0000, v67
	v_and_b32_e32 v62, 0xffff0000, v66
	v_pk_mul_f32 v[2:3], v[2:3], v[62:63]
	s_nop 9
	v_cvt_pk_bf16_f32 v67, v61, v3
	v_cvt_pk_bf16_f32 v66, v60, v2
	ds_write_b128 v201, v[64:67] offset:62464
	s_waitcnt lgkmcnt(0)
	s_barrier
	ds_read_b128 v[60:63], v164
	ds_read_b128 v[64:67], v102 offset:35840
	ds_read_b128 v[68:71], v102 offset:38144
	ds_read_b128 v[72:75], v102 offset:40448
	ds_read_b128 v[76:79], v102 offset:42752
	ds_read_b128 v[88:91], v164 offset:64
	s_waitcnt lgkmcnt(2)
	v_mfma_f32_16x16x32_bf16 v[84:87], v[60:63], v[72:75], 0
	ds_read_b128 v[72:75], v102 offset:35904
	v_mfma_f32_16x16x32_bf16 v[64:67], v[60:63], v[64:67], 0
	s_waitcnt lgkmcnt(0)
	v_mfma_f32_16x16x32_bf16 v[80:83], v[88:91], v[72:75], v[64:67]
	v_mfma_f32_16x16x32_bf16 v[68:71], v[60:63], v[68:71], 0
	s_nop 4
	ds_read_b128 v[64:67], v102 offset:38208
	v_mfma_f32_16x16x32_bf16 v[60:63], v[60:63], v[76:79], 0
	s_waitcnt lgkmcnt(0)
	v_mfma_f32_16x16x32_bf16 v[72:75], v[88:91], v[64:67], v[68:71]
	ds_read_b128 v[64:67], v102 offset:40512
	ds_read_b128 v[76:79], v102 offset:42816
	s_waitcnt lgkmcnt(1)
	v_mfma_f32_16x16x32_bf16 v[68:71], v[88:91], v[64:67], v[84:87]
	ds_read_b128 v[64:67], v157
	s_nop 1
	ds_read_b128 v[84:87], v158 offset:49408
	s_waitcnt lgkmcnt(2)
	v_mfma_f32_16x16x32_bf16 v[60:63], v[88:91], v[76:79], v[60:63]
	ds_read_b128 v[76:79], v158 offset:45056
	ds_read_b128 v[88:91], v158 offset:53760
	ds_read_b128 v[92:95], v158 offset:58112
	ds_read_b128 v[228:231], v157 offset:64
	s_waitcnt lgkmcnt(3)
	v_mfma_f32_16x16x32_bf16 v[76:79], v[64:67], v[76:79], 0
	v_mfma_f32_16x16x32_bf16 v[84:87], v[64:67], v[84:87], 0
	s_waitcnt lgkmcnt(2)
	v_mfma_f32_16x16x32_bf16 v[88:91], v[64:67], v[88:91], 0
	s_waitcnt lgkmcnt(1)
	v_mfma_f32_16x16x32_bf16 v[64:67], v[64:67], v[92:95], 0
	ds_read_b128 v[92:95], v158 offset:45120
	s_waitcnt lgkmcnt(0)
	v_mfma_f32_16x16x32_bf16 v[76:79], v[228:231], v[92:95], v[76:79]
	ds_read_b128 v[92:95], v158 offset:49472
	s_waitcnt lgkmcnt(0)
	v_mfma_f32_16x16x32_bf16 v[84:87], v[228:231], v[92:95], v[84:87]
	ds_read_b128 v[92:95], v158 offset:53824
	ds_read_b128 v[232:235], v158 offset:58176
	s_waitcnt lgkmcnt(1)
	v_mfma_f32_16x16x32_bf16 v[88:91], v[228:231], v[92:95], v[88:91]
	ds_read_b128 v[92:95], v157 offset:128
	s_waitcnt lgkmcnt(1)
	v_mfma_f32_16x16x32_bf16 v[64:67], v[228:231], v[232:235], v[64:67]
	ds_read_b128 v[228:231], v158 offset:45184
	s_waitcnt lgkmcnt(0)
	v_mfma_f32_16x16x32_bf16 v[76:79], v[92:95], v[228:231], v[76:79]
	ds_read_b128 v[228:231], v158 offset:49536
	s_waitcnt lgkmcnt(0)
	v_mfma_f32_16x16x32_bf16 v[84:87], v[92:95], v[228:231], v[84:87]
	ds_read_b128 v[228:231], v158 offset:53888
	ds_read_b128 v[232:235], v158 offset:58240
	ds_read_b128 v[236:239], v157 offset:192
	s_waitcnt lgkmcnt(2)
	v_mfma_f32_16x16x32_bf16 v[228:231], v[92:95], v[228:231], v[88:91]
	s_nop 2
	ds_read_b128 v[88:91], v158 offset:45248
	s_waitcnt lgkmcnt(0)
	v_mfma_f32_16x16x32_bf16 v[88:91], v[236:239], v[88:91], v[76:79]
	s_nop 2
	ds_read_b128 v[76:79], v158 offset:49600
	v_mfma_f32_16x16x32_bf16 v[64:67], v[92:95], v[232:235], v[64:67]
	s_waitcnt lgkmcnt(0)
	v_mfma_f32_16x16x32_bf16 v[84:87], v[236:239], v[76:79], v[84:87]
	ds_read_b128 v[76:79], v158 offset:53952
	ds_read_b128 v[232:235], v158 offset:58304
	ds_read_b128 v[92:95], v220
	ds_read_b64 v[154:155], v225 offset:35840
	s_waitcnt lgkmcnt(3)
	v_mfma_f32_16x16x32_bf16 v[76:79], v[236:239], v[76:79], v[228:231]
	s_waitcnt lgkmcnt(1)
	v_mul_f32_e32 v2, 0x3fb8aa3b, v92
	s_nop 0
	v_exp_f32_e32 v231, v2
	v_mfma_f32_16x16x32_bf16 v[64:67], v[236:239], v[232:235], v[64:67]
	v_add_u32_e32 v2, s77, v163
	v_mov_b32_e32 v228, 0
	v_ashrrev_i32_e32 v3, 31, v2
	v_mov_b32_e32 v229, 0
	s_and_saveexec_b64 s[54:55], vcc
	s_cbranch_execz .LBB0_1742
	v_lshlrev_b64 v[232:233], 12, v[2:3]
	v_lshl_add_u64 v[232:233], v[152:153], 0, v[232:233]
	global_load_ushort v92, v[232:233], off
	s_waitcnt lgkmcnt(0)
	v_lshlrev_b32_e32 v234, 16, v154
	v_fma_f32 v80, v88, v231, v80
	s_waitcnt vmcnt(0)
	v_lshlrev_b32_e32 v235, 16, v92
	v_mul_f32_e32 v92, 0xbfb8aa3b, v235
	v_exp_f32_e32 v92, v92
	s_nop 0
	v_add_f32_e32 v92, 1.0, v92
	v_rcp_f32_e32 v149, v92
	s_nop 0
	v_pk_mul_f32 v[234:235], v[148:149], v[234:235]
	s_nop 0
	v_add_f32_e32 v80, v80, v234
	v_mul_f32_e32 v80, v80, v235
	v_bfe_u32 v88, v80, 16, 1
	v_add3_u32 v88, v80, v88, s85
	v_mul_f32_e32 v229, v80, v80
	global_store_short_d16_hi v[232:233], v88, off

.LBB0_1945:
	s_add_i32 s51, s50, 2
	s_mul_hi_i32 s52, s51, 0x55555556
	s_lshr_b32 s53, s52, 31
	s_add_i32 s52, s52, s53
	s_mul_i32 s52, s52, 3
	s_sub_i32 s51, s51, s52
	s_mulk_i32 s51, 0x6000
	s_mul_i32 s54, s50, 0x6000
	v_readfirstlane_b32 s55, v140
	v_lshl_add_u64 v[232:233], v[132:133], 0, s[0:1]
	v_lshl_add_u64 v[234:235], v[130:131], 0, s[0:1]
	s_add_u32 s55, s55, s51
	s_waitcnt vmcnt(6) lgkmcnt(0)
	s_barrier
	s_setprio 1
	s_mov_b32 m0, s55
	v_lshl_add_u64 v[236:237], v[232:233], 0, s[20:21]
	global_load_lds_dwordx4 v[236:237], off
	s_add_u32 m0, s55, 0x1000
	v_lshl_add_u64 v[236:237], v[232:233], 0, s[22:23]
	global_load_lds_dwordx4 v[236:237], off
	s_add_u32 m0, s55, 0x2000
	v_lshl_add_u64 v[236:237], v[232:233], 0, s[24:25]
	global_load_lds_dwordx4 v[236:237], off
	s_add_u32 m0, s55, 0x3000
	v_lshl_add_u64 v[236:237], v[232:233], 0, s[26:27]
	global_load_lds_dwordx4 v[236:237], off
	s_add_u32 m0, s55, 0x4000
	v_lshl_add_u64 v[236:237], v[234:235], 0, s[28:29]
	global_load_lds_dwordx4 v[236:237], off
	s_add_u32 m0, s55, 0x5000
	v_lshl_add_u64 v[236:237], v[234:235], 0, s[30:31]
	global_load_lds_dwordx4 v[236:237], off
	v_or_b32_e32 v128, s54, v139
	v_add3_u32 v128, v128, v137, v138
	ds_read_b128 v[176:179], v128 offset:16384
	ds_read_b128 v[180:183], v128 offset:17408
	ds_read_b128 v[184:187], v128 offset:18432
	ds_read_b128 v[192:195], v128 offset:19456
	v_add_u32_e32 v128, s54, v141
	v_add3_u32 v128, v128, v137, v138
	ds_read_b128 v[144:147], v128
	ds_read_b128 v[148:151], v128 offset:1024
	ds_read_b128 v[152:155], v128 offset:2048
	ds_read_b128 v[156:159], v128 offset:3072
	ds_read_b128 v[160:163], v128 offset:4096
	ds_read_b128 v[164:167], v128 offset:5120
	ds_read_b128 v[168:171], v128 offset:6144
	ds_read_b128 v[172:175], v128 offset:7168
	s_setprio 0
	s_waitcnt lgkmcnt(7)
	v_mfma_f32_16x16x32_bf16 v[124:127], v[144:147], v[176:179], v[124:127]
	v_mfma_f32_16x16x32_bf16 v[120:123], v[144:147], v[180:183], v[120:123]
	v_mfma_f32_16x16x32_bf16 v[116:119], v[144:147], v[184:187], v[116:119]
	v_mfma_f32_16x16x32_bf16 v[112:115], v[144:147], v[192:195], v[112:115]
	s_waitcnt lgkmcnt(6)
	v_mfma_f32_16x16x32_bf16 v[108:111], v[148:151], v[176:179], v[108:111]
	v_mfma_f32_16x16x32_bf16 v[104:107], v[148:151], v[180:183], v[104:107]
	v_mfma_f32_16x16x32_bf16 v[100:103], v[148:151], v[184:187], v[100:103]
	v_mfma_f32_16x16x32_bf16 v[96:99], v[148:151], v[192:195], v[96:99]
	s_waitcnt lgkmcnt(5)
	v_mfma_f32_16x16x32_bf16 v[92:95], v[152:155], v[176:179], v[92:95]
	v_mfma_f32_16x16x32_bf16 v[88:91], v[152:155], v[180:183], v[88:91]
	v_mfma_f32_16x16x32_bf16 v[84:87], v[152:155], v[184:187], v[84:87]
	v_mfma_f32_16x16x32_bf16 v[80:83], v[152:155], v[192:195], v[80:83]
	s_waitcnt lgkmcnt(4)
	v_mfma_f32_16x16x32_bf16 v[76:79], v[156:159], v[176:179], v[76:79]
	v_mfma_f32_16x16x32_bf16 v[72:75], v[156:159], v[180:183], v[72:75]
	v_mfma_f32_16x16x32_bf16 v[68:71], v[156:159], v[184:187], v[68:71]
	v_mfma_f32_16x16x32_bf16 v[64:67], v[156:159], v[192:195], v[64:67]
	s_waitcnt lgkmcnt(3)
	v_mfma_f32_16x16x32_bf16 v[60:63], v[160:163], v[176:179], v[60:63]
	v_mfma_f32_16x16x32_bf16 v[56:59], v[160:163], v[180:183], v[56:59]
	v_mfma_f32_16x16x32_bf16 v[52:55], v[160:163], v[184:187], v[52:55]
	v_mfma_f32_16x16x32_bf16 v[48:51], v[160:163], v[192:195], v[48:51]
	s_waitcnt lgkmcnt(2)
	v_mfma_f32_16x16x32_bf16 v[44:47], v[164:167], v[176:179], v[44:47]
	v_mfma_f32_16x16x32_bf16 v[40:43], v[164:167], v[180:183], v[40:43]
	v_mfma_f32_16x16x32_bf16 v[36:39], v[164:167], v[184:187], v[36:39]
	v_mfma_f32_16x16x32_bf16 v[32:35], v[164:167], v[192:195], v[32:35]
	s_waitcnt lgkmcnt(1)
	v_mfma_f32_16x16x32_bf16 v[28:31], v[168:171], v[176:179], v[28:31]
	v_mfma_f32_16x16x32_bf16 v[24:27], v[168:171], v[180:183], v[24:27]
	v_mfma_f32_16x16x32_bf16 v[20:23], v[168:171], v[184:187], v[20:23]
	v_mfma_f32_16x16x32_bf16 v[16:19], v[168:171], v[192:195], v[16:19]
	s_waitcnt lgkmcnt(0)
	v_mfma_f32_16x16x32_bf16 v[12:15], v[172:175], v[176:179], v[12:15]
	v_mfma_f32_16x16x32_bf16 v[8:11], v[172:175], v[180:183], v[8:11]
	v_mfma_f32_16x16x32_bf16 v[4:7], v[172:175], v[184:187], v[4:7]
	v_mfma_f32_16x16x32_bf16 v[0:3], v[172:175], v[192:195], v[0:3]
	s_add_i32 s51, s50, 1
	s_cmp_lg_u32 s50, 2
	s_cselect_b32 s50, s51, 0
	s_add_u32 s0, s0, 0x80
	s_addc_u32 s1, s1, 0
	s_cmpk_lg_i32 s0, 0xf00
	s_cbranch_scc1 .LBB0_1945
	s_waitcnt vmcnt(6) lgkmcnt(0)
	s_barrier
	v_add3_u32 v128, v141, v137, v138
	ds_read_b128 v[130:133], v128
	ds_read_b128 v[144:147], v128 offset:1024
	ds_read_b128 v[148:151], v128 offset:2048
	ds_read_b128 v[152:155], v128 offset:3072
	ds_read_b128 v[156:159], v128 offset:4096
	ds_read_b128 v[160:163], v128 offset:5120
	ds_read_b128 v[164:167], v128 offset:6144
	ds_read_b128 v[168:171], v128 offset:7168
	v_add3_u32 v137, v139, v137, v138
	ds_read_b128 v[138:141], v137 offset:16384
	ds_read_b128 v[172:175], v137 offset:17408
	ds_read_b128 v[176:179], v137 offset:18432
	ds_read_b128 v[180:183], v137 offset:19456
	s_setprio 1
	s_waitcnt lgkmcnt(0)
	v_mfma_f32_16x16x32_bf16 v[124:127], v[130:133], v[138:141], v[124:127]
	v_mfma_f32_16x16x32_bf16 v[120:123], v[130:133], v[172:175], v[120:123]
	v_mfma_f32_16x16x32_bf16 v[116:119], v[130:133], v[176:179], v[116:119]
	v_mfma_f32_16x16x32_bf16 v[112:115], v[130:133], v[180:183], v[112:115]
	v_mfma_f32_16x16x32_bf16 v[108:111], v[144:147], v[138:141], v[108:111]
	v_mfma_f32_16x16x32_bf16 v[104:107], v[144:147], v[172:175], v[104:107]
	v_mfma_f32_16x16x32_bf16 v[100:103], v[144:147], v[176:179], v[100:103]
	v_mfma_f32_16x16x32_bf16 v[96:99], v[144:147], v[180:183], v[96:99]
	v_mfma_f32_16x16x32_bf16 v[92:95], v[148:151], v[138:141], v[92:95]
	v_mfma_f32_16x16x32_bf16 v[88:91], v[148:151], v[172:175], v[88:91]
	v_mfma_f32_16x16x32_bf16 v[84:87], v[148:151], v[176:179], v[84:87]
	v_mfma_f32_16x16x32_bf16 v[80:83], v[148:151], v[180:183], v[80:83]
	v_mfma_f32_16x16x32_bf16 v[76:79], v[152:155], v[138:141], v[76:79]
	v_mfma_f32_16x16x32_bf16 v[72:75], v[152:155], v[172:175], v[72:75]
	v_mfma_f32_16x16x32_bf16 v[68:71], v[152:155], v[176:179], v[68:71]
	v_mfma_f32_16x16x32_bf16 v[64:67], v[152:155], v[180:183], v[64:67]
	v_mfma_f32_16x16x32_bf16 v[60:63], v[156:159], v[138:141], v[60:63]
	v_mfma_f32_16x16x32_bf16 v[56:59], v[156:159], v[172:175], v[56:59]
	v_mfma_f32_16x16x32_bf16 v[52:55], v[156:159], v[176:179], v[52:55]
	v_mfma_f32_16x16x32_bf16 v[48:51], v[156:159], v[180:183], v[48:51]
	v_mfma_f32_16x16x32_bf16 v[44:47], v[160:163], v[138:141], v[44:47]
	v_mfma_f32_16x16x32_bf16 v[40:43], v[160:163], v[172:175], v[40:43]
	v_mfma_f32_16x16x32_bf16 v[36:39], v[160:163], v[176:179], v[36:39]
	v_mfma_f32_16x16x32_bf16 v[32:35], v[160:163], v[180:183], v[32:35]
	v_mfma_f32_16x16x32_bf16 v[28:31], v[164:167], v[138:141], v[28:31]
	v_mfma_f32_16x16x32_bf16 v[24:27], v[164:167], v[172:175], v[24:27]
	v_mfma_f32_16x16x32_bf16 v[20:23], v[164:167], v[176:179], v[20:23]
	v_mfma_f32_16x16x32_bf16 v[16:19], v[164:167], v[180:183], v[16:19]
	v_mfma_f32_16x16x32_bf16 v[12:15], v[168:171], v[138:141], v[12:15]
	v_mfma_f32_16x16x32_bf16 v[8:11], v[168:171], v[172:175], v[8:11]
	v_mfma_f32_16x16x32_bf16 v[4:7], v[168:171], v[176:179], v[4:7]
	v_mfma_f32_16x16x32_bf16 v[0:3], v[168:171], v[180:183], v[0:3]
	s_setprio 0
	s_waitcnt vmcnt(0) lgkmcnt(0)
	s_barrier
	ds_read_b128 v[130:133], v128 offset:24576
	ds_read_b128 v[138:141], v128 offset:25600
	ds_read_b128 v[144:147], v128 offset:26624
	ds_read_b128 v[148:151], v128 offset:27648
	ds_read_b128 v[152:155], v128 offset:28672
	ds_read_b128 v[156:159], v128 offset:29696
	ds_read_b128 v[160:163], v128 offset:30720
	ds_read_b128 v[164:167], v128 offset:31744
	ds_read_b128 v[168:171], v137 offset:40960
	ds_read_b128 v[172:175], v137 offset:41984
	ds_read_b128 v[176:179], v137 offset:43008
	ds_read_b128 v[180:183], v137 offset:44032
	s_setprio 1
	s_waitcnt lgkmcnt(0)
	v_mfma_f32_16x16x32_bf16 v[124:127], v[130:133], v[168:171], v[124:127]
	v_mfma_f32_16x16x32_bf16 v[120:123], v[130:133], v[172:175], v[120:123]
	v_mfma_f32_16x16x32_bf16 v[116:119], v[130:133], v[176:179], v[116:119]
	v_mfma_f32_16x16x32_bf16 v[112:115], v[130:133], v[180:183], v[112:115]
	v_mfma_f32_16x16x32_bf16 v[108:111], v[138:141], v[168:171], v[108:111]
	v_mfma_f32_16x16x32_bf16 v[104:107], v[138:141], v[172:175], v[104:107]
	v_mfma_f32_16x16x32_bf16 v[100:103], v[138:141], v[176:179], v[100:103]
	v_mfma_f32_16x16x32_bf16 v[96:99], v[138:141], v[180:183], v[96:99]
	v_mfma_f32_16x16x32_bf16 v[92:95], v[144:147], v[168:171], v[92:95]
	v_mfma_f32_16x16x32_bf16 v[88:91], v[144:147], v[172:175], v[88:91]
	v_mfma_f32_16x16x32_bf16 v[84:87], v[144:147], v[176:179], v[84:87]
	v_mfma_f32_16x16x32_bf16 v[130:133], v[144:147], v[180:183], v[80:83]
	v_mfma_f32_16x16x32_bf16 v[138:141], v[148:151], v[168:171], v[76:79]
	v_mfma_f32_16x16x32_bf16 v[72:75], v[148:151], v[172:175], v[72:75]
	v_mfma_f32_16x16x32_bf16 v[68:71], v[148:151], v[176:179], v[68:71]
	v_mfma_f32_16x16x32_bf16 v[64:67], v[148:151], v[180:183], v[64:67]
	v_mfma_f32_16x16x32_bf16 v[60:63], v[152:155], v[168:171], v[60:63]
	v_mfma_f32_16x16x32_bf16 v[56:59], v[152:155], v[172:175], v[56:59]
	v_mfma_f32_16x16x32_bf16 v[52:55], v[152:155], v[176:179], v[52:55]
	v_mfma_f32_16x16x32_bf16 v[48:51], v[152:155], v[180:183], v[48:51]
	v_mfma_f32_16x16x32_bf16 v[44:47], v[156:159], v[168:171], v[44:47]
	v_mfma_f32_16x16x32_bf16 v[40:43], v[156:159], v[172:175], v[40:43]
	v_mfma_f32_16x16x32_bf16 v[36:39], v[156:159], v[176:179], v[36:39]
	v_mfma_f32_16x16x32_bf16 v[32:35], v[156:159], v[180:183], v[32:35]
	v_mfma_f32_16x16x32_bf16 v[28:31], v[160:163], v[168:171], v[28:31]
	v_mfma_f32_16x16x32_bf16 v[24:27], v[160:163], v[172:175], v[24:27]
	v_mfma_f32_16x16x32_bf16 v[20:23], v[160:163], v[176:179], v[20:23]
	v_mfma_f32_16x16x32_bf16 v[16:19], v[160:163], v[180:183], v[16:19]
	v_mfma_f32_16x16x32_bf16 v[12:15], v[164:167], v[168:171], v[12:15]
	v_mfma_f32_16x16x32_bf16 v[8:11], v[164:167], v[172:175], v[8:11]
	v_mfma_f32_16x16x32_bf16 v[4:7], v[164:167], v[176:179], v[4:7]
	v_mfma_f32_16x16x32_bf16 v[0:3], v[164:167], v[180:183], v[0:3]
	s_setprio 0
	v_and_b32_e32 v76, 0xffffff80, v134
	v_add_u32_e32 v76, s41, v76
	v_lshlrev_b32_e32 v77, 6, v136
	s_add_i32 s0, s4, 0xfffffc00
	v_ashrrev_i32_e32 v76, 6, v76
	v_or3_b32 v136, v77, s0, v135
	v_ashrrev_i32_e32 v77, 31, v76
	v_lshlrev_b64 v[78:79], 17, v[76:77]
	v_readlane_b32 s0, v254, 60
	v_lshrrev_b32_e32 v77, 1, v134
	s_nop 1
	v_readlane_b32 s1, v254, 61
	v_and_b32_e32 v128, 24, v77
	s_nop 3
	v_lshl_add_u64 v[78:79], s[0:1], 0, v[78:79]
	v_mov_b32_e32 v137, v129
	s_nop 4
	v_lshl_add_u64 v[134:135], v[78:79], 0, v[128:129]
	v_lshlrev_b64 v[78:79], 7, v[136:137]
	v_cvt_pk_bf16_f32 v81, v126, v127
	v_cvt_pk_bf16_f32 v80, v124, v125
	s_nop 2
	v_lshl_add_u64 v[144:145], v[134:135], 0, v[78:79]
	s_nop 3
	global_store_dwordx2 v[144:145], v[80:81], off
	v_or_b32_e32 v80, 16, v136
	v_mov_b32_e32 v81, v129
	s_nop 0
	v_cvt_pk_bf16_f32 v83, v122, v123
	v_and_b32_sdwa v77, v118, v142 dst_sel:DWORD dst_unused:UNUSED_PAD src0_sel:WORD_1 src1_sel:DWORD
	v_lshlrev_b64 v[80:81], 7, v[80:81]
	s_nop 0
	v_and_b32_sdwa v122, v116, v142 dst_sel:DWORD dst_unused:UNUSED_PAD src0_sel:WORD_1 src1_sel:DWORD
	v_add3_u32 v77, v118, v77, s46
	v_and_b32_sdwa v118, v119, v142 dst_sel:DWORD dst_unused:UNUSED_PAD src0_sel:WORD_1 src1_sel:DWORD
	v_lshl_add_u64 v[124:125], v[134:135], 0, v[80:81]
	v_cvt_pk_bf16_f32 v82, v120, v121
	v_add3_u32 v116, v116, v122, s46
	v_and_b32_sdwa v122, v117, v142 dst_sel:DWORD dst_unused:UNUSED_PAD src0_sel:WORD_1 src1_sel:DWORD
	v_add3_u32 v118, v119, v118, s46
	global_store_dwordx2 v[124:125], v[82:83], off
	v_or_b32_e32 v82, 32, v136
	v_mov_b32_e32 v83, v129
	v_add3_u32 v117, v117, v122, s46
	v_and_b32_e32 v118, 0xffff0000, v118
	v_lshlrev_b64 v[82:83], 7, v[82:83]
	v_and_b32_e32 v119, 0xffff0000, v117
	v_or_b32_sdwa v117, v118, v77 dst_sel:DWORD dst_unused:UNUSED_PAD src0_sel:DWORD src1_sel:WORD_1
	v_and_b32_sdwa v77, v114, v142 dst_sel:DWORD dst_unused:UNUSED_PAD src0_sel:WORD_1 src1_sel:DWORD
	v_and_b32_sdwa v122, v112, v142 dst_sel:DWORD dst_unused:UNUSED_PAD src0_sel:WORD_1 src1_sel:DWORD
	v_lshl_add_u64 v[120:121], v[134:135], 0, v[82:83]
	v_or_b32_sdwa v116, v119, v116 dst_sel:DWORD dst_unused:UNUSED_PAD src0_sel:DWORD src1_sel:WORD_1
	v_add3_u32 v112, v112, v122, s46
	v_add3_u32 v77, v114, v77, s46
	v_and_b32_sdwa v114, v115, v142 dst_sel:DWORD dst_unused:UNUSED_PAD src0_sel:WORD_1 src1_sel:DWORD
	v_and_b32_sdwa v122, v113, v142 dst_sel:DWORD dst_unused:UNUSED_PAD src0_sel:WORD_1 src1_sel:DWORD
	global_store_dwordx2 v[120:121], v[116:117], off
	v_or_b32_e32 v116, 48, v136
	v_mov_b32_e32 v117, v129
	v_add3_u32 v114, v115, v114, s46
	v_add3_u32 v113, v113, v122, s46
	v_lshlrev_b64 v[116:117], 7, v[116:117]
	v_and_b32_e32 v114, 0xffff0000, v114
	v_and_b32_e32 v115, 0xffff0000, v113
	v_lshl_add_u64 v[118:119], v[134:135], 0, v[116:117]
	v_or_b32_sdwa v113, v114, v77 dst_sel:DWORD dst_unused:UNUSED_PAD src0_sel:DWORD src1_sel:WORD_1
	v_or_b32_sdwa v112, v115, v112 dst_sel:DWORD dst_unused:UNUSED_PAD src0_sel:DWORD src1_sel:WORD_1
	global_store_dwordx2 v[118:119], v[112:113], off
	v_and_b32_sdwa v77, v110, v142 dst_sel:DWORD dst_unused:UNUSED_PAD src0_sel:WORD_1 src1_sel:DWORD
	v_and_b32_sdwa v112, v108, v142 dst_sel:DWORD dst_unused:UNUSED_PAD src0_sel:WORD_1 src1_sel:DWORD
	v_add3_u32 v108, v108, v112, s46
	v_add3_u32 v77, v110, v77, s46
	v_and_b32_sdwa v110, v111, v142 dst_sel:DWORD dst_unused:UNUSED_PAD src0_sel:WORD_1 src1_sel:DWORD
	v_and_b32_sdwa v112, v109, v142 dst_sel:DWORD dst_unused:UNUSED_PAD src0_sel:WORD_1 src1_sel:DWORD
	v_add3_u32 v110, v111, v110, s46
	v_add3_u32 v109, v109, v112, s46
	v_and_b32_e32 v110, 0xffff0000, v110
	v_and_b32_e32 v111, 0xffff0000, v109
	v_or_b32_sdwa v109, v110, v77 dst_sel:DWORD dst_unused:UNUSED_PAD src0_sel:DWORD src1_sel:WORD_1
	v_or_b32_sdwa v108, v111, v108 dst_sel:DWORD dst_unused:UNUSED_PAD src0_sel:DWORD src1_sel:WORD_1
	global_store_dwordx2 v[144:145], v[108:109], off offset:32
	v_and_b32_sdwa v77, v106, v142 dst_sel:DWORD dst_unused:UNUSED_PAD src0_sel:WORD_1 src1_sel:DWORD
	v_and_b32_sdwa v108, v104, v142 dst_sel:DWORD dst_unused:UNUSED_PAD src0_sel:WORD_1 src1_sel:DWORD
	v_add3_u32 v104, v104, v108, s46
	v_add3_u32 v77, v106, v77, s46
	v_and_b32_sdwa v106, v107, v142 dst_sel:DWORD dst_unused:UNUSED_PAD src0_sel:WORD_1 src1_sel:DWORD
	v_and_b32_sdwa v108, v105, v142 dst_sel:DWORD dst_unused:UNUSED_PAD src0_sel:WORD_1 src1_sel:DWORD
	v_add3_u32 v106, v107, v106, s46
	v_add3_u32 v105, v105, v108, s46
	v_and_b32_e32 v106, 0xffff0000, v106
	v_and_b32_e32 v107, 0xffff0000, v105
	v_or_b32_sdwa v105, v106, v77 dst_sel:DWORD dst_unused:UNUSED_PAD src0_sel:DWORD src1_sel:WORD_1
	v_or_b32_sdwa v104, v107, v104 dst_sel:DWORD dst_unused:UNUSED_PAD src0_sel:DWORD src1_sel:WORD_1
	global_store_dwordx2 v[124:125], v[104:105], off offset:32
	v_and_b32_sdwa v77, v102, v142 dst_sel:DWORD dst_unused:UNUSED_PAD src0_sel:WORD_1 src1_sel:DWORD
	v_and_b32_sdwa v104, v100, v142 dst_sel:DWORD dst_unused:UNUSED_PAD src0_sel:WORD_1 src1_sel:DWORD
	v_add3_u32 v100, v100, v104, s46
	v_add3_u32 v77, v102, v77, s46
	v_and_b32_sdwa v102, v103, v142 dst_sel:DWORD dst_unused:UNUSED_PAD src0_sel:WORD_1 src1_sel:DWORD
	v_and_b32_sdwa v104, v101, v142 dst_sel:DWORD dst_unused:UNUSED_PAD src0_sel:WORD_1 src1_sel:DWORD
	v_add3_u32 v102, v103, v102, s46
	v_add3_u32 v101, v101, v104, s46
	v_and_b32_e32 v102, 0xffff0000, v102
	v_and_b32_e32 v103, 0xffff0000, v101
	v_or_b32_sdwa v101, v102, v77 dst_sel:DWORD dst_unused:UNUSED_PAD src0_sel:DWORD src1_sel:WORD_1
	v_or_b32_sdwa v100, v103, v100 dst_sel:DWORD dst_unused:UNUSED_PAD src0_sel:DWORD src1_sel:WORD_1
	global_store_dwordx2 v[120:121], v[100:101], off offset:32
	v_and_b32_sdwa v77, v98, v142 dst_sel:DWORD dst_unused:UNUSED_PAD src0_sel:WORD_1 src1_sel:DWORD
	v_and_b32_sdwa v100, v96, v142 dst_sel:DWORD dst_unused:UNUSED_PAD src0_sel:WORD_1 src1_sel:DWORD
	v_add3_u32 v96, v96, v100, s46
	v_add3_u32 v77, v98, v77, s46
	v_and_b32_sdwa v98, v99, v142 dst_sel:DWORD dst_unused:UNUSED_PAD src0_sel:WORD_1 src1_sel:DWORD
	v_and_b32_sdwa v100, v97, v142 dst_sel:DWORD dst_unused:UNUSED_PAD src0_sel:WORD_1 src1_sel:DWORD
	v_add3_u32 v98, v99, v98, s46
	v_add3_u32 v97, v97, v100, s46
	v_and_b32_e32 v98, 0xffff0000, v98
	v_and_b32_e32 v99, 0xffff0000, v97
	v_or_b32_sdwa v97, v98, v77 dst_sel:DWORD dst_unused:UNUSED_PAD src0_sel:DWORD src1_sel:WORD_1
	v_or_b32_sdwa v96, v99, v96 dst_sel:DWORD dst_unused:UNUSED_PAD src0_sel:DWORD src1_sel:WORD_1
	global_store_dwordx2 v[118:119], v[96:97], off offset:32
	v_and_b32_sdwa v77, v94, v142 dst_sel:DWORD dst_unused:UNUSED_PAD src0_sel:WORD_1 src1_sel:DWORD
	v_and_b32_sdwa v96, v92, v142 dst_sel:DWORD dst_unused:UNUSED_PAD src0_sel:WORD_1 src1_sel:DWORD
	v_add3_u32 v92, v92, v96, s46
	v_add3_u32 v77, v94, v77, s46
	v_and_b32_sdwa v94, v95, v142 dst_sel:DWORD dst_unused:UNUSED_PAD src0_sel:WORD_1 src1_sel:DWORD
	v_and_b32_sdwa v96, v93, v142 dst_sel:DWORD dst_unused:UNUSED_PAD src0_sel:WORD_1 src1_sel:DWORD
	v_add3_u32 v94, v95, v94, s46
	v_add3_u32 v93, v93, v96, s46
	v_and_b32_e32 v94, 0xffff0000, v94
	v_and_b32_e32 v95, 0xffff0000, v93
	v_or_b32_sdwa v93, v94, v77 dst_sel:DWORD dst_unused:UNUSED_PAD src0_sel:DWORD src1_sel:WORD_1
	v_or_b32_sdwa v92, v95, v92 dst_sel:DWORD dst_unused:UNUSED_PAD src0_sel:DWORD src1_sel:WORD_1
	global_store_dwordx2 v[144:145], v[92:93], off offset:64
	v_and_b32_sdwa v77, v90, v142 dst_sel:DWORD dst_unused:UNUSED_PAD src0_sel:WORD_1 src1_sel:DWORD
	v_and_b32_sdwa v92, v88, v142 dst_sel:DWORD dst_unused:UNUSED_PAD src0_sel:WORD_1 src1_sel:DWORD
	v_add3_u32 v88, v88, v92, s46
	v_add3_u32 v77, v90, v77, s46
	v_and_b32_sdwa v90, v91, v142 dst_sel:DWORD dst_unused:UNUSED_PAD src0_sel:WORD_1 src1_sel:DWORD
	v_and_b32_sdwa v92, v89, v142 dst_sel:DWORD dst_unused:UNUSED_PAD src0_sel:WORD_1 src1_sel:DWORD
	v_add3_u32 v90, v91, v90, s46
	v_add3_u32 v89, v89, v92, s46
	v_and_b32_e32 v90, 0xffff0000, v90
	v_and_b32_e32 v91, 0xffff0000, v89
	v_or_b32_sdwa v89, v90, v77 dst_sel:DWORD dst_unused:UNUSED_PAD src0_sel:DWORD src1_sel:WORD_1
	v_or_b32_sdwa v88, v91, v88 dst_sel:DWORD dst_unused:UNUSED_PAD src0_sel:DWORD src1_sel:WORD_1
	global_store_dwordx2 v[124:125], v[88:89], off offset:64
	v_and_b32_sdwa v77, v86, v142 dst_sel:DWORD dst_unused:UNUSED_PAD src0_sel:WORD_1 src1_sel:DWORD
	v_and_b32_sdwa v88, v84, v142 dst_sel:DWORD dst_unused:UNUSED_PAD src0_sel:WORD_1 src1_sel:DWORD
	v_add3_u32 v84, v84, v88, s46
	v_add3_u32 v77, v86, v77, s46
	v_and_b32_sdwa v86, v87, v142 dst_sel:DWORD dst_unused:UNUSED_PAD src0_sel:WORD_1 src1_sel:DWORD
	v_and_b32_sdwa v88, v85, v142 dst_sel:DWORD dst_unused:UNUSED_PAD src0_sel:WORD_1 src1_sel:DWORD
	v_add3_u32 v86, v87, v86, s46
	v_add3_u32 v85, v85, v88, s46
	v_and_b32_e32 v86, 0xffff0000, v86
	v_and_b32_e32 v87, 0xffff0000, v85
	v_or_b32_sdwa v85, v86, v77 dst_sel:DWORD dst_unused:UNUSED_PAD src0_sel:DWORD src1_sel:WORD_1
	v_or_b32_sdwa v84, v87, v84 dst_sel:DWORD dst_unused:UNUSED_PAD src0_sel:DWORD src1_sel:WORD_1
	global_store_dwordx2 v[120:121], v[84:85], off offset:64
	s_nop 9
	v_cvt_pk_bf16_f32 v85, v132, v133
	v_cvt_pk_bf16_f32 v84, v130, v131
	global_store_dwordx2 v[118:119], v[84:85], off offset:64
	s_nop 9
	v_cvt_pk_bf16_f32 v85, v140, v141
	v_cvt_pk_bf16_f32 v84, v138, v139
	global_store_dwordx2 v[144:145], v[84:85], off offset:96
	s_nop 0
	v_and_b32_sdwa v84, v72, v142 dst_sel:DWORD dst_unused:UNUSED_PAD src0_sel:WORD_1 src1_sel:DWORD
	v_add3_u32 v72, v72, v84, s46
	s_nop 1
	v_and_b32_sdwa v84, v73, v142 dst_sel:DWORD dst_unused:UNUSED_PAD src0_sel:WORD_1 src1_sel:DWORD
	s_nop 0
	v_add3_u32 v73, v73, v84, s46
	s_nop 0
	v_and_b32_e32 v77, 0xffff0000, v73
	v_cvt_pk_bf16_f32 v73, v74, v75
	v_or_b32_sdwa v72, v77, v72 dst_sel:DWORD dst_unused:UNUSED_PAD src0_sel:DWORD src1_sel:WORD_1
	global_store_dwordx2 v[124:125], v[72:73], off offset:96
	s_nop 0
	v_and_b32_sdwa v73, v68, v142 dst_sel:DWORD dst_unused:UNUSED_PAD src0_sel:WORD_1 src1_sel:DWORD
	v_add3_u32 v68, v68, v73, s46
	s_nop 1
	v_and_b32_sdwa v73, v69, v142 dst_sel:DWORD dst_unused:UNUSED_PAD src0_sel:WORD_1 src1_sel:DWORD
	s_nop 0
	v_add3_u32 v69, v69, v73, s46
	s_nop 0
	v_and_b32_e32 v72, 0xffff0000, v69
	v_cvt_pk_bf16_f32 v69, v70, v71
	v_or_b32_sdwa v68, v72, v68 dst_sel:DWORD dst_unused:UNUSED_PAD src0_sel:DWORD src1_sel:WORD_1
	global_store_dwordx2 v[120:121], v[68:69], off offset:96
	s_nop 8
	v_cvt_pk_bf16_f32 v64, v64, v65
	s_nop 0
	v_and_b32_sdwa v69, v60, v142 dst_sel:DWORD dst_unused:UNUSED_PAD src0_sel:WORD_1 src1_sel:DWORD
	s_nop 1
	v_add3_u32 v60, v60, v69, s46
	v_and_b32_sdwa v69, v61, v142 dst_sel:DWORD dst_unused:UNUSED_PAD src0_sel:WORD_1 src1_sel:DWORD
	s_nop 0
	v_add3_u32 v61, v61, v69, s46
	s_nop 0
	v_and_b32_e32 v68, 0xffff0000, v61
	v_cvt_pk_bf16_f32 v61, v62, v63
	s_nop 0
	v_and_b32_sdwa v63, v56, v142 dst_sel:DWORD dst_unused:UNUSED_PAD src0_sel:WORD_1 src1_sel:DWORD
	s_nop 2
	v_add3_u32 v56, v56, v63, s46
	v_and_b32_sdwa v63, v57, v142 dst_sel:DWORD dst_unused:UNUSED_PAD src0_sel:WORD_1 src1_sel:DWORD
	s_nop 0
	v_cvt_pk_bf16_f32 v65, v66, v67
	v_add3_u32 v57, v57, v63, s46
	s_nop 0
	global_store_dwordx2 v[118:119], v[64:65], off offset:96
	v_or_b32_e32 v64, 1, v76
	v_and_b32_e32 v62, 0xffff0000, v57
	v_cvt_pk_bf16_f32 v57, v58, v59
	s_nop 0
	v_ashrrev_i32_e32 v65, 31, v64
	v_and_b32_sdwa v59, v52, v142 dst_sel:DWORD dst_unused:UNUSED_PAD src0_sel:WORD_1 src1_sel:DWORD
	s_nop 1
	v_lshlrev_b64 v[64:65], 17, v[64:65]
	v_add3_u32 v52, v52, v59, s46
	v_and_b32_sdwa v59, v53, v142 dst_sel:DWORD dst_unused:UNUSED_PAD src0_sel:WORD_1 src1_sel:DWORD
	s_nop 0
	v_lshl_add_u64 v[64:65], s[0:1], 0, v[64:65]
	v_add3_u32 v53, v53, v59, s46
	s_nop 0
	v_lshl_add_u64 v[64:65], v[64:65], 0, v[128:129]
	v_and_b32_e32 v58, 0xffff0000, v53
	v_cvt_pk_bf16_f32 v53, v54, v55
	s_nop 0
	v_and_b32_sdwa v55, v48, v142 dst_sel:DWORD dst_unused:UNUSED_PAD src0_sel:WORD_1 src1_sel:DWORD
	v_lshl_add_u64 v[66:67], v[64:65], 0, v[78:79]
	v_or_b32_sdwa v60, v68, v60 dst_sel:DWORD dst_unused:UNUSED_PAD src0_sel:DWORD src1_sel:WORD_1
	v_add3_u32 v48, v48, v55, s46
	s_nop 1
	v_and_b32_sdwa v55, v49, v142 dst_sel:DWORD dst_unused:UNUSED_PAD src0_sel:WORD_1 src1_sel:DWORD
	global_store_dwordx2 v[66:67], v[60:61], off
	v_lshl_add_u64 v[60:61], v[64:65], 0, v[80:81]
	v_or_b32_sdwa v56, v62, v56 dst_sel:DWORD dst_unused:UNUSED_PAD src0_sel:DWORD src1_sel:WORD_1
	s_nop 0
	v_add3_u32 v49, v49, v55, s46
	global_store_dwordx2 v[60:61], v[56:57], off
	v_lshl_add_u64 v[56:57], v[64:65], 0, v[82:83]
	v_or_b32_sdwa v52, v58, v52 dst_sel:DWORD dst_unused:UNUSED_PAD src0_sel:DWORD src1_sel:WORD_1
	s_nop 0
	v_and_b32_e32 v54, 0xffff0000, v49
	global_store_dwordx2 v[56:57], v[52:53], off
	v_lshl_add_u64 v[52:53], v[64:65], 0, v[116:117]
	v_cvt_pk_bf16_f32 v49, v50, v51
	v_or_b32_sdwa v48, v54, v48 dst_sel:DWORD dst_unused:UNUSED_PAD src0_sel:DWORD src1_sel:WORD_1
	global_store_dwordx2 v[52:53], v[48:49], off
	s_nop 0
	v_and_b32_sdwa v49, v44, v142 dst_sel:DWORD dst_unused:UNUSED_PAD src0_sel:WORD_1 src1_sel:DWORD
	v_add3_u32 v44, v44, v49, s46
	s_nop 1
	v_and_b32_sdwa v49, v45, v142 dst_sel:DWORD dst_unused:UNUSED_PAD src0_sel:WORD_1 src1_sel:DWORD
	s_nop 0
	v_add3_u32 v45, v45, v49, s46
	s_nop 0
	v_and_b32_e32 v48, 0xffff0000, v45
	v_cvt_pk_bf16_f32 v45, v46, v47
	v_or_b32_sdwa v44, v48, v44 dst_sel:DWORD dst_unused:UNUSED_PAD src0_sel:DWORD src1_sel:WORD_1
	global_store_dwordx2 v[66:67], v[44:45], off offset:32
	s_nop 0
	v_and_b32_sdwa v45, v40, v142 dst_sel:DWORD dst_unused:UNUSED_PAD src0_sel:WORD_1 src1_sel:DWORD
	v_add3_u32 v40, v40, v45, s46
	s_nop 1
	v_and_b32_sdwa v45, v41, v142 dst_sel:DWORD dst_unused:UNUSED_PAD src0_sel:WORD_1 src1_sel:DWORD
	s_nop 0
	v_add3_u32 v41, v41, v45, s46
	s_nop 0
	v_and_b32_e32 v44, 0xffff0000, v41
	v_cvt_pk_bf16_f32 v41, v42, v43
	v_or_b32_sdwa v40, v44, v40 dst_sel:DWORD dst_unused:UNUSED_PAD src0_sel:DWORD src1_sel:WORD_1
	global_store_dwordx2 v[60:61], v[40:41], off offset:32
	s_nop 0
	v_and_b32_sdwa v41, v36, v142 dst_sel:DWORD dst_unused:UNUSED_PAD src0_sel:WORD_1 src1_sel:DWORD
	v_add3_u32 v36, v36, v41, s46
	s_nop 1
	v_and_b32_sdwa v41, v37, v142 dst_sel:DWORD dst_unused:UNUSED_PAD src0_sel:WORD_1 src1_sel:DWORD
	s_nop 0
	v_add3_u32 v37, v37, v41, s46
	s_nop 0
	v_and_b32_e32 v40, 0xffff0000, v37
	v_cvt_pk_bf16_f32 v37, v38, v39
	v_or_b32_sdwa v36, v40, v36 dst_sel:DWORD dst_unused:UNUSED_PAD src0_sel:DWORD src1_sel:WORD_1
	global_store_dwordx2 v[56:57], v[36:37], off offset:32
	s_nop 0
	v_and_b32_sdwa v37, v32, v142 dst_sel:DWORD dst_unused:UNUSED_PAD src0_sel:WORD_1 src1_sel:DWORD
	v_add3_u32 v32, v32, v37, s46
	s_nop 1
	v_and_b32_sdwa v37, v33, v142 dst_sel:DWORD dst_unused:UNUSED_PAD src0_sel:WORD_1 src1_sel:DWORD
	s_nop 0
	v_add3_u32 v33, v33, v37, s46
	s_nop 0
	v_and_b32_e32 v36, 0xffff0000, v33
	v_cvt_pk_bf16_f32 v33, v34, v35
	v_or_b32_sdwa v32, v36, v32 dst_sel:DWORD dst_unused:UNUSED_PAD src0_sel:DWORD src1_sel:WORD_1
	global_store_dwordx2 v[52:53], v[32:33], off offset:32
	s_nop 0
	v_and_b32_sdwa v33, v28, v142 dst_sel:DWORD dst_unused:UNUSED_PAD src0_sel:WORD_1 src1_sel:DWORD
	v_add3_u32 v28, v28, v33, s46
	s_nop 1
	v_and_b32_sdwa v33, v29, v142 dst_sel:DWORD dst_unused:UNUSED_PAD src0_sel:WORD_1 src1_sel:DWORD
	s_nop 0
	v_add3_u32 v29, v29, v33, s46
	s_nop 0
	v_and_b32_e32 v32, 0xffff0000, v29
	v_cvt_pk_bf16_f32 v29, v30, v31
	v_or_b32_sdwa v28, v32, v28 dst_sel:DWORD dst_unused:UNUSED_PAD src0_sel:DWORD src1_sel:WORD_1
	global_store_dwordx2 v[66:67], v[28:29], off offset:64
	s_nop 0
	v_and_b32_sdwa v29, v24, v142 dst_sel:DWORD dst_unused:UNUSED_PAD src0_sel:WORD_1 src1_sel:DWORD
	v_add3_u32 v24, v24, v29, s46
	s_nop 1
	v_and_b32_sdwa v29, v25, v142 dst_sel:DWORD dst_unused:UNUSED_PAD src0_sel:WORD_1 src1_sel:DWORD
	s_nop 0
	v_add3_u32 v25, v25, v29, s46
	s_nop 0
	v_and_b32_e32 v28, 0xffff0000, v25
	v_cvt_pk_bf16_f32 v25, v26, v27
	v_or_b32_sdwa v24, v28, v24 dst_sel:DWORD dst_unused:UNUSED_PAD src0_sel:DWORD src1_sel:WORD_1
	global_store_dwordx2 v[60:61], v[24:25], off offset:64
	s_nop 0
	v_and_b32_sdwa v25, v20, v142 dst_sel:DWORD dst_unused:UNUSED_PAD src0_sel:WORD_1 src1_sel:DWORD
	v_add3_u32 v20, v20, v25, s46
	s_nop 1
	v_and_b32_sdwa v25, v21, v142 dst_sel:DWORD dst_unused:UNUSED_PAD src0_sel:WORD_1 src1_sel:DWORD
	s_nop 0
	v_add3_u32 v21, v21, v25, s46
	s_nop 0
	v_and_b32_e32 v24, 0xffff0000, v21
	v_cvt_pk_bf16_f32 v21, v22, v23
	v_or_b32_sdwa v20, v24, v20 dst_sel:DWORD dst_unused:UNUSED_PAD src0_sel:DWORD src1_sel:WORD_1
	global_store_dwordx2 v[56:57], v[20:21], off offset:64
	s_nop 0
	v_and_b32_sdwa v21, v16, v142 dst_sel:DWORD dst_unused:UNUSED_PAD src0_sel:WORD_1 src1_sel:DWORD
	v_add3_u32 v16, v16, v21, s46
	s_nop 1
	v_and_b32_sdwa v21, v17, v142 dst_sel:DWORD dst_unused:UNUSED_PAD src0_sel:WORD_1 src1_sel:DWORD
	s_nop 0
	v_add3_u32 v17, v17, v21, s46
	s_nop 0
	v_and_b32_e32 v20, 0xffff0000, v17
	v_cvt_pk_bf16_f32 v17, v18, v19
	v_or_b32_sdwa v16, v20, v16 dst_sel:DWORD dst_unused:UNUSED_PAD src0_sel:DWORD src1_sel:WORD_1
	global_store_dwordx2 v[52:53], v[16:17], off offset:64
	v_and_b32_sdwa v16, v14, v142 dst_sel:DWORD dst_unused:UNUSED_PAD src0_sel:WORD_1 src1_sel:DWORD
	v_and_b32_sdwa v17, v12, v142 dst_sel:DWORD dst_unused:UNUSED_PAD src0_sel:WORD_1 src1_sel:DWORD
	v_add3_u32 v12, v12, v17, s46
	v_add3_u32 v14, v14, v16, s46
	v_and_b32_sdwa v16, v15, v142 dst_sel:DWORD dst_unused:UNUSED_PAD src0_sel:WORD_1 src1_sel:DWORD
	v_and_b32_sdwa v17, v13, v142 dst_sel:DWORD dst_unused:UNUSED_PAD src0_sel:WORD_1 src1_sel:DWORD
	v_add3_u32 v15, v15, v16, s46
	v_add3_u32 v13, v13, v17, s46
	v_and_b32_e32 v15, 0xffff0000, v15
	v_and_b32_e32 v16, 0xffff0000, v13
	v_or_b32_sdwa v13, v15, v14 dst_sel:DWORD dst_unused:UNUSED_PAD src0_sel:DWORD src1_sel:WORD_1
	v_or_b32_sdwa v12, v16, v12 dst_sel:DWORD dst_unused:UNUSED_PAD src0_sel:DWORD src1_sel:WORD_1
	global_store_dwordx2 v[66:67], v[12:13], off offset:96
	v_and_b32_sdwa v12, v10, v142 dst_sel:DWORD dst_unused:UNUSED_PAD src0_sel:WORD_1 src1_sel:DWORD
	v_and_b32_sdwa v13, v8, v142 dst_sel:DWORD dst_unused:UNUSED_PAD src0_sel:WORD_1 src1_sel:DWORD
	v_add3_u32 v8, v8, v13, s46
	v_add3_u32 v10, v10, v12, s46
	v_and_b32_sdwa v12, v11, v142 dst_sel:DWORD dst_unused:UNUSED_PAD src0_sel:WORD_1 src1_sel:DWORD
	v_and_b32_sdwa v13, v9, v142 dst_sel:DWORD dst_unused:UNUSED_PAD src0_sel:WORD_1 src1_sel:DWORD
	v_add3_u32 v11, v11, v12, s46
	v_add3_u32 v9, v9, v13, s46
	v_and_b32_e32 v11, 0xffff0000, v11
	v_and_b32_e32 v12, 0xffff0000, v9
	v_or_b32_sdwa v9, v11, v10 dst_sel:DWORD dst_unused:UNUSED_PAD src0_sel:DWORD src1_sel:WORD_1
	v_or_b32_sdwa v8, v12, v8 dst_sel:DWORD dst_unused:UNUSED_PAD src0_sel:DWORD src1_sel:WORD_1
	global_store_dwordx2 v[60:61], v[8:9], off offset:96
	v_and_b32_sdwa v8, v6, v142 dst_sel:DWORD dst_unused:UNUSED_PAD src0_sel:WORD_1 src1_sel:DWORD
	v_and_b32_sdwa v9, v4, v142 dst_sel:DWORD dst_unused:UNUSED_PAD src0_sel:WORD_1 src1_sel:DWORD
	v_add3_u32 v4, v4, v9, s46
	v_add3_u32 v6, v6, v8, s46
	v_and_b32_sdwa v8, v7, v142 dst_sel:DWORD dst_unused:UNUSED_PAD src0_sel:WORD_1 src1_sel:DWORD
	v_and_b32_sdwa v9, v5, v142 dst_sel:DWORD dst_unused:UNUSED_PAD src0_sel:WORD_1 src1_sel:DWORD
	v_add3_u32 v7, v7, v8, s46
	v_add3_u32 v5, v5, v9, s46
	v_and_b32_e32 v7, 0xffff0000, v7
	v_and_b32_e32 v8, 0xffff0000, v5
	v_or_b32_sdwa v5, v7, v6 dst_sel:DWORD dst_unused:UNUSED_PAD src0_sel:DWORD src1_sel:WORD_1
	v_or_b32_sdwa v4, v8, v4 dst_sel:DWORD dst_unused:UNUSED_PAD src0_sel:DWORD src1_sel:WORD_1
	global_store_dwordx2 v[56:57], v[4:5], off offset:96
	v_and_b32_sdwa v4, v2, v142 dst_sel:DWORD dst_unused:UNUSED_PAD src0_sel:WORD_1 src1_sel:DWORD
	v_and_b32_sdwa v5, v0, v142 dst_sel:DWORD dst_unused:UNUSED_PAD src0_sel:WORD_1 src1_sel:DWORD
	v_add3_u32 v0, v0, v5, s46
	v_add3_u32 v2, v2, v4, s46
	v_and_b32_sdwa v4, v3, v142 dst_sel:DWORD dst_unused:UNUSED_PAD src0_sel:WORD_1 src1_sel:DWORD
	v_and_b32_sdwa v5, v1, v142 dst_sel:DWORD dst_unused:UNUSED_PAD src0_sel:WORD_1 src1_sel:DWORD
	v_add3_u32 v3, v3, v4, s46
	v_add3_u32 v1, v1, v5, s46
	v_and_b32_e32 v3, 0xffff0000, v3
	v_and_b32_e32 v4, 0xffff0000, v1
	v_readlane_b32 s52, v254, 58
	v_or_b32_sdwa v1, v3, v2 dst_sel:DWORD dst_unused:UNUSED_PAD src0_sel:DWORD src1_sel:WORD_1
	v_or_b32_sdwa v0, v4, v0 dst_sel:DWORD dst_unused:UNUSED_PAD src0_sel:DWORD src1_sel:WORD_1
	s_mov_b64 s[0:1], 0
	v_readlane_b32 s53, v254, 59
	global_store_dwordx2 v[52:53], v[0:1], off offset:96

.LBB0_1955:
	s_or_saveexec_b64 s[0:1], s[0:1]
	v_lshl_add_u64 v[140:141], s[94:95], 0, v[130:131]
	v_mov_b32_e32 v130, 1.0
	v_ashrrev_i32_e32 v131, 31, v128
	s_xor_b64 exec, exec, s[0:1]
	v_mov_b32_e32 v130, v128
	v_lshl_add_u64 v[138:139], v[130:131], 1, v[140:141]
	v_mov_b32_e32 v130, 0x3db504f3
	s_or_b64 exec, exec, s[0:1]
	v_mov_b32_e32 v144, v125
	v_mov_b32_e32 v145, v127
	v_mov_b32_e32 v125, v126
	v_mov_b32_e32 v126, v121
	v_mov_b32_e32 v127, v123
	v_pk_mul_f32 v[144:145], v[144:145], v[130:131] op_sel_hi:[1,0]
	v_pk_mul_f32 v[126:127], v[126:127], v[130:131] op_sel_hi:[1,0]
	v_mov_b32_e32 v121, v122
	v_pk_mul_f32 v[124:125], v[124:125], v[130:131] op_sel_hi:[1,0]
	v_pk_mul_f32 v[120:121], v[120:121], v[130:131] op_sel_hi:[1,0]
	s_nop 15
	s_nop 3
	v_cvt_pk_bf16_f32 v123, v125, v145
	v_cvt_pk_bf16_f32 v122, v124, v144
	v_cvt_pk_bf16_f32 v121, v121, v127
	v_cvt_pk_bf16_f32 v120, v120, v126
	global_store_dwordx4 v[138:139], v[120:123], off
	s_nop 1
	v_or_b32_e32 v120, 32, v128
	v_cmp_lt_i32_e64 s[6:7], s48, v120
	s_and_saveexec_b64 s[0:1], s[6:7]
	s_xor_b64 s[0:1], exec, s[0:1]
	s_cbranch_execz .LBB0_1963
	s_cmpk_lt_u32 s33, 0x400
	s_mov_b64 s[40:41], -1
	s_cbranch_scc1 .LBB0_1960
	v_lshl_add_u64 v[120:121], v[128:129], 1, v[136:137]
	v_lshl_add_u64 v[120:121], v[120:121], 0, s[36:37]
	s_mov_b64 s[40:41], 0

.LBB0_1962:
.LBB0_1963:
	s_or_saveexec_b64 s[0:1], s[0:1]
	v_mov_b32_e32 v122, 1.0
	s_xor_b64 exec, exec, s[0:1]
	v_mov_b32_e32 v130, v128
	v_lshl_add_u64 v[120:121], v[130:131], 1, v[140:141]
	v_lshl_add_u64 v[120:121], v[120:121], 0, 64
	v_mov_b32_e32 v122, 0x3db504f3
	s_or_b64 exec, exec, s[0:1]
	v_mov_b32_e32 v124, v117
	v_mov_b32_e32 v125, v119
	v_mov_b32_e32 v117, v118
	v_mov_b32_e32 v118, v113
	v_mov_b32_e32 v119, v115
	v_pk_mul_f32 v[124:125], v[124:125], v[122:123] op_sel_hi:[1,0]
	v_pk_mul_f32 v[118:119], v[118:119], v[122:123] op_sel_hi:[1,0]
	v_mov_b32_e32 v113, v114
	v_pk_mul_f32 v[116:117], v[116:117], v[122:123] op_sel_hi:[1,0]
	v_pk_mul_f32 v[112:113], v[112:113], v[122:123] op_sel_hi:[1,0]
	s_nop 15
	s_nop 3
	v_cvt_pk_bf16_f32 v115, v117, v125
	v_cvt_pk_bf16_f32 v114, v116, v124
	v_cvt_pk_bf16_f32 v113, v113, v119
	v_cvt_pk_bf16_f32 v112, v112, v118
	global_store_dwordx4 v[120:121], v[112:115], off
	v_readlane_b32 s0, v254, 62
	v_readlane_b32 s1, v254, 63
	v_or_b32_e32 v112, 16, v132
	v_ashrrev_i32_e32 v113, 31, v112
	v_lshlrev_b64 v[114:115], 11, v[112:113]
	v_lshlrev_b64 v[118:119], 10, v[112:113]
	v_lshl_add_u64 v[114:115], s[0:1], 0, v[114:115]
	v_lshl_add_u64 v[112:113], s[96:97], 0, v[118:119]
	s_and_saveexec_b64 s[0:1], s[4:5]
	s_xor_b64 s[0:1], exec, s[0:1]
	s_cbranch_execz .LBB0_1970
	s_cmpk_lt_u32 s33, 0x400
	s_mov_b64 s[40:41], -1
	s_cbranch_scc1 .LBB0_1968
	v_lshl_add_u64 v[116:117], v[128:129], 1, v[114:115]
	v_lshl_add_u64 v[116:117], v[116:117], 0, s[2:3]
	s_mov_b64 s[40:41], 0

.LBB0_1970:
	s_or_saveexec_b64 s[0:1], s[0:1]
	v_lshl_add_u64 v[118:119], s[94:95], 0, v[118:119]
	v_mov_b32_e32 v120, 1.0
	s_xor_b64 exec, exec, s[0:1]
	v_mov_b32_e32 v130, v128
	v_lshl_add_u64 v[116:117], v[130:131], 1, v[118:119]
	v_mov_b32_e32 v120, 0x3db504f3
	s_or_b64 exec, exec, s[0:1]
	v_mov_b32_e32 v122, v109
	v_mov_b32_e32 v123, v111
	v_mov_b32_e32 v109, v110
	v_mov_b32_e32 v110, v105
	v_mov_b32_e32 v111, v107
	v_pk_mul_f32 v[122:123], v[122:123], v[120:121] op_sel_hi:[1,0]
	v_pk_mul_f32 v[110:111], v[110:111], v[120:121] op_sel_hi:[1,0]
	v_mov_b32_e32 v105, v106
	v_pk_mul_f32 v[108:109], v[108:109], v[120:121] op_sel_hi:[1,0]
	v_pk_mul_f32 v[104:105], v[104:105], v[120:121] op_sel_hi:[1,0]
	s_nop 15
	s_nop 3
	v_cvt_pk_bf16_f32 v107, v109, v123
	v_cvt_pk_bf16_f32 v106, v108, v122
	v_cvt_pk_bf16_f32 v105, v105, v111
	v_cvt_pk_bf16_f32 v104, v104, v110
	global_store_dwordx4 v[116:117], v[104:107], off
	s_and_saveexec_b64 s[0:1], s[6:7]
	s_xor_b64 s[0:1], exec, s[0:1]
	s_cbranch_execz .LBB0_1978
	s_cmpk_lt_u32 s33, 0x400
	s_mov_b64 s[40:41], -1
	s_cbranch_scc1 .LBB0_1975
	v_lshl_add_u64 v[104:105], v[128:129], 1, v[114:115]
	v_lshl_add_u64 v[104:105], v[104:105], 0, s[36:37]
	s_mov_b64 s[40:41], 0

.LBB0_1977:
.LBB0_1978:
	s_or_saveexec_b64 s[0:1], s[0:1]
	v_mov_b32_e32 v106, 1.0
	s_xor_b64 exec, exec, s[0:1]
	v_mov_b32_e32 v130, v128
	v_lshl_add_u64 v[104:105], v[130:131], 1, v[118:119]
	v_lshl_add_u64 v[104:105], v[104:105], 0, 64
	v_mov_b32_e32 v106, 0x3db504f3
	s_or_b64 exec, exec, s[0:1]
	v_mov_b32_e32 v108, v101
	v_mov_b32_e32 v109, v103
	v_mov_b32_e32 v101, v102
	v_mov_b32_e32 v102, v97
	v_mov_b32_e32 v103, v99
	v_pk_mul_f32 v[108:109], v[108:109], v[106:107] op_sel_hi:[1,0]
	v_pk_mul_f32 v[102:103], v[102:103], v[106:107] op_sel_hi:[1,0]
	v_mov_b32_e32 v97, v98
	v_pk_mul_f32 v[100:101], v[100:101], v[106:107] op_sel_hi:[1,0]
	v_pk_mul_f32 v[96:97], v[96:97], v[106:107] op_sel_hi:[1,0]
	s_nop 15
	s_nop 3
	v_cvt_pk_bf16_f32 v99, v101, v109
	v_cvt_pk_bf16_f32 v98, v100, v108
	v_cvt_pk_bf16_f32 v97, v97, v103
	v_cvt_pk_bf16_f32 v96, v96, v102
	global_store_dwordx4 v[104:105], v[96:99], off
	v_readlane_b32 s0, v254, 62
	v_readlane_b32 s1, v254, 63
	v_or_b32_e32 v96, 32, v132
	v_ashrrev_i32_e32 v97, 31, v96
	v_lshlrev_b64 v[98:99], 11, v[96:97]
	v_lshlrev_b64 v[102:103], 10, v[96:97]
	v_lshl_add_u64 v[98:99], s[0:1], 0, v[98:99]
	v_lshl_add_u64 v[96:97], s[96:97], 0, v[102:103]
	s_and_saveexec_b64 s[0:1], s[4:5]
	s_xor_b64 s[0:1], exec, s[0:1]
	s_cbranch_execz .LBB0_1985
	s_cmpk_lt_u32 s33, 0x400
	s_mov_b64 s[40:41], -1
	s_cbranch_scc1 .LBB0_1983
	v_lshl_add_u64 v[100:101], v[128:129], 1, v[98:99]
	v_lshl_add_u64 v[100:101], v[100:101], 0, s[2:3]
	s_mov_b64 s[40:41], 0

.LBB0_1985:
	s_or_saveexec_b64 s[0:1], s[0:1]
	v_lshl_add_u64 v[102:103], s[94:95], 0, v[102:103]
	v_mov_b32_e32 v104, 1.0
	s_xor_b64 exec, exec, s[0:1]
	v_mov_b32_e32 v130, v128
	v_lshl_add_u64 v[100:101], v[130:131], 1, v[102:103]
	v_mov_b32_e32 v104, 0x3db504f3
	s_or_b64 exec, exec, s[0:1]
	v_mov_b32_e32 v106, v93
	v_mov_b32_e32 v107, v95
	v_mov_b32_e32 v93, v94
	v_mov_b32_e32 v94, v89
	v_mov_b32_e32 v95, v91
	v_pk_mul_f32 v[106:107], v[106:107], v[104:105] op_sel_hi:[1,0]
	v_pk_mul_f32 v[94:95], v[94:95], v[104:105] op_sel_hi:[1,0]
	v_mov_b32_e32 v89, v90
	v_pk_mul_f32 v[92:93], v[92:93], v[104:105] op_sel_hi:[1,0]
	v_pk_mul_f32 v[88:89], v[88:89], v[104:105] op_sel_hi:[1,0]
	s_nop 15
	s_nop 3
	v_cvt_pk_bf16_f32 v91, v93, v107
	v_cvt_pk_bf16_f32 v90, v92, v106
	v_cvt_pk_bf16_f32 v89, v89, v95
	v_cvt_pk_bf16_f32 v88, v88, v94
	global_store_dwordx4 v[100:101], v[88:91], off
	s_and_saveexec_b64 s[0:1], s[6:7]
	s_xor_b64 s[0:1], exec, s[0:1]
	s_cbranch_execz .LBB0_1993
	s_cmpk_lt_u32 s33, 0x400
	s_mov_b64 s[40:41], -1
	s_cbranch_scc1 .LBB0_1990
	v_lshl_add_u64 v[88:89], v[128:129], 1, v[98:99]
	v_lshl_add_u64 v[88:89], v[88:89], 0, s[36:37]
	s_mov_b64 s[40:41], 0

.LBB0_1992:
.LBB0_1993:
	s_or_saveexec_b64 s[0:1], s[0:1]
	v_mov_b32_e32 v90, 1.0
	s_xor_b64 exec, exec, s[0:1]
	v_mov_b32_e32 v130, v128
	v_lshl_add_u64 v[88:89], v[130:131], 1, v[102:103]
	v_lshl_add_u64 v[88:89], v[88:89], 0, 64
	v_mov_b32_e32 v90, 0x3db504f3
	s_or_b64 exec, exec, s[0:1]
	v_mov_b32_e32 v92, v85
	v_mov_b32_e32 v93, v87
	v_mov_b32_e32 v85, v86
	v_mov_b32_e32 v86, v81
	v_mov_b32_e32 v87, v83
	v_pk_mul_f32 v[92:93], v[92:93], v[90:91] op_sel_hi:[1,0]
	v_pk_mul_f32 v[86:87], v[86:87], v[90:91] op_sel_hi:[1,0]
	v_mov_b32_e32 v81, v82
	v_pk_mul_f32 v[84:85], v[84:85], v[90:91] op_sel_hi:[1,0]
	v_pk_mul_f32 v[80:81], v[80:81], v[90:91] op_sel_hi:[1,0]
	s_nop 15
	s_nop 3
	v_cvt_pk_bf16_f32 v83, v85, v93
	v_cvt_pk_bf16_f32 v82, v84, v92
	v_cvt_pk_bf16_f32 v81, v81, v87
	v_cvt_pk_bf16_f32 v80, v80, v86
	global_store_dwordx4 v[88:89], v[80:83], off
	v_readlane_b32 s0, v254, 62
	v_readlane_b32 s1, v254, 63
	v_or_b32_e32 v80, 48, v132
	v_ashrrev_i32_e32 v81, 31, v80
	v_lshlrev_b64 v[82:83], 11, v[80:81]
	v_lshlrev_b64 v[86:87], 10, v[80:81]
	v_lshl_add_u64 v[82:83], s[0:1], 0, v[82:83]
	v_lshl_add_u64 v[80:81], s[96:97], 0, v[86:87]
	s_and_saveexec_b64 s[0:1], s[4:5]
	s_xor_b64 s[0:1], exec, s[0:1]
	s_cbranch_execz .LBB0_2000
	s_cmpk_lt_u32 s33, 0x400
	s_mov_b64 s[40:41], -1
	s_cbranch_scc1 .LBB0_1998
	v_lshl_add_u64 v[84:85], v[128:129], 1, v[82:83]
	v_lshl_add_u64 v[84:85], v[84:85], 0, s[2:3]
	s_mov_b64 s[40:41], 0

.LBB0_2000:
	s_or_saveexec_b64 s[0:1], s[0:1]
	v_lshl_add_u64 v[86:87], s[94:95], 0, v[86:87]
	v_mov_b32_e32 v88, 1.0
	s_xor_b64 exec, exec, s[0:1]
	v_mov_b32_e32 v130, v128
	v_lshl_add_u64 v[84:85], v[130:131], 1, v[86:87]
	v_mov_b32_e32 v88, 0x3db504f3
	s_or_b64 exec, exec, s[0:1]
	v_mov_b32_e32 v90, v77
	v_mov_b32_e32 v91, v79
	v_mov_b32_e32 v77, v78
	v_mov_b32_e32 v78, v73
	v_mov_b32_e32 v79, v75
	v_pk_mul_f32 v[90:91], v[90:91], v[88:89] op_sel_hi:[1,0]
	v_pk_mul_f32 v[78:79], v[78:79], v[88:89] op_sel_hi:[1,0]
	v_mov_b32_e32 v73, v74
	v_pk_mul_f32 v[76:77], v[76:77], v[88:89] op_sel_hi:[1,0]
	v_pk_mul_f32 v[72:73], v[72:73], v[88:89] op_sel_hi:[1,0]
	s_nop 15
	s_nop 3
	v_cvt_pk_bf16_f32 v75, v77, v91
	v_cvt_pk_bf16_f32 v74, v76, v90
	v_cvt_pk_bf16_f32 v73, v73, v79
	v_cvt_pk_bf16_f32 v72, v72, v78
	global_store_dwordx4 v[84:85], v[72:75], off
	s_and_saveexec_b64 s[0:1], s[6:7]
	s_xor_b64 s[0:1], exec, s[0:1]
	s_cbranch_execz .LBB0_2008
	s_cmpk_lt_u32 s33, 0x400
	s_mov_b64 s[40:41], -1
	s_cbranch_scc1 .LBB0_2005
	v_lshl_add_u64 v[72:73], v[128:129], 1, v[82:83]
	v_lshl_add_u64 v[72:73], v[72:73], 0, s[36:37]
	s_mov_b64 s[40:41], 0

.LBB0_2007:
.LBB0_2008:
	s_or_saveexec_b64 s[0:1], s[0:1]
	v_mov_b32_e32 v74, 1.0
	s_xor_b64 exec, exec, s[0:1]
	v_mov_b32_e32 v130, v128
	v_lshl_add_u64 v[72:73], v[130:131], 1, v[86:87]
	v_lshl_add_u64 v[72:73], v[72:73], 0, 64
	v_mov_b32_e32 v74, 0x3db504f3
	s_or_b64 exec, exec, s[0:1]
	v_mov_b32_e32 v76, v69
	v_mov_b32_e32 v77, v71
	v_mov_b32_e32 v69, v70
	v_mov_b32_e32 v70, v65
	v_mov_b32_e32 v71, v67
	v_pk_mul_f32 v[76:77], v[76:77], v[74:75] op_sel_hi:[1,0]
	v_pk_mul_f32 v[70:71], v[70:71], v[74:75] op_sel_hi:[1,0]
	v_mov_b32_e32 v65, v66
	v_pk_mul_f32 v[68:69], v[68:69], v[74:75] op_sel_hi:[1,0]
	v_pk_mul_f32 v[64:65], v[64:65], v[74:75] op_sel_hi:[1,0]
	s_nop 15
	s_nop 3
	v_cvt_pk_bf16_f32 v67, v69, v77
	v_cvt_pk_bf16_f32 v66, v68, v76
	v_cvt_pk_bf16_f32 v65, v65, v71
	v_cvt_pk_bf16_f32 v64, v64, v70
	global_store_dwordx4 v[72:73], v[64:67], off
	v_readlane_b32 s0, v254, 62
	v_readlane_b32 s1, v254, 63
	v_or_b32_e32 v64, 64, v132
	v_ashrrev_i32_e32 v65, 31, v64
	v_lshlrev_b64 v[66:67], 11, v[64:65]
	v_lshlrev_b64 v[70:71], 10, v[64:65]
	v_lshl_add_u64 v[66:67], s[0:1], 0, v[66:67]
	v_lshl_add_u64 v[64:65], s[96:97], 0, v[70:71]
	s_and_saveexec_b64 s[0:1], s[4:5]
	s_xor_b64 s[0:1], exec, s[0:1]
	s_cbranch_execz .LBB0_2015
	s_cmpk_lt_u32 s33, 0x400
	s_mov_b64 s[40:41], -1
	s_cbranch_scc1 .LBB0_2013
	v_lshl_add_u64 v[68:69], v[128:129], 1, v[66:67]
	v_lshl_add_u64 v[68:69], v[68:69], 0, s[2:3]
	s_mov_b64 s[40:41], 0

.LBB0_2015:
	s_or_saveexec_b64 s[0:1], s[0:1]
	v_lshl_add_u64 v[70:71], s[94:95], 0, v[70:71]
	v_mov_b32_e32 v72, 1.0
	s_xor_b64 exec, exec, s[0:1]
	v_mov_b32_e32 v130, v128
	v_lshl_add_u64 v[68:69], v[130:131], 1, v[70:71]
	v_mov_b32_e32 v72, 0x3db504f3
	s_or_b64 exec, exec, s[0:1]
	v_mov_b32_e32 v74, v61
	v_mov_b32_e32 v75, v63
	v_mov_b32_e32 v61, v62
	v_mov_b32_e32 v62, v57
	v_mov_b32_e32 v63, v59
	v_pk_mul_f32 v[74:75], v[74:75], v[72:73] op_sel_hi:[1,0]
	v_pk_mul_f32 v[62:63], v[62:63], v[72:73] op_sel_hi:[1,0]
	v_mov_b32_e32 v57, v58
	v_pk_mul_f32 v[60:61], v[60:61], v[72:73] op_sel_hi:[1,0]
	v_pk_mul_f32 v[56:57], v[56:57], v[72:73] op_sel_hi:[1,0]
	s_nop 15
	s_nop 3
	v_cvt_pk_bf16_f32 v59, v61, v75
	v_cvt_pk_bf16_f32 v58, v60, v74
	v_cvt_pk_bf16_f32 v57, v57, v63
	v_cvt_pk_bf16_f32 v56, v56, v62
	global_store_dwordx4 v[68:69], v[56:59], off
	s_and_saveexec_b64 s[0:1], s[6:7]
	s_xor_b64 s[0:1], exec, s[0:1]
	s_cbranch_execz .LBB0_2023
	s_cmpk_lt_u32 s33, 0x400
	s_mov_b64 s[40:41], -1
	s_cbranch_scc1 .LBB0_2020
	v_lshl_add_u64 v[56:57], v[128:129], 1, v[66:67]
	v_lshl_add_u64 v[56:57], v[56:57], 0, s[36:37]
	s_mov_b64 s[40:41], 0

.LBB0_2022:
.LBB0_2023:
	s_or_saveexec_b64 s[0:1], s[0:1]
	v_mov_b32_e32 v58, 1.0
	s_xor_b64 exec, exec, s[0:1]
	v_mov_b32_e32 v130, v128
	v_lshl_add_u64 v[56:57], v[130:131], 1, v[70:71]
	v_lshl_add_u64 v[56:57], v[56:57], 0, 64
	v_mov_b32_e32 v58, 0x3db504f3
	s_or_b64 exec, exec, s[0:1]
	v_mov_b32_e32 v60, v53
	v_mov_b32_e32 v61, v55
	v_mov_b32_e32 v53, v54
	v_mov_b32_e32 v54, v49
	v_mov_b32_e32 v55, v51
	v_pk_mul_f32 v[60:61], v[60:61], v[58:59] op_sel_hi:[1,0]
	v_pk_mul_f32 v[54:55], v[54:55], v[58:59] op_sel_hi:[1,0]
	v_mov_b32_e32 v49, v50
	v_pk_mul_f32 v[52:53], v[52:53], v[58:59] op_sel_hi:[1,0]
	v_pk_mul_f32 v[48:49], v[48:49], v[58:59] op_sel_hi:[1,0]
	s_nop 15
	s_nop 3
	v_cvt_pk_bf16_f32 v51, v53, v61
	v_cvt_pk_bf16_f32 v50, v52, v60
	v_cvt_pk_bf16_f32 v49, v49, v55
	v_cvt_pk_bf16_f32 v48, v48, v54
	global_store_dwordx4 v[56:57], v[48:51], off
	v_readlane_b32 s0, v254, 62
	v_readlane_b32 s1, v254, 63
	v_or_b32_e32 v48, 0x50, v132
	v_ashrrev_i32_e32 v49, 31, v48
	v_lshlrev_b64 v[50:51], 11, v[48:49]
	v_lshlrev_b64 v[54:55], 10, v[48:49]
	v_lshl_add_u64 v[50:51], s[0:1], 0, v[50:51]
	v_lshl_add_u64 v[48:49], s[96:97], 0, v[54:55]
	s_and_saveexec_b64 s[0:1], s[4:5]
	s_xor_b64 s[0:1], exec, s[0:1]
	s_cbranch_execz .LBB0_2030
	s_cmpk_lt_u32 s33, 0x400
	s_mov_b64 s[40:41], -1
	s_cbranch_scc1 .LBB0_2028
	v_lshl_add_u64 v[52:53], v[128:129], 1, v[50:51]
	v_lshl_add_u64 v[52:53], v[52:53], 0, s[2:3]
	s_mov_b64 s[40:41], 0

.LBB0_2030:
	s_or_saveexec_b64 s[0:1], s[0:1]
	v_lshl_add_u64 v[54:55], s[94:95], 0, v[54:55]
	v_mov_b32_e32 v56, 1.0
	s_xor_b64 exec, exec, s[0:1]
	v_mov_b32_e32 v130, v128
	v_lshl_add_u64 v[52:53], v[130:131], 1, v[54:55]
	v_mov_b32_e32 v56, 0x3db504f3
	s_or_b64 exec, exec, s[0:1]
	v_mov_b32_e32 v58, v45
	v_mov_b32_e32 v59, v47
	v_mov_b32_e32 v45, v46
	v_mov_b32_e32 v46, v41
	v_mov_b32_e32 v47, v43
	v_pk_mul_f32 v[58:59], v[58:59], v[56:57] op_sel_hi:[1,0]
	v_pk_mul_f32 v[46:47], v[46:47], v[56:57] op_sel_hi:[1,0]
	v_mov_b32_e32 v41, v42
	v_pk_mul_f32 v[44:45], v[44:45], v[56:57] op_sel_hi:[1,0]
	v_pk_mul_f32 v[40:41], v[40:41], v[56:57] op_sel_hi:[1,0]
	s_nop 15
	s_nop 3
	v_cvt_pk_bf16_f32 v43, v45, v59
	v_cvt_pk_bf16_f32 v42, v44, v58
	v_cvt_pk_bf16_f32 v41, v41, v47
	v_cvt_pk_bf16_f32 v40, v40, v46
	global_store_dwordx4 v[52:53], v[40:43], off
	s_and_saveexec_b64 s[0:1], s[6:7]
	s_xor_b64 s[0:1], exec, s[0:1]
	s_cbranch_execz .LBB0_2038
	s_cmpk_lt_u32 s33, 0x400
	s_mov_b64 s[40:41], -1
	s_cbranch_scc1 .LBB0_2035
	v_lshl_add_u64 v[40:41], v[128:129], 1, v[50:51]
	v_lshl_add_u64 v[40:41], v[40:41], 0, s[36:37]
	s_mov_b64 s[40:41], 0

.LBB0_2037:
.LBB0_2038:
	s_or_saveexec_b64 s[0:1], s[0:1]
	v_mov_b32_e32 v42, 1.0
	s_xor_b64 exec, exec, s[0:1]
	v_mov_b32_e32 v130, v128
	v_lshl_add_u64 v[40:41], v[130:131], 1, v[54:55]
	v_lshl_add_u64 v[40:41], v[40:41], 0, 64
	v_mov_b32_e32 v42, 0x3db504f3
	s_or_b64 exec, exec, s[0:1]
	v_mov_b32_e32 v44, v37
	v_mov_b32_e32 v45, v39
	v_mov_b32_e32 v37, v38
	v_mov_b32_e32 v38, v33
	v_mov_b32_e32 v39, v35
	v_pk_mul_f32 v[44:45], v[44:45], v[42:43] op_sel_hi:[1,0]
	v_pk_mul_f32 v[38:39], v[38:39], v[42:43] op_sel_hi:[1,0]
	v_mov_b32_e32 v33, v34
	v_pk_mul_f32 v[36:37], v[36:37], v[42:43] op_sel_hi:[1,0]
	v_pk_mul_f32 v[32:33], v[32:33], v[42:43] op_sel_hi:[1,0]
	s_nop 15
	s_nop 3
	v_cvt_pk_bf16_f32 v35, v37, v45
	v_cvt_pk_bf16_f32 v34, v36, v44
	v_cvt_pk_bf16_f32 v33, v33, v39
	v_cvt_pk_bf16_f32 v32, v32, v38
	global_store_dwordx4 v[40:41], v[32:35], off
	v_readlane_b32 s0, v254, 62
	v_readlane_b32 s1, v254, 63
	v_or_b32_e32 v32, 0x60, v132
	v_ashrrev_i32_e32 v33, 31, v32
	v_lshlrev_b64 v[34:35], 11, v[32:33]
	v_lshlrev_b64 v[38:39], 10, v[32:33]
	v_lshl_add_u64 v[34:35], s[0:1], 0, v[34:35]
	v_lshl_add_u64 v[32:33], s[96:97], 0, v[38:39]
	s_and_saveexec_b64 s[0:1], s[4:5]
	s_xor_b64 s[0:1], exec, s[0:1]
	s_cbranch_execz .LBB0_2045
	s_cmpk_lt_u32 s33, 0x400
	s_mov_b64 s[40:41], -1
	s_cbranch_scc1 .LBB0_2043
	v_lshl_add_u64 v[36:37], v[128:129], 1, v[34:35]
	v_lshl_add_u64 v[36:37], v[36:37], 0, s[2:3]
	s_mov_b64 s[40:41], 0

.LBB0_2045:
	s_or_saveexec_b64 s[0:1], s[0:1]
	v_lshl_add_u64 v[38:39], s[94:95], 0, v[38:39]
	v_mov_b32_e32 v40, 1.0
	s_xor_b64 exec, exec, s[0:1]
	v_mov_b32_e32 v130, v128
	v_lshl_add_u64 v[36:37], v[130:131], 1, v[38:39]
	v_mov_b32_e32 v40, 0x3db504f3
	s_or_b64 exec, exec, s[0:1]
	v_mov_b32_e32 v42, v29
	v_mov_b32_e32 v43, v31
	v_mov_b32_e32 v29, v30
	v_mov_b32_e32 v30, v25
	v_mov_b32_e32 v31, v27
	v_pk_mul_f32 v[42:43], v[42:43], v[40:41] op_sel_hi:[1,0]
	v_pk_mul_f32 v[30:31], v[30:31], v[40:41] op_sel_hi:[1,0]
	v_mov_b32_e32 v25, v26
	v_pk_mul_f32 v[28:29], v[28:29], v[40:41] op_sel_hi:[1,0]
	v_pk_mul_f32 v[24:25], v[24:25], v[40:41] op_sel_hi:[1,0]
	s_nop 15
	s_nop 3
	v_cvt_pk_bf16_f32 v27, v29, v43
	v_cvt_pk_bf16_f32 v26, v28, v42
	v_cvt_pk_bf16_f32 v25, v25, v31
	v_cvt_pk_bf16_f32 v24, v24, v30
	global_store_dwordx4 v[36:37], v[24:27], off
	s_and_saveexec_b64 s[0:1], s[6:7]
	s_xor_b64 s[0:1], exec, s[0:1]
	s_cbranch_execz .LBB0_2053
	s_cmpk_lt_u32 s33, 0x400
	s_mov_b64 s[40:41], -1
	s_cbranch_scc1 .LBB0_2050
	v_lshl_add_u64 v[24:25], v[128:129], 1, v[34:35]
	v_lshl_add_u64 v[24:25], v[24:25], 0, s[36:37]
	s_mov_b64 s[40:41], 0

.LBB0_2052:
.LBB0_2053:
	s_or_saveexec_b64 s[0:1], s[0:1]
	v_mov_b32_e32 v26, 1.0
	s_xor_b64 exec, exec, s[0:1]
	v_mov_b32_e32 v130, v128
	v_lshl_add_u64 v[24:25], v[130:131], 1, v[38:39]
	v_lshl_add_u64 v[24:25], v[24:25], 0, 64
	v_mov_b32_e32 v26, 0x3db504f3
	s_or_b64 exec, exec, s[0:1]
	v_mov_b32_e32 v28, v21
	v_mov_b32_e32 v29, v23
	v_mov_b32_e32 v21, v22
	v_mov_b32_e32 v22, v17
	v_mov_b32_e32 v23, v19
	v_pk_mul_f32 v[28:29], v[28:29], v[26:27] op_sel_hi:[1,0]
	v_pk_mul_f32 v[22:23], v[22:23], v[26:27] op_sel_hi:[1,0]
	v_mov_b32_e32 v17, v18
	v_pk_mul_f32 v[20:21], v[20:21], v[26:27] op_sel_hi:[1,0]
	v_pk_mul_f32 v[16:17], v[16:17], v[26:27] op_sel_hi:[1,0]
	s_nop 15
	s_nop 3
	v_cvt_pk_bf16_f32 v19, v21, v29
	v_cvt_pk_bf16_f32 v18, v20, v28
	v_cvt_pk_bf16_f32 v17, v17, v23
	v_cvt_pk_bf16_f32 v16, v16, v22
	global_store_dwordx4 v[24:25], v[16:19], off
	v_readlane_b32 s0, v254, 62
	v_readlane_b32 s1, v254, 63
	v_or_b32_e32 v16, 0x70, v132
	v_ashrrev_i32_e32 v17, 31, v16
	v_lshlrev_b64 v[18:19], 11, v[16:17]
	v_lshlrev_b64 v[22:23], 10, v[16:17]
	v_lshl_add_u64 v[18:19], s[0:1], 0, v[18:19]
	v_lshl_add_u64 v[16:17], s[96:97], 0, v[22:23]
	s_and_saveexec_b64 s[0:1], s[4:5]
	s_xor_b64 s[0:1], exec, s[0:1]
	s_cbranch_execz .LBB0_2060
	s_cmpk_lt_u32 s33, 0x400
	s_mov_b64 s[4:5], -1
	s_cbranch_scc1 .LBB0_2058
	v_lshl_add_u64 v[20:21], v[128:129], 1, v[18:19]
	v_lshl_add_u64 v[20:21], v[20:21], 0, s[2:3]
	s_mov_b64 s[4:5], 0

.LBB0_2060:
	s_or_saveexec_b64 s[0:1], s[0:1]
	v_lshl_add_u64 v[22:23], s[94:95], 0, v[22:23]
	v_mov_b32_e32 v24, 1.0
	s_xor_b64 exec, exec, s[0:1]
	v_mov_b32_e32 v130, v128
	v_lshl_add_u64 v[20:21], v[130:131], 1, v[22:23]
	v_mov_b32_e32 v24, 0x3db504f3
	s_or_b64 exec, exec, s[0:1]
	v_mov_b32_e32 v26, v13
	v_mov_b32_e32 v27, v15
	v_mov_b32_e32 v13, v14
	v_mov_b32_e32 v14, v9
	v_mov_b32_e32 v15, v11
	v_pk_mul_f32 v[26:27], v[26:27], v[24:25] op_sel_hi:[1,0]
	v_pk_mul_f32 v[14:15], v[14:15], v[24:25] op_sel_hi:[1,0]
	v_mov_b32_e32 v9, v10
	v_pk_mul_f32 v[12:13], v[12:13], v[24:25] op_sel_hi:[1,0]
	v_pk_mul_f32 v[8:9], v[8:9], v[24:25] op_sel_hi:[1,0]
	s_nop 1
	v_bfe_u32 v24, v15, 16, 1
	v_bfe_u32 v25, v14, 16, 1
	v_add3_u32 v14, v14, v25, s46
	v_add3_u32 v15, v15, v24, s46
	s_nop 1
	v_bfe_u32 v11, v8, 16, 1
	v_bfe_u32 v25, v9, 16, 1
	s_nop 3
	v_add3_u32 v9, v9, v25, s46
	v_add3_u32 v8, v8, v11, s46
	v_lshrrev_b32_e32 v8, 16, v8
	v_lshrrev_b32_e32 v9, 16, v9
	s_nop 1
	v_cvt_pk_bf16_f32 v11, v13, v27
	v_cvt_pk_bf16_f32 v10, v12, v26
	v_and_or_b32 v9, v15, s47, v9
	v_and_or_b32 v8, v14, s47, v8
	global_store_dwordx4 v[20:21], v[8:11], off
	s_and_saveexec_b64 s[0:1], s[6:7]
	s_xor_b64 s[0:1], exec, s[0:1]
	s_cbranch_execz .LBB0_2068
	s_cmpk_lt_u32 s33, 0x400
	s_mov_b64 s[4:5], -1
	s_cbranch_scc1 .LBB0_2065
	v_lshl_add_u64 v[8:9], v[128:129], 1, v[18:19]
	v_lshl_add_u64 v[8:9], v[8:9], 0, s[36:37]
	s_mov_b64 s[4:5], 0

.LBB0_2091:
	s_andn2_b64 vcc, exec, s[8:9]
	s_cbranch_vccnz .LBB0_2093
	v_add_u32_e32 v18, 0xfffffc00, v20
	v_and_b32_sdwa v23, v15, v47 dst_sel:DWORD dst_unused:UNUSED_PAD src0_sel:WORD_1 src1_sel:DWORD
	s_nop 0
	v_lshlrev_b64 v[24:25], 7, v[18:19]
	v_and_b32_sdwa v18, v14, v47 dst_sel:DWORD dst_unused:UNUSED_PAD src0_sel:WORD_1 src1_sel:DWORD
	s_nop 0
	v_add3_u32 v23, v15, v23, s14
	s_nop 1
	v_add3_u32 v18, v14, v18, s14
	v_and_b32_e32 v23, 0xffff0000, v23
	s_nop 0
	v_lshl_add_u64 v[24:25], v[26:27], 0, v[24:25]
	v_or_b32_sdwa v37, v23, v18 dst_sel:DWORD dst_unused:UNUSED_PAD src0_sel:DWORD src1_sel:WORD_1
	v_cvt_pk_bf16_f32 v36, v12, v13
	global_store_dwordx2 v[24:25], v[36:37], off

.LBB0_2096:
	v_or_b32_e32 v24, v49, v42
	v_ashrrev_i32_e32 v25, 31, v24
	v_readlane_b32 s4, v254, 62
	v_lshlrev_b64 v[36:37], 11, v[24:25]
	v_or_b32_e32 v18, s16, v44
	v_readlane_b32 s5, v254, 63
	v_lshlrev_b64 v[40:41], 10, v[24:25]
	s_andn2_b64 vcc, exec, s[8:9]
	v_lshl_add_u64 v[38:39], s[4:5], 0, v[36:37]
	v_lshl_add_u64 v[36:37], s[96:97], 0, v[40:41]
	v_lshl_add_u64 v[40:41], s[94:95], 0, v[40:41]
	v_cmp_lt_i32_e64 s[4:5], s13, v18
	s_cbranch_vccnz .LBB0_2105
	s_and_saveexec_b64 s[8:9], s[4:5]
	s_xor_b64 s[4:5], exec, s[8:9]
	s_cbranch_execz .LBB0_2102
	s_nop 0
	v_and_b32_sdwa v23, v12, v47 dst_sel:DWORD dst_unused:UNUSED_PAD src0_sel:WORD_1 src1_sel:DWORD
	v_add3_u32 v12, v12, v23, s14
	s_nop 1
	v_and_b32_sdwa v23, v13, v47 dst_sel:DWORD dst_unused:UNUSED_PAD src0_sel:WORD_1 src1_sel:DWORD
	s_nop 0
	v_add3_u32 v13, v13, v23, s14
	s_nop 0
	v_and_b32_e32 v13, 0xffff0000, v13
	s_cmpk_gt_u32 s16, 0x3ff
	v_cvt_pk_bf16_f32 v15, v14, v15
	v_or_b32_sdwa v14, v13, v12 dst_sel:DWORD dst_unused:UNUSED_PAD src0_sel:DWORD src1_sel:WORD_1
	s_mov_b64 s[8:9], -1
	s_cbranch_scc0 .LBB0_2100
	v_lshl_add_u64 v[12:13], v[18:19], 1, v[38:39]
	global_store_dwordx2 v[12:13], v[14:15], off offset:-4096
	s_mov_b64 s[8:9], 0

.LBB0_2102:
	s_andn2_saveexec_b64 s[4:5], s[4:5]
	s_cbranch_execz .LBB0_2104
	v_mov_b32_e32 v50, v12
	v_mov_b32_e32 v51, v14
	v_pk_mul_f32 v[50:51], v[50:51], s[2:3] op_sel_hi:[1,0]
	v_mov_b32_e32 v14, v13
	v_pk_mul_f32 v[12:13], v[14:15], s[2:3] op_sel_hi:[1,0]
	s_nop 6
	v_ashrrev_i32_e32 v15, 31, v18
	v_mov_b32_e32 v14, v18
	s_nop 2
	v_lshl_add_u64 v[14:15], v[14:15], 1, v[40:41]
	v_cvt_pk_bf16_f32 v13, v51, v13
	v_cvt_pk_bf16_f32 v12, v50, v12
	global_store_dwordx2 v[14:15], v[12:13], off

.LBB0_2110:
	s_andn2_b64 vcc, exec, s[6:7]
	s_cbranch_vccnz .LBB0_2112
	s_nop 1
	v_add_u32_e32 v14, 0xfffffc00, v12
	v_mov_b32_e32 v15, v19
	s_nop 3
	v_lshlrev_b64 v[14:15], 7, v[14:15]
	s_nop 3
	v_lshl_add_u64 v[14:15], v[26:27], 0, v[14:15]
	v_cvt_pk_bf16_f32 v27, v10, v11
	v_cvt_pk_bf16_f32 v26, v8, v9
	global_store_dwordx2 v[14:15], v[26:27], off

.LBB0_2113:
	v_or_b32_e32 v50, 16, v18
	s_andn2_b64 vcc, exec, s[8:9]
	v_cmp_lt_i32_e64 s[6:7], s13, v50
	s_cbranch_vccnz .LBB0_2122
	s_and_saveexec_b64 s[8:9], s[6:7]
	s_xor_b64 s[6:7], exec, s[8:9]
	s_cbranch_execz .LBB0_2119
	s_nop 0
	v_and_b32_sdwa v14, v8, v47 dst_sel:DWORD dst_unused:UNUSED_PAD src0_sel:WORD_1 src1_sel:DWORD
	v_add3_u32 v8, v8, v14, s14
	s_nop 1
	v_and_b32_sdwa v14, v9, v47 dst_sel:DWORD dst_unused:UNUSED_PAD src0_sel:WORD_1 src1_sel:DWORD
	s_nop 0
	v_add3_u32 v9, v9, v14, s14
	s_nop 0
	v_and_b32_e32 v9, 0xffff0000, v9
	s_cmpk_lt_u32 s16, 0x400
	v_cvt_pk_bf16_f32 v11, v10, v11
	v_or_b32_sdwa v10, v9, v8 dst_sel:DWORD dst_unused:UNUSED_PAD src0_sel:DWORD src1_sel:WORD_1
	s_mov_b64 s[8:9], -1
	s_cbranch_scc1 .LBB0_2117
	v_lshl_add_u64 v[8:9], v[18:19], 1, v[38:39]
	s_mov_b64 s[8:9], 0
	global_store_dwordx2 v[8:9], v[10:11], off offset:-4064

.LBB0_2119:
	s_andn2_saveexec_b64 s[6:7], s[6:7]
	s_cbranch_execz .LBB0_2121
	v_mov_b32_e32 v14, v8
	v_mov_b32_e32 v15, v10
	v_pk_mul_f32 v[14:15], v[14:15], s[2:3] op_sel_hi:[1,0]
	v_mov_b32_e32 v10, v9
	v_pk_mul_f32 v[8:9], v[10:11], s[2:3] op_sel_hi:[1,0]
	s_nop 7
	v_ashrrev_i32_e32 v11, 31, v18
	v_mov_b32_e32 v10, v18
	s_nop 1
	v_lshl_add_u64 v[10:11], v[10:11], 1, v[40:41]
	v_cvt_pk_bf16_f32 v9, v15, v9
	v_cvt_pk_bf16_f32 v8, v14, v8
	global_store_dwordx2 v[10:11], v[8:9], off offset:32

.LBB0_2132:
	s_andn2_b64 vcc, exec, s[8:9]
	s_cbranch_vccnz .LBB0_2134
	v_and_b32_sdwa v23, v7, v47 dst_sel:DWORD dst_unused:UNUSED_PAD src0_sel:WORD_1 src1_sel:DWORD
	s_nop 0
	v_add_u32_e32 v20, 0xfffffc00, v20
	v_mov_b32_e32 v21, v19
	v_and_b32_sdwa v13, v6, v47 dst_sel:DWORD dst_unused:UNUSED_PAD src0_sel:WORD_1 src1_sel:DWORD
	s_nop 0
	v_add3_u32 v23, v7, v23, s14
	s_nop 0
	v_lshlrev_b64 v[20:21], 7, v[20:21]
	s_nop 0
	v_add3_u32 v13, v6, v13, s14
	v_and_b32_e32 v23, 0xffff0000, v23
	s_nop 0
	v_lshl_add_u64 v[20:21], v[8:9], 0, v[20:21]
	v_or_b32_sdwa v23, v23, v13 dst_sel:DWORD dst_unused:UNUSED_PAD src0_sel:DWORD src1_sel:WORD_1
	v_cvt_pk_bf16_f32 v22, v4, v5
	global_store_dwordx2 v[20:21], v[22:23], off

.LBB0_2145:
	s_andn2_saveexec_b64 s[6:7], s[6:7]
	s_cbranch_execz .LBB0_2147
	v_mov_b32_e32 v30, v4
	v_mov_b32_e32 v31, v6
	v_pk_mul_f32 v[30:31], v[30:31], s[2:3] op_sel_hi:[1,0]
	v_mov_b32_e32 v6, v5
	v_pk_mul_f32 v[4:5], v[6:7], s[2:3] op_sel_hi:[1,0]
	v_and_b32_sdwa v13, v31, v47 dst_sel:DWORD dst_unused:UNUSED_PAD src0_sel:WORD_1 src1_sel:DWORD
	s_nop 1
	v_add3_u32 v13, v31, v13, s14
	v_and_b32_sdwa v31, v5, v47 dst_sel:DWORD dst_unused:UNUSED_PAD src0_sel:WORD_1 src1_sel:DWORD
	s_nop 0
	v_add3_u32 v5, v5, v31, s14
	s_nop 0
	v_ashrrev_i32_e32 v7, 31, v18
	v_mov_b32_e32 v6, v18
	v_and_b32_e32 v5, 0xffff0000, v5
	s_nop 0
	v_lshl_add_u64 v[6:7], v[6:7], 1, v[24:25]
	v_or_b32_sdwa v5, v5, v13 dst_sel:DWORD dst_unused:UNUSED_PAD src0_sel:DWORD src1_sel:WORD_1
	v_cvt_pk_bf16_f32 v4, v30, v4
	global_store_dwordx2 v[6:7], v[4:5], off

.LBB0_2152:
	s_andn2_b64 vcc, exec, s[4:5]
	s_cbranch_vccnz .LBB0_2154
	v_add_u32_e32 v4, 0xfffffc00, v12
	v_mov_b32_e32 v5, v19
	v_lshlrev_b64 v[4:5], 7, v[4:5]
	v_and_b32_sdwa v7, v0, v47 dst_sel:DWORD dst_unused:UNUSED_PAD src0_sel:WORD_1 src1_sel:DWORD
	v_lshl_add_u64 v[4:5], v[8:9], 0, v[4:5]
	v_add3_u32 v8, v0, v7, s14
	s_nop 0
	v_and_b32_sdwa v9, v1, v47 dst_sel:DWORD dst_unused:UNUSED_PAD src0_sel:WORD_1 src1_sel:DWORD
	s_nop 1
	v_add3_u32 v9, v1, v9, s14
	s_nop 1
	v_and_b32_e32 v9, 0xffff0000, v9
	v_cvt_pk_bf16_f32 v7, v2, v3
	v_or_b32_sdwa v6, v9, v8 dst_sel:DWORD dst_unused:UNUSED_PAD src0_sel:DWORD src1_sel:WORD_1
	global_store_dwordx2 v[4:5], v[6:7], off

.LBB0_2424:
	ds_read_b128 v[76:79], v135 offset:27648
	ds_read_b128 v[80:83], v137 offset:45056
	ds_read_b128 v[84:87], v135 offset:27712
	ds_read_b128 v[88:91], v137 offset:45120
	ds_read_b128 v[92:95], v137 offset:49408
	ds_read_b128 v[96:99], v137 offset:49472
	ds_read_b128 v[100:103], v137 offset:53760
	ds_read_b128 v[104:107], v137 offset:53824
	ds_read_b128 v[108:111], v137 offset:58112
	ds_read_b128 v[112:115], v137 offset:58176
	s_waitcnt lgkmcnt(8)
	v_mfma_f32_16x16x32_bf16 v[80:83], v[76:79], v[80:83], 0
	s_nop 2
	s_waitcnt lgkmcnt(5)
	v_mfma_f32_16x16x32_bf16 v[92:95], v[76:79], v[92:95], 0
	s_nop 2
	s_waitcnt lgkmcnt(3)
	v_mfma_f32_16x16x32_bf16 v[100:103], v[76:79], v[100:103], 0
	s_nop 0
	v_cvt_pk_bf16_f32 v3, v6, v7
	s_nop 0
	s_waitcnt lgkmcnt(1)
	v_mfma_f32_16x16x32_bf16 v[76:79], v[76:79], v[108:111], 0
	ds_read_b128 v[108:111], v135 offset:27776
	ds_read_b128 v[116:119], v135 offset:27840
	s_nop 0
	v_add_u32_e32 v182, s59, v173
	v_mfma_f32_16x16x32_bf16 v[80:83], v[84:87], v[88:91], v[80:83]
	ds_read_b128 v[88:91], v137 offset:45184
	ds_read_b128 v[120:123], v137 offset:45248
	ds_read_b128 v[178:181], v137 offset:49536
	ds_read_b128 v[208:211], v137 offset:49600
	v_cmp_gt_i32_e64 s[46:47], s60, v173
	v_ashrrev_i32_e32 v183, 31, v182
	v_mfma_f32_16x16x32_bf16 v[92:95], v[84:87], v[96:99], v[92:95]
	ds_read_b128 v[96:99], v137 offset:53888
	ds_read_b128 v[212:215], v137 offset:53952
	ds_read_b128 v[216:219], v137 offset:58240
	ds_read_b128 v[220:223], v137 offset:58304
	v_mfma_f32_16x16x32_bf16 v[100:103], v[84:87], v[104:107], v[100:103]
	s_waitcnt lgkmcnt(10)
	v_mfma_f32_16x16x32_bf16 v[76:79], v[84:87], v[112:115], v[76:79]
	s_nop 0
	s_waitcnt lgkmcnt(7)
	v_mfma_f32_16x16x32_bf16 v[80:83], v[108:111], v[88:91], v[80:83]
	s_nop 1
	v_cvt_pk_bf16_f32 v2, v4, v5
	s_waitcnt lgkmcnt(5)
	v_mfma_f32_16x16x32_bf16 v[84:87], v[108:111], v[178:181], v[92:95]
	s_nop 2
	s_nop 4
	s_waitcnt lgkmcnt(3)
	v_mfma_f32_16x16x32_bf16 v[88:91], v[108:111], v[96:99], v[100:103]
	s_nop 4
	v_cvt_pk_bf16_f32 v93, v10, v11
	v_cvt_pk_bf16_f32 v92, v8, v9
	s_nop 9
	v_cvt_pk_bf16_f32 v95, v14, v15
	v_cvt_pk_bf16_f32 v94, v12, v13
	s_nop 9
	v_cvt_pk_bf16_f32 v97, v18, v19
	v_cvt_pk_bf16_f32 v96, v16, v17
	s_nop 7
	v_cvt_pk_bf16_f32 v99, v22, v23
	v_cvt_pk_bf16_f32 v98, v20, v21
	ds_write2_b64 v204, v[2:3], v[98:99] offset0:128 offset1:132
	s_nop 9
	v_cvt_pk_bf16_f32 v3, v26, v27
	v_cvt_pk_bf16_f32 v2, v24, v25
	ds_write2_b64 v205, v[92:93], v[2:3] offset0:128 offset1:132
	s_nop 9
	v_mfma_f32_16x16x32_bf16 v[80:83], v[116:119], v[120:123], v[80:83]
	v_cvt_pk_bf16_f32 v3, v30, v31
	v_cvt_pk_bf16_f32 v2, v28, v29
	ds_write2_b64 v206, v[94:95], v[2:3] offset0:128 offset1:132
	s_nop 9
	v_cvt_pk_bf16_f32 v3, v34, v35
	v_cvt_pk_bf16_f32 v2, v32, v33
	v_cndmask_b32_e64 v1, v80, 0, s[8:9]
	ds_write2_b64 v207, v[96:97], v[2:3] offset0:128 offset1:132
	v_bfe_u32 v2, v1, 16, 1
	v_add3_u32 v1, v1, v2, s33
	s_waitcnt lgkmcnt(0)
	s_barrier
	ds_write_b16_d16_hi v202, v1 offset:45056
	v_cndmask_b32_e64 v1, v81, 0, s[10:11]
	v_bfe_u32 v2, v1, 16, 1
	v_add3_u32 v1, v1, v2, s33
	ds_write_b16_d16_hi v202, v1 offset:45200
	v_cndmask_b32_e64 v1, v82, 0, s[12:13]
	v_bfe_u32 v2, v1, 16, 1
	v_mfma_f32_16x16x32_bf16 v[84:87], v[116:119], v[208:211], v[84:87]
	v_add3_u32 v1, v1, v2, s33
	ds_write_b16_d16_hi v202, v1 offset:45344
	v_cndmask_b32_e64 v1, v83, 0, s[14:15]
	v_bfe_u32 v2, v1, 16, 1
	v_add3_u32 v1, v1, v2, s33
	ds_write_b16_d16_hi v202, v1 offset:45488
	s_nop 1
	v_cndmask_b32_e64 v1, v84, 0, s[16:17]
	v_bfe_u32 v2, v1, 16, 1
	v_add3_u32 v1, v1, v2, s33
	ds_write_b16_d16_hi v202, v1 offset:45088
	v_cndmask_b32_e64 v1, v85, 0, s[18:19]
	v_bfe_u32 v2, v1, 16, 1
	v_add3_u32 v1, v1, v2, s33
	ds_write_b16_d16_hi v202, v1 offset:45232
	v_cndmask_b32_e64 v1, v86, 0, s[20:21]
	v_bfe_u32 v2, v1, 16, 1
	v_mfma_f32_16x16x32_bf16 v[88:91], v[116:119], v[212:215], v[88:91]
	v_add3_u32 v1, v1, v2, s33
	ds_write_b16_d16_hi v202, v1 offset:45376
	v_cndmask_b32_e64 v1, v87, 0, s[22:23]
	v_bfe_u32 v2, v1, 16, 1
	v_add3_u32 v1, v1, v2, s33
	ds_write_b16_d16_hi v202, v1 offset:45520
	s_nop 1
	v_cndmask_b32_e64 v1, v88, 0, s[24:25]
	v_bfe_u32 v2, v1, 16, 1
	v_add3_u32 v1, v1, v2, s33
	ds_write_b16_d16_hi v202, v1 offset:45120
	v_cndmask_b32_e64 v1, v89, 0, s[26:27]
	v_mfma_f32_16x16x32_bf16 v[76:79], v[108:111], v[216:219], v[76:79]
	v_bfe_u32 v2, v1, 16, 1
	v_add3_u32 v1, v1, v2, s33
	ds_write_b16_d16_hi v202, v1 offset:45264
	v_cndmask_b32_e64 v1, v90, 0, s[28:29]
	v_bfe_u32 v2, v1, 16, 1
	v_mfma_f32_16x16x32_bf16 v[76:79], v[116:119], v[220:223], v[76:79]
	v_add3_u32 v1, v1, v2, s33
	ds_write_b16_d16_hi v202, v1 offset:45408
	v_cndmask_b32_e64 v1, v91, 0, s[30:31]
	v_bfe_u32 v2, v1, 16, 1
	v_add3_u32 v1, v1, v2, s33
	ds_write_b16_d16_hi v202, v1 offset:45552
	s_nop 1
	v_cndmask_b32_e64 v1, v76, 0, s[34:35]
	v_bfe_u32 v2, v1, 16, 1
	v_add3_u32 v1, v1, v2, s33
	ds_write_b16_d16_hi v202, v1 offset:45152
	v_cndmask_b32_e64 v1, v77, 0, s[36:37]
	v_bfe_u32 v2, v1, 16, 1
	v_add3_u32 v1, v1, v2, s33
	ds_write_b16_d16_hi v202, v1 offset:45296
	v_cndmask_b32_e64 v1, v78, 0, s[38:39]
	v_bfe_u32 v2, v1, 16, 1
	v_add3_u32 v1, v1, v2, s33
	ds_write_b16_d16_hi v202, v1 offset:45440
	v_cndmask_b32_e64 v1, v79, 0, s[40:41]
	v_bfe_u32 v2, v1, 16, 1
	v_add3_u32 v1, v1, v2, s33
	ds_write_b16_d16_hi v202, v1 offset:45584
	s_waitcnt lgkmcnt(0)
	s_barrier
	ds_read_b128 v[108:111], v184 offset:45056
	ds_read_b128 v[92:95], v134 offset:18432
	ds_read_b128 v[112:115], v184 offset:45120
	ds_read_b128 v[88:91], v134 offset:18496
	ds_read_b128 v[96:99], v134 offset:20736
	ds_read_b128 v[84:87], v134 offset:20800
	ds_read_b128 v[100:103], v134 offset:23040
	ds_read_b128 v[80:83], v134 offset:23104
	ds_read_b128 v[104:107], v134 offset:25344
	ds_read_b128 v[76:79], v134 offset:25408
	ds_read_b128 v[208:211], v135 offset:27648
	s_waitcnt lgkmcnt(9)
	v_mfma_f32_16x16x32_bf16 v[116:119], v[108:111], v[92:95], 0
	s_waitcnt lgkmcnt(6)
	v_mfma_f32_16x16x32_bf16 v[120:123], v[108:111], v[96:99], 0
	s_waitcnt lgkmcnt(4)
	v_mfma_f32_16x16x32_bf16 v[178:181], v[108:111], v[100:103], 0
	s_waitcnt lgkmcnt(2)
	v_mfma_f32_16x16x32_bf16 v[108:111], v[108:111], v[104:107], 0
	v_mfma_f32_16x16x32_bf16 v[116:119], v[112:115], v[88:91], v[116:119]
	v_mfma_f32_16x16x32_bf16 v[120:123], v[112:115], v[84:87], v[120:123]
	v_mfma_f32_16x16x32_bf16 v[178:181], v[112:115], v[80:83], v[178:181]
	s_waitcnt lgkmcnt(1)
	v_mfma_f32_16x16x32_bf16 v[108:111], v[112:115], v[76:79], v[108:111]
	ds_read_b128 v[112:115], v137 offset:62464
	ds_read_b128 v[212:215], v135 offset:27712
	ds_read_b128 v[216:219], v137 offset:62528
	s_waitcnt lgkmcnt(2)
	v_mfma_f32_16x16x32_bf16 v[112:115], v[208:211], v[112:115], v[116:119]
	s_nop 2
	ds_read_b128 v[116:119], v185 offset:4352
	ds_read_b128 v[220:223], v185 offset:8704
	s_waitcnt lgkmcnt(1)
	v_mfma_f32_16x16x32_bf16 v[116:119], v[208:211], v[116:119], v[120:123]
	s_waitcnt lgkmcnt(0)
	v_mfma_f32_16x16x32_bf16 v[120:123], v[208:211], v[220:223], v[178:181]
	s_nop 2
	ds_read_b128 v[178:181], v185 offset:13056
	ds_read_b128 v[220:223], v186 offset:4352
	s_waitcnt lgkmcnt(1)
	v_mfma_f32_16x16x32_bf16 v[108:111], v[208:211], v[178:181], v[108:111]
	ds_read_b128 v[178:181], v186 offset:8704
	ds_read_b128 v[208:211], v186 offset:13056
	s_waitcnt lgkmcnt(1)
	v_mfma_f32_16x16x32_bf16 v[120:123], v[212:215], v[178:181], v[120:123]
	ds_read_b128 v[178:181], v135 offset:27776
	v_mfma_f32_16x16x32_bf16 v[112:115], v[212:215], v[216:219], v[112:115]
	v_mfma_f32_16x16x32_bf16 v[116:119], v[212:215], v[220:223], v[116:119]
	s_waitcnt lgkmcnt(1)
	v_mfma_f32_16x16x32_bf16 v[108:111], v[212:215], v[208:211], v[108:111]
	ds_read_b128 v[208:211], v137 offset:62592
	ds_read_b128 v[212:215], v135 offset:27840
	ds_read_b128 v[216:219], v137 offset:62656
	s_waitcnt lgkmcnt(2)
	v_mfma_f32_16x16x32_bf16 v[112:115], v[178:181], v[208:211], v[112:115]
	ds_read_b128 v[208:211], v187 offset:4352
	ds_read_b128 v[220:223], v187 offset:8704
	s_waitcnt lgkmcnt(1)
	v_mfma_f32_16x16x32_bf16 v[116:119], v[178:181], v[208:211], v[116:119]
	s_waitcnt lgkmcnt(0)
	v_mfma_f32_16x16x32_bf16 v[208:211], v[178:181], v[220:223], v[120:123]
	s_nop 2
	ds_read_b128 v[120:123], v187 offset:13056
	ds_read_b128 v[220:223], v188 offset:4352
	s_waitcnt lgkmcnt(1)
	v_mfma_f32_16x16x32_bf16 v[178:181], v[178:181], v[120:123], v[108:111]
	v_mfma_f32_16x16x32_bf16 v[108:111], v[212:215], v[216:219], v[112:115]
	s_nop 2
	ds_read_b128 v[112:115], v188 offset:8704
	ds_read_b128 v[216:219], v188 offset:13056
	s_waitcnt lgkmcnt(2)
	v_mfma_f32_16x16x32_bf16 v[120:123], v[212:215], v[220:223], v[116:119]
	s_waitcnt lgkmcnt(1)
	v_mfma_f32_16x16x32_bf16 v[116:119], v[212:215], v[112:115], v[208:211]
	s_waitcnt lgkmcnt(0)
	v_mfma_f32_16x16x32_bf16 v[112:115], v[212:215], v[216:219], v[178:181]
	s_and_saveexec_b64 s[42:43], s[46:47]
	s_cbranch_execz .LBB0_2426
	v_bfe_u32 v1, v108, 16, 1
	v_lshlrev_b64 v[2:3], 11, v[182:183]
	v_add3_u32 v1, v108, v1, s33
	v_lshl_add_u64 v[2:3], v[176:177], 0, v[2:3]
	global_store_short_d16_hi v[2:3], v1, off

.LBB0_2529:
	s_or_b64 exec, exec, s[8:9]
	s_waitcnt vmcnt(1)
	v_add_f32_e32 v50, v50, v51
	v_add_f32_e32 v50, v50, v52
	v_add_f32_e32 v50, v50, v53
	v_fmamk_f32 v50, v50, 0x3b800000, v70
	v_mul_f32_e32 v51, 0x4b800000, v50
	v_cmp_gt_f32_e64 s[8:9], s12, v50
	s_waitcnt vmcnt(0)
	v_lshlrev_b32_e32 v77, 16, v39
	v_lshlrev_b32_e32 v76, 16, v38
	v_cndmask_b32_e64 v50, v50, v51, s[8:9]
	v_rsq_f32_e32 v52, v50
	v_lshlrev_b32_e32 v50, 16, v46
	v_and_b32_e32 v46, 0xffff0000, v46
	v_mul_f32_e32 v72, 0xbfb8aa3b, v46
	v_mul_f32_e32 v53, 0x45800000, v52
	v_cndmask_b32_e64 v52, v52, v53, s[8:9]
	v_mul_f32_e32 v53, 0xbfb8aa3b, v50
	v_exp_f32_e32 v53, v53
	v_exp_f32_e32 v73, v72
	v_lshlrev_b32_e32 v51, 16, v47
	v_and_b32_e32 v47, 0xffff0000, v47
	v_add_f32_e32 v53, 1.0, v53
	v_rcp_f32_e32 v72, v53
	v_add_f32_e32 v53, 1.0, v73
	v_rcp_f32_e32 v74, v53
	v_mul_f32_e32 v53, 0xbfb8aa3b, v51
	v_exp_f32_e32 v53, v53
	v_and_b32_e32 v39, 0xffff0000, v39
	v_and_b32_e32 v38, 0xffff0000, v38
	v_pk_mul_f32 v[76:77], v[52:53], v[76:77] op_sel_hi:[0,1]
	v_add_f32_e32 v53, 1.0, v53
	v_rcp_f32_e32 v73, v53
	v_mul_f32_e32 v53, 0xbfb8aa3b, v47
	v_exp_f32_e32 v53, v53
	v_pk_mul_f32 v[76:77], v[0:1], v[76:77]
	v_pk_mul_f32 v[50:51], v[72:73], v[50:51]
	v_add_f32_e32 v53, 1.0, v53
	v_rcp_f32_e32 v75, v53
	v_pk_mul_f32 v[38:39], v[52:53], v[38:39] op_sel_hi:[0,1]
	v_pk_mul_f32 v[38:39], v[60:61], v[38:39]
	v_pk_mul_f32 v[50:51], v[76:77], v[50:51]
	v_pk_mul_f32 v[46:47], v[74:75], v[46:47]
	v_lshlrev_b32_e32 v77, 16, v41
	v_pk_mul_f32 v[38:39], v[38:39], v[46:47]
	v_lshlrev_b32_e32 v46, 16, v48
	v_mul_f32_e32 v53, 0xbfb8aa3b, v46
	v_and_b32_e32 v48, 0xffff0000, v48
	v_exp_f32_e32 v53, v53
	v_mul_f32_e32 v72, 0xbfb8aa3b, v48
	v_exp_f32_e32 v73, v72
	v_lshlrev_b32_e32 v47, 16, v49
	v_add_f32_e32 v53, 1.0, v53
	v_rcp_f32_e32 v72, v53
	v_add_f32_e32 v53, 1.0, v73
	v_rcp_f32_e32 v74, v53
	v_mul_f32_e32 v53, 0xbfb8aa3b, v47
	v_exp_f32_e32 v53, v53
	v_lshlrev_b32_e32 v76, 16, v40
	v_and_b32_e32 v49, 0xffff0000, v49
	v_and_b32_e32 v41, 0xffff0000, v41
	v_pk_mul_f32 v[76:77], v[52:53], v[76:77] op_sel_hi:[0,1]
	v_add_f32_e32 v53, 1.0, v53
	v_rcp_f32_e32 v73, v53
	v_mul_f32_e32 v53, 0xbfb8aa3b, v49
	v_exp_f32_e32 v53, v53
	v_and_b32_e32 v40, 0xffff0000, v40
	v_pk_mul_f32 v[76:77], v[4:5], v[76:77]
	v_pk_mul_f32 v[46:47], v[72:73], v[46:47]
	v_add_f32_e32 v53, 1.0, v53
	v_rcp_f32_e32 v75, v53
	v_pk_mul_f32 v[40:41], v[52:53], v[40:41] op_sel_hi:[0,1]
	v_pk_mul_f32 v[40:41], v[2:3], v[40:41]
	v_pk_mul_f32 v[46:47], v[76:77], v[46:47]
	v_pk_mul_f32 v[48:49], v[74:75], v[48:49]
	s_nop 0
	v_pk_mul_f32 v[40:41], v[40:41], v[48:49]
	s_nop 15
	s_nop 2
	v_cvt_pk_bf16_f32 v41, v47, v41
	v_cvt_pk_bf16_f32 v40, v46, v40
	v_cvt_pk_bf16_f32 v39, v51, v39
	v_cvt_pk_bf16_f32 v38, v50, v38
	global_store_dwordx4 v[68:69], v[38:41], off
	s_and_saveexec_b64 s[8:9], s[6:7]
	s_cbranch_execnz .LBB0_2532
	s_or_b64 exec, exec, s[8:9]
	s_and_saveexec_b64 s[6:7], s[4:5]
	s_cbranch_execnz .LBB0_2533

.LBB0_2532:
	v_add_f32_e32 v38, v43, v42
	v_add_f32_e32 v38, v44, v38
	v_add_f32_e32 v38, v45, v38
	v_fmamk_f32 v38, v38, 0x3b800000, v70
	v_mul_f32_e32 v39, 0x4b800000, v38
	v_cmp_gt_f32_e64 s[6:7], s12, v38
	v_lshlrev_b32_e32 v47, 16, v31
	v_lshlrev_b32_e32 v46, 16, v30
	v_cndmask_b32_e64 v38, v38, v39, s[6:7]
	v_rsq_f32_e32 v40, v38
	v_lshlrev_b32_e32 v38, 16, v34
	v_and_b32_e32 v34, 0xffff0000, v34
	v_mul_f32_e32 v42, 0xbfb8aa3b, v34
	v_mul_f32_e32 v41, 0x45800000, v40
	v_cndmask_b32_e64 v40, v40, v41, s[6:7]
	v_mul_f32_e32 v41, 0xbfb8aa3b, v38
	v_exp_f32_e32 v41, v41
	v_exp_f32_e32 v43, v42
	v_lshlrev_b32_e32 v39, 16, v35
	v_and_b32_e32 v35, 0xffff0000, v35
	v_add_f32_e32 v41, 1.0, v41
	v_rcp_f32_e32 v42, v41
	v_add_f32_e32 v41, 1.0, v43
	v_rcp_f32_e32 v44, v41
	v_mul_f32_e32 v41, 0xbfb8aa3b, v39
	v_exp_f32_e32 v41, v41
	v_and_b32_e32 v31, 0xffff0000, v31
	v_and_b32_e32 v30, 0xffff0000, v30
	v_pk_mul_f32 v[46:47], v[40:41], v[46:47] op_sel_hi:[0,1]
	v_add_f32_e32 v41, 1.0, v41
	v_rcp_f32_e32 v43, v41
	v_mul_f32_e32 v41, 0xbfb8aa3b, v35
	v_exp_f32_e32 v41, v41
	v_pk_mul_f32 v[46:47], v[0:1], v[46:47]
	v_pk_mul_f32 v[38:39], v[42:43], v[38:39]
	v_add_f32_e32 v41, 1.0, v41
	v_rcp_f32_e32 v45, v41
	v_pk_mul_f32 v[30:31], v[40:41], v[30:31] op_sel_hi:[0,1]
	v_pk_mul_f32 v[30:31], v[60:61], v[30:31]
	v_pk_mul_f32 v[38:39], v[46:47], v[38:39]
	v_pk_mul_f32 v[34:35], v[44:45], v[34:35]
	v_lshlrev_b32_e32 v47, 16, v33
	v_pk_mul_f32 v[30:31], v[30:31], v[34:35]
	v_lshlrev_b32_e32 v34, 16, v36
	v_mul_f32_e32 v41, 0xbfb8aa3b, v34
	v_and_b32_e32 v36, 0xffff0000, v36
	v_exp_f32_e32 v41, v41
	v_mul_f32_e32 v42, 0xbfb8aa3b, v36
	v_exp_f32_e32 v43, v42
	v_lshlrev_b32_e32 v35, 16, v37
	v_add_f32_e32 v41, 1.0, v41
	v_rcp_f32_e32 v42, v41
	v_add_f32_e32 v41, 1.0, v43
	v_rcp_f32_e32 v44, v41
	v_mul_f32_e32 v41, 0xbfb8aa3b, v35
	v_exp_f32_e32 v41, v41
	v_lshlrev_b32_e32 v46, 16, v32
	v_and_b32_e32 v37, 0xffff0000, v37
	v_and_b32_e32 v33, 0xffff0000, v33
	v_pk_mul_f32 v[46:47], v[40:41], v[46:47] op_sel_hi:[0,1]
	v_add_f32_e32 v41, 1.0, v41
	v_rcp_f32_e32 v43, v41
	v_mul_f32_e32 v41, 0xbfb8aa3b, v37
	v_exp_f32_e32 v41, v41
	v_and_b32_e32 v32, 0xffff0000, v32
	v_pk_mul_f32 v[46:47], v[4:5], v[46:47]
	v_pk_mul_f32 v[34:35], v[42:43], v[34:35]
	v_add_f32_e32 v41, 1.0, v41
	v_rcp_f32_e32 v45, v41
	v_pk_mul_f32 v[32:33], v[40:41], v[32:33] op_sel_hi:[0,1]
	v_pk_mul_f32 v[32:33], v[2:3], v[32:33]
	v_pk_mul_f32 v[34:35], v[46:47], v[34:35]
	v_pk_mul_f32 v[36:37], v[44:45], v[36:37]
	s_nop 0
	v_pk_mul_f32 v[32:33], v[32:33], v[36:37]
	s_nop 15
	s_nop 2
	v_cvt_pk_bf16_f32 v33, v35, v33
	v_cvt_pk_bf16_f32 v32, v34, v32
	v_lshlrev_b64 v[34:35], 11, v[66:67]
	v_cvt_pk_bf16_f32 v31, v39, v31
	v_cvt_pk_bf16_f32 v30, v38, v30
	v_lshl_add_u64 v[34:35], v[54:55], 0, v[34:35]
	global_store_dwordx4 v[34:35], v[30:33], off
	s_or_b64 exec, exec, s[8:9]
	s_and_saveexec_b64 s[6:7], s[4:5]
	s_cbranch_execz .LBB0_2531
.LBB0_2533:
	v_add_f32_e32 v18, v19, v18
	v_add_f32_e32 v18, v20, v18
	v_add_f32_e32 v18, v21, v18
	v_fmamk_f32 v18, v18, 0x3b800000, v70
	v_mul_f32_e32 v19, 0x4b800000, v18
	v_cmp_gt_f32_e64 s[4:5], s12, v18
	v_lshlrev_b32_e32 v35, 16, v15
	v_lshlrev_b32_e32 v34, 16, v14
	v_cndmask_b32_e64 v18, v18, v19, s[4:5]
	v_rsq_f32_e32 v20, v18
	v_lshlrev_b32_e32 v18, 16, v26
	v_and_b32_e32 v26, 0xffff0000, v26
	v_mul_f32_e32 v30, 0xbfb8aa3b, v26
	v_mul_f32_e32 v21, 0x45800000, v20
	v_cndmask_b32_e64 v20, v20, v21, s[4:5]
	v_mul_f32_e32 v21, 0xbfb8aa3b, v18
	v_exp_f32_e32 v21, v21
	v_exp_f32_e32 v31, v30
	v_lshlrev_b32_e32 v19, 16, v27
	v_and_b32_e32 v27, 0xffff0000, v27
	v_add_f32_e32 v21, 1.0, v21
	v_rcp_f32_e32 v30, v21
	v_add_f32_e32 v21, 1.0, v31
	v_rcp_f32_e32 v32, v21
	v_mul_f32_e32 v21, 0xbfb8aa3b, v19
	v_exp_f32_e32 v21, v21
	v_and_b32_e32 v15, 0xffff0000, v15
	v_and_b32_e32 v14, 0xffff0000, v14
	v_pk_mul_f32 v[34:35], v[20:21], v[34:35] op_sel_hi:[0,1]
	v_add_f32_e32 v21, 1.0, v21
	v_rcp_f32_e32 v31, v21
	v_mul_f32_e32 v21, 0xbfb8aa3b, v27
	v_exp_f32_e32 v21, v21
	v_pk_mul_f32 v[34:35], v[0:1], v[34:35]
	v_pk_mul_f32 v[18:19], v[30:31], v[18:19]
	v_add_f32_e32 v21, 1.0, v21
	v_rcp_f32_e32 v33, v21
	v_pk_mul_f32 v[14:15], v[20:21], v[14:15] op_sel_hi:[0,1]
	v_pk_mul_f32 v[14:15], v[60:61], v[14:15]
	v_pk_mul_f32 v[18:19], v[34:35], v[18:19]
	v_pk_mul_f32 v[26:27], v[32:33], v[26:27]
	v_lshlrev_b32_e32 v35, 16, v17
	v_pk_mul_f32 v[14:15], v[14:15], v[26:27]
	v_lshlrev_b32_e32 v26, 16, v28
	v_mul_f32_e32 v21, 0xbfb8aa3b, v26
	v_and_b32_e32 v28, 0xffff0000, v28
	v_exp_f32_e32 v21, v21
	v_mul_f32_e32 v30, 0xbfb8aa3b, v28
	v_exp_f32_e32 v31, v30
	v_lshlrev_b32_e32 v27, 16, v29
	v_add_f32_e32 v21, 1.0, v21
	v_rcp_f32_e32 v30, v21
	v_add_f32_e32 v21, 1.0, v31
	v_rcp_f32_e32 v32, v21
	v_mul_f32_e32 v21, 0xbfb8aa3b, v27
	v_exp_f32_e32 v21, v21
	v_lshlrev_b32_e32 v34, 16, v16
	v_and_b32_e32 v29, 0xffff0000, v29
	v_and_b32_e32 v17, 0xffff0000, v17
	v_pk_mul_f32 v[34:35], v[20:21], v[34:35] op_sel_hi:[0,1]
	v_add_f32_e32 v21, 1.0, v21
	v_rcp_f32_e32 v31, v21
	v_mul_f32_e32 v21, 0xbfb8aa3b, v29
	v_exp_f32_e32 v21, v21
	v_and_b32_e32 v16, 0xffff0000, v16
	v_pk_mul_f32 v[34:35], v[4:5], v[34:35]
	v_pk_mul_f32 v[26:27], v[30:31], v[26:27]
	v_add_f32_e32 v21, 1.0, v21
	v_rcp_f32_e32 v33, v21
	v_pk_mul_f32 v[16:17], v[20:21], v[16:17] op_sel_hi:[0,1]
	v_pk_mul_f32 v[16:17], v[2:3], v[16:17]
	v_pk_mul_f32 v[26:27], v[34:35], v[26:27]
	v_pk_mul_f32 v[20:21], v[32:33], v[28:29]
	s_nop 0
	v_pk_mul_f32 v[16:17], v[16:17], v[20:21]
	s_nop 15
	s_nop 2
	v_cvt_pk_bf16_f32 v15, v19, v15
	v_cvt_pk_bf16_f32 v14, v18, v14
	v_lshlrev_b64 v[18:19], 11, v[64:65]
	v_cvt_pk_bf16_f32 v17, v27, v17
	v_cvt_pk_bf16_f32 v16, v26, v16
	v_lshl_add_u64 v[18:19], v[54:55], 0, v[18:19]
	global_store_dwordx4 v[18:19], v[14:17], off
	s_or_b64 exec, exec, s[6:7]
	s_and_saveexec_b64 s[4:5], vcc
	s_cbranch_execz .LBB0_2522
.LBB0_2534:
	v_add_f32_e32 v14, v23, v22
	v_add_f32_e32 v14, v24, v14
	v_add_f32_e32 v14, v25, v14
	v_fmamk_f32 v14, v14, 0x3b800000, v70
	v_mul_f32_e32 v15, 0x4b800000, v14
	v_cmp_gt_f32_e32 vcc, s12, v14
	v_lshlrev_b32_e32 v23, 16, v11
	v_lshlrev_b32_e32 v22, 16, v10
	v_cndmask_b32_e32 v14, v14, v15, vcc
	v_rsq_f32_e32 v16, v14
	v_lshlrev_b32_e32 v14, 16, v6
	v_and_b32_e32 v6, 0xffff0000, v6
	v_mul_f32_e32 v18, 0xbfb8aa3b, v6
	v_mul_f32_e32 v17, 0x45800000, v16
	v_cndmask_b32_e32 v16, v16, v17, vcc
	v_mul_f32_e32 v17, 0xbfb8aa3b, v14
	v_exp_f32_e32 v17, v17
	v_exp_f32_e32 v19, v18
	v_lshlrev_b32_e32 v15, 16, v7
	v_and_b32_e32 v7, 0xffff0000, v7
	v_add_f32_e32 v17, 1.0, v17
	v_rcp_f32_e32 v18, v17
	v_add_f32_e32 v17, 1.0, v19
	v_rcp_f32_e32 v20, v17
	v_mul_f32_e32 v17, 0xbfb8aa3b, v15
	v_exp_f32_e32 v17, v17
	v_and_b32_e32 v11, 0xffff0000, v11
	v_and_b32_e32 v10, 0xffff0000, v10
	v_pk_mul_f32 v[22:23], v[16:17], v[22:23] op_sel_hi:[0,1]
	v_add_f32_e32 v17, 1.0, v17
	v_rcp_f32_e32 v19, v17
	v_mul_f32_e32 v17, 0xbfb8aa3b, v7
	v_exp_f32_e32 v17, v17
	v_pk_mul_f32 v[22:23], v[0:1], v[22:23]
	v_pk_mul_f32 v[14:15], v[18:19], v[14:15]
	v_add_f32_e32 v17, 1.0, v17
	v_rcp_f32_e32 v21, v17
	v_pk_mul_f32 v[10:11], v[16:17], v[10:11] op_sel_hi:[0,1]
	v_pk_mul_f32 v[10:11], v[60:61], v[10:11]
	v_pk_mul_f32 v[14:15], v[14:15], v[22:23]
	v_pk_mul_f32 v[6:7], v[20:21], v[6:7]
	v_lshlrev_b32_e32 v23, 16, v13
	v_pk_mul_f32 v[6:7], v[6:7], v[10:11]
	v_lshlrev_b32_e32 v10, 16, v8
	v_mul_f32_e32 v17, 0xbfb8aa3b, v10
	v_and_b32_e32 v8, 0xffff0000, v8
	v_exp_f32_e32 v17, v17
	v_mul_f32_e32 v18, 0xbfb8aa3b, v8
	v_exp_f32_e32 v19, v18
	v_lshlrev_b32_e32 v11, 16, v9
	v_add_f32_e32 v17, 1.0, v17
	v_rcp_f32_e32 v18, v17
	v_add_f32_e32 v17, 1.0, v19
	v_rcp_f32_e32 v20, v17
	v_mul_f32_e32 v17, 0xbfb8aa3b, v11
	v_exp_f32_e32 v17, v17
	v_lshlrev_b32_e32 v22, 16, v12
	v_and_b32_e32 v9, 0xffff0000, v9
	v_and_b32_e32 v13, 0xffff0000, v13
	v_pk_mul_f32 v[22:23], v[16:17], v[22:23] op_sel_hi:[0,1]
	v_add_f32_e32 v17, 1.0, v17
	v_rcp_f32_e32 v19, v17
	v_mul_f32_e32 v17, 0xbfb8aa3b, v9
	v_exp_f32_e32 v17, v17
	v_and_b32_e32 v12, 0xffff0000, v12
	v_pk_mul_f32 v[22:23], v[4:5], v[22:23]
	v_pk_mul_f32 v[10:11], v[18:19], v[10:11]
	v_add_f32_e32 v17, 1.0, v17
	v_rcp_f32_e32 v21, v17
	v_pk_mul_f32 v[12:13], v[16:17], v[12:13] op_sel_hi:[0,1]
	v_pk_mul_f32 v[12:13], v[2:3], v[12:13]
	v_pk_mul_f32 v[10:11], v[10:11], v[22:23]
	v_pk_mul_f32 v[8:9], v[20:21], v[8:9]
	s_nop 0
	v_pk_mul_f32 v[8:9], v[8:9], v[12:13]
	s_nop 15
	s_nop 2
	v_cvt_pk_bf16_f32 v9, v11, v9
	v_cvt_pk_bf16_f32 v8, v10, v8
	v_lshlrev_b64 v[10:11], 11, v[62:63]
	v_cvt_pk_bf16_f32 v7, v15, v7
	v_cvt_pk_bf16_f32 v6, v14, v6
	v_lshl_add_u64 v[10:11], v[54:55], 0, v[10:11]
	global_store_dwordx4 v[10:11], v[6:9], off
	s_branch .LBB0_2522
